# attn C: packed row-sum adds on top of no-max softmax; hyena twiddle LDS reads hoisted; residual epilogue loads hoisted
# speedup vs baseline: 1.0003x; 1.0003x over previous
.LBB0_723:
	v_or_b32_e32 v152, s2, v176
	v_mad_u32_u24 v172, v152, s30, v177
	ds_read_b64_tr_b16 v[80:81], v186
	ds_read_b64_tr_b16 v[82:83], v186 offset:768
	ds_read_b64_tr_b16 v[96:97], v186 offset:6144
	ds_read_b64_tr_b16 v[98:99], v186 offset:6912
	ds_read2_b64 v[100:103], v172 offset1:1
	v_add_u32_e32 v128, 0x2200, v172
	ds_read2_b64 v[84:87], v128 offset1:1
	v_add_u32_e32 v129, 0x4400, v172
	s_waitcnt lgkmcnt(1)
	v_mfma_f32_32x32x16_bf16 v[64:79], v[80:83], v[100:103], 0
	ds_read2_b64 v[88:91], v129 offset1:1
	ds_read_b64_tr_b16 v[104:105], v186 offset:3072
	ds_read_b64_tr_b16 v[106:107], v186 offset:3840
	ds_read_b64_tr_b16 v[108:109], v186 offset:9216
	ds_read_b64_tr_b16 v[110:111], v186 offset:9984
	ds_read2_b64 v[112:115], v172 offset0:4 offset1:5
	v_add_u32_e32 v173, 0x2220, v172
	ds_read2_b64 v[116:119], v173 offset1:1
	v_add_u32_e32 v204, 0x4420, v172
	ds_read2_b64 v[120:123], v204 offset1:1
	v_lshlrev_b32_e32 v205, 2, v152
	s_waitcnt lgkmcnt(7)
	v_mfma_f32_32x32x16_bf16 v[64:79], v[96:99], v[88:91], v[64:79]
	v_mfma_f32_32x32x16_bf16 v[80:95], v[80:83], v[84:87], 0
	v_mfma_f32_32x32x16_bf16 v[80:95], v[96:99], v[100:103], v[80:95]
	ds_read_b64_tr_b16 v[96:97], v186 offset:64
	ds_read_b64_tr_b16 v[98:99], v186 offset:832
	ds_read_b64_tr_b16 v[100:101], v186 offset:6208
	ds_read_b64_tr_b16 v[102:103], v186 offset:6976
	ds_read2_b64 v[124:127], v172 offset1:1
	ds_read2_b64 v[144:147], v128 offset1:1
	ds_read2_b64 v[148:151], v129 offset1:1
	s_waitcnt lgkmcnt(6)
	v_mul_u32_u24_e32 v233, v152, v178
	v_lshl_add_u32 v234, v233, 2, s26
	ds_read_b32 v235, v234
	v_add_u32_e32 v236, v234, v205
	ds_read_b32 v237, v236
	v_add_u32_e32 v238, v236, v205
	v_add_u32_e32 v239, v238, v205
	ds_read_b32 v240, v238
	ds_read_b32 v241, v239
	v_mul_u32_u24_e32 v242, 5, v152
	v_lshlrev_b32_e32 v243, 2, v242
	v_add_u32_e32 v244, v239, v243
	v_add_u32_e32 v245, v244, v205
	ds_read_b32 v246, v244
	ds_read_b32 v247, v245
	v_add_u32_e32 v248, v245, v205
	v_add_u32_e32 v249, v248, v205
	ds_read_b32 v250, v248
	ds_read_b32 v251, v249
	s_waitcnt lgkmcnt(15)
	v_mfma_f32_32x32x16_bf16 v[64:79], v[104:107], v[112:115], v[64:79]
	s_waitcnt lgkmcnt(15)
	v_mfma_f32_32x32x16_bf16 v[80:95], v[104:107], v[116:119], v[80:95]
	s_waitcnt lgkmcnt(15)
	v_mfma_f32_32x32x16_bf16 v[64:79], v[108:111], v[120:123], v[64:79]
	v_mfma_f32_32x32x16_bf16 v[80:95], v[108:111], v[112:115], v[80:95]
	s_waitcnt lgkmcnt(7)
	s_waitcnt lgkmcnt(6)
	v_add_u32_e32 v252, v249, v243
	v_add_u32_e32 v253, v252, v205
	ds_read_b32 v233, v252
	ds_read_b32 v234, v253
	v_add_u32_e32 v236, v253, v205
	v_add_u32_e32 v238, v236, v205
	ds_read_b32 v242, v236
	ds_read_b32 v239, v238
	v_add_u32_e32 v244, v238, v243
	v_add_u32_e32 v245, v244, v205
	ds_read_b32 v248, v244
	ds_read_b32 v249, v245
	v_add_u32_e32 v252, v245, v205
	v_add_u32_e32 v253, v252, v205
	ds_read_b32 v236, v252
	ds_read_b32 v238, v253
	v_mov_b32_e32 v206, v243
	v_mov_b32_e32 v207, v253
	v_cvt_f32_f16_e32 v104, v235
	v_cvt_f32_f16_sdwa v106, v235 dst_sel:DWORD dst_unused:UNUSED_PAD src0_sel:WORD_1
	s_waitcnt lgkmcnt(14)
	v_cvt_f32_f16_e32 v105, v237
	v_cvt_f32_f16_sdwa v107, v237 dst_sel:DWORD dst_unused:UNUSED_PAD src0_sel:WORD_1
	s_nop 3
	v_pk_mul_f32 v[108:109], v[80:81], v[106:107]
	s_nop 0
	v_pk_fma_f32 v[108:109], v[64:65], v[104:105], v[108:109] neg_lo:[0,0,1] neg_hi:[0,0,1]
	v_pk_mul_f32 v[64:65], v[64:65], v[106:107]
	v_cvt_pk_bf16_f32 v136, v108, v109
	v_pk_fma_f32 v[64:65], v[80:81], v[104:105], v[64:65]
	v_cvt_pk_bf16_f32 v140, v64, v65
	s_waitcnt lgkmcnt(13)
	v_cvt_f32_f16_e32 v80, v240
	s_waitcnt lgkmcnt(12)
	v_cvt_f32_f16_e32 v81, v241
	v_cvt_f32_f16_sdwa v105, v241 dst_sel:DWORD dst_unused:UNUSED_PAD src0_sel:WORD_1
	v_cvt_f32_f16_sdwa v104, v240 dst_sel:DWORD dst_unused:UNUSED_PAD src0_sel:WORD_1
	v_pk_mul_f32 v[106:107], v[82:83], v[104:105]
	s_nop 0
	v_pk_fma_f32 v[106:107], v[66:67], v[80:81], v[106:107] neg_lo:[0,0,1] neg_hi:[0,0,1]
	v_pk_mul_f32 v[66:67], v[66:67], v[104:105]
	v_cvt_pk_bf16_f32 v137, v106, v107
	v_pk_fma_f32 v[66:67], v[82:83], v[80:81], v[66:67]
	v_cvt_pk_bf16_f32 v141, v66, v67
	s_waitcnt lgkmcnt(11)
	v_cvt_f32_f16_e32 v80, v246
	s_waitcnt lgkmcnt(10)
	v_cvt_f32_f16_e32 v81, v247
	v_cvt_f32_f16_sdwa v82, v246 dst_sel:DWORD dst_unused:UNUSED_PAD src0_sel:WORD_1
	v_cvt_f32_f16_sdwa v83, v247 dst_sel:DWORD dst_unused:UNUSED_PAD src0_sel:WORD_1
	v_pk_mul_f32 v[104:105], v[84:85], v[82:83]
	s_nop 0
	v_pk_fma_f32 v[104:105], v[68:69], v[80:81], v[104:105] neg_lo:[0,0,1] neg_hi:[0,0,1]
	v_pk_mul_f32 v[68:69], v[68:69], v[82:83]
	v_cvt_pk_bf16_f32 v138, v104, v105
	v_pk_fma_f32 v[68:69], v[84:85], v[80:81], v[68:69]
	v_cvt_pk_bf16_f32 v142, v68, v69
	s_waitcnt lgkmcnt(9)
	v_cvt_f32_f16_e32 v80, v250
	s_waitcnt lgkmcnt(8)
	v_cvt_f32_f16_e32 v81, v251
	v_cvt_f32_f16_sdwa v82, v250 dst_sel:DWORD dst_unused:UNUSED_PAD src0_sel:WORD_1
	v_cvt_f32_f16_sdwa v83, v251 dst_sel:DWORD dst_unused:UNUSED_PAD src0_sel:WORD_1
	v_pk_mul_f32 v[84:85], v[86:87], v[82:83]
	s_nop 0
	v_pk_fma_f32 v[84:85], v[70:71], v[80:81], v[84:85] neg_lo:[0,0,1] neg_hi:[0,0,1]
	v_pk_mul_f32 v[70:71], v[70:71], v[82:83]
	v_cvt_pk_bf16_f32 v139, v84, v85
	v_pk_fma_f32 v[70:71], v[86:87], v[80:81], v[70:71]
	v_cvt_pk_bf16_f32 v143, v70, v71
	s_waitcnt lgkmcnt(7)
	v_cvt_f32_f16_e32 v80, v233
	s_waitcnt lgkmcnt(6)
	v_cvt_f32_f16_e32 v81, v234
	v_cvt_f32_f16_sdwa v82, v233 dst_sel:DWORD dst_unused:UNUSED_PAD src0_sel:WORD_1
	v_cvt_f32_f16_sdwa v83, v234 dst_sel:DWORD dst_unused:UNUSED_PAD src0_sel:WORD_1
	v_pk_mul_f32 v[86:87], v[88:89], v[82:83]
	s_nop 0
	v_pk_fma_f32 v[86:87], v[72:73], v[80:81], v[86:87] neg_lo:[0,0,1] neg_hi:[0,0,1]
	v_pk_mul_f32 v[72:73], v[72:73], v[82:83]
	v_cvt_pk_bf16_f32 v132, v86, v87
	v_pk_fma_f32 v[72:73], v[88:89], v[80:81], v[72:73]
	v_cvt_pk_bf16_f32 v128, v72, v73
	s_waitcnt lgkmcnt(5)
	v_cvt_f32_f16_e32 v80, v242
	s_waitcnt lgkmcnt(4)
	v_cvt_f32_f16_e32 v81, v239
	v_cvt_f32_f16_sdwa v82, v242 dst_sel:DWORD dst_unused:UNUSED_PAD src0_sel:WORD_1
	v_cvt_f32_f16_sdwa v83, v239 dst_sel:DWORD dst_unused:UNUSED_PAD src0_sel:WORD_1
	v_pk_mul_f32 v[88:89], v[90:91], v[82:83]
	s_nop 0
	v_pk_fma_f32 v[88:89], v[74:75], v[80:81], v[88:89] neg_lo:[0,0,1] neg_hi:[0,0,1]
	v_pk_mul_f32 v[74:75], v[74:75], v[82:83]
	v_cvt_pk_bf16_f32 v133, v88, v89
	v_pk_fma_f32 v[74:75], v[90:91], v[80:81], v[74:75]
	v_cvt_pk_bf16_f32 v129, v74, v75
	s_waitcnt lgkmcnt(3)
	v_cvt_f32_f16_e32 v80, v248
	s_waitcnt lgkmcnt(2)
	v_cvt_f32_f16_e32 v81, v249
	v_cvt_f32_f16_sdwa v82, v248 dst_sel:DWORD dst_unused:UNUSED_PAD src0_sel:WORD_1
	v_cvt_f32_f16_sdwa v83, v249 dst_sel:DWORD dst_unused:UNUSED_PAD src0_sel:WORD_1
	v_pk_mul_f32 v[90:91], v[92:93], v[82:83]
	s_nop 0
	v_pk_fma_f32 v[90:91], v[76:77], v[80:81], v[90:91] neg_lo:[0,0,1] neg_hi:[0,0,1]
	v_pk_mul_f32 v[76:77], v[76:77], v[82:83]
	v_cvt_pk_bf16_f32 v134, v90, v91
	v_pk_fma_f32 v[76:77], v[92:93], v[80:81], v[76:77]
	v_cvt_pk_bf16_f32 v130, v76, v77
	ds_read_b64_tr_b16 v[104:105], v186 offset:3136
	ds_read_b64_tr_b16 v[106:107], v186 offset:3904
	ds_read_b64_tr_b16 v[108:109], v186 offset:9280
	ds_read_b64_tr_b16 v[110:111], v186 offset:10048
	ds_read2_b64 v[112:115], v172 offset0:4 offset1:5
	ds_read2_b64 v[116:119], v173 offset1:1
	ds_read2_b64 v[120:123], v204 offset1:1
	s_waitcnt lgkmcnt(8)
	v_cvt_f32_f16_e32 v80, v236
	s_waitcnt lgkmcnt(7)
	v_cvt_f32_f16_e32 v81, v238
	v_cvt_f32_f16_sdwa v82, v236 dst_sel:DWORD dst_unused:UNUSED_PAD src0_sel:WORD_1
	v_cvt_f32_f16_sdwa v83, v238 dst_sel:DWORD dst_unused:UNUSED_PAD src0_sel:WORD_1
	s_waitcnt lgkmcnt(6)
	v_add_u32_e32 v244, v207, v206
	ds_read_b32 v245, v244
	v_add_u32_e32 v252, v244, v205
	ds_read_b32 v243, v252
	v_add_u32_e32 v253, v252, v205
	v_add_u32_e32 v235, v253, v205
	ds_read_b32 v237, v253
	ds_read_b32 v240, v235
	v_add_u32_e32 v241, v235, v206
	v_add_u32_e32 v246, v241, v205
	ds_read_b32 v247, v241
	ds_read_b32 v250, v246
	v_add_u32_e32 v251, v246, v205
	v_add_u32_e32 v233, v251, v205
	ds_read_b32 v234, v251
	ds_read_b32 v242, v233
	v_add_u32_e32 v204, 0x2000, v182
	v_pk_mul_f32 v[92:93], v[94:95], v[82:83]
	s_nop 0
	v_pk_fma_f32 v[92:93], v[78:79], v[80:81], v[92:93] neg_lo:[0,0,1] neg_hi:[0,0,1]
	v_pk_mul_f32 v[78:79], v[78:79], v[82:83]
	v_cvt_pk_bf16_f32 v135, v92, v93
	v_pk_fma_f32 v[78:79], v[94:95], v[80:81], v[78:79]
	v_mfma_f32_32x32x16_bf16 v[80:95], v[96:99], v[144:147], 0
	v_cvt_pk_bf16_f32 v131, v78, v79
	v_mfma_f32_32x32x16_bf16 v[64:79], v[96:99], v[124:127], 0
	v_mfma_f32_32x32x16_bf16 v[80:95], v[100:103], v[124:127], v[80:95]
	v_mfma_f32_32x32x16_bf16 v[64:79], v[100:103], v[148:151], v[64:79]
	s_waitcnt lgkmcnt(7)
	s_waitcnt lgkmcnt(6)
	v_add_u32_e32 v239, v233, v206
	v_add_u32_e32 v248, v239, v205
	ds_read_b32 v249, v239
	ds_read_b32 v236, v248
	v_add_u32_e32 v238, v248, v205
	v_add_u32_e32 v244, v238, v205
	ds_read_b32 v252, v238
	ds_read_b32 v253, v244
	v_add_u32_e32 v235, v244, v206
	v_add_u32_e32 v241, v235, v205
	ds_read_b32 v246, v235
	ds_read_b32 v251, v241
	v_add_u32_e32 v233, v241, v205
	ds_read_b32 v239, v233
	v_add_u32_e32 v248, v233, v205
	ds_read_b32 v238, v248
	v_cvt_f32_f16_e32 v96, v245
	v_cvt_f32_f16_sdwa v98, v245 dst_sel:DWORD dst_unused:UNUSED_PAD src0_sel:WORD_1
	s_waitcnt lgkmcnt(14)
	v_cvt_f32_f16_e32 v97, v243
	v_mfma_f32_32x32x16_bf16 v[80:95], v[104:107], v[116:119], v[80:95]
	v_cvt_f32_f16_sdwa v99, v243 dst_sel:DWORD dst_unused:UNUSED_PAD src0_sel:WORD_1
	v_mfma_f32_32x32x16_bf16 v[64:79], v[104:107], v[112:115], v[64:79]
	v_mfma_f32_32x32x16_bf16 v[80:95], v[108:111], v[112:115], v[80:95]
	v_mfma_f32_32x32x16_bf16 v[64:79], v[108:111], v[120:123], v[64:79]
	s_nop 10
	v_mul_f32_e64 v100, v80, v98
	v_mul_f32_e64 v101, v81, v99
	v_or_b32_e32 v120, v152, v180
	v_or_b32_e32 v152, v152, v179
	v_mov_b32_e32 v121, v153
	v_pk_fma_f32 v[100:101], v[64:65], v[96:97], v[100:101] neg_lo:[0,0,1] neg_hi:[0,0,1]
	v_pk_mul_f32 v[64:65], v[64:65], v[98:99]
	v_cvt_pk_bf16_f32 v116, v100, v101
	v_pk_fma_f32 v[64:65], v[80:81], v[96:97], v[64:65]
	v_cvt_pk_bf16_f32 v104, v64, v65
	v_lshl_add_u64 v[64:65], v[152:153], 2, s[22:23]
	s_waitcnt lgkmcnt(13)
	v_cvt_f32_f16_e32 v80, v237
	s_waitcnt lgkmcnt(12)
	v_cvt_f32_f16_e32 v81, v240
	v_cvt_f32_f16_sdwa v96, v237 dst_sel:DWORD dst_unused:UNUSED_PAD src0_sel:WORD_1
	v_cvt_f32_f16_sdwa v97, v240 dst_sel:DWORD dst_unused:UNUSED_PAD src0_sel:WORD_1
	v_pk_mul_f32 v[98:99], v[82:83], v[96:97]
	s_nop 0
	v_pk_fma_f32 v[98:99], v[66:67], v[80:81], v[98:99] neg_lo:[0,0,1] neg_hi:[0,0,1]
	v_pk_mul_f32 v[66:67], v[66:67], v[96:97]
	v_cvt_pk_bf16_f32 v117, v98, v99
	v_pk_fma_f32 v[66:67], v[82:83], v[80:81], v[66:67]
	v_cvt_pk_bf16_f32 v105, v66, v67
	s_waitcnt lgkmcnt(11)
	v_cvt_f32_f16_e32 v80, v247
	s_waitcnt lgkmcnt(10)
	v_cvt_f32_f16_e32 v81, v250
	v_cvt_f32_f16_sdwa v82, v247 dst_sel:DWORD dst_unused:UNUSED_PAD src0_sel:WORD_1
	v_cvt_f32_f16_sdwa v83, v250 dst_sel:DWORD dst_unused:UNUSED_PAD src0_sel:WORD_1
	v_pk_mul_f32 v[96:97], v[84:85], v[82:83]
	s_nop 0
	v_pk_fma_f32 v[96:97], v[68:69], v[80:81], v[96:97] neg_lo:[0,0,1] neg_hi:[0,0,1]
	v_pk_mul_f32 v[68:69], v[68:69], v[82:83]
	v_cvt_pk_bf16_f32 v118, v96, v97
	v_pk_fma_f32 v[68:69], v[84:85], v[80:81], v[68:69]
	v_cvt_pk_bf16_f32 v106, v68, v69
	s_waitcnt lgkmcnt(9)
	v_cvt_f32_f16_e32 v80, v234
	s_waitcnt lgkmcnt(8)
	v_cvt_f32_f16_e32 v81, v242
	v_cvt_f32_f16_sdwa v82, v234 dst_sel:DWORD dst_unused:UNUSED_PAD src0_sel:WORD_1
	v_cvt_f32_f16_sdwa v83, v242 dst_sel:DWORD dst_unused:UNUSED_PAD src0_sel:WORD_1
	v_pk_mul_f32 v[84:85], v[86:87], v[82:83]
	s_nop 0
	v_pk_fma_f32 v[84:85], v[70:71], v[80:81], v[84:85] neg_lo:[0,0,1] neg_hi:[0,0,1]
	v_pk_mul_f32 v[70:71], v[70:71], v[82:83]
	v_cvt_pk_bf16_f32 v119, v84, v85
	v_pk_fma_f32 v[70:71], v[86:87], v[80:81], v[70:71]
	v_cvt_pk_bf16_f32 v107, v70, v71
	s_waitcnt lgkmcnt(7)
	v_cvt_f32_f16_e32 v80, v249
	s_waitcnt lgkmcnt(6)
	v_cvt_f32_f16_e32 v81, v236
	v_cvt_f32_f16_sdwa v82, v249 dst_sel:DWORD dst_unused:UNUSED_PAD src0_sel:WORD_1
	v_cvt_f32_f16_sdwa v83, v236 dst_sel:DWORD dst_unused:UNUSED_PAD src0_sel:WORD_1
	v_pk_mul_f32 v[86:87], v[88:89], v[82:83]
	s_nop 0
	v_pk_fma_f32 v[86:87], v[72:73], v[80:81], v[86:87] neg_lo:[0,0,1] neg_hi:[0,0,1]
	v_pk_mul_f32 v[72:73], v[72:73], v[82:83]
	v_cvt_pk_bf16_f32 v100, v86, v87
	v_pk_fma_f32 v[72:73], v[88:89], v[80:81], v[72:73]
	v_cvt_pk_bf16_f32 v108, v72, v73
	s_waitcnt lgkmcnt(5)
	v_cvt_f32_f16_e32 v80, v252
	s_waitcnt lgkmcnt(4)
	v_cvt_f32_f16_e32 v81, v253
	v_cvt_f32_f16_sdwa v82, v252 dst_sel:DWORD dst_unused:UNUSED_PAD src0_sel:WORD_1
	v_cvt_f32_f16_sdwa v83, v253 dst_sel:DWORD dst_unused:UNUSED_PAD src0_sel:WORD_1
	v_pk_mul_f32 v[88:89], v[90:91], v[82:83]
	s_nop 0
	v_pk_fma_f32 v[88:89], v[74:75], v[80:81], v[88:89] neg_lo:[0,0,1] neg_hi:[0,0,1]
	v_pk_mul_f32 v[74:75], v[74:75], v[82:83]
	v_cvt_pk_bf16_f32 v101, v88, v89
	v_pk_fma_f32 v[74:75], v[90:91], v[80:81], v[74:75]
	v_cvt_pk_bf16_f32 v109, v74, v75
	s_waitcnt lgkmcnt(3)
	v_cvt_f32_f16_e32 v80, v246
	s_waitcnt lgkmcnt(2)
	v_cvt_f32_f16_e32 v81, v251
	v_cvt_f32_f16_sdwa v82, v246 dst_sel:DWORD dst_unused:UNUSED_PAD src0_sel:WORD_1
	v_cvt_f32_f16_sdwa v83, v251 dst_sel:DWORD dst_unused:UNUSED_PAD src0_sel:WORD_1
	v_pk_mul_f32 v[90:91], v[92:93], v[82:83]
	s_nop 0
	v_pk_fma_f32 v[90:91], v[76:77], v[80:81], v[90:91] neg_lo:[0,0,1] neg_hi:[0,0,1]
	v_pk_mul_f32 v[76:77], v[76:77], v[82:83]
	s_nop 0
	v_pk_fma_f32 v[76:77], v[92:93], v[80:81], v[76:77]
	global_load_dword v152, v[64:65], off
	global_load_dword v172, v[64:65], off offset:256
	global_load_dword v150, v[64:65], off offset:512
	global_load_dword v151, v[64:65], off offset:768
	global_load_dword v148, v[64:65], off offset:2048
	global_load_dword v149, v[64:65], off offset:2304
	global_load_dword v146, v[64:65], off offset:2560
	global_load_dword v147, v[64:65], off offset:2816
	v_add_co_u32_e32 v64, vcc, s0, v64
	s_waitcnt lgkmcnt(1)
	v_cvt_f32_f16_e32 v80, v239
	s_waitcnt lgkmcnt(0)
	v_cvt_f32_f16_e32 v81, v238
	v_cvt_f32_f16_sdwa v82, v239 dst_sel:DWORD dst_unused:UNUSED_PAD src0_sel:WORD_1
	v_cvt_f32_f16_sdwa v83, v238 dst_sel:DWORD dst_unused:UNUSED_PAD src0_sel:WORD_1
	v_addc_co_u32_e32 v65, vcc, 0, v65, vcc
	global_load_dword v144, v[64:65], off
	global_load_dword v145, v[64:65], off offset:256
	global_load_dword v126, v[64:65], off offset:512
	global_load_dword v127, v[64:65], off offset:768
	global_load_dword v124, v[64:65], off offset:2048
	global_load_dword v125, v[64:65], off offset:2304
	global_load_dword v122, v[64:65], off offset:2560
	global_load_dword v123, v[64:65], off offset:2816
	ds_read2_b64 v[112:115], v182 offset1:2
	ds_read2_b64 v[96:99], v182 offset0:4 offset1:6
	v_pk_mul_f32 v[92:93], v[94:95], v[82:83]
	v_cvt_pk_bf16_f32 v110, v76, v77
	v_pk_fma_f32 v[92:93], v[78:79], v[80:81], v[92:93] neg_lo:[0,0,1] neg_hi:[0,0,1]
	v_pk_mul_f32 v[78:79], v[78:79], v[82:83]
	v_add_u32_e32 v205, 0x4000, v182
	v_pk_fma_f32 v[78:79], v[94:95], v[80:81], v[78:79]
	ds_read2_b64 v[80:83], v204 offset0:64 offset1:66
	v_cvt_pk_bf16_f32 v111, v78, v79
	s_waitcnt lgkmcnt(2)
	v_mfma_f32_32x32x16_bf16 v[64:79], v[112:115], v[136:139], 0
	ds_read2_b64 v[84:87], v205 offset0:128 offset1:130
	ds_read2_b64 v[206:209], v204 offset0:68 offset1:70
	ds_read2_b64 v[210:213], v205 offset0:132 offset1:134
	v_cvt_pk_bf16_f32 v102, v90, v91
	v_cvt_pk_bf16_f32 v103, v92, v93
	s_waitcnt lgkmcnt(2)
	v_mfma_f32_32x32x16_bf16 v[64:79], v[84:87], v[140:143], v[64:79]
	v_mfma_f32_32x32x16_bf16 v[80:95], v[80:83], v[136:139], 0
	v_mfma_f32_32x32x16_bf16 v[80:95], v[112:115], v[140:143], v[80:95]
	ds_read2_b64 v[112:115], v182 offset0:8 offset1:10
	ds_read2_b64 v[214:217], v204 offset0:72 offset1:74
	ds_read2_b64 v[218:221], v205 offset0:136 offset1:138
	s_waitcnt lgkmcnt(4)
	v_mfma_f32_32x32x16_bf16 v[80:95], v[206:209], v[132:135], v[80:95]
	v_mfma_f32_32x32x16_bf16 v[64:79], v[96:99], v[132:135], v[64:79]
	v_mfma_f32_32x32x16_bf16 v[80:95], v[96:99], v[128:131], v[80:95]
	s_waitcnt lgkmcnt(3)
	v_mfma_f32_32x32x16_bf16 v[64:79], v[210:213], v[128:131], v[64:79]
	ds_read2_b64 v[96:99], v182 offset0:12 offset1:14
	ds_read2_b64 v[206:209], v204 offset0:76 offset1:78
	ds_read2_b64 v[210:213], v205 offset0:140 offset1:142
	s_waitcnt lgkmcnt(4)
	v_mfma_f32_32x32x16_bf16 v[80:95], v[214:217], v[116:119], v[80:95]
	v_mfma_f32_32x32x16_bf16 v[64:79], v[112:115], v[116:119], v[64:79]
	v_mfma_f32_32x32x16_bf16 v[80:95], v[112:115], v[104:107], v[80:95]
	s_waitcnt lgkmcnt(3)
	v_mfma_f32_32x32x16_bf16 v[64:79], v[218:221], v[104:107], v[64:79]
	s_waitcnt lgkmcnt(1)
	v_mfma_f32_32x32x16_bf16 v[80:95], v[206:209], v[100:103], v[80:95]
	v_add_u32_e32 v206, 0x2000, v184
	v_add_u32_e32 v207, 0x4000, v184
	v_mfma_f32_32x32x16_bf16 v[64:79], v[96:99], v[100:103], v[64:79]
	v_mfma_f32_32x32x16_bf16 v[80:95], v[96:99], v[108:111], v[80:95]
	v_lshl_add_u64 v[96:97], v[120:121], 2, s[22:23]
	global_load_dword v221, v[96:97], off
	global_load_dword v222, v[96:97], off offset:256
	global_load_dword v219, v[96:97], off offset:512
	global_load_dword v220, v[96:97], off offset:768
	global_load_dword v217, v[96:97], off offset:2048
	global_load_dword v218, v[96:97], off offset:2304
	global_load_dword v215, v[96:97], off offset:2560
	global_load_dword v216, v[96:97], off offset:2816
	v_add_co_u32_e32 v96, vcc, s0, v96
	s_waitcnt vmcnt(22)
	v_and_b32_e32 v99, 0xffff0000, v172
	v_addc_co_u32_e32 v97, vcc, 0, v97, vcc
	s_waitcnt lgkmcnt(0)
	v_mfma_f32_32x32x16_bf16 v[64:79], v[210:213], v[108:111], v[64:79]
	v_and_b32_e32 v98, 0xffff0000, v152
	global_load_dword v213, v[96:97], off
	global_load_dword v214, v[96:97], off offset:256
	global_load_dword v211, v[96:97], off offset:512
	global_load_dword v212, v[96:97], off offset:768
	global_load_dword v209, v[96:97], off offset:2048
	global_load_dword v210, v[96:97], off offset:2304
	global_load_dword v173, v[96:97], off offset:2560
	global_load_dword v208, v[96:97], off offset:2816
	v_lshlrev_b32_e32 v97, 16, v172
	v_lshlrev_b32_e32 v96, 16, v152
	v_pk_mul_f32 v[112:113], v[80:81], v[98:99]
	v_pk_mul_f32 v[80:81], v[80:81], v[96:97]
	v_or_b32_e32 v152, s2, v178
	v_pk_fma_f32 v[112:113], v[64:65], v[96:97], v[112:113] neg_lo:[0,0,1] neg_hi:[0,0,1]
	s_waitcnt vmcnt(28)
	v_and_b32_e32 v97, 0xffff0000, v151
	v_and_b32_e32 v96, 0xffff0000, v150
	v_pk_fma_f32 v[64:65], v[64:65], v[98:99], v[80:81]
	v_lshlrev_b32_e32 v81, 16, v151
	v_lshlrev_b32_e32 v80, 16, v150
	v_pk_mul_f32 v[98:99], v[82:83], v[96:97]
	v_cvt_pk_bf16_f32 v120, v112, v113
	v_pk_fma_f32 v[98:99], v[66:67], v[80:81], v[98:99] neg_lo:[0,0,1] neg_hi:[0,0,1]
	v_pk_mul_f32 v[80:81], v[82:83], v[80:81]
	s_waitcnt vmcnt(26)
	v_and_b32_e32 v83, 0xffff0000, v149
	v_and_b32_e32 v82, 0xffff0000, v148
	v_pk_fma_f32 v[66:67], v[66:67], v[96:97], v[80:81]
	v_lshlrev_b32_e32 v81, 16, v149
	v_lshlrev_b32_e32 v80, 16, v148
	v_pk_mul_f32 v[96:97], v[84:85], v[82:83]
	v_cvt_pk_bf16_f32 v121, v98, v99
	v_pk_fma_f32 v[96:97], v[68:69], v[80:81], v[96:97] neg_lo:[0,0,1] neg_hi:[0,0,1]
	v_pk_mul_f32 v[80:81], v[84:85], v[80:81]
	v_mul_u32_u24_e32 v172, v152, v176
	v_pk_fma_f32 v[68:69], v[68:69], v[82:83], v[80:81]
	s_waitcnt vmcnt(24)
	v_and_b32_e32 v83, 0xffff0000, v147
	v_and_b32_e32 v82, 0xffff0000, v146
	v_lshlrev_b32_e32 v81, 16, v147
	v_lshlrev_b32_e32 v80, 16, v146
	v_pk_mul_f32 v[84:85], v[86:87], v[82:83]
	v_lshl_add_u32 v172, v172, 2, s26
	v_pk_fma_f32 v[84:85], v[70:71], v[80:81], v[84:85] neg_lo:[0,0,1] neg_hi:[0,0,1]
	v_pk_mul_f32 v[80:81], v[86:87], v[80:81]
	s_mov_b32 s2, 32
	v_pk_fma_f32 v[70:71], v[70:71], v[82:83], v[80:81]
	s_waitcnt vmcnt(22)
	v_and_b32_e32 v83, 0xffff0000, v145
	v_and_b32_e32 v82, 0xffff0000, v144
	v_lshlrev_b32_e32 v81, 16, v145
	v_lshlrev_b32_e32 v80, 16, v144
	v_pk_mul_f32 v[86:87], v[88:89], v[82:83]
	ds_read2_b64 v[148:151], v184 offset1:2
	ds_read2_b64 v[144:147], v184 offset0:4 offset1:6
	v_pk_fma_f32 v[86:87], v[72:73], v[80:81], v[86:87] neg_lo:[0,0,1] neg_hi:[0,0,1]
	v_pk_mul_f32 v[80:81], v[88:89], v[80:81]
	s_and_b64 vcc, exec, s[24:25]
	v_pk_fma_f32 v[72:73], v[72:73], v[82:83], v[80:81]
	s_waitcnt vmcnt(20)
	v_and_b32_e32 v83, 0xffff0000, v127
	v_and_b32_e32 v82, 0xffff0000, v126
	v_lshlrev_b32_e32 v81, 16, v127
	v_lshlrev_b32_e32 v80, 16, v126
	v_pk_mul_f32 v[88:89], v[90:91], v[82:83]
	v_cvt_pk_bf16_f32 v126, v68, v69
	v_pk_fma_f32 v[88:89], v[74:75], v[80:81], v[88:89] neg_lo:[0,0,1] neg_hi:[0,0,1]
	v_pk_mul_f32 v[80:81], v[90:91], v[80:81]
	v_cvt_pk_bf16_f32 v127, v70, v71
	v_pk_fma_f32 v[74:75], v[74:75], v[82:83], v[80:81]
	s_waitcnt vmcnt(18)
	v_and_b32_e32 v83, 0xffff0000, v125
	v_and_b32_e32 v82, 0xffff0000, v124
	v_lshlrev_b32_e32 v81, 16, v125
	v_lshlrev_b32_e32 v80, 16, v124
	v_pk_mul_f32 v[90:91], v[92:93], v[82:83]
	v_cvt_pk_bf16_f32 v124, v64, v65
	v_pk_fma_f32 v[90:91], v[76:77], v[80:81], v[90:91] neg_lo:[0,0,1] neg_hi:[0,0,1]
	v_pk_mul_f32 v[80:81], v[92:93], v[80:81]
	v_cvt_pk_bf16_f32 v125, v66, v67
	v_pk_fma_f32 v[76:77], v[76:77], v[82:83], v[80:81]
	s_waitcnt vmcnt(16)
	v_and_b32_e32 v83, 0xffff0000, v123
	v_and_b32_e32 v82, 0xffff0000, v122
	v_lshlrev_b32_e32 v81, 16, v123
	v_lshlrev_b32_e32 v80, 16, v122
	v_pk_mul_f32 v[92:93], v[94:95], v[82:83]
	v_cvt_pk_bf16_f32 v112, v72, v73
	v_pk_fma_f32 v[92:93], v[78:79], v[80:81], v[92:93] neg_lo:[0,0,1] neg_hi:[0,0,1]
	v_pk_mul_f32 v[80:81], v[94:95], v[80:81]
	v_cvt_pk_bf16_f32 v113, v74, v75
	v_pk_fma_f32 v[78:79], v[78:79], v[82:83], v[80:81]
	ds_read2_b64 v[80:83], v206 offset0:64 offset1:66
	v_cvt_pk_bf16_f32 v114, v76, v77
	v_cvt_pk_bf16_f32 v115, v78, v79
	s_waitcnt lgkmcnt(2)
	v_mfma_f32_32x32x16_bf16 v[64:79], v[148:151], v[136:139], 0
	v_cvt_pk_bf16_f32 v122, v96, v97
	v_cvt_pk_bf16_f32 v123, v84, v85
	v_cvt_pk_bf16_f32 v96, v86, v87
	ds_read2_b64 v[84:87], v207 offset0:128 offset1:130
	ds_read2_b64 v[224:227], v206 offset0:68 offset1:70
	ds_read2_b64 v[228:231], v207 offset0:132 offset1:134
	v_cvt_pk_bf16_f32 v97, v88, v89
	v_cvt_pk_bf16_f32 v98, v90, v91
	v_cvt_pk_bf16_f32 v99, v92, v93
	s_waitcnt lgkmcnt(2)
	v_mfma_f32_32x32x16_bf16 v[64:79], v[84:87], v[140:143], v[64:79]
	s_mov_b64 s[24:25], 0
	v_mfma_f32_32x32x16_bf16 v[80:95], v[80:83], v[136:139], 0
	v_mfma_f32_32x32x16_bf16 v[80:95], v[148:151], v[140:143], v[80:95]
	ds_read2_b64 v[136:139], v184 offset0:8 offset1:10
	ds_read2_b64 v[140:143], v206 offset0:72 offset1:74
	ds_read2_b64 v[148:151], v207 offset0:136 offset1:138
	s_waitcnt lgkmcnt(4)
	v_mfma_f32_32x32x16_bf16 v[80:95], v[224:227], v[132:135], v[80:95]
	v_mfma_f32_32x32x16_bf16 v[64:79], v[144:147], v[132:135], v[64:79]
	v_mfma_f32_32x32x16_bf16 v[80:95], v[144:147], v[128:131], v[80:95]
	s_waitcnt lgkmcnt(3)
	v_mfma_f32_32x32x16_bf16 v[64:79], v[228:231], v[128:131], v[64:79]
	ds_read2_b64 v[128:131], v184 offset0:12 offset1:14
	ds_read2_b64 v[132:135], v206 offset0:76 offset1:78
	ds_read2_b64 v[144:147], v207 offset0:140 offset1:142
	s_waitcnt lgkmcnt(4)
	v_mfma_f32_32x32x16_bf16 v[80:95], v[140:143], v[116:119], v[80:95]
	v_mfma_f32_32x32x16_bf16 v[64:79], v[136:139], v[116:119], v[64:79]
	v_mfma_f32_32x32x16_bf16 v[80:95], v[136:139], v[104:107], v[80:95]
	s_waitcnt lgkmcnt(3)
	v_mfma_f32_32x32x16_bf16 v[64:79], v[148:151], v[104:107], v[64:79]
	s_waitcnt lgkmcnt(1)
	v_mfma_f32_32x32x16_bf16 v[80:95], v[132:135], v[100:103], v[80:95]
	v_mfma_f32_32x32x16_bf16 v[64:79], v[128:131], v[100:103], v[64:79]
	s_waitcnt vmcnt(14)
	v_and_b32_e32 v103, 0xffff0000, v222
	v_and_b32_e32 v102, 0xffff0000, v221
	v_lshlrev_b32_e32 v101, 16, v222
	v_lshlrev_b32_e32 v100, 16, v221
	v_mfma_f32_32x32x16_bf16 v[80:95], v[128:131], v[108:111], v[80:95]
	s_waitcnt lgkmcnt(0)
	v_mfma_f32_32x32x16_bf16 v[64:79], v[144:147], v[108:111], v[64:79]
	s_nop 9
	v_mul_f32_e64 v104, v80, v102
	v_mul_f32_e64 v105, v81, v103
	v_mul_f32_e64 v80, v80, v100
	v_mul_f32_e64 v81, v81, v101
	v_pk_fma_f32 v[104:105], v[64:65], v[100:101], v[104:105] neg_lo:[0,0,1] neg_hi:[0,0,1]
	s_waitcnt vmcnt(12)
	v_and_b32_e32 v101, 0xffff0000, v220
	v_and_b32_e32 v100, 0xffff0000, v219
	v_pk_fma_f32 v[64:65], v[64:65], v[102:103], v[80:81]
	v_lshlrev_b32_e32 v81, 16, v220
	v_lshlrev_b32_e32 v80, 16, v219
	v_pk_mul_f32 v[102:103], v[82:83], v[100:101]
	v_cvt_pk_bf16_f32 v108, v64, v65
	v_pk_fma_f32 v[102:103], v[66:67], v[80:81], v[102:103] neg_lo:[0,0,1] neg_hi:[0,0,1]
	v_pk_mul_f32 v[80:81], v[82:83], v[80:81]
	s_waitcnt vmcnt(10)
	v_and_b32_e32 v83, 0xffff0000, v218
	v_and_b32_e32 v82, 0xffff0000, v217
	v_pk_fma_f32 v[66:67], v[66:67], v[100:101], v[80:81]
	v_lshlrev_b32_e32 v81, 16, v218
	v_lshlrev_b32_e32 v80, 16, v217
	v_pk_mul_f32 v[100:101], v[84:85], v[82:83]
	v_cvt_pk_bf16_f32 v109, v66, v67
	v_pk_fma_f32 v[106:107], v[68:69], v[80:81], v[100:101] neg_lo:[0,0,1] neg_hi:[0,0,1]
	v_pk_mul_f32 v[80:81], v[84:85], v[80:81]
	v_cvt_pk_bf16_f32 v100, v104, v105
	v_pk_fma_f32 v[68:69], v[68:69], v[82:83], v[80:81]
	s_waitcnt vmcnt(8)
	v_and_b32_e32 v83, 0xffff0000, v216
	v_and_b32_e32 v82, 0xffff0000, v215
	v_lshlrev_b32_e32 v81, 16, v216
	v_lshlrev_b32_e32 v80, 16, v215
	v_pk_mul_f32 v[84:85], v[86:87], v[82:83]
	v_cvt_pk_bf16_f32 v101, v102, v103
	v_pk_fma_f32 v[84:85], v[70:71], v[80:81], v[84:85] neg_lo:[0,0,1] neg_hi:[0,0,1]
	v_pk_mul_f32 v[80:81], v[86:87], v[80:81]
	v_cvt_pk_bf16_f32 v103, v84, v85
	v_pk_fma_f32 v[70:71], v[70:71], v[82:83], v[80:81]
	s_waitcnt vmcnt(6)
	v_and_b32_e32 v83, 0xffff0000, v214
	v_and_b32_e32 v82, 0xffff0000, v213
	v_lshlrev_b32_e32 v81, 16, v214
	v_lshlrev_b32_e32 v80, 16, v213
	v_pk_mul_f32 v[86:87], v[88:89], v[82:83]
	v_cvt_pk_bf16_f32 v110, v68, v69
	v_pk_fma_f32 v[86:87], v[72:73], v[80:81], v[86:87] neg_lo:[0,0,1] neg_hi:[0,0,1]
	v_pk_mul_f32 v[80:81], v[88:89], v[80:81]
	v_cvt_pk_bf16_f32 v111, v70, v71
	v_pk_fma_f32 v[72:73], v[72:73], v[82:83], v[80:81]
	s_waitcnt vmcnt(4)
	v_and_b32_e32 v83, 0xffff0000, v212
	v_and_b32_e32 v82, 0xffff0000, v211
	v_lshlrev_b32_e32 v81, 16, v212
	v_lshlrev_b32_e32 v80, 16, v211
	v_pk_mul_f32 v[88:89], v[90:91], v[82:83]
	v_cvt_pk_bf16_f32 v104, v86, v87
	v_pk_fma_f32 v[88:89], v[74:75], v[80:81], v[88:89] neg_lo:[0,0,1] neg_hi:[0,0,1]
	v_pk_mul_f32 v[80:81], v[90:91], v[80:81]
	v_cvt_pk_bf16_f32 v116, v72, v73
	v_pk_fma_f32 v[74:75], v[74:75], v[82:83], v[80:81]
	s_waitcnt vmcnt(2)
	v_and_b32_e32 v83, 0xffff0000, v210
	v_and_b32_e32 v82, 0xffff0000, v209
	v_lshlrev_b32_e32 v81, 16, v210
	v_lshlrev_b32_e32 v80, 16, v209
	v_pk_mul_f32 v[90:91], v[92:93], v[82:83]
	v_cvt_pk_bf16_f32 v117, v74, v75
	v_pk_fma_f32 v[90:91], v[76:77], v[80:81], v[90:91] neg_lo:[0,0,1] neg_hi:[0,0,1]
	v_pk_mul_f32 v[80:81], v[92:93], v[80:81]
	v_cvt_pk_bf16_f32 v102, v106, v107
	v_pk_fma_f32 v[76:77], v[76:77], v[82:83], v[80:81]
	s_waitcnt vmcnt(0)
	v_and_b32_e32 v83, 0xffff0000, v208
	v_and_b32_e32 v82, 0xffff0000, v173
	v_lshlrev_b32_e32 v81, 16, v208
	v_lshlrev_b32_e32 v80, 16, v173
	v_pk_mul_f32 v[92:93], v[94:95], v[82:83]
	v_cvt_pk_bf16_f32 v118, v76, v77
	v_pk_fma_f32 v[92:93], v[78:79], v[80:81], v[92:93] neg_lo:[0,0,1] neg_hi:[0,0,1]
	v_pk_mul_f32 v[80:81], v[94:95], v[80:81]
	v_cvt_pk_bf16_f32 v105, v88, v89
	v_pk_fma_f32 v[78:79], v[78:79], v[82:83], v[80:81]
	ds_read2_b64 v[80:83], v182 offset1:2
	ds_read2_b64 v[128:131], v182 offset0:4 offset1:6
	ds_read2_b64 v[84:87], v204 offset0:64 offset1:66
	ds_read2_b64 v[132:135], v205 offset0:128 offset1:130
	ds_read2_b64 v[136:139], v204 offset0:68 offset1:70
	ds_read2_b64 v[140:143], v205 offset0:132 offset1:134
	v_cvt_pk_bf16_f32 v119, v78, v79
	s_waitcnt lgkmcnt(5)
	v_mfma_f32_32x32x16_bf16 v[64:79], v[120:123], v[80:83], 0
	v_cvt_pk_bf16_f32 v106, v90, v91
	v_cvt_pk_bf16_f32 v107, v92, v93
	v_lshl_add_u32 v209, v152, 1, v181
	v_lshlrev_b32_e32 v208, 2, v176
	v_add_u32_e32 v210, 0x2000, v209
	v_add_u32_e32 v211, 0x4000, v209
	s_waitcnt lgkmcnt(3)
	v_mfma_f32_32x32x16_bf16 v[64:79], v[124:127], v[84:87], v[64:79]
	v_add_u32_e32 v216, v172, v208
	v_mfma_f32_32x32x16_bf16 v[80:95], v[124:127], v[80:83], 0
	s_waitcnt lgkmcnt(2)
	v_mfma_f32_32x32x16_bf16 v[80:95], v[120:123], v[132:135], v[80:95]
	ds_read2_b64 v[132:135], v182 offset0:8 offset1:10
	ds_read2_b64 v[144:147], v204 offset0:72 offset1:74
	ds_read2_b64 v[148:151], v205 offset0:136 offset1:138
	v_mfma_f32_32x32x16_bf16 v[64:79], v[96:99], v[128:131], v[64:79]
	v_mfma_f32_32x32x16_bf16 v[80:95], v[112:115], v[128:131], v[80:95]
	s_waitcnt lgkmcnt(4)
	v_mfma_f32_32x32x16_bf16 v[64:79], v[112:115], v[136:139], v[64:79]
	s_waitcnt lgkmcnt(3)
	v_mfma_f32_32x32x16_bf16 v[80:95], v[96:99], v[140:143], v[80:95]
	ds_read2_b64 v[128:131], v182 offset0:12 offset1:14
	ds_read2_b64 v[136:139], v204 offset0:76 offset1:78
	ds_read2_b64 v[140:143], v205 offset0:140 offset1:142
	s_waitcnt lgkmcnt(5)
	v_mfma_f32_32x32x16_bf16 v[64:79], v[100:103], v[132:135], v[64:79]
	v_mfma_f32_32x32x16_bf16 v[80:95], v[108:111], v[132:135], v[80:95]
	s_waitcnt lgkmcnt(4)
	v_mfma_f32_32x32x16_bf16 v[64:79], v[108:111], v[144:147], v[64:79]
	s_waitcnt lgkmcnt(3)
	v_mfma_f32_32x32x16_bf16 v[80:95], v[100:103], v[148:151], v[80:95]
	s_waitcnt lgkmcnt(2)
	v_mfma_f32_32x32x16_bf16 v[64:79], v[104:107], v[128:131], v[64:79]
	v_mfma_f32_32x32x16_bf16 v[80:95], v[116:119], v[128:131], v[80:95]
	s_waitcnt lgkmcnt(1)
	v_mfma_f32_32x32x16_bf16 v[64:79], v[116:119], v[136:139], v[64:79]
	s_waitcnt lgkmcnt(0)
	v_mfma_f32_32x32x16_bf16 v[80:95], v[104:107], v[140:143], v[80:95]
	ds_read2_b64 v[140:143], v209 offset1:2
	ds_read2_b64 v[128:131], v209 offset0:4 offset1:6
	ds_read2_b64 v[148:151], v210 offset0:64 offset1:66
	ds_read2_b64 v[144:147], v211 offset0:128 offset1:130
	ds_read2_b64 v[136:139], v210 offset0:68 offset1:70
	ds_read2_b64 v[132:135], v211 offset0:132 offset1:134
	ds_read_b32 v244, v172
	ds_read_b32 v235, v216
	v_add_u32_e32 v241, v216, v208
	v_add_u32_e32 v233, v241, v208
	ds_read_b32 v248, v241
	ds_read_b32 v245, v233
	v_add_u32_e32 v243, v233, v187
	v_add_u32_e32 v237, v243, v208
	ds_read_b32 v240, v243
	ds_read_b32 v247, v237
	v_add_u32_e32 v250, v237, v208
	v_add_u32_e32 v234, v250, v208
	ds_read_b32 v242, v250
	ds_read_b32 v249, v234
	s_waitcnt lgkmcnt(7)
	s_waitcnt lgkmcnt(6)
	v_add_u32_e32 v236, v234, v187
	v_add_u32_e32 v252, v236, v208
	ds_read_b32 v253, v236
	ds_read_b32 v246, v252
	v_add_u32_e32 v251, v252, v208
	v_add_u32_e32 v239, v251, v208
	ds_read_b32 v238, v251
	ds_read_b32 v241, v239
	v_add_u32_e32 v233, v239, v187
	v_add_u32_e32 v243, v233, v208
	ds_read_b32 v237, v233
	ds_read_b32 v250, v243
	v_add_u32_e32 v234, v243, v208
	ds_read_b32 v236, v234
	v_add_u32_e32 v252, v234, v208
	ds_read_b32 v251, v252
	v_cvt_f32_f16_sdwa v214, v244 dst_sel:DWORD dst_unused:UNUSED_PAD src0_sel:WORD_1
	s_waitcnt lgkmcnt(14)
	v_cvt_f32_f16_sdwa v215, v235 dst_sel:DWORD dst_unused:UNUSED_PAD src0_sel:WORD_1
	v_cvt_f32_f16_e32 v213, v235
	v_cvt_f32_f16_e32 v212, v244
	v_pk_mul_f32 v[172:173], v[64:65], v[214:215]
	s_nop 0
	v_pk_fma_f32 v[172:173], v[80:81], v[212:213], v[172:173] neg_lo:[0,0,1] neg_hi:[0,0,1]
	v_pk_mul_f32 v[80:81], v[80:81], v[214:215]
	s_nop 0
	v_pk_fma_f32 v[64:65], v[64:65], v[212:213], v[80:81]
	v_cvt_pk_bf16_f32 v64, v64, v65
	s_waitcnt lgkmcnt(13)
	v_cvt_f32_f16_sdwa v214, v248 dst_sel:DWORD dst_unused:UNUSED_PAD src0_sel:WORD_1
	s_waitcnt lgkmcnt(12)
	v_cvt_f32_f16_sdwa v215, v245 dst_sel:DWORD dst_unused:UNUSED_PAD src0_sel:WORD_1
	v_cvt_f32_f16_e32 v213, v245
	v_cvt_f32_f16_e32 v212, v248
	v_pk_mul_f32 v[80:81], v[66:67], v[214:215]
	s_nop 0
	v_pk_fma_f32 v[80:81], v[82:83], v[212:213], v[80:81] neg_lo:[0,0,1] neg_hi:[0,0,1]
	v_pk_mul_f32 v[82:83], v[82:83], v[214:215]
	s_nop 0
	v_pk_fma_f32 v[66:67], v[66:67], v[212:213], v[82:83]
	v_cvt_pk_bf16_f32 v65, v66, v67
	s_waitcnt lgkmcnt(11)
	v_cvt_f32_f16_sdwa v214, v240 dst_sel:DWORD dst_unused:UNUSED_PAD src0_sel:WORD_1
	s_waitcnt lgkmcnt(10)
	v_cvt_f32_f16_sdwa v215, v247 dst_sel:DWORD dst_unused:UNUSED_PAD src0_sel:WORD_1
	v_cvt_f32_f16_e32 v213, v247
	v_cvt_f32_f16_e32 v212, v240
	v_pk_mul_f32 v[82:83], v[68:69], v[214:215]
	s_nop 0
	v_pk_fma_f32 v[82:83], v[84:85], v[212:213], v[82:83] neg_lo:[0,0,1] neg_hi:[0,0,1]
	v_pk_mul_f32 v[84:85], v[84:85], v[214:215]
	s_nop 0
	v_pk_fma_f32 v[68:69], v[68:69], v[212:213], v[84:85]
	v_cvt_pk_bf16_f32 v66, v68, v69
	v_cvt_pk_bf16_f32 v68, v172, v173
	v_cvt_pk_bf16_f32 v69, v80, v81
	s_waitcnt lgkmcnt(9)
	v_cvt_f32_f16_e32 v84, v242
	s_waitcnt lgkmcnt(8)
	v_cvt_f32_f16_e32 v85, v249
	v_cvt_f32_f16_sdwa v213, v249 dst_sel:DWORD dst_unused:UNUSED_PAD src0_sel:WORD_1
	v_cvt_f32_f16_sdwa v212, v242 dst_sel:DWORD dst_unused:UNUSED_PAD src0_sel:WORD_1
	v_pk_mul_f32 v[214:215], v[70:71], v[212:213]
	s_nop 0
	v_pk_fma_f32 v[214:215], v[86:87], v[84:85], v[214:215] neg_lo:[0,0,1] neg_hi:[0,0,1]
	v_pk_mul_f32 v[86:87], v[86:87], v[212:213]
	s_nop 0
	v_pk_fma_f32 v[70:71], v[70:71], v[84:85], v[86:87]
	v_cvt_pk_bf16_f32 v67, v70, v71
	v_cvt_pk_bf16_f32 v70, v82, v83
	v_cvt_pk_bf16_f32 v71, v214, v215
	s_waitcnt lgkmcnt(7)
	v_cvt_f32_f16_e32 v84, v253
	s_waitcnt lgkmcnt(6)
	v_cvt_f32_f16_e32 v85, v246
	v_cvt_f32_f16_sdwa v87, v246 dst_sel:DWORD dst_unused:UNUSED_PAD src0_sel:WORD_1
	v_cvt_f32_f16_sdwa v86, v253 dst_sel:DWORD dst_unused:UNUSED_PAD src0_sel:WORD_1
	v_mfma_f32_32x32x16_bf16 v[48:63], v[140:143], v[64:67], v[48:63]
	v_mul_f32_e64 v212, v72, v86
	v_mul_f32_e64 v213, v73, v87
	v_mul_f32_e64 v86, v88, v86
	v_mul_f32_e64 v87, v89, v87
	v_fma_f32 v212, v88, v84, -v212
	v_fma_f32 v213, v89, v85, -v213
	v_pk_fma_f32 v[72:73], v[72:73], v[84:85], v[86:87]
	v_mfma_f32_32x32x16_bf16 v[32:47], v[140:143], v[68:71], v[32:47]
	s_waitcnt lgkmcnt(5)
	v_cvt_f32_f16_e32 v84, v238
	s_waitcnt lgkmcnt(4)
	v_cvt_f32_f16_e32 v85, v241
	v_cvt_f32_f16_sdwa v87, v241 dst_sel:DWORD dst_unused:UNUSED_PAD src0_sel:WORD_1
	v_cvt_f32_f16_sdwa v86, v238 dst_sel:DWORD dst_unused:UNUSED_PAD src0_sel:WORD_1
	v_pk_mul_f32 v[88:89], v[74:75], v[86:87]
	v_pk_mul_f32 v[86:87], v[90:91], v[86:87]
	v_pk_fma_f32 v[88:89], v[90:91], v[84:85], v[88:89] neg_lo:[0,0,1] neg_hi:[0,0,1]
	v_pk_fma_f32 v[74:75], v[74:75], v[84:85], v[86:87]
	v_mfma_f32_32x32x16_bf16 v[48:63], v[148:151], v[68:71], v[48:63]
	v_cvt_pk_bf16_f32 v68, v212, v213
	v_cvt_pk_bf16_f32 v69, v88, v89
	s_waitcnt lgkmcnt(3)
	v_cvt_f32_f16_e32 v84, v237
	s_waitcnt lgkmcnt(2)
	v_cvt_f32_f16_e32 v85, v250
	v_cvt_f32_f16_sdwa v87, v250 dst_sel:DWORD dst_unused:UNUSED_PAD src0_sel:WORD_1
	v_cvt_f32_f16_sdwa v86, v237 dst_sel:DWORD dst_unused:UNUSED_PAD src0_sel:WORD_1
	v_pk_mul_f32 v[90:91], v[76:77], v[86:87]
	v_pk_mul_f32 v[86:87], v[92:93], v[86:87]
	v_pk_fma_f32 v[90:91], v[92:93], v[84:85], v[90:91] neg_lo:[0,0,1] neg_hi:[0,0,1]
	v_pk_fma_f32 v[76:77], v[76:77], v[84:85], v[86:87]
	v_mfma_f32_32x32x16_bf16 v[32:47], v[144:147], v[64:67], v[32:47]
	v_cvt_pk_bf16_f32 v64, v72, v73
	s_waitcnt lgkmcnt(1)
	v_cvt_f32_f16_e32 v84, v236
	v_cvt_f32_f16_sdwa v86, v236 dst_sel:DWORD dst_unused:UNUSED_PAD src0_sel:WORD_1
	s_waitcnt lgkmcnt(0)
	v_cvt_f32_f16_e32 v85, v251
	v_cvt_f32_f16_sdwa v87, v251 dst_sel:DWORD dst_unused:UNUSED_PAD src0_sel:WORD_1
	v_cvt_pk_bf16_f32 v65, v74, v75
	v_cvt_pk_bf16_f32 v66, v76, v77
	v_cvt_pk_bf16_f32 v70, v90, v91
	v_pk_mul_f32 v[92:93], v[78:79], v[86:87]
	v_pk_mul_f32 v[86:87], v[94:95], v[86:87]
	v_pk_fma_f32 v[92:93], v[94:95], v[84:85], v[92:93] neg_lo:[0,0,1] neg_hi:[0,0,1]
	v_pk_fma_f32 v[78:79], v[78:79], v[84:85], v[86:87]
	v_cvt_pk_bf16_f32 v71, v92, v93
	v_cvt_pk_bf16_f32 v67, v78, v79
	s_nop 0
	v_mfma_f32_32x32x16_bf16 v[32:47], v[128:131], v[68:71], v[32:47]
	v_mfma_f32_32x32x16_bf16 v[48:63], v[128:131], v[64:67], v[48:63]
	v_mfma_f32_32x32x16_bf16 v[48:63], v[136:139], v[68:71], v[48:63]
	v_mfma_f32_32x32x16_bf16 v[32:47], v[132:135], v[64:67], v[32:47]
	ds_read2_b64 v[80:83], v184 offset1:2
	ds_read2_b64 v[136:139], v184 offset0:4 offset1:6
	ds_read2_b64 v[84:87], v206 offset0:64 offset1:66
	ds_read2_b64 v[132:135], v207 offset0:128 offset1:130
	ds_read2_b64 v[140:143], v206 offset0:68 offset1:70
	ds_read2_b64 v[128:131], v207 offset0:132 offset1:134
	s_waitcnt lgkmcnt(5)
	v_mfma_f32_32x32x16_bf16 v[64:79], v[120:123], v[80:83], 0
	s_waitcnt lgkmcnt(3)
	v_mfma_f32_32x32x16_bf16 v[64:79], v[124:127], v[84:87], v[64:79]
	v_mfma_f32_32x32x16_bf16 v[80:95], v[124:127], v[80:83], 0
	s_waitcnt lgkmcnt(2)
	v_mfma_f32_32x32x16_bf16 v[80:95], v[120:123], v[132:135], v[80:95]
	ds_read2_b64 v[120:123], v184 offset0:8 offset1:10
	ds_read2_b64 v[132:135], v206 offset0:72 offset1:74
	ds_read2_b64 v[124:127], v207 offset0:136 offset1:138
	v_mfma_f32_32x32x16_bf16 v[64:79], v[96:99], v[136:139], v[64:79]
	v_mfma_f32_32x32x16_bf16 v[80:95], v[112:115], v[136:139], v[80:95]
	s_waitcnt lgkmcnt(4)
	v_mfma_f32_32x32x16_bf16 v[64:79], v[112:115], v[140:143], v[64:79]
	s_waitcnt lgkmcnt(3)
	v_mfma_f32_32x32x16_bf16 v[80:95], v[96:99], v[128:131], v[80:95]
	ds_read2_b64 v[96:99], v184 offset0:12 offset1:14
	ds_read2_b64 v[112:115], v206 offset0:76 offset1:78
	ds_read2_b64 v[128:131], v207 offset0:140 offset1:142
	s_waitcnt lgkmcnt(5)
	v_mfma_f32_32x32x16_bf16 v[64:79], v[100:103], v[120:123], v[64:79]
	v_mfma_f32_32x32x16_bf16 v[80:95], v[108:111], v[120:123], v[80:95]
	v_mul_u32_u24_e32 v120, v152, v183
	v_lshl_add_u32 v120, v120, 2, s26
	s_waitcnt lgkmcnt(4)
	v_mfma_f32_32x32x16_bf16 v[64:79], v[108:111], v[132:135], v[64:79]
	s_waitcnt lgkmcnt(3)
	v_mfma_f32_32x32x16_bf16 v[80:95], v[100:103], v[124:127], v[80:95]
	s_waitcnt lgkmcnt(2)
	v_mfma_f32_32x32x16_bf16 v[64:79], v[104:107], v[96:99], v[64:79]
	v_mfma_f32_32x32x16_bf16 v[80:95], v[116:119], v[96:99], v[80:95]
	s_waitcnt lgkmcnt(1)
	v_mfma_f32_32x32x16_bf16 v[64:79], v[116:119], v[112:115], v[64:79]
	s_waitcnt lgkmcnt(0)
	v_mfma_f32_32x32x16_bf16 v[80:95], v[104:107], v[128:131], v[80:95]
	ds_read2_b64 v[112:115], v209 offset1:2
	ds_read2_b64 v[100:103], v209 offset0:4 offset1:6
	ds_read2_b64 v[116:119], v210 offset0:64 offset1:66
	ds_read2_b64 v[108:111], v211 offset0:128 offset1:130
	ds_read2_b64 v[104:107], v210 offset0:68 offset1:70
	ds_read2_b64 v[96:99], v211 offset0:132 offset1:134
	v_lshlrev_b32_e32 v239, 2, v183
	v_add_u32_e32 v233, v120, v239
	ds_read_b32 v243, v120
	ds_read_b32 v234, v233
	v_add_u32_e32 v252, v233, v239
	v_add_u32_e32 v244, v252, v239
	ds_read_b32 v235, v252
	ds_read_b32 v248, v244
	v_add_u32_e32 v245, v244, v188
	v_add_u32_e32 v240, v245, v239
	ds_read_b32 v247, v245
	ds_read_b32 v242, v240
	v_add_u32_e32 v249, v240, v239
	v_add_u32_e32 v253, v249, v239
	ds_read_b32 v246, v249
	ds_read_b32 v238, v253
	s_waitcnt lgkmcnt(7)
	s_waitcnt lgkmcnt(6)
	v_add_u32_e32 v241, v253, v188
	v_add_u32_e32 v237, v241, v239
	ds_read_b32 v250, v241
	ds_read_b32 v236, v237
	v_add_u32_e32 v251, v237, v239
	v_add_u32_e32 v233, v251, v239
	ds_read_b32 v252, v251
	ds_read_b32 v244, v233
	v_add_u32_e32 v245, v233, v188
	v_add_u32_e32 v240, v245, v239
	ds_read_b32 v249, v245
	ds_read_b32 v253, v240
	v_add_u32_e32 v241, v240, v239
	ds_read_b32 v237, v241
	v_add_u32_e32 v251, v241, v239
	ds_read_b32 v233, v251
	v_mov_b32_e32 v209, v239
	v_cvt_f32_f16_sdwa v124, v243 dst_sel:DWORD dst_unused:UNUSED_PAD src0_sel:WORD_1
	s_waitcnt lgkmcnt(14)
	v_cvt_f32_f16_sdwa v125, v234 dst_sel:DWORD dst_unused:UNUSED_PAD src0_sel:WORD_1
	v_cvt_f32_f16_e32 v123, v234
	v_cvt_f32_f16_e32 v122, v243
	v_pk_mul_f32 v[120:121], v[64:65], v[124:125]
	s_nop 0
	v_pk_fma_f32 v[120:121], v[80:81], v[122:123], v[120:121] neg_lo:[0,0,1] neg_hi:[0,0,1]
	v_pk_mul_f32 v[80:81], v[80:81], v[124:125]
	s_nop 0
	v_pk_fma_f32 v[80:81], v[64:65], v[122:123], v[80:81]
	v_cvt_pk_bf16_f32 v80, v80, v81
	s_waitcnt lgkmcnt(13)
	v_cvt_f32_f16_sdwa v124, v235 dst_sel:DWORD dst_unused:UNUSED_PAD src0_sel:WORD_1
	s_waitcnt lgkmcnt(12)
	v_cvt_f32_f16_sdwa v125, v248 dst_sel:DWORD dst_unused:UNUSED_PAD src0_sel:WORD_1
	v_cvt_f32_f16_e32 v65, v248
	v_cvt_f32_f16_e32 v64, v235
	v_pk_mul_f32 v[122:123], v[66:67], v[124:125]
	s_nop 0
	v_pk_fma_f32 v[122:123], v[82:83], v[64:65], v[122:123] neg_lo:[0,0,1] neg_hi:[0,0,1]
	v_pk_mul_f32 v[82:83], v[82:83], v[124:125]
	s_nop 0
	v_pk_fma_f32 v[82:83], v[66:67], v[64:65], v[82:83]
	v_cvt_pk_bf16_f32 v81, v82, v83
	s_waitcnt lgkmcnt(11)
	v_cvt_f32_f16_e32 v64, v247
	s_waitcnt lgkmcnt(10)
	v_cvt_f32_f16_e32 v65, v242
	v_cvt_f32_f16_sdwa v67, v242 dst_sel:DWORD dst_unused:UNUSED_PAD src0_sel:WORD_1
	v_cvt_f32_f16_sdwa v66, v247 dst_sel:DWORD dst_unused:UNUSED_PAD src0_sel:WORD_1
	v_pk_mul_f32 v[124:125], v[68:69], v[66:67]
	v_pk_mul_f32 v[66:67], v[84:85], v[66:67]
	v_pk_fma_f32 v[124:125], v[84:85], v[64:65], v[124:125] neg_lo:[0,0,1] neg_hi:[0,0,1]
	v_pk_fma_f32 v[84:85], v[68:69], v[64:65], v[66:67]
	v_cvt_pk_bf16_f32 v82, v84, v85
	v_cvt_pk_bf16_f32 v84, v120, v121
	v_cvt_pk_bf16_f32 v85, v122, v123
	s_waitcnt lgkmcnt(9)
	v_cvt_f32_f16_e32 v64, v246
	s_waitcnt lgkmcnt(8)
	v_cvt_f32_f16_e32 v65, v238
	v_cvt_f32_f16_sdwa v67, v238 dst_sel:DWORD dst_unused:UNUSED_PAD src0_sel:WORD_1
	v_cvt_f32_f16_sdwa v66, v246 dst_sel:DWORD dst_unused:UNUSED_PAD src0_sel:WORD_1
	v_pk_mul_f32 v[68:69], v[70:71], v[66:67]
	v_pk_mul_f32 v[66:67], v[86:87], v[66:67]
	v_pk_fma_f32 v[126:127], v[86:87], v[64:65], v[68:69] neg_lo:[0,0,1] neg_hi:[0,0,1]
	v_pk_fma_f32 v[86:87], v[70:71], v[64:65], v[66:67]
	v_cvt_pk_bf16_f32 v83, v86, v87
	v_cvt_pk_bf16_f32 v86, v124, v125
	v_cvt_pk_bf16_f32 v87, v126, v127
	s_waitcnt lgkmcnt(7)
	v_cvt_f32_f16_sdwa v68, v250 dst_sel:DWORD dst_unused:UNUSED_PAD src0_sel:WORD_1
	s_waitcnt lgkmcnt(6)
	v_cvt_f32_f16_sdwa v69, v236 dst_sel:DWORD dst_unused:UNUSED_PAD src0_sel:WORD_1
	v_cvt_f32_f16_e32 v67, v236
	v_cvt_f32_f16_e32 v66, v250
	v_mfma_f32_32x32x16_bf16 v[16:31], v[112:115], v[80:83], v[16:31]
	v_mul_f32_e64 v64, v72, v68
	v_mul_f32_e64 v65, v73, v69
	v_mul_f32_e64 v68, v88, v68
	v_mul_f32_e64 v69, v89, v69
	v_fma_f32 v64, v88, v66, -v64
	v_fma_f32 v65, v89, v67, -v65
	v_pk_fma_f32 v[66:67], v[72:73], v[66:67], v[68:69]
	v_mfma_f32_32x32x16_bf16 v[0:15], v[112:115], v[84:87], v[0:15]
	v_cvt_pk_bf16_f32 v64, v64, v65
	s_waitcnt lgkmcnt(5)
	v_cvt_f32_f16_sdwa v72, v252 dst_sel:DWORD dst_unused:UNUSED_PAD src0_sel:WORD_1
	s_waitcnt lgkmcnt(4)
	v_cvt_f32_f16_sdwa v73, v244 dst_sel:DWORD dst_unused:UNUSED_PAD src0_sel:WORD_1
	v_cvt_f32_f16_e32 v71, v244
	v_cvt_f32_f16_e32 v70, v252
	v_pk_mul_f32 v[68:69], v[74:75], v[72:73]
	v_pk_mul_f32 v[72:73], v[90:91], v[72:73]
	v_pk_fma_f32 v[68:69], v[90:91], v[70:71], v[68:69] neg_lo:[0,0,1] neg_hi:[0,0,1]
	v_pk_fma_f32 v[70:71], v[74:75], v[70:71], v[72:73]
	v_mfma_f32_32x32x16_bf16 v[16:31], v[116:119], v[84:87], v[16:31]
	v_cvt_pk_bf16_f32 v65, v68, v69
	s_waitcnt lgkmcnt(3)
	v_cvt_f32_f16_sdwa v88, v249 dst_sel:DWORD dst_unused:UNUSED_PAD src0_sel:WORD_1
	s_waitcnt lgkmcnt(2)
	v_cvt_f32_f16_sdwa v89, v253 dst_sel:DWORD dst_unused:UNUSED_PAD src0_sel:WORD_1
	v_cvt_f32_f16_e32 v75, v253
	v_cvt_f32_f16_e32 v74, v249
	v_pk_mul_f32 v[72:73], v[76:77], v[88:89]
	v_pk_mul_f32 v[88:89], v[92:93], v[88:89]
	v_pk_fma_f32 v[72:73], v[92:93], v[74:75], v[72:73] neg_lo:[0,0,1] neg_hi:[0,0,1]
	v_pk_fma_f32 v[74:75], v[76:77], v[74:75], v[88:89]
	v_mfma_f32_32x32x16_bf16 v[0:15], v[108:111], v[80:83], v[0:15]
	v_cvt_pk_bf16_f32 v80, v66, v67
	s_waitcnt lgkmcnt(1)
	v_cvt_f32_f16_sdwa v90, v237 dst_sel:DWORD dst_unused:UNUSED_PAD src0_sel:WORD_1
	v_cvt_f32_f16_e32 v88, v237
	s_waitcnt lgkmcnt(0)
	v_cvt_f32_f16_sdwa v91, v233 dst_sel:DWORD dst_unused:UNUSED_PAD src0_sel:WORD_1
	v_cvt_f32_f16_e32 v89, v233
	v_cvt_pk_bf16_f32 v81, v70, v71
	v_cvt_pk_bf16_f32 v82, v74, v75
	v_pk_mul_f32 v[76:77], v[78:79], v[90:91]
	v_pk_mul_f32 v[90:91], v[94:95], v[90:91]
	v_pk_fma_f32 v[76:77], v[94:95], v[88:89], v[76:77] neg_lo:[0,0,1] neg_hi:[0,0,1]
	v_pk_fma_f32 v[78:79], v[78:79], v[88:89], v[90:91]
	v_cvt_pk_bf16_f32 v66, v72, v73
	v_cvt_pk_bf16_f32 v83, v78, v79
	v_cvt_pk_bf16_f32 v67, v76, v77
	s_nop 0
	v_mfma_f32_32x32x16_bf16 v[16:31], v[100:103], v[80:83], v[16:31]
	v_mfma_f32_32x32x16_bf16 v[0:15], v[100:103], v[64:67], v[0:15]
	v_mfma_f32_32x32x16_bf16 v[16:31], v[104:107], v[64:67], v[16:31]
	v_mfma_f32_32x32x16_bf16 v[0:15], v[96:99], v[80:83], v[0:15]
	s_cbranch_vccnz .LBB0_723
	v_cvt_pk_bf16_f32 v32, v32, s0
	s_waitcnt lgkmcnt(0)
	v_cvt_pk_bf16_f32 v48, v48, s0
	ds_write_b16 v189, v32 offset:6144
	v_cvt_pk_bf16_f32 v32, v49, s0
	v_add_u32_e32 v210, s48, v185
	ds_write_b16 v189, v48
	ds_write_b16 v210, v32
	v_cvt_pk_bf16_f32 v32, v33, s0
	ds_write_b16 v210, v32 offset:6144
	v_cvt_pk_bf16_f32 v32, v50, s0
	ds_write_b16 v190, v32
	v_cvt_pk_bf16_f32 v32, v34, s0
	ds_write_b16 v190, v32 offset:6144
	v_cvt_pk_bf16_f32 v32, v51, s0
	ds_write_b16 v191, v32
	v_cvt_pk_bf16_f32 v32, v35, s0
	ds_write_b16 v191, v32 offset:6144
	v_cvt_pk_bf16_f32 v32, v52, s0
	ds_write_b16 v192, v32
	v_cvt_pk_bf16_f32 v32, v36, s0
	ds_write_b16 v192, v32 offset:6144
	v_cvt_pk_bf16_f32 v32, v53, s0
	ds_write_b16 v193, v32
	v_cvt_pk_bf16_f32 v32, v37, s0
	ds_write_b16 v193, v32 offset:6144
	v_cvt_pk_bf16_f32 v32, v54, s0
	ds_write_b16 v194, v32
	v_cvt_pk_bf16_f32 v32, v38, s0
	ds_write_b16 v194, v32 offset:6144
	v_cvt_pk_bf16_f32 v32, v55, s0
	ds_write_b16 v195, v32
	v_cvt_pk_bf16_f32 v32, v39, s0
	ds_write_b16 v195, v32 offset:6144
	v_cvt_pk_bf16_f32 v32, v56, s0
	ds_write_b16 v196, v32
	v_cvt_pk_bf16_f32 v32, v40, s0
	ds_write_b16 v196, v32 offset:6144
	v_cvt_pk_bf16_f32 v32, v57, s0
	ds_write_b16 v197, v32
	v_cvt_pk_bf16_f32 v32, v41, s0
	ds_write_b16 v197, v32 offset:6144
	v_cvt_pk_bf16_f32 v32, v58, s0
	ds_write_b16 v198, v32
	v_cvt_pk_bf16_f32 v32, v42, s0
	ds_write_b16 v198, v32 offset:6144
	v_cvt_pk_bf16_f32 v32, v59, s0
	ds_write_b16 v199, v32
	v_cvt_pk_bf16_f32 v32, v43, s0
	ds_write_b16 v199, v32 offset:6144
	v_cvt_pk_bf16_f32 v32, v60, s0
	ds_write_b16 v200, v32
	v_cvt_pk_bf16_f32 v32, v44, s0
	ds_write_b16 v200, v32 offset:6144
	v_cvt_pk_bf16_f32 v32, v61, s0
	ds_write_b16 v201, v32
	v_cvt_pk_bf16_f32 v32, v45, s0
	ds_write_b16 v201, v32 offset:6144
	v_cvt_pk_bf16_f32 v32, v62, s0
	ds_write_b16 v202, v32
	v_cvt_pk_bf16_f32 v32, v46, s0
	ds_write_b16 v202, v32 offset:6144
	v_cvt_pk_bf16_f32 v32, v63, s0
	ds_write_b16 v203, v32
	v_cvt_pk_bf16_f32 v32, v47, s0
	v_cvt_pk_bf16_f32 v0, v0, s0
	ds_write_b16 v203, v32 offset:6144
	v_cvt_pk_bf16_f32 v16, v16, s0
	ds_write_b16 v189, v0 offset:6208
	v_cvt_pk_bf16_f32 v0, v17, s0
	ds_write_b16 v189, v16 offset:64
	ds_write_b16 v210, v0 offset:64
	v_cvt_pk_bf16_f32 v0, v1, s0
	ds_write_b16 v210, v0 offset:6208
	v_cvt_pk_bf16_f32 v0, v18, s0
	ds_write_b16 v190, v0 offset:64
	v_cvt_pk_bf16_f32 v0, v2, s0
	ds_write_b16 v190, v0 offset:6208
	v_cvt_pk_bf16_f32 v0, v19, s0
	ds_write_b16 v191, v0 offset:64
	v_cvt_pk_bf16_f32 v0, v3, s0
	ds_write_b16 v191, v0 offset:6208
	v_cvt_pk_bf16_f32 v0, v20, s0
	ds_write_b16 v192, v0 offset:64
	v_cvt_pk_bf16_f32 v0, v4, s0
	ds_write_b16 v192, v0 offset:6208
	v_cvt_pk_bf16_f32 v0, v21, s0
	ds_write_b16 v193, v0 offset:64
	v_cvt_pk_bf16_f32 v0, v5, s0
	ds_write_b16 v193, v0 offset:6208
	v_cvt_pk_bf16_f32 v0, v22, s0
	ds_write_b16 v194, v0 offset:64
	v_cvt_pk_bf16_f32 v0, v6, s0
	ds_write_b16 v194, v0 offset:6208
	v_cvt_pk_bf16_f32 v0, v23, s0
	ds_write_b16 v195, v0 offset:64
	v_cvt_pk_bf16_f32 v0, v7, s0
	ds_write_b16 v195, v0 offset:6208
	v_cvt_pk_bf16_f32 v0, v24, s0
	ds_write_b16 v196, v0 offset:64
	v_cvt_pk_bf16_f32 v0, v8, s0
	ds_write_b16 v196, v0 offset:6208
	v_cvt_pk_bf16_f32 v0, v25, s0
	ds_write_b16 v197, v0 offset:64
	v_cvt_pk_bf16_f32 v0, v9, s0
	ds_write_b16 v197, v0 offset:6208
	v_cvt_pk_bf16_f32 v0, v26, s0
	ds_write_b16 v198, v0 offset:64
	v_cvt_pk_bf16_f32 v0, v10, s0
	ds_write_b16 v198, v0 offset:6208
	v_cvt_pk_bf16_f32 v0, v27, s0
	ds_write_b16 v199, v0 offset:64
	v_cvt_pk_bf16_f32 v0, v11, s0
	ds_write_b16 v199, v0 offset:6208
	v_cvt_pk_bf16_f32 v0, v28, s0
	ds_write_b16 v200, v0 offset:64
	v_cvt_pk_bf16_f32 v0, v12, s0
	ds_write_b16 v200, v0 offset:6208
	v_cvt_pk_bf16_f32 v0, v29, s0
	ds_write_b16 v201, v0 offset:64
	v_cvt_pk_bf16_f32 v0, v13, s0
	ds_write_b16 v201, v0 offset:6208
	v_cvt_pk_bf16_f32 v0, v30, s0
	ds_write_b16 v202, v0 offset:64
	v_cvt_pk_bf16_f32 v0, v14, s0
	ds_write_b16 v202, v0 offset:6208
	v_cvt_pk_bf16_f32 v0, v31, s0
	s_or_b32 s2, s49, 0x200
	ds_write_b16 v203, v0 offset:64
	v_cvt_pk_bf16_f32 v0, v15, s0
	s_lshl_b32 s16, s2, 11
	ds_write_b16 v203, v0 offset:6208
	v_lshl_add_u64 v[0:1], v[170:171], 0, s[16:17]
	v_or_b32_e32 v0, v0, v154
	v_lshl_add_u64 v[40:41], v[0:1], 4, s[18:19]
	v_mov_b32_e32 v4, 0
	v_mov_b32_e32 v0, 0
	v_mov_b32_e32 v1, 0
	v_mov_b32_e32 v2, 0
	v_mov_b32_e32 v3, 0
	s_waitcnt lgkmcnt(0)
	s_barrier
	s_and_saveexec_b64 s[22:23], s[4:5]
	s_cbranch_execz .LBB0_726
	global_load_dwordx4 v[0:3], v[40:41], off offset:-16

.LBB0_729:
	v_or_b32_e32 v144, s2, v176
	v_mad_u32_u24 v145, v144, s30, v177
	ds_read_b64_tr_b16 v[80:81], v186
	ds_read_b64_tr_b16 v[82:83], v186 offset:768
	ds_read_b64_tr_b16 v[96:97], v186 offset:6144
	ds_read_b64_tr_b16 v[98:99], v186 offset:6912
	ds_read2_b64 v[100:103], v145 offset1:1
	v_add_u32_e32 v108, 0x2200, v145
	ds_read2_b64 v[84:87], v108 offset1:1
	v_add_u32_e32 v112, 0x4400, v145
	s_waitcnt lgkmcnt(1)
	v_mfma_f32_32x32x16_bf16 v[64:79], v[80:83], v[100:103], 0
	ds_read2_b64 v[88:91], v112 offset1:1
	ds_read_b64_tr_b16 v[116:117], v186 offset:3072
	ds_read_b64_tr_b16 v[118:119], v186 offset:3840
	ds_read_b64_tr_b16 v[120:121], v186 offset:9216
	ds_read_b64_tr_b16 v[122:123], v186 offset:9984
	ds_read2_b64 v[124:127], v145 offset0:4 offset1:5
	v_add_u32_e32 v146, 0x2220, v145
	ds_read2_b64 v[128:131], v146 offset1:1
	v_add_u32_e32 v150, 0x4420, v145
	ds_read2_b64 v[132:135], v150 offset1:1
	v_lshlrev_b32_e32 v151, 2, v144
	s_waitcnt lgkmcnt(7)
	v_mfma_f32_32x32x16_bf16 v[64:79], v[96:99], v[88:91], v[64:79]
	v_mfma_f32_32x32x16_bf16 v[80:95], v[80:83], v[84:87], 0
	v_mfma_f32_32x32x16_bf16 v[80:95], v[96:99], v[100:103], v[80:95]
	ds_read_b64_tr_b16 v[96:97], v186 offset:64
	ds_read_b64_tr_b16 v[98:99], v186 offset:832
	ds_read_b64_tr_b16 v[100:101], v186 offset:6208
	ds_read_b64_tr_b16 v[102:103], v186 offset:6976
	ds_read2_b64 v[104:107], v145 offset1:1
	ds_read2_b64 v[108:111], v108 offset1:1
	ds_read2_b64 v[112:115], v112 offset1:1
	s_waitcnt lgkmcnt(6)
	v_mul_u32_u24_e32 v233, v144, v178
	v_lshl_add_u32 v234, v233, 2, s26
	ds_read_b32 v235, v234
	v_add_u32_e32 v236, v234, v151
	ds_read_b32 v237, v236
	v_add_u32_e32 v238, v236, v151
	v_add_u32_e32 v239, v238, v151
	ds_read_b32 v240, v238
	ds_read_b32 v241, v239
	v_mul_u32_u24_e32 v242, 5, v144
	v_lshlrev_b32_e32 v243, 2, v242
	v_add_u32_e32 v244, v239, v243
	v_add_u32_e32 v245, v244, v151
	ds_read_b32 v246, v244
	ds_read_b32 v247, v245
	v_add_u32_e32 v248, v245, v151
	v_add_u32_e32 v249, v248, v151
	ds_read_b32 v250, v248
	ds_read_b32 v251, v249
	s_waitcnt lgkmcnt(15)
	v_mfma_f32_32x32x16_bf16 v[64:79], v[116:119], v[124:127], v[64:79]
	s_waitcnt lgkmcnt(15)
	v_mfma_f32_32x32x16_bf16 v[80:95], v[116:119], v[128:131], v[80:95]
	s_waitcnt lgkmcnt(15)
	v_mfma_f32_32x32x16_bf16 v[64:79], v[120:123], v[132:135], v[64:79]
	v_mfma_f32_32x32x16_bf16 v[80:95], v[120:123], v[124:127], v[80:95]
	s_waitcnt lgkmcnt(7)
	s_waitcnt lgkmcnt(6)
	v_add_u32_e32 v252, v249, v243
	v_add_u32_e32 v253, v252, v151
	ds_read_b32 v233, v252
	ds_read_b32 v234, v253
	v_add_u32_e32 v236, v253, v151
	v_add_u32_e32 v238, v236, v151
	ds_read_b32 v242, v236
	ds_read_b32 v239, v238
	v_add_u32_e32 v244, v238, v243
	v_add_u32_e32 v245, v244, v151
	ds_read_b32 v248, v244
	ds_read_b32 v249, v245
	v_add_u32_e32 v252, v245, v151
	v_add_u32_e32 v253, v252, v151
	ds_read_b32 v236, v252
	ds_read_b32 v238, v253
	v_mov_b32_e32 v172, v253
	v_mov_b32_e32 v152, v243
	v_cvt_f32_f16_e32 v116, v235
	v_cvt_f32_f16_sdwa v118, v235 dst_sel:DWORD dst_unused:UNUSED_PAD src0_sel:WORD_1
	s_waitcnt lgkmcnt(14)
	v_cvt_f32_f16_e32 v117, v237
	v_cvt_f32_f16_sdwa v119, v237 dst_sel:DWORD dst_unused:UNUSED_PAD src0_sel:WORD_1
	s_nop 3
	v_pk_mul_f32 v[120:121], v[80:81], v[118:119]
	s_nop 0
	v_pk_fma_f32 v[120:121], v[64:65], v[116:117], v[120:121] neg_lo:[0,0,1] neg_hi:[0,0,1]
	v_pk_mul_f32 v[64:65], v[64:65], v[118:119]
	v_cvt_pk_bf16_f32 v136, v120, v121
	v_pk_fma_f32 v[64:65], v[80:81], v[116:117], v[64:65]
	v_cvt_pk_bf16_f32 v140, v64, v65
	s_waitcnt lgkmcnt(13)
	v_cvt_f32_f16_e32 v80, v240
	s_waitcnt lgkmcnt(12)
	v_cvt_f32_f16_e32 v81, v241
	v_cvt_f32_f16_sdwa v117, v241 dst_sel:DWORD dst_unused:UNUSED_PAD src0_sel:WORD_1
	v_cvt_f32_f16_sdwa v116, v240 dst_sel:DWORD dst_unused:UNUSED_PAD src0_sel:WORD_1
	v_pk_mul_f32 v[118:119], v[82:83], v[116:117]
	s_nop 0
	v_pk_fma_f32 v[118:119], v[66:67], v[80:81], v[118:119] neg_lo:[0,0,1] neg_hi:[0,0,1]
	v_pk_mul_f32 v[66:67], v[66:67], v[116:117]
	v_cvt_pk_bf16_f32 v137, v118, v119
	v_pk_fma_f32 v[66:67], v[82:83], v[80:81], v[66:67]
	v_cvt_pk_bf16_f32 v141, v66, v67
	s_waitcnt lgkmcnt(11)
	v_cvt_f32_f16_e32 v80, v246
	s_waitcnt lgkmcnt(10)
	v_cvt_f32_f16_e32 v81, v247
	v_cvt_f32_f16_sdwa v82, v246 dst_sel:DWORD dst_unused:UNUSED_PAD src0_sel:WORD_1
	v_cvt_f32_f16_sdwa v83, v247 dst_sel:DWORD dst_unused:UNUSED_PAD src0_sel:WORD_1
	v_pk_mul_f32 v[116:117], v[84:85], v[82:83]
	s_nop 0
	v_pk_fma_f32 v[116:117], v[68:69], v[80:81], v[116:117] neg_lo:[0,0,1] neg_hi:[0,0,1]
	v_pk_mul_f32 v[68:69], v[68:69], v[82:83]
	v_cvt_pk_bf16_f32 v138, v116, v117
	v_pk_fma_f32 v[68:69], v[84:85], v[80:81], v[68:69]
	v_cvt_pk_bf16_f32 v142, v68, v69
	s_waitcnt lgkmcnt(9)
	v_cvt_f32_f16_e32 v80, v250
	s_waitcnt lgkmcnt(8)
	v_cvt_f32_f16_e32 v81, v251
	v_cvt_f32_f16_sdwa v82, v250 dst_sel:DWORD dst_unused:UNUSED_PAD src0_sel:WORD_1
	v_cvt_f32_f16_sdwa v83, v251 dst_sel:DWORD dst_unused:UNUSED_PAD src0_sel:WORD_1
	v_pk_mul_f32 v[84:85], v[86:87], v[82:83]
	s_nop 0
	v_pk_fma_f32 v[84:85], v[70:71], v[80:81], v[84:85] neg_lo:[0,0,1] neg_hi:[0,0,1]
	v_pk_mul_f32 v[70:71], v[70:71], v[82:83]
	v_cvt_pk_bf16_f32 v139, v84, v85
	v_pk_fma_f32 v[70:71], v[86:87], v[80:81], v[70:71]
	v_cvt_pk_bf16_f32 v143, v70, v71
	s_waitcnt lgkmcnt(7)
	v_cvt_f32_f16_e32 v80, v233
	s_waitcnt lgkmcnt(6)
	v_cvt_f32_f16_e32 v81, v234
	v_cvt_f32_f16_sdwa v82, v233 dst_sel:DWORD dst_unused:UNUSED_PAD src0_sel:WORD_1
	v_cvt_f32_f16_sdwa v83, v234 dst_sel:DWORD dst_unused:UNUSED_PAD src0_sel:WORD_1
	v_pk_mul_f32 v[86:87], v[88:89], v[82:83]
	s_nop 0
	v_pk_fma_f32 v[86:87], v[72:73], v[80:81], v[86:87] neg_lo:[0,0,1] neg_hi:[0,0,1]
	v_pk_mul_f32 v[72:73], v[72:73], v[82:83]
	v_cvt_pk_bf16_f32 v132, v86, v87
	v_pk_fma_f32 v[72:73], v[88:89], v[80:81], v[72:73]
	v_cvt_pk_bf16_f32 v128, v72, v73
	s_waitcnt lgkmcnt(5)
	v_cvt_f32_f16_e32 v80, v242
	s_waitcnt lgkmcnt(4)
	v_cvt_f32_f16_e32 v81, v239
	v_cvt_f32_f16_sdwa v82, v242 dst_sel:DWORD dst_unused:UNUSED_PAD src0_sel:WORD_1
	v_cvt_f32_f16_sdwa v83, v239 dst_sel:DWORD dst_unused:UNUSED_PAD src0_sel:WORD_1
	v_pk_mul_f32 v[88:89], v[90:91], v[82:83]
	s_nop 0
	v_pk_fma_f32 v[88:89], v[74:75], v[80:81], v[88:89] neg_lo:[0,0,1] neg_hi:[0,0,1]
	v_pk_mul_f32 v[74:75], v[74:75], v[82:83]
	v_cvt_pk_bf16_f32 v133, v88, v89
	v_pk_fma_f32 v[74:75], v[90:91], v[80:81], v[74:75]
	v_cvt_pk_bf16_f32 v129, v74, v75
	s_waitcnt lgkmcnt(3)
	v_cvt_f32_f16_e32 v80, v248
	s_waitcnt lgkmcnt(2)
	v_cvt_f32_f16_e32 v81, v249
	v_cvt_f32_f16_sdwa v82, v248 dst_sel:DWORD dst_unused:UNUSED_PAD src0_sel:WORD_1
	v_cvt_f32_f16_sdwa v83, v249 dst_sel:DWORD dst_unused:UNUSED_PAD src0_sel:WORD_1
	v_pk_mul_f32 v[90:91], v[92:93], v[82:83]
	s_nop 0
	v_pk_fma_f32 v[90:91], v[76:77], v[80:81], v[90:91] neg_lo:[0,0,1] neg_hi:[0,0,1]
	v_pk_mul_f32 v[76:77], v[76:77], v[82:83]
	v_cvt_pk_bf16_f32 v134, v90, v91
	v_pk_fma_f32 v[76:77], v[92:93], v[80:81], v[76:77]
	v_cvt_pk_bf16_f32 v130, v76, v77
	ds_read_b64_tr_b16 v[116:117], v186 offset:3136
	ds_read_b64_tr_b16 v[118:119], v186 offset:3904
	ds_read_b64_tr_b16 v[120:121], v186 offset:9280
	ds_read_b64_tr_b16 v[122:123], v186 offset:10048
	ds_read2_b64 v[124:127], v145 offset0:4 offset1:5
	ds_read2_b64 v[146:149], v146 offset1:1
	ds_read2_b64 v[212:215], v150 offset1:1
	s_waitcnt lgkmcnt(8)
	v_cvt_f32_f16_e32 v80, v236
	s_waitcnt lgkmcnt(7)
	v_cvt_f32_f16_e32 v81, v238
	v_cvt_f32_f16_sdwa v82, v236 dst_sel:DWORD dst_unused:UNUSED_PAD src0_sel:WORD_1
	v_cvt_f32_f16_sdwa v83, v238 dst_sel:DWORD dst_unused:UNUSED_PAD src0_sel:WORD_1
	s_waitcnt lgkmcnt(6)
	v_add_u32_e32 v244, v172, v152
	ds_read_b32 v245, v244
	v_add_u32_e32 v252, v244, v151
	ds_read_b32 v253, v252
	v_add_u32_e32 v243, v252, v151
	v_add_u32_e32 v235, v243, v151
	ds_read_b32 v237, v243
	ds_read_b32 v240, v235
	v_add_u32_e32 v241, v235, v152
	v_add_u32_e32 v246, v241, v151
	ds_read_b32 v247, v241
	ds_read_b32 v250, v246
	v_add_u32_e32 v251, v246, v151
	v_add_u32_e32 v233, v251, v151
	ds_read_b32 v234, v251
	ds_read_b32 v242, v233
	v_pk_mul_f32 v[92:93], v[94:95], v[82:83]
	s_nop 0
	v_pk_fma_f32 v[92:93], v[78:79], v[80:81], v[92:93] neg_lo:[0,0,1] neg_hi:[0,0,1]
	v_pk_mul_f32 v[78:79], v[78:79], v[82:83]
	v_cvt_pk_bf16_f32 v135, v92, v93
	v_pk_fma_f32 v[78:79], v[94:95], v[80:81], v[78:79]
	v_mfma_f32_32x32x16_bf16 v[80:95], v[96:99], v[108:111], 0
	v_cvt_pk_bf16_f32 v131, v78, v79
	v_mfma_f32_32x32x16_bf16 v[64:79], v[96:99], v[104:107], 0
	v_mfma_f32_32x32x16_bf16 v[80:95], v[100:103], v[104:107], v[80:95]
	v_mfma_f32_32x32x16_bf16 v[64:79], v[100:103], v[112:115], v[64:79]
	s_waitcnt lgkmcnt(7)
	s_waitcnt lgkmcnt(6)
	v_add_u32_e32 v239, v233, v152
	v_add_u32_e32 v248, v239, v151
	ds_read_b32 v249, v239
	ds_read_b32 v236, v248
	v_add_u32_e32 v238, v248, v151
	v_add_u32_e32 v252, v238, v151
	ds_read_b32 v243, v238
	ds_read_b32 v235, v252
	v_add_u32_e32 v241, v252, v152
	v_add_u32_e32 v246, v241, v151
	ds_read_b32 v251, v241
	ds_read_b32 v233, v246
	v_add_u32_e32 v239, v246, v151
	ds_read_b32 v248, v239
	v_add_u32_e32 v238, v239, v151
	ds_read_b32 v252, v238
	v_mov_b32_e32 v96, v244
	v_cvt_f32_f16_e32 v96, v245
	v_cvt_f32_f16_sdwa v98, v245 dst_sel:DWORD dst_unused:UNUSED_PAD src0_sel:WORD_1
	s_waitcnt lgkmcnt(14)
	v_cvt_f32_f16_e32 v97, v253
	v_mfma_f32_32x32x16_bf16 v[80:95], v[116:119], v[146:149], v[80:95]
	v_cvt_f32_f16_sdwa v99, v253 dst_sel:DWORD dst_unused:UNUSED_PAD src0_sel:WORD_1
	v_mfma_f32_32x32x16_bf16 v[64:79], v[116:119], v[124:127], v[64:79]
	v_mfma_f32_32x32x16_bf16 v[80:95], v[120:123], v[124:127], v[80:95]
	v_mfma_f32_32x32x16_bf16 v[64:79], v[120:123], v[212:215], v[64:79]
	s_nop 10
	v_mul_f32_e64 v100, v80, v98
	v_mul_f32_e64 v101, v81, v99
	v_pk_fma_f32 v[100:101], v[64:65], v[96:97], v[100:101] neg_lo:[0,0,1] neg_hi:[0,0,1]
	v_pk_mul_f32 v[64:65], v[64:65], v[98:99]
	v_cvt_pk_bf16_f32 v124, v100, v101
	v_pk_fma_f32 v[64:65], v[80:81], v[96:97], v[64:65]
	v_cvt_pk_bf16_f32 v120, v64, v65
	s_waitcnt lgkmcnt(13)
	v_cvt_f32_f16_e32 v80, v237
	s_waitcnt lgkmcnt(12)
	v_cvt_f32_f16_e32 v81, v240
	v_cvt_f32_f16_sdwa v96, v237 dst_sel:DWORD dst_unused:UNUSED_PAD src0_sel:WORD_1
	v_cvt_f32_f16_sdwa v97, v240 dst_sel:DWORD dst_unused:UNUSED_PAD src0_sel:WORD_1
	v_pk_mul_f32 v[98:99], v[82:83], v[96:97]
	s_nop 0
	v_pk_fma_f32 v[98:99], v[66:67], v[80:81], v[98:99] neg_lo:[0,0,1] neg_hi:[0,0,1]
	v_pk_mul_f32 v[66:67], v[66:67], v[96:97]
	v_cvt_pk_bf16_f32 v125, v98, v99
	v_pk_fma_f32 v[66:67], v[82:83], v[80:81], v[66:67]
	v_cvt_pk_bf16_f32 v121, v66, v67
	s_waitcnt lgkmcnt(11)
	v_cvt_f32_f16_e32 v80, v247
	s_waitcnt lgkmcnt(10)
	v_cvt_f32_f16_e32 v81, v250
	v_cvt_f32_f16_sdwa v82, v247 dst_sel:DWORD dst_unused:UNUSED_PAD src0_sel:WORD_1
	v_cvt_f32_f16_sdwa v83, v250 dst_sel:DWORD dst_unused:UNUSED_PAD src0_sel:WORD_1
	v_pk_mul_f32 v[96:97], v[84:85], v[82:83]
	s_nop 0
	v_pk_fma_f32 v[96:97], v[68:69], v[80:81], v[96:97] neg_lo:[0,0,1] neg_hi:[0,0,1]
	v_pk_mul_f32 v[68:69], v[68:69], v[82:83]
	v_cvt_pk_bf16_f32 v126, v96, v97
	v_pk_fma_f32 v[68:69], v[84:85], v[80:81], v[68:69]
	v_cvt_pk_bf16_f32 v122, v68, v69
	v_or_b32_e32 v96, v144, v180
	v_mov_b32_e32 v97, v153
	s_waitcnt lgkmcnt(9)
	v_cvt_f32_f16_e32 v80, v234
	s_waitcnt lgkmcnt(8)
	v_cvt_f32_f16_e32 v81, v242
	v_cvt_f32_f16_sdwa v82, v234 dst_sel:DWORD dst_unused:UNUSED_PAD src0_sel:WORD_1
	v_cvt_f32_f16_sdwa v83, v242 dst_sel:DWORD dst_unused:UNUSED_PAD src0_sel:WORD_1
	v_lshl_add_u64 v[96:97], v[96:97], 2, s[14:15]
	v_pk_mul_f32 v[84:85], v[86:87], v[82:83]
	s_nop 0
	v_pk_fma_f32 v[84:85], v[70:71], v[80:81], v[84:85] neg_lo:[0,0,1] neg_hi:[0,0,1]
	v_pk_mul_f32 v[70:71], v[70:71], v[82:83]
	v_cvt_pk_bf16_f32 v127, v84, v85
	v_pk_fma_f32 v[70:71], v[86:87], v[80:81], v[70:71]
	v_cvt_pk_bf16_f32 v123, v70, v71
	s_waitcnt lgkmcnt(7)
	v_cvt_f32_f16_e32 v80, v249
	s_waitcnt lgkmcnt(6)
	v_cvt_f32_f16_e32 v81, v236
	v_cvt_f32_f16_sdwa v82, v249 dst_sel:DWORD dst_unused:UNUSED_PAD src0_sel:WORD_1
	v_cvt_f32_f16_sdwa v83, v236 dst_sel:DWORD dst_unused:UNUSED_PAD src0_sel:WORD_1
	v_pk_mul_f32 v[86:87], v[88:89], v[82:83]
	s_nop 0
	v_pk_fma_f32 v[86:87], v[72:73], v[80:81], v[86:87] neg_lo:[0,0,1] neg_hi:[0,0,1]
	v_pk_mul_f32 v[72:73], v[72:73], v[82:83]
	v_cvt_pk_bf16_f32 v112, v86, v87
	v_pk_fma_f32 v[72:73], v[88:89], v[80:81], v[72:73]
	v_cvt_pk_bf16_f32 v116, v72, v73
	s_waitcnt lgkmcnt(5)
	v_cvt_f32_f16_e32 v80, v243
	s_waitcnt lgkmcnt(4)
	v_cvt_f32_f16_e32 v81, v235
	v_cvt_f32_f16_sdwa v82, v243 dst_sel:DWORD dst_unused:UNUSED_PAD src0_sel:WORD_1
	v_cvt_f32_f16_sdwa v83, v235 dst_sel:DWORD dst_unused:UNUSED_PAD src0_sel:WORD_1
	v_pk_mul_f32 v[88:89], v[90:91], v[82:83]
	s_nop 0
	v_pk_fma_f32 v[88:89], v[74:75], v[80:81], v[88:89] neg_lo:[0,0,1] neg_hi:[0,0,1]
	v_pk_mul_f32 v[74:75], v[74:75], v[82:83]
	v_cvt_pk_bf16_f32 v113, v88, v89
	v_pk_fma_f32 v[74:75], v[90:91], v[80:81], v[74:75]
	v_or_b32_e32 v152, v144, v179
	v_lshl_add_u64 v[64:65], v[152:153], 2, s[14:15]
	v_cvt_pk_bf16_f32 v117, v74, v75
	s_waitcnt lgkmcnt(3)
	v_cvt_f32_f16_e32 v80, v251
	s_waitcnt lgkmcnt(2)
	v_cvt_f32_f16_e32 v81, v233
	v_cvt_f32_f16_sdwa v82, v251 dst_sel:DWORD dst_unused:UNUSED_PAD src0_sel:WORD_1
	v_cvt_f32_f16_sdwa v83, v233 dst_sel:DWORD dst_unused:UNUSED_PAD src0_sel:WORD_1
	v_pk_mul_f32 v[90:91], v[92:93], v[82:83]
	s_nop 0
	v_pk_fma_f32 v[90:91], v[76:77], v[80:81], v[90:91] neg_lo:[0,0,1] neg_hi:[0,0,1]
	v_pk_mul_f32 v[76:77], v[76:77], v[82:83]
	v_cvt_pk_bf16_f32 v114, v90, v91
	v_pk_fma_f32 v[76:77], v[92:93], v[80:81], v[76:77]
	global_load_dword v104, v[64:65], off
	global_load_dword v105, v[64:65], off offset:256
	global_load_dword v102, v[64:65], off offset:512
	global_load_dword v103, v[64:65], off offset:768
	global_load_dword v100, v[64:65], off offset:2048
	global_load_dword v101, v[64:65], off offset:2304
	global_load_dword v98, v[64:65], off offset:2560
	global_load_dword v99, v[64:65], off offset:2816
	v_add_co_u32_e32 v64, vcc, s0, v64
	s_waitcnt lgkmcnt(1)
	v_cvt_f32_f16_e32 v80, v248
	s_waitcnt lgkmcnt(0)
	v_cvt_f32_f16_e32 v81, v252
	v_cvt_f32_f16_sdwa v82, v248 dst_sel:DWORD dst_unused:UNUSED_PAD src0_sel:WORD_1
	v_cvt_f32_f16_sdwa v83, v252 dst_sel:DWORD dst_unused:UNUSED_PAD src0_sel:WORD_1
	v_addc_co_u32_e32 v65, vcc, 0, v65, vcc
	v_cvt_pk_bf16_f32 v118, v76, v77
	v_pk_mul_f32 v[92:93], v[94:95], v[82:83]
	global_load_dword v110, v[64:65], off
	global_load_dword v111, v[64:65], off offset:256
	global_load_dword v224, v[64:65], off offset:512
	global_load_dword v225, v[64:65], off offset:768
	global_load_dword v226, v[64:65], off offset:2048
	global_load_dword v227, v[64:65], off offset:2304
	global_load_dword v228, v[64:65], off offset:2560
	global_load_dword v229, v[64:65], off offset:2816
	v_pk_fma_f32 v[92:93], v[78:79], v[80:81], v[92:93] neg_lo:[0,0,1] neg_hi:[0,0,1]
	v_pk_mul_f32 v[78:79], v[78:79], v[82:83]
	v_cvt_pk_bf16_f32 v115, v92, v93
	v_pk_fma_f32 v[78:79], v[94:95], v[80:81], v[78:79]
	ds_read2_b64 v[106:109], v182 offset1:2
	ds_read2_b64 v[144:147], v182 offset0:4 offset1:6
	ds_read2_b64 v[80:83], v204 offset0:64 offset1:66
	ds_read2_b64 v[84:87], v205 offset0:128 offset1:130
	ds_read2_b64 v[148:151], v204 offset0:68 offset1:70
	ds_read2_b64 v[212:215], v205 offset0:132 offset1:134
	v_cvt_pk_bf16_f32 v119, v78, v79
	s_waitcnt lgkmcnt(5)
	v_mfma_f32_32x32x16_bf16 v[64:79], v[106:109], v[136:139], 0
	s_waitcnt lgkmcnt(2)
	v_mfma_f32_32x32x16_bf16 v[64:79], v[84:87], v[140:143], v[64:79]
	v_mfma_f32_32x32x16_bf16 v[80:95], v[80:83], v[136:139], 0
	v_mfma_f32_32x32x16_bf16 v[80:95], v[106:109], v[140:143], v[80:95]
	ds_read2_b64 v[106:109], v182 offset0:8 offset1:10
	ds_read2_b64 v[216:219], v204 offset0:72 offset1:74
	ds_read2_b64 v[220:223], v205 offset0:136 offset1:138
	s_waitcnt lgkmcnt(4)
	v_mfma_f32_32x32x16_bf16 v[80:95], v[148:151], v[132:135], v[80:95]
	v_mfma_f32_32x32x16_bf16 v[64:79], v[144:147], v[132:135], v[64:79]
	v_mfma_f32_32x32x16_bf16 v[80:95], v[144:147], v[128:131], v[80:95]
	s_waitcnt lgkmcnt(3)
	v_mfma_f32_32x32x16_bf16 v[64:79], v[212:215], v[128:131], v[64:79]
	ds_read2_b64 v[144:147], v182 offset0:12 offset1:14
	ds_read2_b64 v[148:151], v204 offset0:76 offset1:78
	ds_read2_b64 v[212:215], v205 offset0:140 offset1:142
	s_waitcnt lgkmcnt(4)
	v_mfma_f32_32x32x16_bf16 v[80:95], v[216:219], v[124:127], v[80:95]
	v_mfma_f32_32x32x16_bf16 v[64:79], v[106:109], v[124:127], v[64:79]
	v_mfma_f32_32x32x16_bf16 v[80:95], v[106:109], v[120:123], v[80:95]
	s_waitcnt lgkmcnt(3)
	v_mfma_f32_32x32x16_bf16 v[64:79], v[220:223], v[120:123], v[64:79]
	s_waitcnt lgkmcnt(1)
	v_mfma_f32_32x32x16_bf16 v[80:95], v[148:151], v[112:115], v[80:95]
	v_mfma_f32_32x32x16_bf16 v[64:79], v[144:147], v[112:115], v[64:79]
	v_mfma_f32_32x32x16_bf16 v[80:95], v[144:147], v[116:119], v[80:95]
	s_waitcnt lgkmcnt(0)
	v_mfma_f32_32x32x16_bf16 v[64:79], v[212:215], v[116:119], v[64:79]
	global_load_dword v218, v[96:97], off
	global_load_dword v219, v[96:97], off offset:256
	global_load_dword v216, v[96:97], off offset:512
	global_load_dword v217, v[96:97], off offset:768
	global_load_dword v214, v[96:97], off offset:2048
	global_load_dword v215, v[96:97], off offset:2304
	global_load_dword v212, v[96:97], off offset:2560
	global_load_dword v213, v[96:97], off offset:2816
	v_add_co_u32_e32 v96, vcc, s0, v96
	s_nop 1
	v_addc_co_u32_e32 v97, vcc, 0, v97, vcc
	global_load_dword v173, v[96:97], off
	global_load_dword v211, v[96:97], off offset:256
	global_load_dword v152, v[96:97], off offset:512
	global_load_dword v172, v[96:97], off offset:768
	global_load_dword v150, v[96:97], off offset:2048
	global_load_dword v151, v[96:97], off offset:2304
	global_load_dword v148, v[96:97], off offset:2560
	global_load_dword v149, v[96:97], off offset:2816
	s_waitcnt vmcnt(30)
	v_lshlrev_b32_e32 v97, 16, v105
	v_lshlrev_b32_e32 v96, 16, v104
	v_and_b32_e32 v105, 0xffff0000, v105
	v_and_b32_e32 v104, 0xffff0000, v104
	v_pk_mul_f32 v[106:107], v[80:81], v[104:105]
	v_pk_mul_f32 v[80:81], v[80:81], v[96:97]
	v_pk_fma_f32 v[106:107], v[64:65], v[96:97], v[106:107] neg_lo:[0,0,1] neg_hi:[0,0,1]
	s_waitcnt vmcnt(28)
	v_and_b32_e32 v97, 0xffff0000, v103
	v_and_b32_e32 v96, 0xffff0000, v102
	v_pk_fma_f32 v[64:65], v[64:65], v[104:105], v[80:81]
	v_lshlrev_b32_e32 v81, 16, v103
	v_lshlrev_b32_e32 v80, 16, v102
	v_pk_mul_f32 v[102:103], v[82:83], v[96:97]
	v_cvt_pk_bf16_f32 v104, v106, v107
	v_pk_fma_f32 v[102:103], v[66:67], v[80:81], v[102:103] neg_lo:[0,0,1] neg_hi:[0,0,1]
	v_pk_mul_f32 v[80:81], v[82:83], v[80:81]
	s_waitcnt vmcnt(26)
	v_and_b32_e32 v83, 0xffff0000, v101
	v_and_b32_e32 v82, 0xffff0000, v100
	v_pk_fma_f32 v[66:67], v[66:67], v[96:97], v[80:81]
	v_lshlrev_b32_e32 v81, 16, v101
	v_lshlrev_b32_e32 v80, 16, v100
	v_pk_mul_f32 v[96:97], v[84:85], v[82:83]
	v_cvt_pk_bf16_f32 v105, v102, v103
	v_pk_fma_f32 v[96:97], v[68:69], v[80:81], v[96:97] neg_lo:[0,0,1] neg_hi:[0,0,1]
	v_pk_mul_f32 v[80:81], v[84:85], v[80:81]
	v_cvt_pk_bf16_f32 v106, v96, v97
	v_pk_fma_f32 v[68:69], v[68:69], v[82:83], v[80:81]
	s_waitcnt vmcnt(24)
	v_and_b32_e32 v83, 0xffff0000, v99
	v_and_b32_e32 v82, 0xffff0000, v98
	v_lshlrev_b32_e32 v81, 16, v99
	v_lshlrev_b32_e32 v80, 16, v98
	v_pk_mul_f32 v[84:85], v[86:87], v[82:83]
	v_cvt_pk_bf16_f32 v108, v64, v65
	v_pk_fma_f32 v[84:85], v[70:71], v[80:81], v[84:85] neg_lo:[0,0,1] neg_hi:[0,0,1]
	v_pk_mul_f32 v[80:81], v[86:87], v[80:81]
	v_cvt_pk_bf16_f32 v107, v84, v85
	v_pk_fma_f32 v[70:71], v[70:71], v[82:83], v[80:81]
	s_waitcnt vmcnt(22)
	v_and_b32_e32 v83, 0xffff0000, v111
	v_and_b32_e32 v82, 0xffff0000, v110
	v_lshlrev_b32_e32 v81, 16, v111
	v_lshlrev_b32_e32 v80, 16, v110
	v_pk_mul_f32 v[86:87], v[88:89], v[82:83]
	v_cvt_pk_bf16_f32 v109, v66, v67
	v_pk_fma_f32 v[86:87], v[72:73], v[80:81], v[86:87] neg_lo:[0,0,1] neg_hi:[0,0,1]
	v_pk_mul_f32 v[80:81], v[88:89], v[80:81]
	v_cvt_pk_bf16_f32 v110, v68, v69
	v_pk_fma_f32 v[72:73], v[72:73], v[82:83], v[80:81]
	s_waitcnt vmcnt(20)
	v_and_b32_e32 v83, 0xffff0000, v225
	v_and_b32_e32 v82, 0xffff0000, v224
	v_lshlrev_b32_e32 v81, 16, v225
	v_lshlrev_b32_e32 v80, 16, v224
	v_pk_mul_f32 v[88:89], v[90:91], v[82:83]
	v_cvt_pk_bf16_f32 v111, v70, v71
	v_pk_fma_f32 v[88:89], v[74:75], v[80:81], v[88:89] neg_lo:[0,0,1] neg_hi:[0,0,1]
	v_pk_mul_f32 v[80:81], v[90:91], v[80:81]
	v_cvt_pk_bf16_f32 v96, v86, v87
	v_pk_fma_f32 v[74:75], v[74:75], v[82:83], v[80:81]
	s_waitcnt vmcnt(18)
	v_and_b32_e32 v83, 0xffff0000, v227
	v_and_b32_e32 v82, 0xffff0000, v226
	v_lshlrev_b32_e32 v81, 16, v227
	v_lshlrev_b32_e32 v80, 16, v226
	v_pk_mul_f32 v[90:91], v[92:93], v[82:83]
	v_cvt_pk_bf16_f32 v100, v72, v73
	v_pk_fma_f32 v[90:91], v[76:77], v[80:81], v[90:91] neg_lo:[0,0,1] neg_hi:[0,0,1]
	v_pk_mul_f32 v[80:81], v[92:93], v[80:81]
	v_cvt_pk_bf16_f32 v101, v74, v75
	v_pk_fma_f32 v[76:77], v[76:77], v[82:83], v[80:81]
	s_waitcnt vmcnt(16)
	v_and_b32_e32 v83, 0xffff0000, v229
	v_and_b32_e32 v82, 0xffff0000, v228
	v_lshlrev_b32_e32 v81, 16, v229
	v_lshlrev_b32_e32 v80, 16, v228
	v_pk_mul_f32 v[92:93], v[94:95], v[82:83]
	v_cvt_pk_bf16_f32 v102, v76, v77
	v_pk_fma_f32 v[92:93], v[78:79], v[80:81], v[92:93] neg_lo:[0,0,1] neg_hi:[0,0,1]
	v_pk_mul_f32 v[80:81], v[94:95], v[80:81]
	v_cvt_pk_bf16_f32 v97, v88, v89
	v_pk_fma_f32 v[78:79], v[78:79], v[82:83], v[80:81]
	ds_read2_b64 v[220:223], v184 offset1:2
	ds_read2_b64 v[144:147], v184 offset0:4 offset1:6
	ds_read2_b64 v[80:83], v206 offset0:64 offset1:66
	ds_read2_b64 v[84:87], v207 offset0:128 offset1:130
	ds_read2_b64 v[224:227], v206 offset0:68 offset1:70
	ds_read2_b64 v[228:231], v207 offset0:132 offset1:134
	v_cvt_pk_bf16_f32 v103, v78, v79
	s_waitcnt lgkmcnt(5)
	v_mfma_f32_32x32x16_bf16 v[64:79], v[220:223], v[136:139], 0
	v_cvt_pk_bf16_f32 v98, v90, v91
	v_cvt_pk_bf16_f32 v99, v92, v93
	s_and_b64 vcc, exec, s[20:21]
	s_mov_b64 s[20:21], 0
	s_waitcnt lgkmcnt(2)
	v_mfma_f32_32x32x16_bf16 v[64:79], v[84:87], v[140:143], v[64:79]
	v_mfma_f32_32x32x16_bf16 v[80:95], v[80:83], v[136:139], 0
	v_mfma_f32_32x32x16_bf16 v[80:95], v[220:223], v[140:143], v[80:95]
	ds_read2_b64 v[136:139], v184 offset0:8 offset1:10
	ds_read2_b64 v[140:143], v206 offset0:72 offset1:74
	ds_read2_b64 v[220:223], v207 offset0:136 offset1:138
	s_waitcnt lgkmcnt(4)
	v_mfma_f32_32x32x16_bf16 v[80:95], v[224:227], v[132:135], v[80:95]
	v_mfma_f32_32x32x16_bf16 v[64:79], v[144:147], v[132:135], v[64:79]
	v_mfma_f32_32x32x16_bf16 v[80:95], v[144:147], v[128:131], v[80:95]
	s_waitcnt lgkmcnt(3)
	v_mfma_f32_32x32x16_bf16 v[64:79], v[228:231], v[128:131], v[64:79]
	ds_read2_b64 v[128:131], v184 offset0:12 offset1:14
	ds_read2_b64 v[132:135], v206 offset0:76 offset1:78
	ds_read2_b64 v[144:147], v207 offset0:140 offset1:142
	s_waitcnt lgkmcnt(4)
	v_mfma_f32_32x32x16_bf16 v[80:95], v[140:143], v[124:127], v[80:95]
	v_mfma_f32_32x32x16_bf16 v[64:79], v[136:139], v[124:127], v[64:79]
	v_mfma_f32_32x32x16_bf16 v[80:95], v[136:139], v[120:123], v[80:95]
	s_waitcnt lgkmcnt(3)
	v_mfma_f32_32x32x16_bf16 v[64:79], v[220:223], v[120:123], v[64:79]
	s_waitcnt lgkmcnt(1)
	v_mfma_f32_32x32x16_bf16 v[80:95], v[132:135], v[112:115], v[80:95]
	v_mfma_f32_32x32x16_bf16 v[64:79], v[128:131], v[112:115], v[64:79]
	s_waitcnt vmcnt(14)
	v_and_b32_e32 v115, 0xffff0000, v219
	v_and_b32_e32 v114, 0xffff0000, v218
	v_lshlrev_b32_e32 v113, 16, v219
	v_lshlrev_b32_e32 v112, 16, v218
	v_mfma_f32_32x32x16_bf16 v[80:95], v[128:131], v[116:119], v[80:95]
	s_waitcnt lgkmcnt(0)
	v_mfma_f32_32x32x16_bf16 v[64:79], v[144:147], v[116:119], v[64:79]
	s_nop 9
	v_mul_f32_e64 v116, v80, v114
	v_mul_f32_e64 v117, v81, v115
	v_mul_f32_e64 v80, v80, v112
	v_mul_f32_e64 v81, v81, v113
	v_pk_fma_f32 v[116:117], v[64:65], v[112:113], v[116:117] neg_lo:[0,0,1] neg_hi:[0,0,1]
	s_waitcnt vmcnt(12)
	v_and_b32_e32 v113, 0xffff0000, v217
	v_and_b32_e32 v112, 0xffff0000, v216
	v_pk_fma_f32 v[64:65], v[64:65], v[114:115], v[80:81]
	v_lshlrev_b32_e32 v81, 16, v217
	v_lshlrev_b32_e32 v80, 16, v216
	v_pk_mul_f32 v[114:115], v[82:83], v[112:113]
	v_cvt_pk_bf16_f32 v120, v64, v65
	v_pk_fma_f32 v[114:115], v[66:67], v[80:81], v[114:115] neg_lo:[0,0,1] neg_hi:[0,0,1]
	v_pk_mul_f32 v[80:81], v[82:83], v[80:81]
	s_waitcnt vmcnt(10)
	v_and_b32_e32 v83, 0xffff0000, v215
	v_and_b32_e32 v82, 0xffff0000, v214
	v_pk_fma_f32 v[66:67], v[66:67], v[112:113], v[80:81]
	v_lshlrev_b32_e32 v81, 16, v215
	v_lshlrev_b32_e32 v80, 16, v214
	v_pk_mul_f32 v[112:113], v[84:85], v[82:83]
	v_cvt_pk_bf16_f32 v121, v66, v67
	v_pk_fma_f32 v[118:119], v[68:69], v[80:81], v[112:113] neg_lo:[0,0,1] neg_hi:[0,0,1]
	v_pk_mul_f32 v[80:81], v[84:85], v[80:81]
	v_cvt_pk_bf16_f32 v112, v116, v117
	v_pk_fma_f32 v[68:69], v[68:69], v[82:83], v[80:81]
	s_waitcnt vmcnt(8)
	v_and_b32_e32 v83, 0xffff0000, v213
	v_and_b32_e32 v82, 0xffff0000, v212
	v_lshlrev_b32_e32 v81, 16, v213
	v_lshlrev_b32_e32 v80, 16, v212
	v_pk_mul_f32 v[84:85], v[86:87], v[82:83]
	v_cvt_pk_bf16_f32 v113, v114, v115
	v_pk_fma_f32 v[84:85], v[70:71], v[80:81], v[84:85] neg_lo:[0,0,1] neg_hi:[0,0,1]
	v_pk_mul_f32 v[80:81], v[86:87], v[80:81]
	v_cvt_pk_bf16_f32 v115, v84, v85
	v_pk_fma_f32 v[70:71], v[70:71], v[82:83], v[80:81]
	s_waitcnt vmcnt(6)
	v_and_b32_e32 v83, 0xffff0000, v211
	v_and_b32_e32 v82, 0xffff0000, v173
	v_lshlrev_b32_e32 v81, 16, v211
	v_lshlrev_b32_e32 v80, 16, v173
	v_pk_mul_f32 v[86:87], v[88:89], v[82:83]
	v_cvt_pk_bf16_f32 v122, v68, v69
	v_pk_fma_f32 v[86:87], v[72:73], v[80:81], v[86:87] neg_lo:[0,0,1] neg_hi:[0,0,1]
	v_pk_mul_f32 v[80:81], v[88:89], v[80:81]
	v_cvt_pk_bf16_f32 v123, v70, v71
	v_pk_fma_f32 v[72:73], v[72:73], v[82:83], v[80:81]
	s_waitcnt vmcnt(4)
	v_and_b32_e32 v83, 0xffff0000, v172
	v_and_b32_e32 v82, 0xffff0000, v152
	v_lshlrev_b32_e32 v81, 16, v172
	v_lshlrev_b32_e32 v80, 16, v152
	v_pk_mul_f32 v[88:89], v[90:91], v[82:83]
	v_cvt_pk_bf16_f32 v116, v86, v87
	v_pk_fma_f32 v[88:89], v[74:75], v[80:81], v[88:89] neg_lo:[0,0,1] neg_hi:[0,0,1]
	v_pk_mul_f32 v[80:81], v[90:91], v[80:81]
	v_cvt_pk_bf16_f32 v124, v72, v73
	v_pk_fma_f32 v[74:75], v[74:75], v[82:83], v[80:81]
	s_waitcnt vmcnt(2)
	v_and_b32_e32 v83, 0xffff0000, v151
	v_and_b32_e32 v82, 0xffff0000, v150
	v_lshlrev_b32_e32 v81, 16, v151
	v_lshlrev_b32_e32 v80, 16, v150
	v_pk_mul_f32 v[90:91], v[92:93], v[82:83]
	v_cvt_pk_bf16_f32 v125, v74, v75
	v_pk_fma_f32 v[90:91], v[76:77], v[80:81], v[90:91] neg_lo:[0,0,1] neg_hi:[0,0,1]
	v_pk_mul_f32 v[80:81], v[92:93], v[80:81]
	v_cvt_pk_bf16_f32 v114, v118, v119
	v_pk_fma_f32 v[76:77], v[76:77], v[82:83], v[80:81]
	s_waitcnt vmcnt(0)
	v_and_b32_e32 v83, 0xffff0000, v149
	v_and_b32_e32 v82, 0xffff0000, v148
	v_lshlrev_b32_e32 v81, 16, v149
	v_lshlrev_b32_e32 v80, 16, v148
	v_pk_mul_f32 v[92:93], v[94:95], v[82:83]
	v_cvt_pk_bf16_f32 v126, v76, v77
	v_pk_fma_f32 v[92:93], v[78:79], v[80:81], v[92:93] neg_lo:[0,0,1] neg_hi:[0,0,1]
	v_pk_mul_f32 v[80:81], v[94:95], v[80:81]
	v_cvt_pk_bf16_f32 v117, v88, v89
	v_pk_fma_f32 v[78:79], v[78:79], v[82:83], v[80:81]
	ds_read2_b64 v[80:83], v182 offset1:2
	ds_read2_b64 v[128:131], v182 offset0:4 offset1:6
	ds_read2_b64 v[84:87], v204 offset0:64 offset1:66
	ds_read2_b64 v[132:135], v205 offset0:128 offset1:130
	ds_read2_b64 v[136:139], v204 offset0:68 offset1:70
	ds_read2_b64 v[140:143], v205 offset0:132 offset1:134
	v_cvt_pk_bf16_f32 v127, v78, v79
	s_waitcnt lgkmcnt(5)
	v_mfma_f32_32x32x16_bf16 v[64:79], v[104:107], v[80:83], 0
	v_cvt_pk_bf16_f32 v118, v90, v91
	v_cvt_pk_bf16_f32 v119, v92, v93
	v_or_b32_e32 v152, s2, v178
	v_mul_u32_u24_e32 v172, v152, v176
	v_lshl_add_u32 v211, v152, 1, v181
	v_lshl_add_u32 v172, v172, 2, s26
	s_waitcnt lgkmcnt(3)
	v_mfma_f32_32x32x16_bf16 v[64:79], v[108:111], v[84:87], v[64:79]
	v_add_u32_e32 v212, 0x2000, v211
	v_add_u32_e32 v213, 0x4000, v211
	v_add_u32_e32 v218, v172, v208
	s_mov_b32 s2, 32
	v_mfma_f32_32x32x16_bf16 v[80:95], v[108:111], v[80:83], 0
	s_waitcnt lgkmcnt(2)
	v_mfma_f32_32x32x16_bf16 v[80:95], v[104:107], v[132:135], v[80:95]
	ds_read2_b64 v[132:135], v182 offset0:8 offset1:10
	ds_read2_b64 v[144:147], v204 offset0:72 offset1:74
	ds_read2_b64 v[148:151], v205 offset0:136 offset1:138
	v_mfma_f32_32x32x16_bf16 v[64:79], v[96:99], v[128:131], v[64:79]
	v_mfma_f32_32x32x16_bf16 v[80:95], v[100:103], v[128:131], v[80:95]
	s_waitcnt lgkmcnt(4)
	v_mfma_f32_32x32x16_bf16 v[64:79], v[100:103], v[136:139], v[64:79]
	s_waitcnt lgkmcnt(3)
	v_mfma_f32_32x32x16_bf16 v[80:95], v[96:99], v[140:143], v[80:95]
	ds_read2_b64 v[128:131], v182 offset0:12 offset1:14
	ds_read2_b64 v[136:139], v204 offset0:76 offset1:78
	ds_read2_b64 v[140:143], v205 offset0:140 offset1:142
	s_waitcnt lgkmcnt(5)
	v_mfma_f32_32x32x16_bf16 v[64:79], v[112:115], v[132:135], v[64:79]
	v_mfma_f32_32x32x16_bf16 v[80:95], v[120:123], v[132:135], v[80:95]
	s_waitcnt lgkmcnt(4)
	v_mfma_f32_32x32x16_bf16 v[64:79], v[120:123], v[144:147], v[64:79]
	s_waitcnt lgkmcnt(3)
	v_mfma_f32_32x32x16_bf16 v[80:95], v[112:115], v[148:151], v[80:95]
	s_waitcnt lgkmcnt(2)
	v_mfma_f32_32x32x16_bf16 v[64:79], v[116:119], v[128:131], v[64:79]
	v_mfma_f32_32x32x16_bf16 v[80:95], v[124:127], v[128:131], v[80:95]
	s_waitcnt lgkmcnt(1)
	v_mfma_f32_32x32x16_bf16 v[64:79], v[124:127], v[136:139], v[64:79]
	s_waitcnt lgkmcnt(0)
	v_mfma_f32_32x32x16_bf16 v[80:95], v[116:119], v[140:143], v[80:95]
	ds_read2_b64 v[140:143], v211 offset1:2
	ds_read2_b64 v[128:131], v211 offset0:4 offset1:6
	ds_read2_b64 v[148:151], v212 offset0:64 offset1:66
	ds_read2_b64 v[144:147], v213 offset0:128 offset1:130
	ds_read2_b64 v[136:139], v212 offset0:68 offset1:70
	ds_read2_b64 v[132:135], v213 offset0:132 offset1:134
	ds_read_b32 v241, v172
	ds_read_b32 v246, v218
	v_add_u32_e32 v239, v218, v208
	v_add_u32_e32 v238, v239, v208
	ds_read_b32 v244, v239
	ds_read_b32 v245, v238
	v_add_u32_e32 v253, v238, v187
	v_add_u32_e32 v237, v253, v208
	ds_read_b32 v240, v253
	ds_read_b32 v247, v237
	v_add_u32_e32 v250, v237, v208
	v_add_u32_e32 v234, v250, v208
	ds_read_b32 v242, v250
	ds_read_b32 v249, v234
	s_waitcnt lgkmcnt(7)
	s_waitcnt lgkmcnt(6)
	v_add_u32_e32 v236, v234, v187
	v_add_u32_e32 v243, v236, v208
	ds_read_b32 v235, v236
	ds_read_b32 v251, v243
	v_add_u32_e32 v233, v243, v208
	v_add_u32_e32 v248, v233, v208
	ds_read_b32 v252, v233
	ds_read_b32 v239, v248
	v_add_u32_e32 v238, v248, v187
	v_add_u32_e32 v253, v238, v208
	ds_read_b32 v237, v238
	ds_read_b32 v250, v253
	v_add_u32_e32 v234, v253, v208
	ds_read_b32 v236, v234
	v_add_u32_e32 v243, v234, v208
	ds_read_b32 v233, v243
	v_cvt_f32_f16_sdwa v216, v241 dst_sel:DWORD dst_unused:UNUSED_PAD src0_sel:WORD_1
	s_waitcnt lgkmcnt(14)
	v_cvt_f32_f16_sdwa v217, v246 dst_sel:DWORD dst_unused:UNUSED_PAD src0_sel:WORD_1
	v_cvt_f32_f16_e32 v215, v246
	v_cvt_f32_f16_e32 v214, v241
	v_pk_mul_f32 v[172:173], v[64:65], v[216:217]
	s_nop 0
	v_pk_fma_f32 v[172:173], v[80:81], v[214:215], v[172:173] neg_lo:[0,0,1] neg_hi:[0,0,1]
	v_pk_mul_f32 v[80:81], v[80:81], v[216:217]
	s_nop 0
	v_pk_fma_f32 v[64:65], v[64:65], v[214:215], v[80:81]
	v_cvt_pk_bf16_f32 v64, v64, v65
	s_waitcnt lgkmcnt(13)
	v_cvt_f32_f16_sdwa v216, v244 dst_sel:DWORD dst_unused:UNUSED_PAD src0_sel:WORD_1
	s_waitcnt lgkmcnt(12)
	v_cvt_f32_f16_sdwa v217, v245 dst_sel:DWORD dst_unused:UNUSED_PAD src0_sel:WORD_1
	v_cvt_f32_f16_e32 v215, v245
	v_cvt_f32_f16_e32 v214, v244
	v_pk_mul_f32 v[80:81], v[66:67], v[216:217]
	s_nop 0
	v_pk_fma_f32 v[80:81], v[82:83], v[214:215], v[80:81] neg_lo:[0,0,1] neg_hi:[0,0,1]
	v_pk_mul_f32 v[82:83], v[82:83], v[216:217]
	s_nop 0
	v_pk_fma_f32 v[66:67], v[66:67], v[214:215], v[82:83]
	v_cvt_pk_bf16_f32 v65, v66, v67
	s_waitcnt lgkmcnt(11)
	v_cvt_f32_f16_sdwa v216, v240 dst_sel:DWORD dst_unused:UNUSED_PAD src0_sel:WORD_1
	s_waitcnt lgkmcnt(10)
	v_cvt_f32_f16_sdwa v217, v247 dst_sel:DWORD dst_unused:UNUSED_PAD src0_sel:WORD_1
	v_cvt_f32_f16_e32 v215, v247
	v_cvt_f32_f16_e32 v214, v240
	v_pk_mul_f32 v[82:83], v[68:69], v[216:217]
	s_nop 0
	v_pk_fma_f32 v[82:83], v[84:85], v[214:215], v[82:83] neg_lo:[0,0,1] neg_hi:[0,0,1]
	v_pk_mul_f32 v[84:85], v[84:85], v[216:217]
	s_nop 0
	v_pk_fma_f32 v[68:69], v[68:69], v[214:215], v[84:85]
	v_cvt_pk_bf16_f32 v66, v68, v69
	v_cvt_pk_bf16_f32 v68, v172, v173
	v_cvt_pk_bf16_f32 v69, v80, v81
	s_waitcnt lgkmcnt(9)
	v_cvt_f32_f16_e32 v84, v242
	s_waitcnt lgkmcnt(8)
	v_cvt_f32_f16_e32 v85, v249
	v_cvt_f32_f16_sdwa v215, v249 dst_sel:DWORD dst_unused:UNUSED_PAD src0_sel:WORD_1
	v_cvt_f32_f16_sdwa v214, v242 dst_sel:DWORD dst_unused:UNUSED_PAD src0_sel:WORD_1
	v_pk_mul_f32 v[216:217], v[70:71], v[214:215]
	s_nop 0
	v_pk_fma_f32 v[216:217], v[86:87], v[84:85], v[216:217] neg_lo:[0,0,1] neg_hi:[0,0,1]
	v_pk_mul_f32 v[86:87], v[86:87], v[214:215]
	s_nop 0
	v_pk_fma_f32 v[70:71], v[70:71], v[84:85], v[86:87]
	v_cvt_pk_bf16_f32 v67, v70, v71
	v_cvt_pk_bf16_f32 v70, v82, v83
	v_cvt_pk_bf16_f32 v71, v216, v217
	s_waitcnt lgkmcnt(7)
	v_cvt_f32_f16_e32 v84, v235
	s_waitcnt lgkmcnt(6)
	v_cvt_f32_f16_e32 v85, v251
	v_cvt_f32_f16_sdwa v87, v251 dst_sel:DWORD dst_unused:UNUSED_PAD src0_sel:WORD_1
	v_cvt_f32_f16_sdwa v86, v235 dst_sel:DWORD dst_unused:UNUSED_PAD src0_sel:WORD_1
	v_mfma_f32_32x32x16_bf16 v[48:63], v[140:143], v[64:67], v[48:63]
	v_mul_f32_e64 v214, v72, v86
	v_mul_f32_e64 v215, v73, v87
	v_mul_f32_e64 v86, v88, v86
	v_mul_f32_e64 v87, v89, v87
	v_fma_f32 v214, v88, v84, -v214
	v_fma_f32 v215, v89, v85, -v215
	v_pk_fma_f32 v[72:73], v[72:73], v[84:85], v[86:87]
	v_mfma_f32_32x32x16_bf16 v[32:47], v[140:143], v[68:71], v[32:47]
	s_waitcnt lgkmcnt(5)
	v_cvt_f32_f16_e32 v84, v252
	s_waitcnt lgkmcnt(4)
	v_cvt_f32_f16_e32 v85, v239
	v_cvt_f32_f16_sdwa v87, v239 dst_sel:DWORD dst_unused:UNUSED_PAD src0_sel:WORD_1
	v_cvt_f32_f16_sdwa v86, v252 dst_sel:DWORD dst_unused:UNUSED_PAD src0_sel:WORD_1
	v_pk_mul_f32 v[88:89], v[74:75], v[86:87]
	v_pk_mul_f32 v[86:87], v[90:91], v[86:87]
	v_pk_fma_f32 v[88:89], v[90:91], v[84:85], v[88:89] neg_lo:[0,0,1] neg_hi:[0,0,1]
	v_pk_fma_f32 v[74:75], v[74:75], v[84:85], v[86:87]
	v_mfma_f32_32x32x16_bf16 v[48:63], v[148:151], v[68:71], v[48:63]
	v_cvt_pk_bf16_f32 v68, v214, v215
	v_cvt_pk_bf16_f32 v69, v88, v89
	s_waitcnt lgkmcnt(3)
	v_cvt_f32_f16_e32 v84, v237
	s_waitcnt lgkmcnt(2)
	v_cvt_f32_f16_e32 v85, v250
	v_cvt_f32_f16_sdwa v87, v250 dst_sel:DWORD dst_unused:UNUSED_PAD src0_sel:WORD_1
	v_cvt_f32_f16_sdwa v86, v237 dst_sel:DWORD dst_unused:UNUSED_PAD src0_sel:WORD_1
	v_pk_mul_f32 v[90:91], v[76:77], v[86:87]
	v_pk_mul_f32 v[86:87], v[92:93], v[86:87]
	v_pk_fma_f32 v[90:91], v[92:93], v[84:85], v[90:91] neg_lo:[0,0,1] neg_hi:[0,0,1]
	v_pk_fma_f32 v[76:77], v[76:77], v[84:85], v[86:87]
	v_mfma_f32_32x32x16_bf16 v[32:47], v[144:147], v[64:67], v[32:47]
	v_cvt_pk_bf16_f32 v64, v72, v73
	s_waitcnt lgkmcnt(1)
	v_cvt_f32_f16_e32 v84, v236
	v_cvt_f32_f16_sdwa v86, v236 dst_sel:DWORD dst_unused:UNUSED_PAD src0_sel:WORD_1
	s_waitcnt lgkmcnt(0)
	v_cvt_f32_f16_e32 v85, v233
	v_cvt_f32_f16_sdwa v87, v233 dst_sel:DWORD dst_unused:UNUSED_PAD src0_sel:WORD_1
	v_cvt_pk_bf16_f32 v65, v74, v75
	v_cvt_pk_bf16_f32 v66, v76, v77
	v_cvt_pk_bf16_f32 v70, v90, v91
	v_pk_mul_f32 v[92:93], v[78:79], v[86:87]
	v_pk_mul_f32 v[86:87], v[94:95], v[86:87]
	v_pk_fma_f32 v[92:93], v[94:95], v[84:85], v[92:93] neg_lo:[0,0,1] neg_hi:[0,0,1]
	v_pk_fma_f32 v[78:79], v[78:79], v[84:85], v[86:87]
	v_cvt_pk_bf16_f32 v71, v92, v93
	v_cvt_pk_bf16_f32 v67, v78, v79
	s_nop 0
	v_mfma_f32_32x32x16_bf16 v[32:47], v[128:131], v[68:71], v[32:47]
	v_mfma_f32_32x32x16_bf16 v[48:63], v[128:131], v[64:67], v[48:63]
	v_mfma_f32_32x32x16_bf16 v[48:63], v[136:139], v[68:71], v[48:63]
	v_mfma_f32_32x32x16_bf16 v[32:47], v[132:135], v[64:67], v[32:47]
	ds_read2_b64 v[80:83], v184 offset1:2
	ds_read2_b64 v[132:135], v184 offset0:4 offset1:6
	ds_read2_b64 v[84:87], v206 offset0:64 offset1:66
	ds_read2_b64 v[128:131], v207 offset0:128 offset1:130
	ds_read2_b64 v[136:139], v206 offset0:68 offset1:70
	ds_read2_b64 v[140:143], v207 offset0:132 offset1:134
	s_waitcnt lgkmcnt(5)
	v_mfma_f32_32x32x16_bf16 v[64:79], v[104:107], v[80:83], 0
	s_waitcnt lgkmcnt(3)
	v_mfma_f32_32x32x16_bf16 v[64:79], v[108:111], v[84:87], v[64:79]
	v_mfma_f32_32x32x16_bf16 v[80:95], v[108:111], v[80:83], 0
	s_waitcnt lgkmcnt(2)
	v_mfma_f32_32x32x16_bf16 v[80:95], v[104:107], v[128:131], v[80:95]
	ds_read2_b64 v[104:107], v184 offset0:8 offset1:10
	ds_read2_b64 v[128:131], v206 offset0:72 offset1:74
	ds_read2_b64 v[108:111], v207 offset0:136 offset1:138
	v_mfma_f32_32x32x16_bf16 v[64:79], v[96:99], v[132:135], v[64:79]
	v_mfma_f32_32x32x16_bf16 v[80:95], v[100:103], v[132:135], v[80:95]
	s_waitcnt lgkmcnt(4)
	v_mfma_f32_32x32x16_bf16 v[64:79], v[100:103], v[136:139], v[64:79]
	s_waitcnt lgkmcnt(3)
	v_mfma_f32_32x32x16_bf16 v[80:95], v[96:99], v[140:143], v[80:95]
	ds_read2_b64 v[96:99], v184 offset0:12 offset1:14
	ds_read2_b64 v[100:103], v206 offset0:76 offset1:78
	ds_read2_b64 v[132:135], v207 offset0:140 offset1:142
	s_waitcnt lgkmcnt(5)
	v_mfma_f32_32x32x16_bf16 v[64:79], v[112:115], v[104:107], v[64:79]
	v_mfma_f32_32x32x16_bf16 v[80:95], v[120:123], v[104:107], v[80:95]
	s_waitcnt lgkmcnt(4)
	v_mfma_f32_32x32x16_bf16 v[64:79], v[120:123], v[128:131], v[64:79]
	v_mul_u32_u24_e32 v120, v152, v183
	v_lshl_add_u32 v120, v120, 2, s26
	s_waitcnt lgkmcnt(3)
	v_mfma_f32_32x32x16_bf16 v[80:95], v[112:115], v[108:111], v[80:95]
	s_waitcnt lgkmcnt(2)
	v_mfma_f32_32x32x16_bf16 v[64:79], v[116:119], v[96:99], v[64:79]
	v_mfma_f32_32x32x16_bf16 v[80:95], v[124:127], v[96:99], v[80:95]
	s_waitcnt lgkmcnt(1)
	v_mfma_f32_32x32x16_bf16 v[64:79], v[124:127], v[100:103], v[64:79]
	v_add_u32_e32 v126, v120, v209
	s_waitcnt lgkmcnt(0)
	v_mfma_f32_32x32x16_bf16 v[80:95], v[116:119], v[132:135], v[80:95]
	ds_read2_b64 v[112:115], v211 offset1:2
	ds_read2_b64 v[100:103], v211 offset0:4 offset1:6
	ds_read2_b64 v[116:119], v212 offset0:64 offset1:66
	ds_read2_b64 v[108:111], v213 offset0:128 offset1:130
	ds_read2_b64 v[104:107], v212 offset0:68 offset1:70
	ds_read2_b64 v[96:99], v213 offset0:132 offset1:134
	ds_read_b32 v248, v120
	ds_read_b32 v238, v126
	v_add_u32_e32 v253, v126, v209
	v_add_u32_e32 v234, v253, v209
	ds_read_b32 v243, v253
	ds_read_b32 v241, v234
	v_add_u32_e32 v246, v234, v188
	v_add_u32_e32 v244, v246, v209
	ds_read_b32 v245, v246
	ds_read_b32 v240, v244
	v_add_u32_e32 v247, v244, v209
	v_add_u32_e32 v242, v247, v209
	ds_read_b32 v249, v247
	ds_read_b32 v235, v242
	s_waitcnt lgkmcnt(7)
	s_waitcnt lgkmcnt(6)
	v_add_u32_e32 v251, v242, v188
	v_add_u32_e32 v252, v251, v209
	ds_read_b32 v239, v251
	ds_read_b32 v237, v252
	v_add_u32_e32 v250, v252, v209
	v_add_u32_e32 v236, v250, v209
	ds_read_b32 v233, v250
	ds_read_b32 v253, v236
	v_add_u32_e32 v234, v236, v188
	v_add_u32_e32 v246, v234, v209
	ds_read_b32 v244, v234
	ds_read_b32 v247, v246
	v_add_u32_e32 v242, v246, v209
	ds_read_b32 v251, v242
	v_add_u32_e32 v252, v242, v209
	ds_read_b32 v250, v252
	v_cvt_f32_f16_sdwa v124, v248 dst_sel:DWORD dst_unused:UNUSED_PAD src0_sel:WORD_1
	s_waitcnt lgkmcnt(14)
	v_cvt_f32_f16_sdwa v125, v238 dst_sel:DWORD dst_unused:UNUSED_PAD src0_sel:WORD_1
	v_cvt_f32_f16_e32 v123, v238
	v_cvt_f32_f16_e32 v122, v248
	v_pk_mul_f32 v[120:121], v[64:65], v[124:125]
	s_nop 0
	v_pk_fma_f32 v[120:121], v[80:81], v[122:123], v[120:121] neg_lo:[0,0,1] neg_hi:[0,0,1]
	v_pk_mul_f32 v[80:81], v[80:81], v[124:125]
	s_nop 0
	v_pk_fma_f32 v[80:81], v[64:65], v[122:123], v[80:81]
	v_cvt_pk_bf16_f32 v80, v80, v81
	s_waitcnt lgkmcnt(13)
	v_cvt_f32_f16_sdwa v124, v243 dst_sel:DWORD dst_unused:UNUSED_PAD src0_sel:WORD_1
	s_waitcnt lgkmcnt(12)
	v_cvt_f32_f16_sdwa v125, v241 dst_sel:DWORD dst_unused:UNUSED_PAD src0_sel:WORD_1
	v_cvt_f32_f16_e32 v65, v241
	v_cvt_f32_f16_e32 v64, v243
	v_pk_mul_f32 v[122:123], v[66:67], v[124:125]
	s_nop 0
	v_pk_fma_f32 v[122:123], v[82:83], v[64:65], v[122:123] neg_lo:[0,0,1] neg_hi:[0,0,1]
	v_pk_mul_f32 v[82:83], v[82:83], v[124:125]
	s_nop 0
	v_pk_fma_f32 v[82:83], v[66:67], v[64:65], v[82:83]
	v_cvt_pk_bf16_f32 v81, v82, v83
	s_waitcnt lgkmcnt(11)
	v_cvt_f32_f16_e32 v64, v245
	s_waitcnt lgkmcnt(10)
	v_cvt_f32_f16_e32 v65, v240
	v_cvt_f32_f16_sdwa v67, v240 dst_sel:DWORD dst_unused:UNUSED_PAD src0_sel:WORD_1
	v_cvt_f32_f16_sdwa v66, v245 dst_sel:DWORD dst_unused:UNUSED_PAD src0_sel:WORD_1
	v_pk_mul_f32 v[124:125], v[68:69], v[66:67]
	v_pk_mul_f32 v[66:67], v[84:85], v[66:67]
	v_pk_fma_f32 v[124:125], v[84:85], v[64:65], v[124:125] neg_lo:[0,0,1] neg_hi:[0,0,1]
	v_pk_fma_f32 v[84:85], v[68:69], v[64:65], v[66:67]
	v_cvt_pk_bf16_f32 v82, v84, v85
	v_cvt_pk_bf16_f32 v84, v120, v121
	v_cvt_pk_bf16_f32 v85, v122, v123
	s_waitcnt lgkmcnt(9)
	v_cvt_f32_f16_e32 v64, v249
	s_waitcnt lgkmcnt(8)
	v_cvt_f32_f16_e32 v65, v235
	v_cvt_f32_f16_sdwa v67, v235 dst_sel:DWORD dst_unused:UNUSED_PAD src0_sel:WORD_1
	v_cvt_f32_f16_sdwa v66, v249 dst_sel:DWORD dst_unused:UNUSED_PAD src0_sel:WORD_1
	v_pk_mul_f32 v[68:69], v[70:71], v[66:67]
	v_pk_mul_f32 v[66:67], v[86:87], v[66:67]
	v_pk_fma_f32 v[126:127], v[86:87], v[64:65], v[68:69] neg_lo:[0,0,1] neg_hi:[0,0,1]
	v_pk_fma_f32 v[86:87], v[70:71], v[64:65], v[66:67]
	v_cvt_pk_bf16_f32 v83, v86, v87
	v_cvt_pk_bf16_f32 v86, v124, v125
	v_cvt_pk_bf16_f32 v87, v126, v127
	s_waitcnt lgkmcnt(7)
	v_cvt_f32_f16_sdwa v68, v239 dst_sel:DWORD dst_unused:UNUSED_PAD src0_sel:WORD_1
	s_waitcnt lgkmcnt(6)
	v_cvt_f32_f16_sdwa v69, v237 dst_sel:DWORD dst_unused:UNUSED_PAD src0_sel:WORD_1
	v_cvt_f32_f16_e32 v67, v237
	v_cvt_f32_f16_e32 v66, v239
	v_mfma_f32_32x32x16_bf16 v[16:31], v[112:115], v[80:83], v[16:31]
	v_mul_f32_e64 v64, v72, v68
	v_mul_f32_e64 v65, v73, v69
	v_mul_f32_e64 v68, v88, v68
	v_mul_f32_e64 v69, v89, v69
	v_fma_f32 v64, v88, v66, -v64
	v_fma_f32 v65, v89, v67, -v65
	v_pk_fma_f32 v[66:67], v[72:73], v[66:67], v[68:69]
	v_mfma_f32_32x32x16_bf16 v[0:15], v[112:115], v[84:87], v[0:15]
	v_cvt_pk_bf16_f32 v64, v64, v65
	s_waitcnt lgkmcnt(5)
	v_cvt_f32_f16_sdwa v72, v233 dst_sel:DWORD dst_unused:UNUSED_PAD src0_sel:WORD_1
	s_waitcnt lgkmcnt(4)
	v_cvt_f32_f16_sdwa v73, v253 dst_sel:DWORD dst_unused:UNUSED_PAD src0_sel:WORD_1
	v_cvt_f32_f16_e32 v71, v253
	v_cvt_f32_f16_e32 v70, v233
	v_pk_mul_f32 v[68:69], v[74:75], v[72:73]
	v_pk_mul_f32 v[72:73], v[90:91], v[72:73]
	v_pk_fma_f32 v[68:69], v[90:91], v[70:71], v[68:69] neg_lo:[0,0,1] neg_hi:[0,0,1]
	v_pk_fma_f32 v[70:71], v[74:75], v[70:71], v[72:73]
	v_mfma_f32_32x32x16_bf16 v[16:31], v[116:119], v[84:87], v[16:31]
	v_cvt_pk_bf16_f32 v65, v68, v69
	s_waitcnt lgkmcnt(3)
	v_cvt_f32_f16_sdwa v88, v244 dst_sel:DWORD dst_unused:UNUSED_PAD src0_sel:WORD_1
	s_waitcnt lgkmcnt(2)
	v_cvt_f32_f16_sdwa v89, v247 dst_sel:DWORD dst_unused:UNUSED_PAD src0_sel:WORD_1
	v_cvt_f32_f16_e32 v75, v247
	v_cvt_f32_f16_e32 v74, v244
	v_pk_mul_f32 v[72:73], v[76:77], v[88:89]
	v_pk_mul_f32 v[88:89], v[92:93], v[88:89]
	v_pk_fma_f32 v[72:73], v[92:93], v[74:75], v[72:73] neg_lo:[0,0,1] neg_hi:[0,0,1]
	v_pk_fma_f32 v[74:75], v[76:77], v[74:75], v[88:89]
	v_mfma_f32_32x32x16_bf16 v[0:15], v[108:111], v[80:83], v[0:15]
	v_cvt_pk_bf16_f32 v80, v66, v67
	s_waitcnt lgkmcnt(1)
	v_cvt_f32_f16_sdwa v90, v251 dst_sel:DWORD dst_unused:UNUSED_PAD src0_sel:WORD_1
	v_cvt_f32_f16_e32 v88, v251
	s_waitcnt lgkmcnt(0)
	v_cvt_f32_f16_sdwa v91, v250 dst_sel:DWORD dst_unused:UNUSED_PAD src0_sel:WORD_1
	v_cvt_f32_f16_e32 v89, v250
	v_cvt_pk_bf16_f32 v81, v70, v71
	v_cvt_pk_bf16_f32 v82, v74, v75
	v_pk_mul_f32 v[76:77], v[78:79], v[90:91]
	v_pk_mul_f32 v[90:91], v[94:95], v[90:91]
	v_pk_fma_f32 v[76:77], v[94:95], v[88:89], v[76:77] neg_lo:[0,0,1] neg_hi:[0,0,1]
	v_pk_fma_f32 v[78:79], v[78:79], v[88:89], v[90:91]
	v_cvt_pk_bf16_f32 v66, v72, v73
	v_cvt_pk_bf16_f32 v83, v78, v79
	v_cvt_pk_bf16_f32 v67, v76, v77
	s_nop 0
	v_mfma_f32_32x32x16_bf16 v[16:31], v[100:103], v[80:83], v[16:31]
	v_mfma_f32_32x32x16_bf16 v[0:15], v[100:103], v[64:67], v[0:15]
	v_mfma_f32_32x32x16_bf16 v[16:31], v[104:107], v[64:67], v[16:31]
	v_mfma_f32_32x32x16_bf16 v[0:15], v[96:99], v[80:83], v[0:15]
	s_cbranch_vccnz .LBB0_729
	v_cvt_pk_bf16_f32 v32, v32, s0
	s_waitcnt lgkmcnt(0)
	v_cvt_pk_bf16_f32 v48, v48, s0
	ds_write_b16 v189, v32 offset:6144
	v_cvt_pk_bf16_f32 v32, v49, s0
	ds_write_b16 v189, v48
	ds_write_b16 v210, v32
	v_cvt_pk_bf16_f32 v32, v33, s0
	ds_write_b16 v210, v32 offset:6144
	v_cvt_pk_bf16_f32 v32, v50, s0
	ds_write_b16 v190, v32
	v_cvt_pk_bf16_f32 v32, v34, s0
	ds_write_b16 v190, v32 offset:6144
	v_cvt_pk_bf16_f32 v32, v51, s0
	ds_write_b16 v191, v32
	v_cvt_pk_bf16_f32 v32, v35, s0
	ds_write_b16 v191, v32 offset:6144
	v_cvt_pk_bf16_f32 v32, v52, s0
	ds_write_b16 v192, v32
	v_cvt_pk_bf16_f32 v32, v36, s0
	ds_write_b16 v192, v32 offset:6144
	v_cvt_pk_bf16_f32 v32, v53, s0
	ds_write_b16 v193, v32
	v_cvt_pk_bf16_f32 v32, v37, s0
	ds_write_b16 v193, v32 offset:6144
	v_cvt_pk_bf16_f32 v32, v54, s0
	ds_write_b16 v194, v32
	v_cvt_pk_bf16_f32 v32, v38, s0
	ds_write_b16 v194, v32 offset:6144
	v_cvt_pk_bf16_f32 v32, v55, s0
	ds_write_b16 v195, v32
	v_cvt_pk_bf16_f32 v32, v39, s0
	ds_write_b16 v195, v32 offset:6144
	v_cvt_pk_bf16_f32 v32, v56, s0
	ds_write_b16 v196, v32
	v_cvt_pk_bf16_f32 v32, v40, s0
	ds_write_b16 v196, v32 offset:6144
	v_cvt_pk_bf16_f32 v32, v57, s0
	ds_write_b16 v197, v32
	v_cvt_pk_bf16_f32 v32, v41, s0
	ds_write_b16 v197, v32 offset:6144
	v_cvt_pk_bf16_f32 v32, v58, s0
	ds_write_b16 v198, v32
	v_cvt_pk_bf16_f32 v32, v42, s0
	ds_write_b16 v198, v32 offset:6144
	v_cvt_pk_bf16_f32 v32, v59, s0
	ds_write_b16 v199, v32
	v_cvt_pk_bf16_f32 v32, v43, s0
	ds_write_b16 v199, v32 offset:6144
	v_cvt_pk_bf16_f32 v32, v60, s0
	ds_write_b16 v200, v32
	v_cvt_pk_bf16_f32 v32, v44, s0
	ds_write_b16 v200, v32 offset:6144
	v_cvt_pk_bf16_f32 v32, v61, s0
	ds_write_b16 v201, v32
	v_cvt_pk_bf16_f32 v32, v45, s0
	ds_write_b16 v201, v32 offset:6144
	v_cvt_pk_bf16_f32 v32, v62, s0
	ds_write_b16 v202, v32
	v_cvt_pk_bf16_f32 v32, v46, s0
	ds_write_b16 v202, v32 offset:6144
	v_cvt_pk_bf16_f32 v32, v63, s0
	ds_write_b16 v203, v32
	v_cvt_pk_bf16_f32 v32, v47, s0
	v_cvt_pk_bf16_f32 v0, v0, s0
	ds_write_b16 v203, v32 offset:6144
	v_cvt_pk_bf16_f32 v16, v16, s0
	ds_write_b16 v189, v0 offset:6208
	v_cvt_pk_bf16_f32 v0, v17, s0
	ds_write_b16 v189, v16 offset:64
	ds_write_b16 v210, v0 offset:64
	v_cvt_pk_bf16_f32 v0, v1, s0
	ds_write_b16 v210, v0 offset:6208
	v_cvt_pk_bf16_f32 v0, v18, s0
	ds_write_b16 v190, v0 offset:64
	v_cvt_pk_bf16_f32 v0, v2, s0
	ds_write_b16 v190, v0 offset:6208
	v_cvt_pk_bf16_f32 v0, v19, s0
	ds_write_b16 v191, v0 offset:64
	v_cvt_pk_bf16_f32 v0, v3, s0
	ds_write_b16 v191, v0 offset:6208
	v_cvt_pk_bf16_f32 v0, v20, s0
	ds_write_b16 v192, v0 offset:64
	v_cvt_pk_bf16_f32 v0, v4, s0
	ds_write_b16 v192, v0 offset:6208
	v_cvt_pk_bf16_f32 v0, v21, s0
	ds_write_b16 v193, v0 offset:64
	v_cvt_pk_bf16_f32 v0, v5, s0
	ds_write_b16 v193, v0 offset:6208
	v_cvt_pk_bf16_f32 v0, v22, s0
	ds_write_b16 v194, v0 offset:64
	v_cvt_pk_bf16_f32 v0, v6, s0
	ds_write_b16 v194, v0 offset:6208
	v_cvt_pk_bf16_f32 v0, v23, s0
	ds_write_b16 v195, v0 offset:64
	v_cvt_pk_bf16_f32 v0, v7, s0
	ds_write_b16 v195, v0 offset:6208
	v_cvt_pk_bf16_f32 v0, v24, s0
	ds_write_b16 v196, v0 offset:64
	v_cvt_pk_bf16_f32 v0, v8, s0
	ds_write_b16 v196, v0 offset:6208
	v_cvt_pk_bf16_f32 v0, v25, s0
	ds_write_b16 v197, v0 offset:64
	v_cvt_pk_bf16_f32 v0, v9, s0
	ds_write_b16 v197, v0 offset:6208
	v_cvt_pk_bf16_f32 v0, v26, s0
	ds_write_b16 v198, v0 offset:64
	v_cvt_pk_bf16_f32 v0, v10, s0
	ds_write_b16 v198, v0 offset:6208
	v_cvt_pk_bf16_f32 v0, v27, s0
	ds_write_b16 v199, v0 offset:64
	v_cvt_pk_bf16_f32 v0, v11, s0
	ds_write_b16 v199, v0 offset:6208
	v_cvt_pk_bf16_f32 v0, v28, s0
	ds_write_b16 v200, v0 offset:64
	v_cvt_pk_bf16_f32 v0, v12, s0
	ds_write_b16 v200, v0 offset:6208
	v_cvt_pk_bf16_f32 v0, v29, s0
	ds_write_b16 v201, v0 offset:64
	v_cvt_pk_bf16_f32 v0, v13, s0
	ds_write_b16 v201, v0 offset:6208
	v_cvt_pk_bf16_f32 v0, v30, s0
	ds_write_b16 v202, v0 offset:64
	v_cvt_pk_bf16_f32 v0, v14, s0
	ds_write_b16 v202, v0 offset:6208
	v_cvt_pk_bf16_f32 v0, v31, s0
	s_or_b32 s2, s49, 0x400
	ds_write_b16 v203, v0 offset:64
	v_cvt_pk_bf16_f32 v0, v15, s0
	s_lshl_b32 s16, s2, 11
	ds_write_b16 v203, v0 offset:6208
	v_lshl_add_u64 v[0:1], v[170:171], 0, s[16:17]
	v_or_b32_e32 v0, v0, v154
	v_lshl_add_u64 v[40:41], v[0:1], 4, s[18:19]
	v_mov_b32_e32 v4, 0
	v_mov_b32_e32 v0, 0
	v_mov_b32_e32 v1, 0
	v_mov_b32_e32 v2, 0
	v_mov_b32_e32 v3, 0
	s_waitcnt lgkmcnt(0)
	s_barrier
	s_and_saveexec_b64 s[14:15], s[4:5]
	s_cbranch_execz .LBB0_732
	global_load_dwordx4 v[0:3], v[40:41], off offset:-16

.LBB0_751:
	v_pk_add_f32 v[128:129], v[130:131], v[128:129]
	v_pk_add_f32 v[144:145], v[146:147], v[144:145]
	v_pk_add_f32 v[128:129], v[132:133], v[128:129]
	v_pk_add_f32 v[144:145], v[148:149], v[144:145]
	v_pk_add_f32 v[128:129], v[134:135], v[128:129]
	v_pk_add_f32 v[144:145], v[150:151], v[144:145]
	v_pk_add_f32 v[128:129], v[136:137], v[128:129]
	v_pk_add_f32 v[144:145], v[152:153], v[144:145]
	v_pk_add_f32 v[128:129], v[138:139], v[128:129]
	v_pk_add_f32 v[144:145], v[154:155], v[144:145]
	v_pk_add_f32 v[128:129], v[140:141], v[128:129]
	v_pk_add_f32 v[144:145], v[156:157], v[144:145]
	v_pk_add_f32 v[128:129], v[142:143], v[128:129]
	v_pk_add_f32 v[144:145], v[158:159], v[144:145]
	v_add_f32_e32 v128, v128, v129
	v_add_f32_e32 v129, v144, v145
	v_add_f32_e32 v128, v128, v129
	v_add_f32_e32 v128, v246, v128

.LBB0_757:
	v_pk_add_f32 v[96:97], v[98:99], v[96:97]
	v_pk_add_f32 v[112:113], v[114:115], v[112:113]
	v_pk_add_f32 v[96:97], v[100:101], v[96:97]
	v_pk_add_f32 v[112:113], v[116:117], v[112:113]
	v_pk_add_f32 v[96:97], v[102:103], v[96:97]
	v_pk_add_f32 v[112:113], v[118:119], v[112:113]
	v_pk_add_f32 v[96:97], v[104:105], v[96:97]
	v_pk_add_f32 v[112:113], v[120:121], v[112:113]
	v_pk_add_f32 v[96:97], v[106:107], v[96:97]
	v_pk_add_f32 v[112:113], v[122:123], v[112:113]
	v_pk_add_f32 v[96:97], v[108:109], v[96:97]
	v_pk_add_f32 v[112:113], v[124:125], v[112:113]
	v_pk_add_f32 v[96:97], v[126:127], v[96:97]
	v_pk_add_f32 v[96:97], v[112:113], v[96:97]
	v_add_f32_e32 v96, v96, v97
	v_add_f32_e32 v96, v129, v96
	s_add_u32 s18, s18, 0x20000
	v_add_f32_e32 v96, v130, v96
	s_addc_u32 s19, s19, 0
	s_add_i32 s20, s17, 2
	v_add_f32_e32 v246, v128, v96
	s_cmp_lt_u32 s17, 29
	s_waitcnt lgkmcnt(0)
	s_barrier
	s_cbranch_scc0 .LBB0_759
	s_mov_b32 s17, s20
	s_branch .LBB0_740

.LBB0_1172:
	s_lshl_b32 s45, s58, 8
	v_add_u32_e32 v148, s45, v168
	v_ashrrev_i32_e32 v149, 31, v148
	s_lshl_b32 s60, s56, 8
	v_lshlrev_b64 v[150:151], 11, v[148:149]
	s_ashr_i32 s61, s60, 31
	v_lshl_add_u64 v[150:151], s[22:23], 0, v[150:151]
	v_lshl_add_u64 v[150:151], s[60:61], 1, v[150:151]
	s_lshl_b32 s14, s34, 1
	v_lshl_add_u64 v[150:151], v[150:151], 0, s[14:15]
	v_lshlrev_b32_e32 v0, 1, v142
	v_lshl_add_u64 v[194:195], v[150:151], 0, v[0:1]
	global_load_dwordx4 v[200:203], v[194:195], off
	global_load_dwordx4 v[204:207], v[194:195], off offset:256
	v_or_b32_e32 v234, 16, v148
	v_ashrrev_i32_e32 v235, 31, v234
	v_lshlrev_b64 v[234:235], 11, v[234:235]
	v_lshl_add_u64 v[234:235], s[22:23], 0, v[234:235]
	v_lshl_add_u64 v[234:235], s[60:61], 1, v[234:235]
	v_lshl_add_u64 v[234:235], v[234:235], 0, s[14:15]
	v_lshl_add_u64 v[252:253], v[234:235], 0, v[0:1]
	global_load_dwordx4 v[208:211], v[252:253], off
	global_load_dwordx4 v[212:215], v[252:253], off offset:256
	v_or_b32_e32 v234, 32, v148
	v_ashrrev_i32_e32 v235, 31, v234
	v_lshlrev_b64 v[234:235], 11, v[234:235]
	v_lshl_add_u64 v[234:235], s[22:23], 0, v[234:235]
	v_lshl_add_u64 v[234:235], s[60:61], 1, v[234:235]
	v_lshl_add_u64 v[234:235], v[234:235], 0, s[14:15]
	v_lshl_add_u64 v[252:253], v[234:235], 0, v[0:1]
	global_load_dwordx4 v[216:219], v[252:253], off
	global_load_dwordx4 v[220:223], v[252:253], off offset:256
	v_or_b32_e32 v234, 48, v148
	v_ashrrev_i32_e32 v235, 31, v234
	v_lshlrev_b64 v[234:235], 11, v[234:235]
	v_lshl_add_u64 v[234:235], s[22:23], 0, v[234:235]
	v_lshl_add_u64 v[234:235], s[60:61], 1, v[234:235]
	v_lshl_add_u64 v[234:235], v[234:235], 0, s[14:15]
	v_lshl_add_u64 v[252:253], v[234:235], 0, v[0:1]
	global_load_dwordx4 v[224:227], v[252:253], off
	global_load_dwordx4 v[228:231], v[252:253], off offset:256
	v_add_u32_e32 v234, 0x80, v148
	v_ashrrev_i32_e32 v235, 31, v234
	v_lshlrev_b64 v[234:235], 11, v[234:235]
	v_lshl_add_u64 v[234:235], s[22:23], 0, v[234:235]
	v_lshl_add_u64 v[234:235], s[60:61], 1, v[234:235]
	v_lshl_add_u64 v[234:235], v[234:235], 0, s[14:15]
	v_lshl_add_u64 v[252:253], v[234:235], 0, v[0:1]
	global_load_dwordx4 v[236:239], v[252:253], off
	global_load_dwordx4 v[240:243], v[252:253], off offset:256
	v_add_u32_e32 v234, 0x90, v148
	v_ashrrev_i32_e32 v235, 31, v234
	v_lshlrev_b64 v[234:235], 11, v[234:235]
	v_lshl_add_u64 v[234:235], s[22:23], 0, v[234:235]
	v_lshl_add_u64 v[234:235], s[60:61], 1, v[234:235]
	v_lshl_add_u64 v[234:235], v[234:235], 0, s[14:15]
	v_lshl_add_u64 v[252:253], v[234:235], 0, v[0:1]
	global_load_dwordx4 v[244:247], v[252:253], off
	global_load_dwordx4 v[248:251], v[252:253], off offset:256
	v_and_b32_e32 v151, 64, v164
	v_xor_b32_e32 v150, 16, v164
	v_add_u32_e32 v160, 64, v151
	v_cmp_lt_i32_e32 vcc, v150, v160
	v_xor_b32_e32 v153, 32, v164
	s_waitcnt vmcnt(10)
	v_and_b32_e32 v151, 0xffff0000, v200
	v_cndmask_b32_e32 v150, v164, v150, vcc
	v_lshlrev_b32_e32 v152, 2, v150
	v_lshlrev_b32_e32 v150, 16, v200
	v_lshlrev_b32_e32 v158, 16, v202
	v_and_b32_e32 v159, 0xffff0000, v202
	v_lshlrev_b32_e32 v156, 16, v203
	v_and_b32_e32 v157, 0xffff0000, v203
	v_pk_add_f32 v[126:127], v[126:127], v[150:151]
	v_lshlrev_b32_e32 v154, 16, v201
	v_and_b32_e32 v155, 0xffff0000, v201
	v_pk_add_f32 v[122:123], v[122:123], v[158:159]
	v_pk_add_f32 v[124:125], v[124:125], v[156:157]
	v_cvt_pk_bf16_f32 v156, v126, v127
	v_pk_add_f32 v[128:129], v[128:129], v[154:155]
	v_cvt_pk_bf16_f32 v158, v122, v123
	v_and_b32_e32 v123, 0xffff0000, v156
	v_cvt_pk_bf16_f32 v157, v128, v129
	v_lshlrev_b32_e32 v122, 16, v156
	v_mul_f32_e32 v151, v123, v123
	v_lshlrev_b32_e32 v126, 16, v157
	v_fmac_f32_e32 v151, v122, v122
	v_and_b32_e32 v127, 0xffff0000, v157
	v_fmac_f32_e32 v151, v126, v126
	v_cvt_pk_bf16_f32 v159, v124, v125
	v_lshlrev_b32_e32 v124, 16, v158
	v_fmac_f32_e32 v151, v127, v127
	v_lshlrev_b32_e32 v196, 16, v204
	v_and_b32_e32 v197, 0xffff0000, v204
	v_and_b32_e32 v125, 0xffff0000, v158
	v_fmac_f32_e32 v151, v124, v124
	v_lshlrev_b32_e32 v190, 16, v205
	v_and_b32_e32 v191, 0xffff0000, v205
	v_lshlrev_b32_e32 v198, 16, v206
	v_and_b32_e32 v199, 0xffff0000, v206
	v_pk_add_f32 v[118:119], v[118:119], v[196:197]
	v_lshlrev_b32_e32 v128, 16, v159
	v_fmac_f32_e32 v151, v125, v125
	v_lshlrev_b32_e32 v192, 16, v207
	v_and_b32_e32 v193, 0xffff0000, v207
	v_pk_add_f32 v[120:121], v[120:121], v[190:191]
	v_pk_add_f32 v[114:115], v[114:115], v[198:199]
	v_cvt_pk_bf16_f32 v190, v118, v119
	v_and_b32_e32 v129, 0xffff0000, v159
	v_fmac_f32_e32 v151, v128, v128
	v_pk_add_f32 v[116:117], v[116:117], v[192:193]
	v_cvt_pk_bf16_f32 v192, v114, v115
	v_lshlrev_b32_e32 v114, 16, v190
	v_max3_f32 v150, |v122|, 0, |v123|
	v_fmac_f32_e32 v151, v129, v129
	v_cvt_pk_bf16_f32 v191, v120, v121
	v_and_b32_e32 v115, 0xffff0000, v190
	v_max3_f32 v150, v150, |v126|, |v127|
	v_fmac_f32_e32 v151, v114, v114
	v_lshlrev_b32_e32 v118, 16, v191
	v_max3_f32 v150, v150, |v124|, |v125|
	v_fmac_f32_e32 v151, v115, v115
	v_and_b32_e32 v119, 0xffff0000, v191
	v_max3_f32 v150, v150, |v128|, |v129|
	v_fmac_f32_e32 v151, v118, v118
	v_cvt_pk_bf16_f32 v193, v116, v117
	v_lshlrev_b32_e32 v116, 16, v192
	v_max3_f32 v150, v150, |v114|, |v115|
	v_fmac_f32_e32 v151, v119, v119
	v_and_b32_e32 v117, 0xffff0000, v192
	v_max3_f32 v150, v150, |v118|, |v119|
	v_fmac_f32_e32 v151, v116, v116
	v_lshlrev_b32_e32 v120, 16, v193
	v_and_b32_e32 v121, 0xffff0000, v193
	v_max3_f32 v150, v150, |v116|, |v117|
	v_fmac_f32_e32 v151, v117, v117
	v_max3_f32 v150, v150, |v120|, |v121|
	v_fmac_f32_e32 v151, v120, v120
	ds_bpermute_b32 v154, v152, v150
	v_fmac_f32_e32 v151, v121, v121
	ds_bpermute_b32 v155, v152, v151
	v_cmp_lt_i32_e32 vcc, v153, v160
	global_store_dwordx4 v[194:195], v[156:159], off
	global_store_dwordx4 v[194:195], v[190:193], off offset:256
	v_cndmask_b32_e32 v153, v164, v153, vcc
	s_waitcnt lgkmcnt(1)
	v_max_f32_e32 v154, v154, v154
	v_lshlrev_b32_e32 v153, 2, v153
	v_max_f32_e32 v150, v150, v154
	s_waitcnt lgkmcnt(0)
	v_add_f32_e32 v151, v151, v155
	ds_bpermute_b32 v154, v153, v151
	ds_bpermute_b32 v155, v153, v150
	s_and_saveexec_b64 s[48:49], s[4:5]
	s_cbranch_execz .LBB0_1174
	s_waitcnt lgkmcnt(1)
	v_add_f32_e32 v151, v151, v154
	s_waitcnt lgkmcnt(0)
	v_max_f32_e32 v154, v155, v155
	v_max_f32_e32 v150, v150, v150
	v_max_f32_e32 v150, v150, v154
	ds_write2st64_b32 v177, v151, v150 offset1:16
.LBB0_1174:
	s_or_b64 exec, exec, s[48:49]
	v_add_u32_e32 v234, 0xa0, v148
	v_ashrrev_i32_e32 v235, 31, v234
	v_lshlrev_b64 v[234:235], 11, v[234:235]
	v_lshl_add_u64 v[234:235], s[22:23], 0, v[234:235]
	v_lshl_add_u64 v[234:235], s[60:61], 1, v[234:235]
	v_lshl_add_u64 v[234:235], v[234:235], 0, s[14:15]
	v_lshl_add_u64 v[252:253], v[234:235], 0, v[0:1]
	global_load_dwordx4 v[200:203], v[252:253], off
	global_load_dwordx4 v[204:207], v[252:253], off offset:256
	v_or_b32_e32 v150, 16, v148
	v_ashrrev_i32_e32 v151, 31, v150
	v_lshlrev_b64 v[150:151], 11, v[150:151]
	v_lshl_add_u64 v[150:151], s[22:23], 0, v[150:151]
	v_lshl_add_u64 v[150:151], s[60:61], 1, v[150:151]
	v_lshl_add_u64 v[150:151], v[150:151], 0, s[14:15]
	v_lshl_add_u64 v[194:195], v[150:151], 0, v[0:1]
	s_waitcnt lgkmcnt(0)
	s_waitcnt vmcnt(13)
	v_lshlrev_b32_e32 v150, 16, v208
	v_and_b32_e32 v151, 0xffff0000, v208
	v_lshlrev_b32_e32 v158, 16, v210
	v_and_b32_e32 v159, 0xffff0000, v210
	v_lshlrev_b32_e32 v156, 16, v211
	v_and_b32_e32 v157, 0xffff0000, v211
	v_pk_add_f32 v[110:111], v[110:111], v[150:151]
	v_lshlrev_b32_e32 v154, 16, v209
	v_and_b32_e32 v155, 0xffff0000, v209
	v_pk_add_f32 v[106:107], v[106:107], v[158:159]
	v_pk_add_f32 v[108:109], v[108:109], v[156:157]
	v_cvt_pk_bf16_f32 v156, v110, v111
	v_pk_add_f32 v[112:113], v[112:113], v[154:155]
	v_cvt_pk_bf16_f32 v158, v106, v107
	v_and_b32_e32 v107, 0xffff0000, v156
	v_cvt_pk_bf16_f32 v157, v112, v113
	v_lshlrev_b32_e32 v106, 16, v156
	v_mul_f32_e32 v151, v107, v107
	v_lshlrev_b32_e32 v110, 16, v157
	v_fmac_f32_e32 v151, v106, v106
	v_and_b32_e32 v111, 0xffff0000, v157
	v_fmac_f32_e32 v151, v110, v110
	v_cvt_pk_bf16_f32 v159, v108, v109
	v_lshlrev_b32_e32 v108, 16, v158
	v_fmac_f32_e32 v151, v111, v111
	s_waitcnt vmcnt(12)
	v_lshlrev_b32_e32 v196, 16, v212
	v_and_b32_e32 v197, 0xffff0000, v212
	v_and_b32_e32 v109, 0xffff0000, v158
	v_fmac_f32_e32 v151, v108, v108
	v_lshlrev_b32_e32 v190, 16, v213
	v_and_b32_e32 v191, 0xffff0000, v213
	v_lshlrev_b32_e32 v198, 16, v214
	v_and_b32_e32 v199, 0xffff0000, v214
	v_pk_add_f32 v[102:103], v[102:103], v[196:197]
	v_lshlrev_b32_e32 v112, 16, v159
	v_fmac_f32_e32 v151, v109, v109
	v_lshlrev_b32_e32 v192, 16, v215
	v_and_b32_e32 v193, 0xffff0000, v215
	v_pk_add_f32 v[104:105], v[104:105], v[190:191]
	v_pk_add_f32 v[98:99], v[98:99], v[198:199]
	v_cvt_pk_bf16_f32 v190, v102, v103
	v_and_b32_e32 v113, 0xffff0000, v159
	v_fmac_f32_e32 v151, v112, v112
	v_pk_add_f32 v[100:101], v[100:101], v[192:193]
	v_cvt_pk_bf16_f32 v192, v98, v99
	v_lshlrev_b32_e32 v98, 16, v190
	v_max3_f32 v150, |v106|, 0, |v107|
	v_fmac_f32_e32 v151, v113, v113
	v_cvt_pk_bf16_f32 v191, v104, v105
	v_and_b32_e32 v99, 0xffff0000, v190
	v_max3_f32 v150, v150, |v110|, |v111|
	v_fmac_f32_e32 v151, v98, v98
	v_lshlrev_b32_e32 v102, 16, v191
	v_max3_f32 v150, v150, |v108|, |v109|
	v_fmac_f32_e32 v151, v99, v99
	v_and_b32_e32 v103, 0xffff0000, v191
	v_max3_f32 v150, v150, |v112|, |v113|
	v_fmac_f32_e32 v151, v102, v102
	v_cvt_pk_bf16_f32 v193, v100, v101
	v_lshlrev_b32_e32 v100, 16, v192
	v_max3_f32 v150, v150, |v98|, |v99|
	v_fmac_f32_e32 v151, v103, v103
	v_and_b32_e32 v101, 0xffff0000, v192
	v_max3_f32 v150, v150, |v102|, |v103|
	v_fmac_f32_e32 v151, v100, v100
	v_lshlrev_b32_e32 v104, 16, v193
	v_and_b32_e32 v105, 0xffff0000, v193
	v_max3_f32 v150, v150, |v100|, |v101|
	v_fmac_f32_e32 v151, v101, v101
	v_max3_f32 v150, v150, |v104|, |v105|
	v_fmac_f32_e32 v151, v104, v104
	ds_bpermute_b32 v154, v152, v150
	v_fmac_f32_e32 v151, v105, v105
	ds_bpermute_b32 v155, v152, v151
	global_store_dwordx4 v[194:195], v[156:159], off
	global_store_dwordx4 v[194:195], v[190:193], off offset:256
	s_waitcnt lgkmcnt(1)
	v_max_f32_e32 v154, v154, v154
	v_max_f32_e32 v150, v150, v154
	s_waitcnt lgkmcnt(0)
	v_add_f32_e32 v151, v151, v155
	ds_bpermute_b32 v154, v153, v151
	ds_bpermute_b32 v155, v153, v150
	s_and_saveexec_b64 s[48:49], s[4:5]
	s_cbranch_execz .LBB0_1176
	s_waitcnt lgkmcnt(1)
	v_add_f32_e32 v151, v151, v154
	s_waitcnt lgkmcnt(0)
	v_max_f32_e32 v154, v155, v155
	v_max_f32_e32 v150, v150, v150
	v_max_f32_e32 v150, v150, v154
	ds_write2st64_b32 v177, v151, v150 offset0:1 offset1:17
.LBB0_1176:
	s_or_b64 exec, exec, s[48:49]
	v_add_u32_e32 v234, 0xb0, v148
	v_ashrrev_i32_e32 v235, 31, v234
	v_lshlrev_b64 v[234:235], 11, v[234:235]
	v_lshl_add_u64 v[234:235], s[22:23], 0, v[234:235]
	v_lshl_add_u64 v[234:235], s[60:61], 1, v[234:235]
	v_lshl_add_u64 v[234:235], v[234:235], 0, s[14:15]
	v_lshl_add_u64 v[252:253], v[234:235], 0, v[0:1]
	global_load_dwordx4 v[208:211], v[252:253], off
	global_load_dwordx4 v[212:215], v[252:253], off offset:256
	v_or_b32_e32 v150, 32, v148
	v_ashrrev_i32_e32 v151, 31, v150
	v_lshlrev_b64 v[150:151], 11, v[150:151]
	v_lshl_add_u64 v[150:151], s[22:23], 0, v[150:151]
	v_lshl_add_u64 v[150:151], s[60:61], 1, v[150:151]
	v_lshl_add_u64 v[150:151], v[150:151], 0, s[14:15]
	v_lshl_add_u64 v[194:195], v[150:151], 0, v[0:1]
	s_waitcnt lgkmcnt(0)
	s_waitcnt vmcnt(15)
	v_lshlrev_b32_e32 v150, 16, v216
	v_and_b32_e32 v151, 0xffff0000, v216
	v_lshlrev_b32_e32 v158, 16, v218
	v_and_b32_e32 v159, 0xffff0000, v218
	v_lshlrev_b32_e32 v156, 16, v219
	v_and_b32_e32 v157, 0xffff0000, v219
	v_pk_add_f32 v[94:95], v[94:95], v[150:151]
	v_lshlrev_b32_e32 v154, 16, v217
	v_and_b32_e32 v155, 0xffff0000, v217
	v_pk_add_f32 v[90:91], v[90:91], v[158:159]
	v_pk_add_f32 v[92:93], v[92:93], v[156:157]
	v_cvt_pk_bf16_f32 v156, v94, v95
	v_pk_add_f32 v[96:97], v[96:97], v[154:155]
	v_cvt_pk_bf16_f32 v158, v90, v91
	v_and_b32_e32 v91, 0xffff0000, v156
	v_cvt_pk_bf16_f32 v157, v96, v97
	v_lshlrev_b32_e32 v90, 16, v156
	v_mul_f32_e32 v151, v91, v91
	v_lshlrev_b32_e32 v94, 16, v157
	v_fmac_f32_e32 v151, v90, v90
	v_and_b32_e32 v95, 0xffff0000, v157
	v_fmac_f32_e32 v151, v94, v94
	v_cvt_pk_bf16_f32 v159, v92, v93
	v_lshlrev_b32_e32 v92, 16, v158
	v_fmac_f32_e32 v151, v95, v95
	s_waitcnt vmcnt(14)
	v_lshlrev_b32_e32 v196, 16, v220
	v_and_b32_e32 v197, 0xffff0000, v220
	v_and_b32_e32 v93, 0xffff0000, v158
	v_fmac_f32_e32 v151, v92, v92
	v_lshlrev_b32_e32 v190, 16, v221
	v_and_b32_e32 v191, 0xffff0000, v221
	v_lshlrev_b32_e32 v198, 16, v222
	v_and_b32_e32 v199, 0xffff0000, v222
	v_pk_add_f32 v[86:87], v[86:87], v[196:197]
	v_lshlrev_b32_e32 v96, 16, v159
	v_fmac_f32_e32 v151, v93, v93
	v_lshlrev_b32_e32 v192, 16, v223
	v_and_b32_e32 v193, 0xffff0000, v223
	v_pk_add_f32 v[88:89], v[88:89], v[190:191]
	v_pk_add_f32 v[82:83], v[82:83], v[198:199]
	v_cvt_pk_bf16_f32 v190, v86, v87
	v_and_b32_e32 v97, 0xffff0000, v159
	v_fmac_f32_e32 v151, v96, v96
	v_pk_add_f32 v[84:85], v[84:85], v[192:193]
	v_cvt_pk_bf16_f32 v192, v82, v83
	v_lshlrev_b32_e32 v82, 16, v190
	v_max3_f32 v150, |v90|, 0, |v91|
	v_fmac_f32_e32 v151, v97, v97
	v_cvt_pk_bf16_f32 v191, v88, v89
	v_and_b32_e32 v83, 0xffff0000, v190
	v_max3_f32 v150, v150, |v94|, |v95|
	v_fmac_f32_e32 v151, v82, v82
	v_lshlrev_b32_e32 v86, 16, v191
	v_max3_f32 v150, v150, |v92|, |v93|
	v_fmac_f32_e32 v151, v83, v83
	v_and_b32_e32 v87, 0xffff0000, v191
	v_max3_f32 v150, v150, |v96|, |v97|
	v_fmac_f32_e32 v151, v86, v86
	v_cvt_pk_bf16_f32 v193, v84, v85
	v_lshlrev_b32_e32 v84, 16, v192
	v_max3_f32 v150, v150, |v82|, |v83|
	v_fmac_f32_e32 v151, v87, v87
	v_and_b32_e32 v85, 0xffff0000, v192
	v_max3_f32 v150, v150, |v86|, |v87|
	v_fmac_f32_e32 v151, v84, v84
	v_lshlrev_b32_e32 v88, 16, v193
	v_and_b32_e32 v89, 0xffff0000, v193
	v_max3_f32 v150, v150, |v84|, |v85|
	v_fmac_f32_e32 v151, v85, v85
	v_max3_f32 v150, v150, |v88|, |v89|
	v_fmac_f32_e32 v151, v88, v88
	ds_bpermute_b32 v154, v152, v150
	v_fmac_f32_e32 v151, v89, v89
	ds_bpermute_b32 v155, v152, v151
	global_store_dwordx4 v[194:195], v[156:159], off
	global_store_dwordx4 v[194:195], v[190:193], off offset:256
	s_waitcnt lgkmcnt(1)
	v_max_f32_e32 v154, v154, v154
	v_max_f32_e32 v150, v150, v154
	s_waitcnt lgkmcnt(0)
	v_add_f32_e32 v151, v151, v155
	ds_bpermute_b32 v154, v153, v151
	ds_bpermute_b32 v155, v153, v150
	s_and_saveexec_b64 s[48:49], s[4:5]
	s_cbranch_execz .LBB0_1178
	s_waitcnt lgkmcnt(1)
	v_add_f32_e32 v151, v151, v154
	s_waitcnt lgkmcnt(0)
	v_max_f32_e32 v154, v155, v155
	v_max_f32_e32 v150, v150, v150
	v_max_f32_e32 v150, v150, v154
	ds_write2st64_b32 v177, v151, v150 offset0:2 offset1:18
.LBB0_1178:
	s_or_b64 exec, exec, s[48:49]
	v_or_b32_e32 v150, 48, v148
	v_ashrrev_i32_e32 v151, 31, v150
	v_lshlrev_b64 v[150:151], 11, v[150:151]
	v_lshl_add_u64 v[150:151], s[22:23], 0, v[150:151]
	v_lshl_add_u64 v[150:151], s[60:61], 1, v[150:151]
	v_lshl_add_u64 v[150:151], v[150:151], 0, s[14:15]
	v_lshl_add_u64 v[194:195], v[150:151], 0, v[0:1]
	s_waitcnt lgkmcnt(0)
	s_waitcnt vmcnt(15)
	v_lshlrev_b32_e32 v150, 16, v224
	v_and_b32_e32 v151, 0xffff0000, v224
	v_lshlrev_b32_e32 v158, 16, v226
	v_and_b32_e32 v159, 0xffff0000, v226
	v_lshlrev_b32_e32 v156, 16, v227
	v_and_b32_e32 v157, 0xffff0000, v227
	v_pk_add_f32 v[78:79], v[78:79], v[150:151]
	v_lshlrev_b32_e32 v154, 16, v225
	v_and_b32_e32 v155, 0xffff0000, v225
	v_pk_add_f32 v[74:75], v[74:75], v[158:159]
	v_pk_add_f32 v[76:77], v[76:77], v[156:157]
	v_cvt_pk_bf16_f32 v156, v78, v79
	v_pk_add_f32 v[80:81], v[80:81], v[154:155]
	v_cvt_pk_bf16_f32 v158, v74, v75
	v_and_b32_e32 v75, 0xffff0000, v156
	v_cvt_pk_bf16_f32 v157, v80, v81
	v_lshlrev_b32_e32 v74, 16, v156
	v_mul_f32_e32 v151, v75, v75
	v_lshlrev_b32_e32 v78, 16, v157
	v_fmac_f32_e32 v151, v74, v74
	v_and_b32_e32 v79, 0xffff0000, v157
	v_fmac_f32_e32 v151, v78, v78
	v_cvt_pk_bf16_f32 v159, v76, v77
	v_lshlrev_b32_e32 v76, 16, v158
	v_fmac_f32_e32 v151, v79, v79
	s_waitcnt vmcnt(14)
	v_lshlrev_b32_e32 v196, 16, v228
	v_and_b32_e32 v197, 0xffff0000, v228
	v_and_b32_e32 v77, 0xffff0000, v158
	v_fmac_f32_e32 v151, v76, v76
	v_lshlrev_b32_e32 v190, 16, v229
	v_and_b32_e32 v191, 0xffff0000, v229
	v_lshlrev_b32_e32 v198, 16, v230
	v_and_b32_e32 v199, 0xffff0000, v230
	v_pk_add_f32 v[70:71], v[70:71], v[196:197]
	v_lshlrev_b32_e32 v80, 16, v159
	v_fmac_f32_e32 v151, v77, v77
	v_lshlrev_b32_e32 v192, 16, v231
	v_and_b32_e32 v193, 0xffff0000, v231
	v_pk_add_f32 v[72:73], v[72:73], v[190:191]
	v_pk_add_f32 v[66:67], v[66:67], v[198:199]
	v_cvt_pk_bf16_f32 v190, v70, v71
	v_and_b32_e32 v81, 0xffff0000, v159
	v_fmac_f32_e32 v151, v80, v80
	v_pk_add_f32 v[68:69], v[68:69], v[192:193]
	v_cvt_pk_bf16_f32 v192, v66, v67
	v_lshlrev_b32_e32 v66, 16, v190
	v_max3_f32 v150, |v74|, 0, |v75|
	v_fmac_f32_e32 v151, v81, v81
	v_cvt_pk_bf16_f32 v191, v72, v73
	v_and_b32_e32 v67, 0xffff0000, v190
	v_max3_f32 v150, v150, |v78|, |v79|
	v_fmac_f32_e32 v151, v66, v66
	v_lshlrev_b32_e32 v70, 16, v191
	v_max3_f32 v150, v150, |v76|, |v77|
	v_fmac_f32_e32 v151, v67, v67
	v_and_b32_e32 v71, 0xffff0000, v191
	v_max3_f32 v150, v150, |v80|, |v81|
	v_fmac_f32_e32 v151, v70, v70
	v_cvt_pk_bf16_f32 v193, v68, v69
	v_lshlrev_b32_e32 v68, 16, v192
	v_max3_f32 v150, v150, |v66|, |v67|
	v_fmac_f32_e32 v151, v71, v71
	v_and_b32_e32 v69, 0xffff0000, v192
	v_max3_f32 v150, v150, |v70|, |v71|
	v_fmac_f32_e32 v151, v68, v68
	v_lshlrev_b32_e32 v72, 16, v193
	v_and_b32_e32 v73, 0xffff0000, v193
	v_max3_f32 v150, v150, |v68|, |v69|
	v_fmac_f32_e32 v151, v69, v69
	v_max3_f32 v150, v150, |v72|, |v73|
	v_fmac_f32_e32 v151, v72, v72
	ds_bpermute_b32 v154, v152, v150
	v_fmac_f32_e32 v151, v73, v73
	ds_bpermute_b32 v155, v152, v151
	global_store_dwordx4 v[194:195], v[156:159], off
	global_store_dwordx4 v[194:195], v[190:193], off offset:256
	s_waitcnt lgkmcnt(1)
	v_max_f32_e32 v154, v154, v154
	v_max_f32_e32 v150, v150, v154
	s_waitcnt lgkmcnt(0)
	v_add_f32_e32 v151, v151, v155
	ds_bpermute_b32 v154, v153, v151
	ds_bpermute_b32 v155, v153, v150
	s_and_saveexec_b64 s[48:49], s[4:5]
	s_cbranch_execz .LBB0_1180
	s_waitcnt lgkmcnt(1)
	v_add_f32_e32 v151, v151, v154
	s_waitcnt lgkmcnt(0)
	v_max_f32_e32 v154, v155, v155
	v_max_f32_e32 v150, v150, v150
	v_max_f32_e32 v150, v150, v154
	ds_write2st64_b32 v177, v151, v150 offset0:3 offset1:19
.LBB0_1180:
	s_or_b64 exec, exec, s[48:49]
	v_add_u32_e32 v150, 0x80, v148
	v_ashrrev_i32_e32 v151, 31, v150
	v_lshlrev_b64 v[150:151], 11, v[150:151]
	v_lshl_add_u64 v[150:151], s[22:23], 0, v[150:151]
	v_lshl_add_u64 v[150:151], s[60:61], 1, v[150:151]
	v_lshl_add_u64 v[150:151], v[150:151], 0, s[14:15]
	v_lshl_add_u64 v[194:195], v[150:151], 0, v[0:1]
	s_waitcnt lgkmcnt(0)
	s_waitcnt vmcnt(15)
	v_lshlrev_b32_e32 v150, 16, v236
	v_and_b32_e32 v151, 0xffff0000, v236
	v_lshlrev_b32_e32 v158, 16, v238
	v_and_b32_e32 v159, 0xffff0000, v238
	v_lshlrev_b32_e32 v156, 16, v239
	v_and_b32_e32 v157, 0xffff0000, v239
	v_pk_add_f32 v[62:63], v[62:63], v[150:151]
	v_lshlrev_b32_e32 v154, 16, v237
	v_and_b32_e32 v155, 0xffff0000, v237
	v_pk_add_f32 v[58:59], v[58:59], v[158:159]
	v_pk_add_f32 v[60:61], v[60:61], v[156:157]
	v_cvt_pk_bf16_f32 v156, v62, v63
	v_pk_add_f32 v[64:65], v[64:65], v[154:155]
	v_cvt_pk_bf16_f32 v158, v58, v59
	v_and_b32_e32 v59, 0xffff0000, v156
	v_cvt_pk_bf16_f32 v157, v64, v65
	v_lshlrev_b32_e32 v58, 16, v156
	v_mul_f32_e32 v151, v59, v59
	v_lshlrev_b32_e32 v62, 16, v157
	v_fmac_f32_e32 v151, v58, v58
	v_and_b32_e32 v63, 0xffff0000, v157
	v_fmac_f32_e32 v151, v62, v62
	v_cvt_pk_bf16_f32 v159, v60, v61
	v_lshlrev_b32_e32 v60, 16, v158
	v_fmac_f32_e32 v151, v63, v63
	s_waitcnt vmcnt(14)
	v_lshlrev_b32_e32 v196, 16, v240
	v_and_b32_e32 v197, 0xffff0000, v240
	v_and_b32_e32 v61, 0xffff0000, v158
	v_fmac_f32_e32 v151, v60, v60
	v_lshlrev_b32_e32 v190, 16, v241
	v_and_b32_e32 v191, 0xffff0000, v241
	v_lshlrev_b32_e32 v198, 16, v242
	v_and_b32_e32 v199, 0xffff0000, v242
	v_pk_add_f32 v[54:55], v[54:55], v[196:197]
	v_lshlrev_b32_e32 v64, 16, v159
	v_fmac_f32_e32 v151, v61, v61
	v_lshlrev_b32_e32 v192, 16, v243
	v_and_b32_e32 v193, 0xffff0000, v243
	v_pk_add_f32 v[56:57], v[56:57], v[190:191]
	v_pk_add_f32 v[50:51], v[50:51], v[198:199]
	v_cvt_pk_bf16_f32 v190, v54, v55
	v_and_b32_e32 v65, 0xffff0000, v159
	v_fmac_f32_e32 v151, v64, v64
	v_pk_add_f32 v[52:53], v[52:53], v[192:193]
	v_cvt_pk_bf16_f32 v192, v50, v51
	v_lshlrev_b32_e32 v50, 16, v190
	v_max3_f32 v150, |v58|, 0, |v59|
	v_fmac_f32_e32 v151, v65, v65
	v_cvt_pk_bf16_f32 v191, v56, v57
	v_and_b32_e32 v51, 0xffff0000, v190
	v_max3_f32 v150, v150, |v62|, |v63|
	v_fmac_f32_e32 v151, v50, v50
	v_lshlrev_b32_e32 v54, 16, v191
	v_max3_f32 v150, v150, |v60|, |v61|
	v_fmac_f32_e32 v151, v51, v51
	v_and_b32_e32 v55, 0xffff0000, v191
	v_max3_f32 v150, v150, |v64|, |v65|
	v_fmac_f32_e32 v151, v54, v54
	v_cvt_pk_bf16_f32 v193, v52, v53
	v_lshlrev_b32_e32 v52, 16, v192
	v_max3_f32 v150, v150, |v50|, |v51|
	v_fmac_f32_e32 v151, v55, v55
	v_and_b32_e32 v53, 0xffff0000, v192
	v_max3_f32 v150, v150, |v54|, |v55|
	v_fmac_f32_e32 v151, v52, v52
	v_lshlrev_b32_e32 v56, 16, v193
	v_and_b32_e32 v57, 0xffff0000, v193
	v_max3_f32 v150, v150, |v52|, |v53|
	v_fmac_f32_e32 v151, v53, v53
	v_max3_f32 v150, v150, |v56|, |v57|
	v_fmac_f32_e32 v151, v56, v56
	ds_bpermute_b32 v154, v152, v150
	v_fmac_f32_e32 v151, v57, v57
	ds_bpermute_b32 v155, v152, v151
	global_store_dwordx4 v[194:195], v[156:159], off
	global_store_dwordx4 v[194:195], v[190:193], off offset:256
	s_waitcnt lgkmcnt(1)
	v_max_f32_e32 v154, v154, v154
	v_max_f32_e32 v150, v150, v154
	s_waitcnt lgkmcnt(0)
	v_add_f32_e32 v151, v151, v155
	ds_bpermute_b32 v154, v153, v151
	ds_bpermute_b32 v155, v153, v150
	s_and_saveexec_b64 s[48:49], s[4:5]
	s_cbranch_execz .LBB0_1182
	s_waitcnt lgkmcnt(1)
	v_add_f32_e32 v151, v151, v154
	s_waitcnt lgkmcnt(0)
	v_max_f32_e32 v154, v155, v155
	v_max_f32_e32 v150, v150, v150
	v_max_f32_e32 v150, v150, v154
	ds_write2st64_b32 v178, v151, v150 offset1:16
.LBB0_1182:
	s_or_b64 exec, exec, s[48:49]
	v_add_u32_e32 v150, 0x90, v148
	v_ashrrev_i32_e32 v151, 31, v150
	v_lshlrev_b64 v[150:151], 11, v[150:151]
	v_lshl_add_u64 v[150:151], s[22:23], 0, v[150:151]
	v_lshl_add_u64 v[150:151], s[60:61], 1, v[150:151]
	v_lshl_add_u64 v[150:151], v[150:151], 0, s[14:15]
	v_lshl_add_u64 v[194:195], v[150:151], 0, v[0:1]
	s_waitcnt lgkmcnt(0)
	s_waitcnt vmcnt(15)
	v_lshlrev_b32_e32 v150, 16, v244
	v_and_b32_e32 v151, 0xffff0000, v244
	v_lshlrev_b32_e32 v158, 16, v246
	v_and_b32_e32 v159, 0xffff0000, v246
	v_lshlrev_b32_e32 v156, 16, v247
	v_and_b32_e32 v157, 0xffff0000, v247
	v_pk_add_f32 v[46:47], v[46:47], v[150:151]
	v_lshlrev_b32_e32 v154, 16, v245
	v_and_b32_e32 v155, 0xffff0000, v245
	v_pk_add_f32 v[42:43], v[42:43], v[158:159]
	v_pk_add_f32 v[44:45], v[44:45], v[156:157]
	v_cvt_pk_bf16_f32 v156, v46, v47
	v_pk_add_f32 v[48:49], v[48:49], v[154:155]
	v_cvt_pk_bf16_f32 v158, v42, v43
	v_and_b32_e32 v43, 0xffff0000, v156
	v_cvt_pk_bf16_f32 v157, v48, v49
	v_lshlrev_b32_e32 v42, 16, v156
	v_mul_f32_e32 v151, v43, v43
	v_lshlrev_b32_e32 v46, 16, v157
	v_fmac_f32_e32 v151, v42, v42
	v_and_b32_e32 v47, 0xffff0000, v157
	v_fmac_f32_e32 v151, v46, v46
	v_cvt_pk_bf16_f32 v159, v44, v45
	v_lshlrev_b32_e32 v44, 16, v158
	v_fmac_f32_e32 v151, v47, v47
	s_waitcnt vmcnt(14)
	v_lshlrev_b32_e32 v196, 16, v248
	v_and_b32_e32 v197, 0xffff0000, v248
	v_and_b32_e32 v45, 0xffff0000, v158
	v_fmac_f32_e32 v151, v44, v44
	v_lshlrev_b32_e32 v190, 16, v249
	v_and_b32_e32 v191, 0xffff0000, v249
	v_lshlrev_b32_e32 v198, 16, v250
	v_and_b32_e32 v199, 0xffff0000, v250
	v_pk_add_f32 v[38:39], v[38:39], v[196:197]
	v_lshlrev_b32_e32 v48, 16, v159
	v_fmac_f32_e32 v151, v45, v45
	v_lshlrev_b32_e32 v192, 16, v251
	v_and_b32_e32 v193, 0xffff0000, v251
	v_pk_add_f32 v[40:41], v[40:41], v[190:191]
	v_pk_add_f32 v[34:35], v[34:35], v[198:199]
	v_cvt_pk_bf16_f32 v190, v38, v39
	v_and_b32_e32 v49, 0xffff0000, v159
	v_fmac_f32_e32 v151, v48, v48
	v_pk_add_f32 v[36:37], v[36:37], v[192:193]
	v_cvt_pk_bf16_f32 v192, v34, v35
	v_lshlrev_b32_e32 v34, 16, v190
	v_max3_f32 v150, |v42|, 0, |v43|
	v_fmac_f32_e32 v151, v49, v49
	v_cvt_pk_bf16_f32 v191, v40, v41
	v_and_b32_e32 v35, 0xffff0000, v190
	v_max3_f32 v150, v150, |v46|, |v47|
	v_fmac_f32_e32 v151, v34, v34
	v_lshlrev_b32_e32 v38, 16, v191
	v_max3_f32 v150, v150, |v44|, |v45|
	v_fmac_f32_e32 v151, v35, v35
	v_and_b32_e32 v39, 0xffff0000, v191
	v_max3_f32 v150, v150, |v48|, |v49|
	v_fmac_f32_e32 v151, v38, v38
	v_cvt_pk_bf16_f32 v193, v36, v37
	v_lshlrev_b32_e32 v36, 16, v192
	v_max3_f32 v150, v150, |v34|, |v35|
	v_fmac_f32_e32 v151, v39, v39
	v_and_b32_e32 v37, 0xffff0000, v192
	v_max3_f32 v150, v150, |v38|, |v39|
	v_fmac_f32_e32 v151, v36, v36
	v_lshlrev_b32_e32 v40, 16, v193
	v_and_b32_e32 v41, 0xffff0000, v193
	v_max3_f32 v150, v150, |v36|, |v37|
	v_fmac_f32_e32 v151, v37, v37
	v_max3_f32 v150, v150, |v40|, |v41|
	v_fmac_f32_e32 v151, v40, v40
	ds_bpermute_b32 v154, v152, v150
	v_fmac_f32_e32 v151, v41, v41
	ds_bpermute_b32 v155, v152, v151
	global_store_dwordx4 v[194:195], v[156:159], off
	global_store_dwordx4 v[194:195], v[190:193], off offset:256
	s_waitcnt lgkmcnt(1)
	v_max_f32_e32 v154, v154, v154
	v_max_f32_e32 v150, v150, v154
	s_waitcnt lgkmcnt(0)
	v_add_f32_e32 v151, v151, v155
	ds_bpermute_b32 v154, v153, v151
	ds_bpermute_b32 v155, v153, v150
	s_and_saveexec_b64 s[48:49], s[4:5]
	s_cbranch_execz .LBB0_1184
	s_waitcnt lgkmcnt(1)
	v_add_f32_e32 v151, v151, v154
	s_waitcnt lgkmcnt(0)
	v_max_f32_e32 v154, v155, v155
	v_max_f32_e32 v150, v150, v150
	v_max_f32_e32 v150, v150, v154
	ds_write2st64_b32 v177, v151, v150 offset0:9 offset1:25
.LBB0_1184:
	s_or_b64 exec, exec, s[48:49]
	v_add_u32_e32 v150, 0xa0, v148
	v_ashrrev_i32_e32 v151, 31, v150
	v_lshlrev_b64 v[150:151], 11, v[150:151]
	v_lshl_add_u64 v[150:151], s[22:23], 0, v[150:151]
	v_lshl_add_u64 v[150:151], s[60:61], 1, v[150:151]
	v_lshl_add_u64 v[150:151], v[150:151], 0, s[14:15]
	v_lshl_add_u64 v[194:195], v[150:151], 0, v[0:1]
	s_waitcnt lgkmcnt(0)
	s_waitcnt vmcnt(13)
	v_lshlrev_b32_e32 v150, 16, v200
	v_and_b32_e32 v151, 0xffff0000, v200
	v_lshlrev_b32_e32 v158, 16, v202
	v_and_b32_e32 v159, 0xffff0000, v202
	v_lshlrev_b32_e32 v156, 16, v203
	v_and_b32_e32 v157, 0xffff0000, v203
	v_pk_add_f32 v[30:31], v[30:31], v[150:151]
	v_lshlrev_b32_e32 v154, 16, v201
	v_and_b32_e32 v155, 0xffff0000, v201
	v_pk_add_f32 v[26:27], v[26:27], v[158:159]
	v_pk_add_f32 v[28:29], v[28:29], v[156:157]
	v_cvt_pk_bf16_f32 v156, v30, v31
	v_pk_add_f32 v[32:33], v[32:33], v[154:155]
	v_cvt_pk_bf16_f32 v158, v26, v27
	v_and_b32_e32 v27, 0xffff0000, v156
	v_cvt_pk_bf16_f32 v157, v32, v33
	v_lshlrev_b32_e32 v26, 16, v156
	v_mul_f32_e32 v151, v27, v27
	v_lshlrev_b32_e32 v30, 16, v157
	v_fmac_f32_e32 v151, v26, v26
	v_and_b32_e32 v31, 0xffff0000, v157
	v_fmac_f32_e32 v151, v30, v30
	v_cvt_pk_bf16_f32 v159, v28, v29
	v_lshlrev_b32_e32 v28, 16, v158
	v_fmac_f32_e32 v151, v31, v31
	s_waitcnt vmcnt(12)
	v_lshlrev_b32_e32 v196, 16, v204
	v_and_b32_e32 v197, 0xffff0000, v204
	v_and_b32_e32 v29, 0xffff0000, v158
	v_fmac_f32_e32 v151, v28, v28
	v_lshlrev_b32_e32 v190, 16, v205
	v_and_b32_e32 v191, 0xffff0000, v205
	v_lshlrev_b32_e32 v198, 16, v206
	v_and_b32_e32 v199, 0xffff0000, v206
	v_pk_add_f32 v[22:23], v[22:23], v[196:197]
	v_lshlrev_b32_e32 v32, 16, v159
	v_fmac_f32_e32 v151, v29, v29
	v_lshlrev_b32_e32 v192, 16, v207
	v_and_b32_e32 v193, 0xffff0000, v207
	v_pk_add_f32 v[24:25], v[24:25], v[190:191]
	v_pk_add_f32 v[18:19], v[18:19], v[198:199]
	v_cvt_pk_bf16_f32 v190, v22, v23
	v_and_b32_e32 v33, 0xffff0000, v159
	v_fmac_f32_e32 v151, v32, v32
	v_pk_add_f32 v[20:21], v[20:21], v[192:193]
	v_cvt_pk_bf16_f32 v192, v18, v19
	v_lshlrev_b32_e32 v18, 16, v190
	v_max3_f32 v150, |v26|, 0, |v27|
	v_fmac_f32_e32 v151, v33, v33
	v_cvt_pk_bf16_f32 v191, v24, v25
	v_and_b32_e32 v19, 0xffff0000, v190
	v_max3_f32 v150, v150, |v30|, |v31|
	v_fmac_f32_e32 v151, v18, v18
	v_lshlrev_b32_e32 v22, 16, v191
	v_max3_f32 v150, v150, |v28|, |v29|
	v_fmac_f32_e32 v151, v19, v19
	v_and_b32_e32 v23, 0xffff0000, v191
	v_max3_f32 v150, v150, |v32|, |v33|
	v_fmac_f32_e32 v151, v22, v22
	v_cvt_pk_bf16_f32 v193, v20, v21
	v_lshlrev_b32_e32 v20, 16, v192
	v_max3_f32 v150, v150, |v18|, |v19|
	v_fmac_f32_e32 v151, v23, v23
	v_and_b32_e32 v21, 0xffff0000, v192
	v_max3_f32 v150, v150, |v22|, |v23|
	v_fmac_f32_e32 v151, v20, v20
	v_lshlrev_b32_e32 v24, 16, v193
	v_and_b32_e32 v25, 0xffff0000, v193
	v_max3_f32 v150, v150, |v20|, |v21|
	v_fmac_f32_e32 v151, v21, v21
	v_max3_f32 v150, v150, |v24|, |v25|
	v_fmac_f32_e32 v151, v24, v24
	ds_bpermute_b32 v154, v152, v150
	v_fmac_f32_e32 v151, v25, v25
	ds_bpermute_b32 v155, v152, v151
	global_store_dwordx4 v[194:195], v[156:159], off
	global_store_dwordx4 v[194:195], v[190:193], off offset:256
	s_waitcnt lgkmcnt(1)
	v_max_f32_e32 v154, v154, v154
	v_max_f32_e32 v150, v150, v154
	s_waitcnt lgkmcnt(0)
	v_add_f32_e32 v151, v151, v155
	ds_bpermute_b32 v154, v153, v151
	ds_bpermute_b32 v155, v153, v150
	s_and_saveexec_b64 s[48:49], s[4:5]
	s_cbranch_execz .LBB0_1186
	s_waitcnt lgkmcnt(1)
	v_add_f32_e32 v151, v151, v154
	s_waitcnt lgkmcnt(0)
	v_max_f32_e32 v154, v155, v155
	v_max_f32_e32 v150, v150, v150
	v_max_f32_e32 v150, v150, v154
	ds_write2st64_b32 v177, v151, v150 offset0:10 offset1:26
.LBB0_1186:
	s_or_b64 exec, exec, s[48:49]
	v_add_u32_e32 v150, 0xb0, v148
	v_ashrrev_i32_e32 v151, 31, v150
	v_lshlrev_b64 v[150:151], 11, v[150:151]
	v_lshl_add_u64 v[150:151], s[22:23], 0, v[150:151]
	v_lshl_add_u64 v[150:151], s[60:61], 1, v[150:151]
	v_lshl_add_u64 v[150:151], v[150:151], 0, s[14:15]
	v_lshl_add_u64 v[158:159], v[150:151], 0, v[0:1]
	s_waitcnt lgkmcnt(0)
	s_waitcnt vmcnt(11)
	v_lshlrev_b32_e32 v150, 16, v208
	v_and_b32_e32 v151, 0xffff0000, v208
	v_lshlrev_b32_e32 v154, 16, v209
	v_and_b32_e32 v155, 0xffff0000, v209
	v_pk_add_f32 v[14:15], v[14:15], v[150:151]
	s_waitcnt vmcnt(10)
	v_lshlrev_b32_e32 v198, 16, v214
	v_and_b32_e32 v199, 0xffff0000, v214
	v_pk_add_f32 v[16:17], v[16:17], v[154:155]
	v_cvt_pk_bf16_f32 v154, v14, v15
	v_lshlrev_b32_e32 v192, 16, v215
	v_and_b32_e32 v193, 0xffff0000, v215
	v_pk_add_f32 v[2:3], v[2:3], v[198:199]
	v_and_b32_e32 v15, 0xffff0000, v154
	v_lshlrev_b32_e32 v194, 16, v210
	v_and_b32_e32 v195, 0xffff0000, v210
	v_pk_add_f32 v[4:5], v[4:5], v[192:193]
	v_cvt_pk_bf16_f32 v155, v16, v17
	v_cvt_pk_bf16_f32 v192, v2, v3
	v_lshlrev_b32_e32 v14, 16, v154
	v_mul_f32_e32 v2, v15, v15
	v_lshlrev_b32_e32 v156, 16, v211
	v_and_b32_e32 v157, 0xffff0000, v211
	v_pk_add_f32 v[10:11], v[10:11], v[194:195]
	v_lshlrev_b32_e32 v150, 16, v155
	v_fmac_f32_e32 v2, v14, v14
	v_pk_add_f32 v[12:13], v[12:13], v[156:157]
	v_cvt_pk_bf16_f32 v156, v10, v11
	v_and_b32_e32 v151, 0xffff0000, v155
	v_fmac_f32_e32 v2, v150, v150
	v_cvt_pk_bf16_f32 v157, v12, v13
	v_lshlrev_b32_e32 v12, 16, v156
	v_fmac_f32_e32 v2, v151, v151
	v_lshlrev_b32_e32 v196, 16, v212
	v_and_b32_e32 v197, 0xffff0000, v212
	v_and_b32_e32 v13, 0xffff0000, v156
	v_fmac_f32_e32 v2, v12, v12
	v_lshlrev_b32_e32 v190, 16, v213
	v_and_b32_e32 v191, 0xffff0000, v213
	v_pk_add_f32 v[6:7], v[6:7], v[196:197]
	v_lshlrev_b32_e32 v16, 16, v157
	v_fmac_f32_e32 v2, v13, v13
	v_pk_add_f32 v[8:9], v[8:9], v[190:191]
	v_cvt_pk_bf16_f32 v190, v6, v7
	v_and_b32_e32 v17, 0xffff0000, v157
	v_fmac_f32_e32 v2, v16, v16
	v_lshlrev_b32_e32 v6, 16, v190
	v_max3_f32 v0, |v14|, 0, |v15|
	v_fmac_f32_e32 v2, v17, v17
	v_cvt_pk_bf16_f32 v191, v8, v9
	v_and_b32_e32 v7, 0xffff0000, v190
	v_max3_f32 v0, v0, |v150|, |v151|
	v_fmac_f32_e32 v2, v6, v6
	v_lshlrev_b32_e32 v10, 16, v191
	v_max3_f32 v0, v0, |v12|, |v13|
	v_fmac_f32_e32 v2, v7, v7
	v_and_b32_e32 v11, 0xffff0000, v191
	v_max3_f32 v0, v0, |v16|, |v17|
	v_fmac_f32_e32 v2, v10, v10
	v_cvt_pk_bf16_f32 v193, v4, v5
	v_lshlrev_b32_e32 v4, 16, v192
	v_max3_f32 v0, v0, |v6|, |v7|
	v_fmac_f32_e32 v2, v11, v11
	v_and_b32_e32 v5, 0xffff0000, v192
	v_max3_f32 v0, v0, |v10|, |v11|
	v_fmac_f32_e32 v2, v4, v4
	v_lshlrev_b32_e32 v8, 16, v193
	v_and_b32_e32 v9, 0xffff0000, v193
	v_max3_f32 v0, v0, |v4|, |v5|
	v_fmac_f32_e32 v2, v5, v5
	v_max3_f32 v0, v0, |v8|, |v9|
	v_fmac_f32_e32 v2, v8, v8
	ds_bpermute_b32 v3, v152, v0
	v_fmac_f32_e32 v2, v9, v9
	ds_bpermute_b32 v152, v152, v2
	global_store_dwordx4 v[158:159], v[154:157], off
	global_store_dwordx4 v[158:159], v[190:193], off offset:256
	s_waitcnt lgkmcnt(1)
	v_max_f32_e32 v3, v3, v3
	v_max_f32_e32 v0, v0, v3
	s_waitcnt lgkmcnt(0)
	v_add_f32_e32 v2, v2, v152
	ds_bpermute_b32 v3, v153, v2
	ds_bpermute_b32 v152, v153, v0
	s_and_saveexec_b64 s[48:49], s[4:5]
	s_cbranch_execz .LBB0_1188
	s_waitcnt lgkmcnt(1)
	v_add_f32_e32 v2, v2, v3
	s_waitcnt lgkmcnt(0)
	v_max_f32_e32 v3, v152, v152
	v_max_f32_e32 v0, v0, v0
	v_max_f32_e32 v0, v0, v3
	ds_write2st64_b32 v177, v2, v0 offset0:11 offset1:27

.LBB0_1641:
	s_lshl_b32 s91, s62, 8
	v_add_u32_e32 v148, s91, v168
	v_ashrrev_i32_e32 v149, 31, v148
	s_lshl_b32 s56, s54, 8
	v_lshlrev_b64 v[150:151], 11, v[148:149]
	s_ashr_i32 s57, s56, 31
	v_lshl_add_u64 v[150:151], s[26:27], 0, v[150:151]
	v_lshl_add_u64 v[150:151], s[56:57], 1, v[150:151]
	s_lshl_b32 s16, s40, 1
	v_lshl_add_u64 v[150:151], v[150:151], 0, s[16:17]
	v_lshlrev_b32_e32 v0, 1, v142
	v_lshl_add_u64 v[194:195], v[150:151], 0, v[0:1]
	global_load_dwordx4 v[200:203], v[194:195], off
	global_load_dwordx4 v[204:207], v[194:195], off offset:256
	v_or_b32_e32 v234, 16, v148
	v_ashrrev_i32_e32 v235, 31, v234
	v_lshlrev_b64 v[234:235], 11, v[234:235]
	v_lshl_add_u64 v[234:235], s[26:27], 0, v[234:235]
	v_lshl_add_u64 v[234:235], s[56:57], 1, v[234:235]
	v_lshl_add_u64 v[234:235], v[234:235], 0, s[16:17]
	v_lshl_add_u64 v[252:253], v[234:235], 0, v[0:1]
	global_load_dwordx4 v[208:211], v[252:253], off
	global_load_dwordx4 v[212:215], v[252:253], off offset:256
	v_or_b32_e32 v234, 32, v148
	v_ashrrev_i32_e32 v235, 31, v234
	v_lshlrev_b64 v[234:235], 11, v[234:235]
	v_lshl_add_u64 v[234:235], s[26:27], 0, v[234:235]
	v_lshl_add_u64 v[234:235], s[56:57], 1, v[234:235]
	v_lshl_add_u64 v[234:235], v[234:235], 0, s[16:17]
	v_lshl_add_u64 v[252:253], v[234:235], 0, v[0:1]
	global_load_dwordx4 v[216:219], v[252:253], off
	global_load_dwordx4 v[220:223], v[252:253], off offset:256
	v_or_b32_e32 v234, 48, v148
	v_ashrrev_i32_e32 v235, 31, v234
	v_lshlrev_b64 v[234:235], 11, v[234:235]
	v_lshl_add_u64 v[234:235], s[26:27], 0, v[234:235]
	v_lshl_add_u64 v[234:235], s[56:57], 1, v[234:235]
	v_lshl_add_u64 v[234:235], v[234:235], 0, s[16:17]
	v_lshl_add_u64 v[252:253], v[234:235], 0, v[0:1]
	global_load_dwordx4 v[224:227], v[252:253], off
	global_load_dwordx4 v[228:231], v[252:253], off offset:256
	v_add_u32_e32 v234, 0x80, v148
	v_ashrrev_i32_e32 v235, 31, v234
	v_lshlrev_b64 v[234:235], 11, v[234:235]
	v_lshl_add_u64 v[234:235], s[26:27], 0, v[234:235]
	v_lshl_add_u64 v[234:235], s[56:57], 1, v[234:235]
	v_lshl_add_u64 v[234:235], v[234:235], 0, s[16:17]
	v_lshl_add_u64 v[252:253], v[234:235], 0, v[0:1]
	global_load_dwordx4 v[236:239], v[252:253], off
	global_load_dwordx4 v[240:243], v[252:253], off offset:256
	v_add_u32_e32 v234, 0x90, v148
	v_ashrrev_i32_e32 v235, 31, v234
	v_lshlrev_b64 v[234:235], 11, v[234:235]
	v_lshl_add_u64 v[234:235], s[26:27], 0, v[234:235]
	v_lshl_add_u64 v[234:235], s[56:57], 1, v[234:235]
	v_lshl_add_u64 v[234:235], v[234:235], 0, s[16:17]
	v_lshl_add_u64 v[252:253], v[234:235], 0, v[0:1]
	global_load_dwordx4 v[244:247], v[252:253], off
	global_load_dwordx4 v[248:251], v[252:253], off offset:256
	v_and_b32_e32 v151, 64, v164
	v_xor_b32_e32 v150, 16, v164
	v_add_u32_e32 v160, 64, v151
	v_cmp_lt_i32_e32 vcc, v150, v160
	v_xor_b32_e32 v153, 32, v164
	s_waitcnt vmcnt(10)
	v_and_b32_e32 v151, 0xffff0000, v200
	v_cndmask_b32_e32 v150, v164, v150, vcc
	v_lshlrev_b32_e32 v152, 2, v150
	v_lshlrev_b32_e32 v150, 16, v200
	v_lshlrev_b32_e32 v158, 16, v202
	v_and_b32_e32 v159, 0xffff0000, v202
	v_lshlrev_b32_e32 v156, 16, v203
	v_and_b32_e32 v157, 0xffff0000, v203
	v_pk_add_f32 v[126:127], v[126:127], v[150:151]
	v_lshlrev_b32_e32 v154, 16, v201
	v_and_b32_e32 v155, 0xffff0000, v201
	v_pk_add_f32 v[122:123], v[122:123], v[158:159]
	v_pk_add_f32 v[124:125], v[124:125], v[156:157]
	v_cvt_pk_bf16_f32 v156, v126, v127
	v_pk_add_f32 v[128:129], v[128:129], v[154:155]
	v_cvt_pk_bf16_f32 v158, v122, v123
	v_and_b32_e32 v123, 0xffff0000, v156
	v_cvt_pk_bf16_f32 v157, v128, v129
	v_lshlrev_b32_e32 v122, 16, v156
	v_mul_f32_e32 v151, v123, v123
	v_lshlrev_b32_e32 v126, 16, v157
	v_fmac_f32_e32 v151, v122, v122
	v_and_b32_e32 v127, 0xffff0000, v157
	v_fmac_f32_e32 v151, v126, v126
	v_cvt_pk_bf16_f32 v159, v124, v125
	v_lshlrev_b32_e32 v124, 16, v158
	v_fmac_f32_e32 v151, v127, v127
	v_lshlrev_b32_e32 v196, 16, v204
	v_and_b32_e32 v197, 0xffff0000, v204
	v_and_b32_e32 v125, 0xffff0000, v158
	v_fmac_f32_e32 v151, v124, v124
	v_lshlrev_b32_e32 v190, 16, v205
	v_and_b32_e32 v191, 0xffff0000, v205
	v_lshlrev_b32_e32 v198, 16, v206
	v_and_b32_e32 v199, 0xffff0000, v206
	v_pk_add_f32 v[118:119], v[118:119], v[196:197]
	v_lshlrev_b32_e32 v128, 16, v159
	v_fmac_f32_e32 v151, v125, v125
	v_lshlrev_b32_e32 v192, 16, v207
	v_and_b32_e32 v193, 0xffff0000, v207
	v_pk_add_f32 v[120:121], v[120:121], v[190:191]
	v_pk_add_f32 v[114:115], v[114:115], v[198:199]
	v_cvt_pk_bf16_f32 v190, v118, v119
	v_and_b32_e32 v129, 0xffff0000, v159
	v_fmac_f32_e32 v151, v128, v128
	v_pk_add_f32 v[116:117], v[116:117], v[192:193]
	v_cvt_pk_bf16_f32 v192, v114, v115
	v_lshlrev_b32_e32 v114, 16, v190
	v_max3_f32 v150, |v122|, 0, |v123|
	v_fmac_f32_e32 v151, v129, v129
	v_cvt_pk_bf16_f32 v191, v120, v121
	v_and_b32_e32 v115, 0xffff0000, v190
	v_max3_f32 v150, v150, |v126|, |v127|
	v_fmac_f32_e32 v151, v114, v114
	v_lshlrev_b32_e32 v118, 16, v191
	v_max3_f32 v150, v150, |v124|, |v125|
	v_fmac_f32_e32 v151, v115, v115
	v_and_b32_e32 v119, 0xffff0000, v191
	v_max3_f32 v150, v150, |v128|, |v129|
	v_fmac_f32_e32 v151, v118, v118
	v_cvt_pk_bf16_f32 v193, v116, v117
	v_lshlrev_b32_e32 v116, 16, v192
	v_max3_f32 v150, v150, |v114|, |v115|
	v_fmac_f32_e32 v151, v119, v119
	v_and_b32_e32 v117, 0xffff0000, v192
	v_max3_f32 v150, v150, |v118|, |v119|
	v_fmac_f32_e32 v151, v116, v116
	v_lshlrev_b32_e32 v120, 16, v193
	v_and_b32_e32 v121, 0xffff0000, v193
	v_max3_f32 v150, v150, |v116|, |v117|
	v_fmac_f32_e32 v151, v117, v117
	v_max3_f32 v150, v150, |v120|, |v121|
	v_fmac_f32_e32 v151, v120, v120
	ds_bpermute_b32 v154, v152, v150
	v_fmac_f32_e32 v151, v121, v121
	ds_bpermute_b32 v155, v152, v151
	v_cmp_lt_i32_e32 vcc, v153, v160
	global_store_dwordx4 v[194:195], v[156:159], off
	global_store_dwordx4 v[194:195], v[190:193], off offset:256
	v_cndmask_b32_e32 v153, v164, v153, vcc
	s_waitcnt lgkmcnt(1)
	v_max_f32_e32 v154, v154, v154
	v_lshlrev_b32_e32 v153, 2, v153
	v_max_f32_e32 v150, v150, v154
	s_waitcnt lgkmcnt(0)
	v_add_f32_e32 v151, v151, v155
	ds_bpermute_b32 v154, v153, v151
	ds_bpermute_b32 v155, v153, v150
	s_and_saveexec_b64 s[48:49], s[4:5]
	s_cbranch_execz .LBB0_1643
	s_waitcnt lgkmcnt(1)
	v_add_f32_e32 v151, v151, v154
	s_waitcnt lgkmcnt(0)
	v_max_f32_e32 v154, v155, v155
	v_max_f32_e32 v150, v150, v150
	v_max_f32_e32 v150, v150, v154
	ds_write2st64_b32 v177, v151, v150 offset1:16
.LBB0_1643:
	s_or_b64 exec, exec, s[48:49]
	v_add_u32_e32 v234, 0xa0, v148
	v_ashrrev_i32_e32 v235, 31, v234
	v_lshlrev_b64 v[234:235], 11, v[234:235]
	v_lshl_add_u64 v[234:235], s[26:27], 0, v[234:235]
	v_lshl_add_u64 v[234:235], s[56:57], 1, v[234:235]
	v_lshl_add_u64 v[234:235], v[234:235], 0, s[16:17]
	v_lshl_add_u64 v[252:253], v[234:235], 0, v[0:1]
	global_load_dwordx4 v[200:203], v[252:253], off
	global_load_dwordx4 v[204:207], v[252:253], off offset:256
	v_or_b32_e32 v150, 16, v148
	v_ashrrev_i32_e32 v151, 31, v150
	v_lshlrev_b64 v[150:151], 11, v[150:151]
	v_lshl_add_u64 v[150:151], s[26:27], 0, v[150:151]
	v_lshl_add_u64 v[150:151], s[56:57], 1, v[150:151]
	v_lshl_add_u64 v[150:151], v[150:151], 0, s[16:17]
	v_lshl_add_u64 v[194:195], v[150:151], 0, v[0:1]
	s_waitcnt lgkmcnt(0)
	s_waitcnt vmcnt(13)
	v_lshlrev_b32_e32 v150, 16, v208
	v_and_b32_e32 v151, 0xffff0000, v208
	v_lshlrev_b32_e32 v158, 16, v210
	v_and_b32_e32 v159, 0xffff0000, v210
	v_lshlrev_b32_e32 v156, 16, v211
	v_and_b32_e32 v157, 0xffff0000, v211
	v_pk_add_f32 v[110:111], v[110:111], v[150:151]
	v_lshlrev_b32_e32 v154, 16, v209
	v_and_b32_e32 v155, 0xffff0000, v209
	v_pk_add_f32 v[106:107], v[106:107], v[158:159]
	v_pk_add_f32 v[108:109], v[108:109], v[156:157]
	v_cvt_pk_bf16_f32 v156, v110, v111
	v_pk_add_f32 v[112:113], v[112:113], v[154:155]
	v_cvt_pk_bf16_f32 v158, v106, v107
	v_and_b32_e32 v107, 0xffff0000, v156
	v_cvt_pk_bf16_f32 v157, v112, v113
	v_lshlrev_b32_e32 v106, 16, v156
	v_mul_f32_e32 v151, v107, v107
	v_lshlrev_b32_e32 v110, 16, v157
	v_fmac_f32_e32 v151, v106, v106
	v_and_b32_e32 v111, 0xffff0000, v157
	v_fmac_f32_e32 v151, v110, v110
	v_cvt_pk_bf16_f32 v159, v108, v109
	v_lshlrev_b32_e32 v108, 16, v158
	v_fmac_f32_e32 v151, v111, v111
	s_waitcnt vmcnt(12)
	v_lshlrev_b32_e32 v196, 16, v212
	v_and_b32_e32 v197, 0xffff0000, v212
	v_and_b32_e32 v109, 0xffff0000, v158
	v_fmac_f32_e32 v151, v108, v108
	v_lshlrev_b32_e32 v190, 16, v213
	v_and_b32_e32 v191, 0xffff0000, v213
	v_lshlrev_b32_e32 v198, 16, v214
	v_and_b32_e32 v199, 0xffff0000, v214
	v_pk_add_f32 v[102:103], v[102:103], v[196:197]
	v_lshlrev_b32_e32 v112, 16, v159
	v_fmac_f32_e32 v151, v109, v109
	v_lshlrev_b32_e32 v192, 16, v215
	v_and_b32_e32 v193, 0xffff0000, v215
	v_pk_add_f32 v[104:105], v[104:105], v[190:191]
	v_pk_add_f32 v[98:99], v[98:99], v[198:199]
	v_cvt_pk_bf16_f32 v190, v102, v103
	v_and_b32_e32 v113, 0xffff0000, v159
	v_fmac_f32_e32 v151, v112, v112
	v_pk_add_f32 v[100:101], v[100:101], v[192:193]
	v_cvt_pk_bf16_f32 v192, v98, v99
	v_lshlrev_b32_e32 v98, 16, v190
	v_max3_f32 v150, |v106|, 0, |v107|
	v_fmac_f32_e32 v151, v113, v113
	v_cvt_pk_bf16_f32 v191, v104, v105
	v_and_b32_e32 v99, 0xffff0000, v190
	v_max3_f32 v150, v150, |v110|, |v111|
	v_fmac_f32_e32 v151, v98, v98
	v_lshlrev_b32_e32 v102, 16, v191
	v_max3_f32 v150, v150, |v108|, |v109|
	v_fmac_f32_e32 v151, v99, v99
	v_and_b32_e32 v103, 0xffff0000, v191
	v_max3_f32 v150, v150, |v112|, |v113|
	v_fmac_f32_e32 v151, v102, v102
	v_cvt_pk_bf16_f32 v193, v100, v101
	v_lshlrev_b32_e32 v100, 16, v192
	v_max3_f32 v150, v150, |v98|, |v99|
	v_fmac_f32_e32 v151, v103, v103
	v_and_b32_e32 v101, 0xffff0000, v192
	v_max3_f32 v150, v150, |v102|, |v103|
	v_fmac_f32_e32 v151, v100, v100
	v_lshlrev_b32_e32 v104, 16, v193
	v_and_b32_e32 v105, 0xffff0000, v193
	v_max3_f32 v150, v150, |v100|, |v101|
	v_fmac_f32_e32 v151, v101, v101
	v_max3_f32 v150, v150, |v104|, |v105|
	v_fmac_f32_e32 v151, v104, v104
	ds_bpermute_b32 v154, v152, v150
	v_fmac_f32_e32 v151, v105, v105
	ds_bpermute_b32 v155, v152, v151
	global_store_dwordx4 v[194:195], v[156:159], off
	global_store_dwordx4 v[194:195], v[190:193], off offset:256
	s_waitcnt lgkmcnt(1)
	v_max_f32_e32 v154, v154, v154
	v_max_f32_e32 v150, v150, v154
	s_waitcnt lgkmcnt(0)
	v_add_f32_e32 v151, v151, v155
	ds_bpermute_b32 v154, v153, v151
	ds_bpermute_b32 v155, v153, v150
	s_and_saveexec_b64 s[48:49], s[4:5]
	s_cbranch_execz .LBB0_1645
	s_waitcnt lgkmcnt(1)
	v_add_f32_e32 v151, v151, v154
	s_waitcnt lgkmcnt(0)
	v_max_f32_e32 v154, v155, v155
	v_max_f32_e32 v150, v150, v150
	v_max_f32_e32 v150, v150, v154
	ds_write2st64_b32 v177, v151, v150 offset0:1 offset1:17
.LBB0_1645:
	s_or_b64 exec, exec, s[48:49]
	v_add_u32_e32 v234, 0xb0, v148
	v_ashrrev_i32_e32 v235, 31, v234
	v_lshlrev_b64 v[234:235], 11, v[234:235]
	v_lshl_add_u64 v[234:235], s[26:27], 0, v[234:235]
	v_lshl_add_u64 v[234:235], s[56:57], 1, v[234:235]
	v_lshl_add_u64 v[234:235], v[234:235], 0, s[16:17]
	v_lshl_add_u64 v[252:253], v[234:235], 0, v[0:1]
	global_load_dwordx4 v[208:211], v[252:253], off
	global_load_dwordx4 v[212:215], v[252:253], off offset:256
	v_or_b32_e32 v150, 32, v148
	v_ashrrev_i32_e32 v151, 31, v150
	v_lshlrev_b64 v[150:151], 11, v[150:151]
	v_lshl_add_u64 v[150:151], s[26:27], 0, v[150:151]
	v_lshl_add_u64 v[150:151], s[56:57], 1, v[150:151]
	v_lshl_add_u64 v[150:151], v[150:151], 0, s[16:17]
	v_lshl_add_u64 v[194:195], v[150:151], 0, v[0:1]
	s_waitcnt lgkmcnt(0)
	s_waitcnt vmcnt(15)
	v_lshlrev_b32_e32 v150, 16, v216
	v_and_b32_e32 v151, 0xffff0000, v216
	v_lshlrev_b32_e32 v158, 16, v218
	v_and_b32_e32 v159, 0xffff0000, v218
	v_lshlrev_b32_e32 v156, 16, v219
	v_and_b32_e32 v157, 0xffff0000, v219
	v_pk_add_f32 v[94:95], v[94:95], v[150:151]
	v_lshlrev_b32_e32 v154, 16, v217
	v_and_b32_e32 v155, 0xffff0000, v217
	v_pk_add_f32 v[90:91], v[90:91], v[158:159]
	v_pk_add_f32 v[92:93], v[92:93], v[156:157]
	v_cvt_pk_bf16_f32 v156, v94, v95
	v_pk_add_f32 v[96:97], v[96:97], v[154:155]
	v_cvt_pk_bf16_f32 v158, v90, v91
	v_and_b32_e32 v91, 0xffff0000, v156
	v_cvt_pk_bf16_f32 v157, v96, v97
	v_lshlrev_b32_e32 v90, 16, v156
	v_mul_f32_e32 v151, v91, v91
	v_lshlrev_b32_e32 v94, 16, v157
	v_fmac_f32_e32 v151, v90, v90
	v_and_b32_e32 v95, 0xffff0000, v157
	v_fmac_f32_e32 v151, v94, v94
	v_cvt_pk_bf16_f32 v159, v92, v93
	v_lshlrev_b32_e32 v92, 16, v158
	v_fmac_f32_e32 v151, v95, v95
	s_waitcnt vmcnt(14)
	v_lshlrev_b32_e32 v196, 16, v220
	v_and_b32_e32 v197, 0xffff0000, v220
	v_and_b32_e32 v93, 0xffff0000, v158
	v_fmac_f32_e32 v151, v92, v92
	v_lshlrev_b32_e32 v190, 16, v221
	v_and_b32_e32 v191, 0xffff0000, v221
	v_lshlrev_b32_e32 v198, 16, v222
	v_and_b32_e32 v199, 0xffff0000, v222
	v_pk_add_f32 v[86:87], v[86:87], v[196:197]
	v_lshlrev_b32_e32 v96, 16, v159
	v_fmac_f32_e32 v151, v93, v93
	v_lshlrev_b32_e32 v192, 16, v223
	v_and_b32_e32 v193, 0xffff0000, v223
	v_pk_add_f32 v[88:89], v[88:89], v[190:191]
	v_pk_add_f32 v[82:83], v[82:83], v[198:199]
	v_cvt_pk_bf16_f32 v190, v86, v87
	v_and_b32_e32 v97, 0xffff0000, v159
	v_fmac_f32_e32 v151, v96, v96
	v_pk_add_f32 v[84:85], v[84:85], v[192:193]
	v_cvt_pk_bf16_f32 v192, v82, v83
	v_lshlrev_b32_e32 v82, 16, v190
	v_max3_f32 v150, |v90|, 0, |v91|
	v_fmac_f32_e32 v151, v97, v97
	v_cvt_pk_bf16_f32 v191, v88, v89
	v_and_b32_e32 v83, 0xffff0000, v190
	v_max3_f32 v150, v150, |v94|, |v95|
	v_fmac_f32_e32 v151, v82, v82
	v_lshlrev_b32_e32 v86, 16, v191
	v_max3_f32 v150, v150, |v92|, |v93|
	v_fmac_f32_e32 v151, v83, v83
	v_and_b32_e32 v87, 0xffff0000, v191
	v_max3_f32 v150, v150, |v96|, |v97|
	v_fmac_f32_e32 v151, v86, v86
	v_cvt_pk_bf16_f32 v193, v84, v85
	v_lshlrev_b32_e32 v84, 16, v192
	v_max3_f32 v150, v150, |v82|, |v83|
	v_fmac_f32_e32 v151, v87, v87
	v_and_b32_e32 v85, 0xffff0000, v192
	v_max3_f32 v150, v150, |v86|, |v87|
	v_fmac_f32_e32 v151, v84, v84
	v_lshlrev_b32_e32 v88, 16, v193
	v_and_b32_e32 v89, 0xffff0000, v193
	v_max3_f32 v150, v150, |v84|, |v85|
	v_fmac_f32_e32 v151, v85, v85
	v_max3_f32 v150, v150, |v88|, |v89|
	v_fmac_f32_e32 v151, v88, v88
	ds_bpermute_b32 v154, v152, v150
	v_fmac_f32_e32 v151, v89, v89
	ds_bpermute_b32 v155, v152, v151
	global_store_dwordx4 v[194:195], v[156:159], off
	global_store_dwordx4 v[194:195], v[190:193], off offset:256
	s_waitcnt lgkmcnt(1)
	v_max_f32_e32 v154, v154, v154
	v_max_f32_e32 v150, v150, v154
	s_waitcnt lgkmcnt(0)
	v_add_f32_e32 v151, v151, v155
	ds_bpermute_b32 v154, v153, v151
	ds_bpermute_b32 v155, v153, v150
	s_and_saveexec_b64 s[48:49], s[4:5]
	s_cbranch_execz .LBB0_1647
	s_waitcnt lgkmcnt(1)
	v_add_f32_e32 v151, v151, v154
	s_waitcnt lgkmcnt(0)
	v_max_f32_e32 v154, v155, v155
	v_max_f32_e32 v150, v150, v150
	v_max_f32_e32 v150, v150, v154
	ds_write2st64_b32 v177, v151, v150 offset0:2 offset1:18
.LBB0_1647:
	s_or_b64 exec, exec, s[48:49]
	v_or_b32_e32 v150, 48, v148
	v_ashrrev_i32_e32 v151, 31, v150
	v_lshlrev_b64 v[150:151], 11, v[150:151]
	v_lshl_add_u64 v[150:151], s[26:27], 0, v[150:151]
	v_lshl_add_u64 v[150:151], s[56:57], 1, v[150:151]
	v_lshl_add_u64 v[150:151], v[150:151], 0, s[16:17]
	v_lshl_add_u64 v[194:195], v[150:151], 0, v[0:1]
	s_waitcnt lgkmcnt(0)
	s_waitcnt vmcnt(15)
	v_lshlrev_b32_e32 v150, 16, v224
	v_and_b32_e32 v151, 0xffff0000, v224
	v_lshlrev_b32_e32 v158, 16, v226
	v_and_b32_e32 v159, 0xffff0000, v226
	v_lshlrev_b32_e32 v156, 16, v227
	v_and_b32_e32 v157, 0xffff0000, v227
	v_pk_add_f32 v[78:79], v[78:79], v[150:151]
	v_lshlrev_b32_e32 v154, 16, v225
	v_and_b32_e32 v155, 0xffff0000, v225
	v_pk_add_f32 v[74:75], v[74:75], v[158:159]
	v_pk_add_f32 v[76:77], v[76:77], v[156:157]
	v_cvt_pk_bf16_f32 v156, v78, v79
	v_pk_add_f32 v[80:81], v[80:81], v[154:155]
	v_cvt_pk_bf16_f32 v158, v74, v75
	v_and_b32_e32 v75, 0xffff0000, v156
	v_cvt_pk_bf16_f32 v157, v80, v81
	v_lshlrev_b32_e32 v74, 16, v156
	v_mul_f32_e32 v151, v75, v75
	v_lshlrev_b32_e32 v78, 16, v157
	v_fmac_f32_e32 v151, v74, v74
	v_and_b32_e32 v79, 0xffff0000, v157
	v_fmac_f32_e32 v151, v78, v78
	v_cvt_pk_bf16_f32 v159, v76, v77
	v_lshlrev_b32_e32 v76, 16, v158
	v_fmac_f32_e32 v151, v79, v79
	s_waitcnt vmcnt(14)
	v_lshlrev_b32_e32 v196, 16, v228
	v_and_b32_e32 v197, 0xffff0000, v228
	v_and_b32_e32 v77, 0xffff0000, v158
	v_fmac_f32_e32 v151, v76, v76
	v_lshlrev_b32_e32 v190, 16, v229
	v_and_b32_e32 v191, 0xffff0000, v229
	v_lshlrev_b32_e32 v198, 16, v230
	v_and_b32_e32 v199, 0xffff0000, v230
	v_pk_add_f32 v[70:71], v[70:71], v[196:197]
	v_lshlrev_b32_e32 v80, 16, v159
	v_fmac_f32_e32 v151, v77, v77
	v_lshlrev_b32_e32 v192, 16, v231
	v_and_b32_e32 v193, 0xffff0000, v231
	v_pk_add_f32 v[72:73], v[72:73], v[190:191]
	v_pk_add_f32 v[66:67], v[66:67], v[198:199]
	v_cvt_pk_bf16_f32 v190, v70, v71
	v_and_b32_e32 v81, 0xffff0000, v159
	v_fmac_f32_e32 v151, v80, v80
	v_pk_add_f32 v[68:69], v[68:69], v[192:193]
	v_cvt_pk_bf16_f32 v192, v66, v67
	v_lshlrev_b32_e32 v66, 16, v190
	v_max3_f32 v150, |v74|, 0, |v75|
	v_fmac_f32_e32 v151, v81, v81
	v_cvt_pk_bf16_f32 v191, v72, v73
	v_and_b32_e32 v67, 0xffff0000, v190
	v_max3_f32 v150, v150, |v78|, |v79|
	v_fmac_f32_e32 v151, v66, v66
	v_lshlrev_b32_e32 v70, 16, v191
	v_max3_f32 v150, v150, |v76|, |v77|
	v_fmac_f32_e32 v151, v67, v67
	v_and_b32_e32 v71, 0xffff0000, v191
	v_max3_f32 v150, v150, |v80|, |v81|
	v_fmac_f32_e32 v151, v70, v70
	v_cvt_pk_bf16_f32 v193, v68, v69
	v_lshlrev_b32_e32 v68, 16, v192
	v_max3_f32 v150, v150, |v66|, |v67|
	v_fmac_f32_e32 v151, v71, v71
	v_and_b32_e32 v69, 0xffff0000, v192
	v_max3_f32 v150, v150, |v70|, |v71|
	v_fmac_f32_e32 v151, v68, v68
	v_lshlrev_b32_e32 v72, 16, v193
	v_and_b32_e32 v73, 0xffff0000, v193
	v_max3_f32 v150, v150, |v68|, |v69|
	v_fmac_f32_e32 v151, v69, v69
	v_max3_f32 v150, v150, |v72|, |v73|
	v_fmac_f32_e32 v151, v72, v72
	ds_bpermute_b32 v154, v152, v150
	v_fmac_f32_e32 v151, v73, v73
	ds_bpermute_b32 v155, v152, v151
	global_store_dwordx4 v[194:195], v[156:159], off
	global_store_dwordx4 v[194:195], v[190:193], off offset:256
	s_waitcnt lgkmcnt(1)
	v_max_f32_e32 v154, v154, v154
	v_max_f32_e32 v150, v150, v154
	s_waitcnt lgkmcnt(0)
	v_add_f32_e32 v151, v151, v155
	ds_bpermute_b32 v154, v153, v151
	ds_bpermute_b32 v155, v153, v150
	s_and_saveexec_b64 s[48:49], s[4:5]
	s_cbranch_execz .LBB0_1649
	s_waitcnt lgkmcnt(1)
	v_add_f32_e32 v151, v151, v154
	s_waitcnt lgkmcnt(0)
	v_max_f32_e32 v154, v155, v155
	v_max_f32_e32 v150, v150, v150
	v_max_f32_e32 v150, v150, v154
	ds_write2st64_b32 v177, v151, v150 offset0:3 offset1:19
.LBB0_1649:
	s_or_b64 exec, exec, s[48:49]
	v_add_u32_e32 v150, 0x80, v148
	v_ashrrev_i32_e32 v151, 31, v150
	v_lshlrev_b64 v[150:151], 11, v[150:151]
	v_lshl_add_u64 v[150:151], s[26:27], 0, v[150:151]
	v_lshl_add_u64 v[150:151], s[56:57], 1, v[150:151]
	v_lshl_add_u64 v[150:151], v[150:151], 0, s[16:17]
	v_lshl_add_u64 v[194:195], v[150:151], 0, v[0:1]
	s_waitcnt lgkmcnt(0)
	s_waitcnt vmcnt(15)
	v_lshlrev_b32_e32 v150, 16, v236
	v_and_b32_e32 v151, 0xffff0000, v236
	v_lshlrev_b32_e32 v158, 16, v238
	v_and_b32_e32 v159, 0xffff0000, v238
	v_lshlrev_b32_e32 v156, 16, v239
	v_and_b32_e32 v157, 0xffff0000, v239
	v_pk_add_f32 v[62:63], v[62:63], v[150:151]
	v_lshlrev_b32_e32 v154, 16, v237
	v_and_b32_e32 v155, 0xffff0000, v237
	v_pk_add_f32 v[58:59], v[58:59], v[158:159]
	v_pk_add_f32 v[60:61], v[60:61], v[156:157]
	v_cvt_pk_bf16_f32 v156, v62, v63
	v_pk_add_f32 v[64:65], v[64:65], v[154:155]
	v_cvt_pk_bf16_f32 v158, v58, v59
	v_and_b32_e32 v59, 0xffff0000, v156
	v_cvt_pk_bf16_f32 v157, v64, v65
	v_lshlrev_b32_e32 v58, 16, v156
	v_mul_f32_e32 v151, v59, v59
	v_lshlrev_b32_e32 v62, 16, v157
	v_fmac_f32_e32 v151, v58, v58
	v_and_b32_e32 v63, 0xffff0000, v157
	v_fmac_f32_e32 v151, v62, v62
	v_cvt_pk_bf16_f32 v159, v60, v61
	v_lshlrev_b32_e32 v60, 16, v158
	v_fmac_f32_e32 v151, v63, v63
	s_waitcnt vmcnt(14)
	v_lshlrev_b32_e32 v196, 16, v240
	v_and_b32_e32 v197, 0xffff0000, v240
	v_and_b32_e32 v61, 0xffff0000, v158
	v_fmac_f32_e32 v151, v60, v60
	v_lshlrev_b32_e32 v190, 16, v241
	v_and_b32_e32 v191, 0xffff0000, v241
	v_lshlrev_b32_e32 v198, 16, v242
	v_and_b32_e32 v199, 0xffff0000, v242
	v_pk_add_f32 v[54:55], v[54:55], v[196:197]
	v_lshlrev_b32_e32 v64, 16, v159
	v_fmac_f32_e32 v151, v61, v61
	v_lshlrev_b32_e32 v192, 16, v243
	v_and_b32_e32 v193, 0xffff0000, v243
	v_pk_add_f32 v[56:57], v[56:57], v[190:191]
	v_pk_add_f32 v[50:51], v[50:51], v[198:199]
	v_cvt_pk_bf16_f32 v190, v54, v55
	v_and_b32_e32 v65, 0xffff0000, v159
	v_fmac_f32_e32 v151, v64, v64
	v_pk_add_f32 v[52:53], v[52:53], v[192:193]
	v_cvt_pk_bf16_f32 v192, v50, v51
	v_lshlrev_b32_e32 v50, 16, v190
	v_max3_f32 v150, |v58|, 0, |v59|
	v_fmac_f32_e32 v151, v65, v65
	v_cvt_pk_bf16_f32 v191, v56, v57
	v_and_b32_e32 v51, 0xffff0000, v190
	v_max3_f32 v150, v150, |v62|, |v63|
	v_fmac_f32_e32 v151, v50, v50
	v_lshlrev_b32_e32 v54, 16, v191
	v_max3_f32 v150, v150, |v60|, |v61|
	v_fmac_f32_e32 v151, v51, v51
	v_and_b32_e32 v55, 0xffff0000, v191
	v_max3_f32 v150, v150, |v64|, |v65|
	v_fmac_f32_e32 v151, v54, v54
	v_cvt_pk_bf16_f32 v193, v52, v53
	v_lshlrev_b32_e32 v52, 16, v192
	v_max3_f32 v150, v150, |v50|, |v51|
	v_fmac_f32_e32 v151, v55, v55
	v_and_b32_e32 v53, 0xffff0000, v192
	v_max3_f32 v150, v150, |v54|, |v55|
	v_fmac_f32_e32 v151, v52, v52
	v_lshlrev_b32_e32 v56, 16, v193
	v_and_b32_e32 v57, 0xffff0000, v193
	v_max3_f32 v150, v150, |v52|, |v53|
	v_fmac_f32_e32 v151, v53, v53
	v_max3_f32 v150, v150, |v56|, |v57|
	v_fmac_f32_e32 v151, v56, v56
	ds_bpermute_b32 v154, v152, v150
	v_fmac_f32_e32 v151, v57, v57
	ds_bpermute_b32 v155, v152, v151
	global_store_dwordx4 v[194:195], v[156:159], off
	global_store_dwordx4 v[194:195], v[190:193], off offset:256
	s_waitcnt lgkmcnt(1)
	v_max_f32_e32 v154, v154, v154
	v_max_f32_e32 v150, v150, v154
	s_waitcnt lgkmcnt(0)
	v_add_f32_e32 v151, v151, v155
	ds_bpermute_b32 v154, v153, v151
	ds_bpermute_b32 v155, v153, v150
	s_and_saveexec_b64 s[48:49], s[4:5]
	s_cbranch_execz .LBB0_1651
	s_waitcnt lgkmcnt(1)
	v_add_f32_e32 v151, v151, v154
	s_waitcnt lgkmcnt(0)
	v_max_f32_e32 v154, v155, v155
	v_max_f32_e32 v150, v150, v150
	v_max_f32_e32 v150, v150, v154
	ds_write2st64_b32 v178, v151, v150 offset1:16
.LBB0_1651:
	s_or_b64 exec, exec, s[48:49]
	v_add_u32_e32 v150, 0x90, v148
	v_ashrrev_i32_e32 v151, 31, v150
	v_lshlrev_b64 v[150:151], 11, v[150:151]
	v_lshl_add_u64 v[150:151], s[26:27], 0, v[150:151]
	v_lshl_add_u64 v[150:151], s[56:57], 1, v[150:151]
	v_lshl_add_u64 v[150:151], v[150:151], 0, s[16:17]
	v_lshl_add_u64 v[194:195], v[150:151], 0, v[0:1]
	s_waitcnt lgkmcnt(0)
	s_waitcnt vmcnt(15)
	v_lshlrev_b32_e32 v150, 16, v244
	v_and_b32_e32 v151, 0xffff0000, v244
	v_lshlrev_b32_e32 v158, 16, v246
	v_and_b32_e32 v159, 0xffff0000, v246
	v_lshlrev_b32_e32 v156, 16, v247
	v_and_b32_e32 v157, 0xffff0000, v247
	v_pk_add_f32 v[46:47], v[46:47], v[150:151]
	v_lshlrev_b32_e32 v154, 16, v245
	v_and_b32_e32 v155, 0xffff0000, v245
	v_pk_add_f32 v[42:43], v[42:43], v[158:159]
	v_pk_add_f32 v[44:45], v[44:45], v[156:157]
	v_cvt_pk_bf16_f32 v156, v46, v47
	v_pk_add_f32 v[48:49], v[48:49], v[154:155]
	v_cvt_pk_bf16_f32 v158, v42, v43
	v_and_b32_e32 v43, 0xffff0000, v156
	v_cvt_pk_bf16_f32 v157, v48, v49
	v_lshlrev_b32_e32 v42, 16, v156
	v_mul_f32_e32 v151, v43, v43
	v_lshlrev_b32_e32 v46, 16, v157
	v_fmac_f32_e32 v151, v42, v42
	v_and_b32_e32 v47, 0xffff0000, v157
	v_fmac_f32_e32 v151, v46, v46
	v_cvt_pk_bf16_f32 v159, v44, v45
	v_lshlrev_b32_e32 v44, 16, v158
	v_fmac_f32_e32 v151, v47, v47
	s_waitcnt vmcnt(14)
	v_lshlrev_b32_e32 v196, 16, v248
	v_and_b32_e32 v197, 0xffff0000, v248
	v_and_b32_e32 v45, 0xffff0000, v158
	v_fmac_f32_e32 v151, v44, v44
	v_lshlrev_b32_e32 v190, 16, v249
	v_and_b32_e32 v191, 0xffff0000, v249
	v_lshlrev_b32_e32 v198, 16, v250
	v_and_b32_e32 v199, 0xffff0000, v250
	v_pk_add_f32 v[38:39], v[38:39], v[196:197]
	v_lshlrev_b32_e32 v48, 16, v159
	v_fmac_f32_e32 v151, v45, v45
	v_lshlrev_b32_e32 v192, 16, v251
	v_and_b32_e32 v193, 0xffff0000, v251
	v_pk_add_f32 v[40:41], v[40:41], v[190:191]
	v_pk_add_f32 v[34:35], v[34:35], v[198:199]
	v_cvt_pk_bf16_f32 v190, v38, v39
	v_and_b32_e32 v49, 0xffff0000, v159
	v_fmac_f32_e32 v151, v48, v48
	v_pk_add_f32 v[36:37], v[36:37], v[192:193]
	v_cvt_pk_bf16_f32 v192, v34, v35
	v_lshlrev_b32_e32 v34, 16, v190
	v_max3_f32 v150, |v42|, 0, |v43|
	v_fmac_f32_e32 v151, v49, v49
	v_cvt_pk_bf16_f32 v191, v40, v41
	v_and_b32_e32 v35, 0xffff0000, v190
	v_max3_f32 v150, v150, |v46|, |v47|
	v_fmac_f32_e32 v151, v34, v34
	v_lshlrev_b32_e32 v38, 16, v191
	v_max3_f32 v150, v150, |v44|, |v45|
	v_fmac_f32_e32 v151, v35, v35
	v_and_b32_e32 v39, 0xffff0000, v191
	v_max3_f32 v150, v150, |v48|, |v49|
	v_fmac_f32_e32 v151, v38, v38
	v_cvt_pk_bf16_f32 v193, v36, v37
	v_lshlrev_b32_e32 v36, 16, v192
	v_max3_f32 v150, v150, |v34|, |v35|
	v_fmac_f32_e32 v151, v39, v39
	v_and_b32_e32 v37, 0xffff0000, v192
	v_max3_f32 v150, v150, |v38|, |v39|
	v_fmac_f32_e32 v151, v36, v36
	v_lshlrev_b32_e32 v40, 16, v193
	v_and_b32_e32 v41, 0xffff0000, v193
	v_max3_f32 v150, v150, |v36|, |v37|
	v_fmac_f32_e32 v151, v37, v37
	v_max3_f32 v150, v150, |v40|, |v41|
	v_fmac_f32_e32 v151, v40, v40
	ds_bpermute_b32 v154, v152, v150
	v_fmac_f32_e32 v151, v41, v41
	ds_bpermute_b32 v155, v152, v151
	global_store_dwordx4 v[194:195], v[156:159], off
	global_store_dwordx4 v[194:195], v[190:193], off offset:256
	s_waitcnt lgkmcnt(1)
	v_max_f32_e32 v154, v154, v154
	v_max_f32_e32 v150, v150, v154
	s_waitcnt lgkmcnt(0)
	v_add_f32_e32 v151, v151, v155
	ds_bpermute_b32 v154, v153, v151
	ds_bpermute_b32 v155, v153, v150
	s_and_saveexec_b64 s[48:49], s[4:5]
	s_cbranch_execz .LBB0_1653
	s_waitcnt lgkmcnt(1)
	v_add_f32_e32 v151, v151, v154
	s_waitcnt lgkmcnt(0)
	v_max_f32_e32 v154, v155, v155
	v_max_f32_e32 v150, v150, v150
	v_max_f32_e32 v150, v150, v154
	ds_write2st64_b32 v177, v151, v150 offset0:9 offset1:25
.LBB0_1653:
	s_or_b64 exec, exec, s[48:49]
	v_add_u32_e32 v150, 0xa0, v148
	v_ashrrev_i32_e32 v151, 31, v150
	v_lshlrev_b64 v[150:151], 11, v[150:151]
	v_lshl_add_u64 v[150:151], s[26:27], 0, v[150:151]
	v_lshl_add_u64 v[150:151], s[56:57], 1, v[150:151]
	v_lshl_add_u64 v[150:151], v[150:151], 0, s[16:17]
	v_lshl_add_u64 v[194:195], v[150:151], 0, v[0:1]
	s_waitcnt lgkmcnt(0)
	s_waitcnt vmcnt(13)
	v_lshlrev_b32_e32 v150, 16, v200
	v_and_b32_e32 v151, 0xffff0000, v200
	v_lshlrev_b32_e32 v158, 16, v202
	v_and_b32_e32 v159, 0xffff0000, v202
	v_lshlrev_b32_e32 v156, 16, v203
	v_and_b32_e32 v157, 0xffff0000, v203
	v_pk_add_f32 v[30:31], v[30:31], v[150:151]
	v_lshlrev_b32_e32 v154, 16, v201
	v_and_b32_e32 v155, 0xffff0000, v201
	v_pk_add_f32 v[26:27], v[26:27], v[158:159]
	v_pk_add_f32 v[28:29], v[28:29], v[156:157]
	v_cvt_pk_bf16_f32 v156, v30, v31
	v_pk_add_f32 v[32:33], v[32:33], v[154:155]
	v_cvt_pk_bf16_f32 v158, v26, v27
	v_and_b32_e32 v27, 0xffff0000, v156
	v_cvt_pk_bf16_f32 v157, v32, v33
	v_lshlrev_b32_e32 v26, 16, v156
	v_mul_f32_e32 v151, v27, v27
	v_lshlrev_b32_e32 v30, 16, v157
	v_fmac_f32_e32 v151, v26, v26
	v_and_b32_e32 v31, 0xffff0000, v157
	v_fmac_f32_e32 v151, v30, v30
	v_cvt_pk_bf16_f32 v159, v28, v29
	v_lshlrev_b32_e32 v28, 16, v158
	v_fmac_f32_e32 v151, v31, v31
	s_waitcnt vmcnt(12)
	v_lshlrev_b32_e32 v196, 16, v204
	v_and_b32_e32 v197, 0xffff0000, v204
	v_and_b32_e32 v29, 0xffff0000, v158
	v_fmac_f32_e32 v151, v28, v28
	v_lshlrev_b32_e32 v190, 16, v205
	v_and_b32_e32 v191, 0xffff0000, v205
	v_lshlrev_b32_e32 v198, 16, v206
	v_and_b32_e32 v199, 0xffff0000, v206
	v_pk_add_f32 v[22:23], v[22:23], v[196:197]
	v_lshlrev_b32_e32 v32, 16, v159
	v_fmac_f32_e32 v151, v29, v29
	v_lshlrev_b32_e32 v192, 16, v207
	v_and_b32_e32 v193, 0xffff0000, v207
	v_pk_add_f32 v[24:25], v[24:25], v[190:191]
	v_pk_add_f32 v[18:19], v[18:19], v[198:199]
	v_cvt_pk_bf16_f32 v190, v22, v23
	v_and_b32_e32 v33, 0xffff0000, v159
	v_fmac_f32_e32 v151, v32, v32
	v_pk_add_f32 v[20:21], v[20:21], v[192:193]
	v_cvt_pk_bf16_f32 v192, v18, v19
	v_lshlrev_b32_e32 v18, 16, v190
	v_max3_f32 v150, |v26|, 0, |v27|
	v_fmac_f32_e32 v151, v33, v33
	v_cvt_pk_bf16_f32 v191, v24, v25
	v_and_b32_e32 v19, 0xffff0000, v190
	v_max3_f32 v150, v150, |v30|, |v31|
	v_fmac_f32_e32 v151, v18, v18
	v_lshlrev_b32_e32 v22, 16, v191
	v_max3_f32 v150, v150, |v28|, |v29|
	v_fmac_f32_e32 v151, v19, v19
	v_and_b32_e32 v23, 0xffff0000, v191
	v_max3_f32 v150, v150, |v32|, |v33|
	v_fmac_f32_e32 v151, v22, v22
	v_cvt_pk_bf16_f32 v193, v20, v21
	v_lshlrev_b32_e32 v20, 16, v192
	v_max3_f32 v150, v150, |v18|, |v19|
	v_fmac_f32_e32 v151, v23, v23
	v_and_b32_e32 v21, 0xffff0000, v192
	v_max3_f32 v150, v150, |v22|, |v23|
	v_fmac_f32_e32 v151, v20, v20
	v_lshlrev_b32_e32 v24, 16, v193
	v_and_b32_e32 v25, 0xffff0000, v193
	v_max3_f32 v150, v150, |v20|, |v21|
	v_fmac_f32_e32 v151, v21, v21
	v_max3_f32 v150, v150, |v24|, |v25|
	v_fmac_f32_e32 v151, v24, v24
	ds_bpermute_b32 v154, v152, v150
	v_fmac_f32_e32 v151, v25, v25
	ds_bpermute_b32 v155, v152, v151
	global_store_dwordx4 v[194:195], v[156:159], off
	global_store_dwordx4 v[194:195], v[190:193], off offset:256
	s_waitcnt lgkmcnt(1)
	v_max_f32_e32 v154, v154, v154
	v_max_f32_e32 v150, v150, v154
	s_waitcnt lgkmcnt(0)
	v_add_f32_e32 v151, v151, v155
	ds_bpermute_b32 v154, v153, v151
	ds_bpermute_b32 v155, v153, v150
	s_and_saveexec_b64 s[48:49], s[4:5]
	s_cbranch_execz .LBB0_1655
	s_waitcnt lgkmcnt(1)
	v_add_f32_e32 v151, v151, v154
	s_waitcnt lgkmcnt(0)
	v_max_f32_e32 v154, v155, v155
	v_max_f32_e32 v150, v150, v150
	v_max_f32_e32 v150, v150, v154
	ds_write2st64_b32 v177, v151, v150 offset0:10 offset1:26
.LBB0_1655:
	s_or_b64 exec, exec, s[48:49]
	v_add_u32_e32 v150, 0xb0, v148
	v_ashrrev_i32_e32 v151, 31, v150
	v_lshlrev_b64 v[150:151], 11, v[150:151]
	v_lshl_add_u64 v[150:151], s[26:27], 0, v[150:151]
	v_lshl_add_u64 v[150:151], s[56:57], 1, v[150:151]
	v_lshl_add_u64 v[150:151], v[150:151], 0, s[16:17]
	v_lshl_add_u64 v[158:159], v[150:151], 0, v[0:1]
	s_waitcnt lgkmcnt(0)
	s_waitcnt vmcnt(11)
	v_lshlrev_b32_e32 v150, 16, v208
	v_and_b32_e32 v151, 0xffff0000, v208
	v_lshlrev_b32_e32 v154, 16, v209
	v_and_b32_e32 v155, 0xffff0000, v209
	v_pk_add_f32 v[14:15], v[14:15], v[150:151]
	s_waitcnt vmcnt(10)
	v_lshlrev_b32_e32 v198, 16, v214
	v_and_b32_e32 v199, 0xffff0000, v214
	v_pk_add_f32 v[16:17], v[16:17], v[154:155]
	v_cvt_pk_bf16_f32 v154, v14, v15
	v_lshlrev_b32_e32 v192, 16, v215
	v_and_b32_e32 v193, 0xffff0000, v215
	v_pk_add_f32 v[2:3], v[2:3], v[198:199]
	v_and_b32_e32 v15, 0xffff0000, v154
	v_lshlrev_b32_e32 v194, 16, v210
	v_and_b32_e32 v195, 0xffff0000, v210
	v_pk_add_f32 v[4:5], v[4:5], v[192:193]
	v_cvt_pk_bf16_f32 v155, v16, v17
	v_cvt_pk_bf16_f32 v192, v2, v3
	v_lshlrev_b32_e32 v14, 16, v154
	v_mul_f32_e32 v2, v15, v15
	v_lshlrev_b32_e32 v156, 16, v211
	v_and_b32_e32 v157, 0xffff0000, v211
	v_pk_add_f32 v[10:11], v[10:11], v[194:195]
	v_lshlrev_b32_e32 v150, 16, v155
	v_fmac_f32_e32 v2, v14, v14
	v_pk_add_f32 v[12:13], v[12:13], v[156:157]
	v_cvt_pk_bf16_f32 v156, v10, v11
	v_and_b32_e32 v151, 0xffff0000, v155
	v_fmac_f32_e32 v2, v150, v150
	v_cvt_pk_bf16_f32 v157, v12, v13
	v_lshlrev_b32_e32 v12, 16, v156
	v_fmac_f32_e32 v2, v151, v151
	v_lshlrev_b32_e32 v196, 16, v212
	v_and_b32_e32 v197, 0xffff0000, v212
	v_and_b32_e32 v13, 0xffff0000, v156
	v_fmac_f32_e32 v2, v12, v12
	v_lshlrev_b32_e32 v190, 16, v213
	v_and_b32_e32 v191, 0xffff0000, v213
	v_pk_add_f32 v[6:7], v[6:7], v[196:197]
	v_lshlrev_b32_e32 v16, 16, v157
	v_fmac_f32_e32 v2, v13, v13
	v_pk_add_f32 v[8:9], v[8:9], v[190:191]
	v_cvt_pk_bf16_f32 v190, v6, v7
	v_and_b32_e32 v17, 0xffff0000, v157
	v_fmac_f32_e32 v2, v16, v16
	v_lshlrev_b32_e32 v6, 16, v190
	v_max3_f32 v0, |v14|, 0, |v15|
	v_fmac_f32_e32 v2, v17, v17
	v_cvt_pk_bf16_f32 v191, v8, v9
	v_and_b32_e32 v7, 0xffff0000, v190
	v_max3_f32 v0, v0, |v150|, |v151|
	v_fmac_f32_e32 v2, v6, v6
	v_lshlrev_b32_e32 v10, 16, v191
	v_max3_f32 v0, v0, |v12|, |v13|
	v_fmac_f32_e32 v2, v7, v7
	v_and_b32_e32 v11, 0xffff0000, v191
	v_max3_f32 v0, v0, |v16|, |v17|
	v_fmac_f32_e32 v2, v10, v10
	v_cvt_pk_bf16_f32 v193, v4, v5
	v_lshlrev_b32_e32 v4, 16, v192
	v_max3_f32 v0, v0, |v6|, |v7|
	v_fmac_f32_e32 v2, v11, v11
	v_and_b32_e32 v5, 0xffff0000, v192
	v_max3_f32 v0, v0, |v10|, |v11|
	v_fmac_f32_e32 v2, v4, v4
	v_lshlrev_b32_e32 v8, 16, v193
	v_and_b32_e32 v9, 0xffff0000, v193
	v_max3_f32 v0, v0, |v4|, |v5|
	v_fmac_f32_e32 v2, v5, v5
	v_max3_f32 v0, v0, |v8|, |v9|
	v_fmac_f32_e32 v2, v8, v8
	ds_bpermute_b32 v3, v152, v0
	v_fmac_f32_e32 v2, v9, v9
	ds_bpermute_b32 v152, v152, v2
	global_store_dwordx4 v[158:159], v[154:157], off
	global_store_dwordx4 v[158:159], v[190:193], off offset:256
	s_waitcnt lgkmcnt(1)
	v_max_f32_e32 v3, v3, v3
	v_max_f32_e32 v0, v0, v3
	s_waitcnt lgkmcnt(0)
	v_add_f32_e32 v2, v2, v152
	ds_bpermute_b32 v3, v153, v2
	ds_bpermute_b32 v152, v153, v0
	s_and_saveexec_b64 s[48:49], s[4:5]
	s_cbranch_execz .LBB0_1657
	s_waitcnt lgkmcnt(1)
	v_add_f32_e32 v2, v2, v3
	s_waitcnt lgkmcnt(0)
	v_max_f32_e32 v3, v152, v152
	v_max_f32_e32 v0, v0, v0
	v_max_f32_e32 v0, v0, v3
	ds_write2st64_b32 v177, v2, v0 offset0:11 offset1:27

.LBB0_2783:
	v_or_b32_e32 v152, s2, v175
	v_mad_u32_u24 v172, v152, s28, v176
	ds_read_b64_tr_b16 v[80:81], v185
	ds_read_b64_tr_b16 v[82:83], v185 offset:768
	ds_read_b64_tr_b16 v[96:97], v185 offset:6144
	ds_read_b64_tr_b16 v[98:99], v185 offset:6912
	ds_read2_b64 v[100:103], v172 offset1:1
	v_add_u32_e32 v128, 0x2200, v172
	ds_read2_b64 v[84:87], v128 offset1:1
	v_add_u32_e32 v129, 0x4400, v172
	s_waitcnt lgkmcnt(1)
	v_mfma_f32_32x32x16_bf16 v[64:79], v[80:83], v[100:103], 0
	ds_read2_b64 v[88:91], v129 offset1:1
	ds_read_b64_tr_b16 v[104:105], v185 offset:3072
	ds_read_b64_tr_b16 v[106:107], v185 offset:3840
	ds_read_b64_tr_b16 v[108:109], v185 offset:9216
	ds_read_b64_tr_b16 v[110:111], v185 offset:9984
	ds_read2_b64 v[112:115], v172 offset0:4 offset1:5
	v_add_u32_e32 v173, 0x2220, v172
	ds_read2_b64 v[116:119], v173 offset1:1
	v_add_u32_e32 v203, 0x4420, v172
	ds_read2_b64 v[120:123], v203 offset1:1
	v_lshlrev_b32_e32 v204, 2, v152
	s_waitcnt lgkmcnt(7)
	v_mfma_f32_32x32x16_bf16 v[64:79], v[96:99], v[88:91], v[64:79]
	v_mfma_f32_32x32x16_bf16 v[80:95], v[80:83], v[84:87], 0
	v_mfma_f32_32x32x16_bf16 v[80:95], v[96:99], v[100:103], v[80:95]
	ds_read_b64_tr_b16 v[96:97], v185 offset:64
	ds_read_b64_tr_b16 v[98:99], v185 offset:832
	ds_read_b64_tr_b16 v[100:101], v185 offset:6208
	ds_read_b64_tr_b16 v[102:103], v185 offset:6976
	ds_read2_b64 v[124:127], v172 offset1:1
	ds_read2_b64 v[144:147], v128 offset1:1
	ds_read2_b64 v[148:151], v129 offset1:1
	s_waitcnt lgkmcnt(6)
	v_mul_u32_u24_e32 v233, v152, v177
	v_lshl_add_u32 v234, v233, 2, s24
	ds_read_b32 v235, v234
	v_add_u32_e32 v236, v234, v204
	ds_read_b32 v237, v236
	v_add_u32_e32 v238, v236, v204
	v_add_u32_e32 v239, v238, v204
	ds_read_b32 v240, v238
	ds_read_b32 v241, v239
	v_mul_u32_u24_e32 v242, 5, v152
	v_lshlrev_b32_e32 v243, 2, v242
	v_add_u32_e32 v244, v239, v243
	v_add_u32_e32 v245, v244, v204
	ds_read_b32 v246, v244
	ds_read_b32 v247, v245
	v_add_u32_e32 v248, v245, v204
	v_add_u32_e32 v249, v248, v204
	ds_read_b32 v250, v248
	ds_read_b32 v251, v249
	s_waitcnt lgkmcnt(15)
	v_mfma_f32_32x32x16_bf16 v[64:79], v[104:107], v[112:115], v[64:79]
	s_waitcnt lgkmcnt(15)
	v_mfma_f32_32x32x16_bf16 v[80:95], v[104:107], v[116:119], v[80:95]
	s_waitcnt lgkmcnt(15)
	v_mfma_f32_32x32x16_bf16 v[64:79], v[108:111], v[120:123], v[64:79]
	v_mfma_f32_32x32x16_bf16 v[80:95], v[108:111], v[112:115], v[80:95]
	s_waitcnt lgkmcnt(7)
	s_waitcnt lgkmcnt(6)
	v_add_u32_e32 v252, v249, v243
	v_add_u32_e32 v253, v252, v204
	ds_read_b32 v233, v252
	ds_read_b32 v234, v253
	v_add_u32_e32 v236, v253, v204
	v_add_u32_e32 v238, v236, v204
	ds_read_b32 v242, v236
	ds_read_b32 v239, v238
	v_add_u32_e32 v244, v238, v243
	v_add_u32_e32 v245, v244, v204
	ds_read_b32 v248, v244
	ds_read_b32 v249, v245
	v_add_u32_e32 v252, v245, v204
	v_add_u32_e32 v253, v252, v204
	ds_read_b32 v236, v252
	ds_read_b32 v238, v253
	v_mov_b32_e32 v205, v243
	v_mov_b32_e32 v206, v253
	v_cvt_f32_f16_e32 v104, v235
	v_cvt_f32_f16_sdwa v106, v235 dst_sel:DWORD dst_unused:UNUSED_PAD src0_sel:WORD_1
	s_waitcnt lgkmcnt(14)
	v_cvt_f32_f16_e32 v105, v237
	v_cvt_f32_f16_sdwa v107, v237 dst_sel:DWORD dst_unused:UNUSED_PAD src0_sel:WORD_1
	s_nop 3
	v_pk_mul_f32 v[108:109], v[80:81], v[106:107]
	s_nop 0
	v_pk_fma_f32 v[108:109], v[64:65], v[104:105], v[108:109] neg_lo:[0,0,1] neg_hi:[0,0,1]
	v_pk_mul_f32 v[64:65], v[64:65], v[106:107]
	v_cvt_pk_bf16_f32 v136, v108, v109
	v_pk_fma_f32 v[64:65], v[80:81], v[104:105], v[64:65]
	v_cvt_pk_bf16_f32 v140, v64, v65
	s_waitcnt lgkmcnt(13)
	v_cvt_f32_f16_e32 v80, v240
	s_waitcnt lgkmcnt(12)
	v_cvt_f32_f16_e32 v81, v241
	v_cvt_f32_f16_sdwa v105, v241 dst_sel:DWORD dst_unused:UNUSED_PAD src0_sel:WORD_1
	v_cvt_f32_f16_sdwa v104, v240 dst_sel:DWORD dst_unused:UNUSED_PAD src0_sel:WORD_1
	v_pk_mul_f32 v[106:107], v[82:83], v[104:105]
	s_nop 0
	v_pk_fma_f32 v[106:107], v[66:67], v[80:81], v[106:107] neg_lo:[0,0,1] neg_hi:[0,0,1]
	v_pk_mul_f32 v[66:67], v[66:67], v[104:105]
	v_cvt_pk_bf16_f32 v137, v106, v107
	v_pk_fma_f32 v[66:67], v[82:83], v[80:81], v[66:67]
	v_cvt_pk_bf16_f32 v141, v66, v67
	s_waitcnt lgkmcnt(11)
	v_cvt_f32_f16_e32 v80, v246
	s_waitcnt lgkmcnt(10)
	v_cvt_f32_f16_e32 v81, v247
	v_cvt_f32_f16_sdwa v82, v246 dst_sel:DWORD dst_unused:UNUSED_PAD src0_sel:WORD_1
	v_cvt_f32_f16_sdwa v83, v247 dst_sel:DWORD dst_unused:UNUSED_PAD src0_sel:WORD_1
	v_pk_mul_f32 v[104:105], v[84:85], v[82:83]
	s_nop 0
	v_pk_fma_f32 v[104:105], v[68:69], v[80:81], v[104:105] neg_lo:[0,0,1] neg_hi:[0,0,1]
	v_pk_mul_f32 v[68:69], v[68:69], v[82:83]
	v_cvt_pk_bf16_f32 v138, v104, v105
	v_pk_fma_f32 v[68:69], v[84:85], v[80:81], v[68:69]
	v_cvt_pk_bf16_f32 v142, v68, v69
	s_waitcnt lgkmcnt(9)
	v_cvt_f32_f16_e32 v80, v250
	s_waitcnt lgkmcnt(8)
	v_cvt_f32_f16_e32 v81, v251
	v_cvt_f32_f16_sdwa v82, v250 dst_sel:DWORD dst_unused:UNUSED_PAD src0_sel:WORD_1
	v_cvt_f32_f16_sdwa v83, v251 dst_sel:DWORD dst_unused:UNUSED_PAD src0_sel:WORD_1
	v_pk_mul_f32 v[84:85], v[86:87], v[82:83]
	s_nop 0
	v_pk_fma_f32 v[84:85], v[70:71], v[80:81], v[84:85] neg_lo:[0,0,1] neg_hi:[0,0,1]
	v_pk_mul_f32 v[70:71], v[70:71], v[82:83]
	v_cvt_pk_bf16_f32 v139, v84, v85
	v_pk_fma_f32 v[70:71], v[86:87], v[80:81], v[70:71]
	v_cvt_pk_bf16_f32 v143, v70, v71
	s_waitcnt lgkmcnt(7)
	v_cvt_f32_f16_e32 v80, v233
	s_waitcnt lgkmcnt(6)
	v_cvt_f32_f16_e32 v81, v234
	v_cvt_f32_f16_sdwa v82, v233 dst_sel:DWORD dst_unused:UNUSED_PAD src0_sel:WORD_1
	v_cvt_f32_f16_sdwa v83, v234 dst_sel:DWORD dst_unused:UNUSED_PAD src0_sel:WORD_1
	v_pk_mul_f32 v[86:87], v[88:89], v[82:83]
	s_nop 0
	v_pk_fma_f32 v[86:87], v[72:73], v[80:81], v[86:87] neg_lo:[0,0,1] neg_hi:[0,0,1]
	v_pk_mul_f32 v[72:73], v[72:73], v[82:83]
	v_cvt_pk_bf16_f32 v132, v86, v87
	v_pk_fma_f32 v[72:73], v[88:89], v[80:81], v[72:73]
	v_cvt_pk_bf16_f32 v128, v72, v73
	s_waitcnt lgkmcnt(5)
	v_cvt_f32_f16_e32 v80, v242
	s_waitcnt lgkmcnt(4)
	v_cvt_f32_f16_e32 v81, v239
	v_cvt_f32_f16_sdwa v82, v242 dst_sel:DWORD dst_unused:UNUSED_PAD src0_sel:WORD_1
	v_cvt_f32_f16_sdwa v83, v239 dst_sel:DWORD dst_unused:UNUSED_PAD src0_sel:WORD_1
	v_pk_mul_f32 v[88:89], v[90:91], v[82:83]
	s_nop 0
	v_pk_fma_f32 v[88:89], v[74:75], v[80:81], v[88:89] neg_lo:[0,0,1] neg_hi:[0,0,1]
	v_pk_mul_f32 v[74:75], v[74:75], v[82:83]
	v_cvt_pk_bf16_f32 v133, v88, v89
	v_pk_fma_f32 v[74:75], v[90:91], v[80:81], v[74:75]
	v_cvt_pk_bf16_f32 v129, v74, v75
	s_waitcnt lgkmcnt(3)
	v_cvt_f32_f16_e32 v80, v248
	s_waitcnt lgkmcnt(2)
	v_cvt_f32_f16_e32 v81, v249
	v_cvt_f32_f16_sdwa v82, v248 dst_sel:DWORD dst_unused:UNUSED_PAD src0_sel:WORD_1
	v_cvt_f32_f16_sdwa v83, v249 dst_sel:DWORD dst_unused:UNUSED_PAD src0_sel:WORD_1
	v_pk_mul_f32 v[90:91], v[92:93], v[82:83]
	s_nop 0
	v_pk_fma_f32 v[90:91], v[76:77], v[80:81], v[90:91] neg_lo:[0,0,1] neg_hi:[0,0,1]
	v_pk_mul_f32 v[76:77], v[76:77], v[82:83]
	v_cvt_pk_bf16_f32 v134, v90, v91
	v_pk_fma_f32 v[76:77], v[92:93], v[80:81], v[76:77]
	v_cvt_pk_bf16_f32 v130, v76, v77
	ds_read_b64_tr_b16 v[104:105], v185 offset:3136
	ds_read_b64_tr_b16 v[106:107], v185 offset:3904
	ds_read_b64_tr_b16 v[108:109], v185 offset:9280
	ds_read_b64_tr_b16 v[110:111], v185 offset:10048
	ds_read2_b64 v[112:115], v172 offset0:4 offset1:5
	ds_read2_b64 v[116:119], v173 offset1:1
	ds_read2_b64 v[120:123], v203 offset1:1
	s_waitcnt lgkmcnt(8)
	v_cvt_f32_f16_e32 v80, v236
	s_waitcnt lgkmcnt(7)
	v_cvt_f32_f16_e32 v81, v238
	v_cvt_f32_f16_sdwa v82, v236 dst_sel:DWORD dst_unused:UNUSED_PAD src0_sel:WORD_1
	v_cvt_f32_f16_sdwa v83, v238 dst_sel:DWORD dst_unused:UNUSED_PAD src0_sel:WORD_1
	s_waitcnt lgkmcnt(6)
	v_add_u32_e32 v244, v206, v205
	ds_read_b32 v245, v244
	v_add_u32_e32 v252, v244, v204
	ds_read_b32 v243, v252
	v_add_u32_e32 v253, v252, v204
	v_add_u32_e32 v235, v253, v204
	ds_read_b32 v237, v253
	ds_read_b32 v240, v235
	v_add_u32_e32 v241, v235, v205
	v_add_u32_e32 v246, v241, v204
	ds_read_b32 v247, v241
	ds_read_b32 v250, v246
	v_add_u32_e32 v251, v246, v204
	v_add_u32_e32 v233, v251, v204
	ds_read_b32 v234, v251
	ds_read_b32 v242, v233
	v_add_u32_e32 v203, 0x2000, v181
	v_pk_mul_f32 v[92:93], v[94:95], v[82:83]
	s_nop 0
	v_pk_fma_f32 v[92:93], v[78:79], v[80:81], v[92:93] neg_lo:[0,0,1] neg_hi:[0,0,1]
	v_pk_mul_f32 v[78:79], v[78:79], v[82:83]
	v_cvt_pk_bf16_f32 v135, v92, v93
	v_pk_fma_f32 v[78:79], v[94:95], v[80:81], v[78:79]
	v_mfma_f32_32x32x16_bf16 v[80:95], v[96:99], v[144:147], 0
	v_cvt_pk_bf16_f32 v131, v78, v79
	v_mfma_f32_32x32x16_bf16 v[64:79], v[96:99], v[124:127], 0
	v_mfma_f32_32x32x16_bf16 v[80:95], v[100:103], v[124:127], v[80:95]
	v_mfma_f32_32x32x16_bf16 v[64:79], v[100:103], v[148:151], v[64:79]
	s_waitcnt lgkmcnt(7)
	s_waitcnt lgkmcnt(6)
	v_add_u32_e32 v239, v233, v205
	v_add_u32_e32 v248, v239, v204
	ds_read_b32 v249, v239
	ds_read_b32 v236, v248
	v_add_u32_e32 v238, v248, v204
	v_add_u32_e32 v244, v238, v204
	ds_read_b32 v252, v238
	ds_read_b32 v253, v244
	v_add_u32_e32 v235, v244, v205
	v_add_u32_e32 v241, v235, v204
	ds_read_b32 v246, v235
	ds_read_b32 v251, v241
	v_add_u32_e32 v233, v241, v204
	ds_read_b32 v239, v233
	v_add_u32_e32 v248, v233, v204
	ds_read_b32 v238, v248
	v_cvt_f32_f16_e32 v96, v245
	v_cvt_f32_f16_sdwa v98, v245 dst_sel:DWORD dst_unused:UNUSED_PAD src0_sel:WORD_1
	s_waitcnt lgkmcnt(14)
	v_cvt_f32_f16_e32 v97, v243
	v_mfma_f32_32x32x16_bf16 v[80:95], v[104:107], v[116:119], v[80:95]
	v_cvt_f32_f16_sdwa v99, v243 dst_sel:DWORD dst_unused:UNUSED_PAD src0_sel:WORD_1
	v_mfma_f32_32x32x16_bf16 v[64:79], v[104:107], v[112:115], v[64:79]
	v_mfma_f32_32x32x16_bf16 v[80:95], v[108:111], v[112:115], v[80:95]
	v_mfma_f32_32x32x16_bf16 v[64:79], v[108:111], v[120:123], v[64:79]
	s_nop 10
	v_mul_f32_e64 v100, v80, v98
	v_mul_f32_e64 v101, v81, v99
	v_or_b32_e32 v120, v152, v179
	v_or_b32_e32 v152, v152, v178
	v_mov_b32_e32 v121, v153
	v_pk_fma_f32 v[100:101], v[64:65], v[96:97], v[100:101] neg_lo:[0,0,1] neg_hi:[0,0,1]
	v_pk_mul_f32 v[64:65], v[64:65], v[98:99]
	v_cvt_pk_bf16_f32 v116, v100, v101
	v_pk_fma_f32 v[64:65], v[80:81], v[96:97], v[64:65]
	v_cvt_pk_bf16_f32 v104, v64, v65
	v_lshl_add_u64 v[64:65], v[152:153], 2, s[20:21]
	s_waitcnt lgkmcnt(13)
	v_cvt_f32_f16_e32 v80, v237
	s_waitcnt lgkmcnt(12)
	v_cvt_f32_f16_e32 v81, v240
	v_cvt_f32_f16_sdwa v96, v237 dst_sel:DWORD dst_unused:UNUSED_PAD src0_sel:WORD_1
	v_cvt_f32_f16_sdwa v97, v240 dst_sel:DWORD dst_unused:UNUSED_PAD src0_sel:WORD_1
	v_pk_mul_f32 v[98:99], v[82:83], v[96:97]
	s_nop 0
	v_pk_fma_f32 v[98:99], v[66:67], v[80:81], v[98:99] neg_lo:[0,0,1] neg_hi:[0,0,1]
	v_pk_mul_f32 v[66:67], v[66:67], v[96:97]
	v_cvt_pk_bf16_f32 v117, v98, v99
	v_pk_fma_f32 v[66:67], v[82:83], v[80:81], v[66:67]
	v_cvt_pk_bf16_f32 v105, v66, v67
	s_waitcnt lgkmcnt(11)
	v_cvt_f32_f16_e32 v80, v247
	s_waitcnt lgkmcnt(10)
	v_cvt_f32_f16_e32 v81, v250
	v_cvt_f32_f16_sdwa v82, v247 dst_sel:DWORD dst_unused:UNUSED_PAD src0_sel:WORD_1
	v_cvt_f32_f16_sdwa v83, v250 dst_sel:DWORD dst_unused:UNUSED_PAD src0_sel:WORD_1
	v_pk_mul_f32 v[96:97], v[84:85], v[82:83]
	s_nop 0
	v_pk_fma_f32 v[96:97], v[68:69], v[80:81], v[96:97] neg_lo:[0,0,1] neg_hi:[0,0,1]
	v_pk_mul_f32 v[68:69], v[68:69], v[82:83]
	v_cvt_pk_bf16_f32 v118, v96, v97
	v_pk_fma_f32 v[68:69], v[84:85], v[80:81], v[68:69]
	v_cvt_pk_bf16_f32 v106, v68, v69
	s_waitcnt lgkmcnt(9)
	v_cvt_f32_f16_e32 v80, v234
	s_waitcnt lgkmcnt(8)
	v_cvt_f32_f16_e32 v81, v242
	v_cvt_f32_f16_sdwa v82, v234 dst_sel:DWORD dst_unused:UNUSED_PAD src0_sel:WORD_1
	v_cvt_f32_f16_sdwa v83, v242 dst_sel:DWORD dst_unused:UNUSED_PAD src0_sel:WORD_1
	v_pk_mul_f32 v[84:85], v[86:87], v[82:83]
	s_nop 0
	v_pk_fma_f32 v[84:85], v[70:71], v[80:81], v[84:85] neg_lo:[0,0,1] neg_hi:[0,0,1]
	v_pk_mul_f32 v[70:71], v[70:71], v[82:83]
	v_cvt_pk_bf16_f32 v119, v84, v85
	v_pk_fma_f32 v[70:71], v[86:87], v[80:81], v[70:71]
	v_cvt_pk_bf16_f32 v107, v70, v71
	s_waitcnt lgkmcnt(7)
	v_cvt_f32_f16_e32 v80, v249
	s_waitcnt lgkmcnt(6)
	v_cvt_f32_f16_e32 v81, v236
	v_cvt_f32_f16_sdwa v82, v249 dst_sel:DWORD dst_unused:UNUSED_PAD src0_sel:WORD_1
	v_cvt_f32_f16_sdwa v83, v236 dst_sel:DWORD dst_unused:UNUSED_PAD src0_sel:WORD_1
	v_pk_mul_f32 v[86:87], v[88:89], v[82:83]
	s_nop 0
	v_pk_fma_f32 v[86:87], v[72:73], v[80:81], v[86:87] neg_lo:[0,0,1] neg_hi:[0,0,1]
	v_pk_mul_f32 v[72:73], v[72:73], v[82:83]
	v_cvt_pk_bf16_f32 v100, v86, v87
	v_pk_fma_f32 v[72:73], v[88:89], v[80:81], v[72:73]
	v_cvt_pk_bf16_f32 v108, v72, v73
	s_waitcnt lgkmcnt(5)
	v_cvt_f32_f16_e32 v80, v252
	s_waitcnt lgkmcnt(4)
	v_cvt_f32_f16_e32 v81, v253
	v_cvt_f32_f16_sdwa v82, v252 dst_sel:DWORD dst_unused:UNUSED_PAD src0_sel:WORD_1
	v_cvt_f32_f16_sdwa v83, v253 dst_sel:DWORD dst_unused:UNUSED_PAD src0_sel:WORD_1
	v_pk_mul_f32 v[88:89], v[90:91], v[82:83]
	s_nop 0
	v_pk_fma_f32 v[88:89], v[74:75], v[80:81], v[88:89] neg_lo:[0,0,1] neg_hi:[0,0,1]
	v_pk_mul_f32 v[74:75], v[74:75], v[82:83]
	v_cvt_pk_bf16_f32 v101, v88, v89
	v_pk_fma_f32 v[74:75], v[90:91], v[80:81], v[74:75]
	v_cvt_pk_bf16_f32 v109, v74, v75
	v_add_u32_e32 v205, 0x2000, v183
	s_waitcnt lgkmcnt(3)
	v_cvt_f32_f16_e32 v80, v246
	s_waitcnt lgkmcnt(2)
	v_cvt_f32_f16_e32 v81, v251
	v_cvt_f32_f16_sdwa v82, v246 dst_sel:DWORD dst_unused:UNUSED_PAD src0_sel:WORD_1
	v_cvt_f32_f16_sdwa v83, v251 dst_sel:DWORD dst_unused:UNUSED_PAD src0_sel:WORD_1
	v_pk_mul_f32 v[90:91], v[92:93], v[82:83]
	s_nop 0
	v_pk_fma_f32 v[90:91], v[76:77], v[80:81], v[90:91] neg_lo:[0,0,1] neg_hi:[0,0,1]
	v_pk_mul_f32 v[76:77], v[76:77], v[82:83]
	s_nop 0
	v_pk_fma_f32 v[76:77], v[92:93], v[80:81], v[76:77]
	global_load_dword v152, v[64:65], off
	global_load_dword v172, v[64:65], off offset:256
	global_load_dword v150, v[64:65], off offset:512
	global_load_dword v151, v[64:65], off offset:768
	global_load_dword v148, v[64:65], off offset:2048
	global_load_dword v149, v[64:65], off offset:2304
	global_load_dword v146, v[64:65], off offset:2560
	global_load_dword v147, v[64:65], off offset:2816
	v_add_co_u32_e32 v64, vcc, s1, v64
	s_waitcnt lgkmcnt(1)
	v_cvt_f32_f16_e32 v80, v239
	s_waitcnt lgkmcnt(0)
	v_cvt_f32_f16_e32 v81, v238
	v_cvt_f32_f16_sdwa v82, v239 dst_sel:DWORD dst_unused:UNUSED_PAD src0_sel:WORD_1
	v_cvt_f32_f16_sdwa v83, v238 dst_sel:DWORD dst_unused:UNUSED_PAD src0_sel:WORD_1
	v_addc_co_u32_e32 v65, vcc, 0, v65, vcc
	global_load_dword v144, v[64:65], off
	global_load_dword v145, v[64:65], off offset:256
	global_load_dword v126, v[64:65], off offset:512
	global_load_dword v127, v[64:65], off offset:768
	global_load_dword v124, v[64:65], off offset:2048
	global_load_dword v125, v[64:65], off offset:2304
	global_load_dword v122, v[64:65], off offset:2560
	global_load_dword v123, v[64:65], off offset:2816
	ds_read2_b64 v[112:115], v181 offset1:2
	ds_read2_b64 v[96:99], v181 offset0:4 offset1:6
	v_pk_mul_f32 v[92:93], v[94:95], v[82:83]
	v_cvt_pk_bf16_f32 v110, v76, v77
	v_pk_fma_f32 v[92:93], v[78:79], v[80:81], v[92:93] neg_lo:[0,0,1] neg_hi:[0,0,1]
	v_pk_mul_f32 v[78:79], v[78:79], v[82:83]
	v_add_u32_e32 v204, 0x4000, v181
	v_pk_fma_f32 v[78:79], v[94:95], v[80:81], v[78:79]
	ds_read2_b64 v[80:83], v203 offset0:64 offset1:66
	v_cvt_pk_bf16_f32 v111, v78, v79
	s_waitcnt lgkmcnt(2)
	v_mfma_f32_32x32x16_bf16 v[64:79], v[112:115], v[136:139], 0
	ds_read2_b64 v[84:87], v204 offset0:128 offset1:130
	ds_read2_b64 v[206:209], v203 offset0:68 offset1:70
	ds_read2_b64 v[210:213], v204 offset0:132 offset1:134
	v_cvt_pk_bf16_f32 v102, v90, v91
	v_cvt_pk_bf16_f32 v103, v92, v93
	s_waitcnt lgkmcnt(2)
	v_mfma_f32_32x32x16_bf16 v[64:79], v[84:87], v[140:143], v[64:79]
	v_mfma_f32_32x32x16_bf16 v[80:95], v[80:83], v[136:139], 0
	v_mfma_f32_32x32x16_bf16 v[80:95], v[112:115], v[140:143], v[80:95]
	ds_read2_b64 v[112:115], v181 offset0:8 offset1:10
	ds_read2_b64 v[214:217], v203 offset0:72 offset1:74
	ds_read2_b64 v[218:221], v204 offset0:136 offset1:138
	s_waitcnt lgkmcnt(4)
	v_mfma_f32_32x32x16_bf16 v[80:95], v[206:209], v[132:135], v[80:95]
	v_mfma_f32_32x32x16_bf16 v[64:79], v[96:99], v[132:135], v[64:79]
	v_mfma_f32_32x32x16_bf16 v[80:95], v[96:99], v[128:131], v[80:95]
	s_waitcnt lgkmcnt(3)
	v_mfma_f32_32x32x16_bf16 v[64:79], v[210:213], v[128:131], v[64:79]
	ds_read2_b64 v[96:99], v181 offset0:12 offset1:14
	ds_read2_b64 v[206:209], v203 offset0:76 offset1:78
	ds_read2_b64 v[210:213], v204 offset0:140 offset1:142
	s_waitcnt lgkmcnt(4)
	v_mfma_f32_32x32x16_bf16 v[80:95], v[214:217], v[116:119], v[80:95]
	v_mfma_f32_32x32x16_bf16 v[64:79], v[112:115], v[116:119], v[64:79]
	v_mfma_f32_32x32x16_bf16 v[80:95], v[112:115], v[104:107], v[80:95]
	s_waitcnt lgkmcnt(3)
	v_mfma_f32_32x32x16_bf16 v[64:79], v[218:221], v[104:107], v[64:79]
	s_waitcnt lgkmcnt(1)
	v_mfma_f32_32x32x16_bf16 v[80:95], v[206:209], v[100:103], v[80:95]
	v_add_u32_e32 v206, 0x4000, v183
	v_mfma_f32_32x32x16_bf16 v[64:79], v[96:99], v[100:103], v[64:79]
	v_mfma_f32_32x32x16_bf16 v[80:95], v[96:99], v[108:111], v[80:95]
	v_lshl_add_u64 v[96:97], v[120:121], 2, s[20:21]
	global_load_dword v220, v[96:97], off
	global_load_dword v221, v[96:97], off offset:256
	global_load_dword v218, v[96:97], off offset:512
	global_load_dword v219, v[96:97], off offset:768
	global_load_dword v216, v[96:97], off offset:2048
	global_load_dword v217, v[96:97], off offset:2304
	global_load_dword v214, v[96:97], off offset:2560
	global_load_dword v215, v[96:97], off offset:2816
	v_add_co_u32_e32 v96, vcc, s1, v96
	s_waitcnt vmcnt(22)
	v_and_b32_e32 v99, 0xffff0000, v172
	v_addc_co_u32_e32 v97, vcc, 0, v97, vcc
	s_waitcnt lgkmcnt(0)
	v_mfma_f32_32x32x16_bf16 v[64:79], v[210:213], v[108:111], v[64:79]
	v_and_b32_e32 v98, 0xffff0000, v152
	global_load_dword v212, v[96:97], off
	global_load_dword v213, v[96:97], off offset:256
	global_load_dword v210, v[96:97], off offset:512
	global_load_dword v211, v[96:97], off offset:768
	global_load_dword v208, v[96:97], off offset:2048
	global_load_dword v209, v[96:97], off offset:2304
	global_load_dword v173, v[96:97], off offset:2560
	global_load_dword v207, v[96:97], off offset:2816
	v_lshlrev_b32_e32 v97, 16, v172
	v_lshlrev_b32_e32 v96, 16, v152
	v_pk_mul_f32 v[112:113], v[80:81], v[98:99]
	v_pk_mul_f32 v[80:81], v[80:81], v[96:97]
	v_or_b32_e32 v152, s2, v177
	v_pk_fma_f32 v[112:113], v[64:65], v[96:97], v[112:113] neg_lo:[0,0,1] neg_hi:[0,0,1]
	s_waitcnt vmcnt(28)
	v_and_b32_e32 v97, 0xffff0000, v151
	v_and_b32_e32 v96, 0xffff0000, v150
	v_pk_fma_f32 v[64:65], v[64:65], v[98:99], v[80:81]
	v_lshlrev_b32_e32 v81, 16, v151
	v_lshlrev_b32_e32 v80, 16, v150
	v_pk_mul_f32 v[98:99], v[82:83], v[96:97]
	v_cvt_pk_bf16_f32 v120, v112, v113
	v_pk_fma_f32 v[98:99], v[66:67], v[80:81], v[98:99] neg_lo:[0,0,1] neg_hi:[0,0,1]
	v_pk_mul_f32 v[80:81], v[82:83], v[80:81]
	s_waitcnt vmcnt(26)
	v_and_b32_e32 v83, 0xffff0000, v149
	v_and_b32_e32 v82, 0xffff0000, v148
	v_pk_fma_f32 v[66:67], v[66:67], v[96:97], v[80:81]
	v_lshlrev_b32_e32 v81, 16, v149
	v_lshlrev_b32_e32 v80, 16, v148
	v_pk_mul_f32 v[96:97], v[84:85], v[82:83]
	v_cvt_pk_bf16_f32 v121, v98, v99
	v_pk_fma_f32 v[96:97], v[68:69], v[80:81], v[96:97] neg_lo:[0,0,1] neg_hi:[0,0,1]
	v_pk_mul_f32 v[80:81], v[84:85], v[80:81]
	v_mul_u32_u24_e32 v172, v152, v175
	v_pk_fma_f32 v[68:69], v[68:69], v[82:83], v[80:81]
	s_waitcnt vmcnt(24)
	v_and_b32_e32 v83, 0xffff0000, v147
	v_and_b32_e32 v82, 0xffff0000, v146
	v_lshlrev_b32_e32 v81, 16, v147
	v_lshlrev_b32_e32 v80, 16, v146
	v_pk_mul_f32 v[84:85], v[86:87], v[82:83]
	v_lshl_add_u32 v172, v172, 2, s24
	v_pk_fma_f32 v[84:85], v[70:71], v[80:81], v[84:85] neg_lo:[0,0,1] neg_hi:[0,0,1]
	v_pk_mul_f32 v[80:81], v[86:87], v[80:81]
	s_mov_b32 s2, 32
	v_pk_fma_f32 v[70:71], v[70:71], v[82:83], v[80:81]
	s_waitcnt vmcnt(22)
	v_and_b32_e32 v83, 0xffff0000, v145
	v_and_b32_e32 v82, 0xffff0000, v144
	v_lshlrev_b32_e32 v81, 16, v145
	v_lshlrev_b32_e32 v80, 16, v144
	v_pk_mul_f32 v[86:87], v[88:89], v[82:83]
	ds_read2_b64 v[148:151], v183 offset1:2
	ds_read2_b64 v[144:147], v183 offset0:4 offset1:6
	v_pk_fma_f32 v[86:87], v[72:73], v[80:81], v[86:87] neg_lo:[0,0,1] neg_hi:[0,0,1]
	v_pk_mul_f32 v[80:81], v[88:89], v[80:81]
	s_and_b64 vcc, exec, s[22:23]
	v_pk_fma_f32 v[72:73], v[72:73], v[82:83], v[80:81]
	s_waitcnt vmcnt(20)
	v_and_b32_e32 v83, 0xffff0000, v127
	v_and_b32_e32 v82, 0xffff0000, v126
	v_lshlrev_b32_e32 v81, 16, v127
	v_lshlrev_b32_e32 v80, 16, v126
	v_pk_mul_f32 v[88:89], v[90:91], v[82:83]
	v_cvt_pk_bf16_f32 v126, v68, v69
	v_pk_fma_f32 v[88:89], v[74:75], v[80:81], v[88:89] neg_lo:[0,0,1] neg_hi:[0,0,1]
	v_pk_mul_f32 v[80:81], v[90:91], v[80:81]
	v_cvt_pk_bf16_f32 v127, v70, v71
	v_pk_fma_f32 v[74:75], v[74:75], v[82:83], v[80:81]
	s_waitcnt vmcnt(18)
	v_and_b32_e32 v83, 0xffff0000, v125
	v_and_b32_e32 v82, 0xffff0000, v124
	v_lshlrev_b32_e32 v81, 16, v125
	v_lshlrev_b32_e32 v80, 16, v124
	v_pk_mul_f32 v[90:91], v[92:93], v[82:83]
	v_cvt_pk_bf16_f32 v124, v64, v65
	v_pk_fma_f32 v[90:91], v[76:77], v[80:81], v[90:91] neg_lo:[0,0,1] neg_hi:[0,0,1]
	v_pk_mul_f32 v[80:81], v[92:93], v[80:81]
	v_cvt_pk_bf16_f32 v125, v66, v67
	v_pk_fma_f32 v[76:77], v[76:77], v[82:83], v[80:81]
	s_waitcnt vmcnt(16)
	v_and_b32_e32 v83, 0xffff0000, v123
	v_and_b32_e32 v82, 0xffff0000, v122
	v_lshlrev_b32_e32 v81, 16, v123
	v_lshlrev_b32_e32 v80, 16, v122
	v_pk_mul_f32 v[92:93], v[94:95], v[82:83]
	v_cvt_pk_bf16_f32 v112, v72, v73
	v_pk_fma_f32 v[92:93], v[78:79], v[80:81], v[92:93] neg_lo:[0,0,1] neg_hi:[0,0,1]
	v_pk_mul_f32 v[80:81], v[94:95], v[80:81]
	v_cvt_pk_bf16_f32 v113, v74, v75
	v_pk_fma_f32 v[78:79], v[78:79], v[82:83], v[80:81]
	ds_read2_b64 v[80:83], v205 offset0:64 offset1:66
	v_cvt_pk_bf16_f32 v114, v76, v77
	v_cvt_pk_bf16_f32 v115, v78, v79
	s_waitcnt lgkmcnt(2)
	v_mfma_f32_32x32x16_bf16 v[64:79], v[148:151], v[136:139], 0
	v_cvt_pk_bf16_f32 v122, v96, v97
	v_cvt_pk_bf16_f32 v123, v84, v85
	v_cvt_pk_bf16_f32 v96, v86, v87
	ds_read2_b64 v[84:87], v206 offset0:128 offset1:130
	ds_read2_b64 v[222:225], v205 offset0:68 offset1:70
	ds_read2_b64 v[226:229], v206 offset0:132 offset1:134
	v_cvt_pk_bf16_f32 v97, v88, v89
	v_cvt_pk_bf16_f32 v98, v90, v91
	v_cvt_pk_bf16_f32 v99, v92, v93
	s_waitcnt lgkmcnt(2)
	v_mfma_f32_32x32x16_bf16 v[64:79], v[84:87], v[140:143], v[64:79]
	s_mov_b64 s[22:23], 0
	v_mfma_f32_32x32x16_bf16 v[80:95], v[80:83], v[136:139], 0
	v_mfma_f32_32x32x16_bf16 v[80:95], v[148:151], v[140:143], v[80:95]
	ds_read2_b64 v[136:139], v183 offset0:8 offset1:10
	ds_read2_b64 v[140:143], v205 offset0:72 offset1:74
	ds_read2_b64 v[148:151], v206 offset0:136 offset1:138
	s_waitcnt lgkmcnt(4)
	v_mfma_f32_32x32x16_bf16 v[80:95], v[222:225], v[132:135], v[80:95]
	v_mfma_f32_32x32x16_bf16 v[64:79], v[144:147], v[132:135], v[64:79]
	v_mfma_f32_32x32x16_bf16 v[80:95], v[144:147], v[128:131], v[80:95]
	s_waitcnt lgkmcnt(3)
	v_mfma_f32_32x32x16_bf16 v[64:79], v[226:229], v[128:131], v[64:79]
	ds_read2_b64 v[128:131], v183 offset0:12 offset1:14
	ds_read2_b64 v[132:135], v205 offset0:76 offset1:78
	ds_read2_b64 v[144:147], v206 offset0:140 offset1:142
	s_waitcnt lgkmcnt(4)
	v_mfma_f32_32x32x16_bf16 v[80:95], v[140:143], v[116:119], v[80:95]
	v_mfma_f32_32x32x16_bf16 v[64:79], v[136:139], v[116:119], v[64:79]
	v_mfma_f32_32x32x16_bf16 v[80:95], v[136:139], v[104:107], v[80:95]
	s_waitcnt lgkmcnt(3)
	v_mfma_f32_32x32x16_bf16 v[64:79], v[148:151], v[104:107], v[64:79]
	s_waitcnt lgkmcnt(1)
	v_mfma_f32_32x32x16_bf16 v[80:95], v[132:135], v[100:103], v[80:95]
	v_mfma_f32_32x32x16_bf16 v[64:79], v[128:131], v[100:103], v[64:79]
	s_waitcnt vmcnt(14)
	v_and_b32_e32 v103, 0xffff0000, v221
	v_and_b32_e32 v102, 0xffff0000, v220
	v_lshlrev_b32_e32 v101, 16, v221
	v_lshlrev_b32_e32 v100, 16, v220
	v_mfma_f32_32x32x16_bf16 v[80:95], v[128:131], v[108:111], v[80:95]
	s_waitcnt lgkmcnt(0)
	v_mfma_f32_32x32x16_bf16 v[64:79], v[144:147], v[108:111], v[64:79]
	s_nop 9
	v_mul_f32_e64 v104, v80, v102
	v_mul_f32_e64 v105, v81, v103
	v_mul_f32_e64 v80, v80, v100
	v_mul_f32_e64 v81, v81, v101
	v_pk_fma_f32 v[104:105], v[64:65], v[100:101], v[104:105] neg_lo:[0,0,1] neg_hi:[0,0,1]
	s_waitcnt vmcnt(12)
	v_and_b32_e32 v101, 0xffff0000, v219
	v_and_b32_e32 v100, 0xffff0000, v218
	v_pk_fma_f32 v[64:65], v[64:65], v[102:103], v[80:81]
	v_lshlrev_b32_e32 v81, 16, v219
	v_lshlrev_b32_e32 v80, 16, v218
	v_pk_mul_f32 v[102:103], v[82:83], v[100:101]
	v_cvt_pk_bf16_f32 v108, v64, v65
	v_pk_fma_f32 v[102:103], v[66:67], v[80:81], v[102:103] neg_lo:[0,0,1] neg_hi:[0,0,1]
	v_pk_mul_f32 v[80:81], v[82:83], v[80:81]
	s_waitcnt vmcnt(10)
	v_and_b32_e32 v83, 0xffff0000, v217
	v_and_b32_e32 v82, 0xffff0000, v216
	v_pk_fma_f32 v[66:67], v[66:67], v[100:101], v[80:81]
	v_lshlrev_b32_e32 v81, 16, v217
	v_lshlrev_b32_e32 v80, 16, v216
	v_pk_mul_f32 v[100:101], v[84:85], v[82:83]
	v_cvt_pk_bf16_f32 v109, v66, v67
	v_pk_fma_f32 v[106:107], v[68:69], v[80:81], v[100:101] neg_lo:[0,0,1] neg_hi:[0,0,1]
	v_pk_mul_f32 v[80:81], v[84:85], v[80:81]
	v_cvt_pk_bf16_f32 v100, v104, v105
	v_pk_fma_f32 v[68:69], v[68:69], v[82:83], v[80:81]
	s_waitcnt vmcnt(8)
	v_and_b32_e32 v83, 0xffff0000, v215
	v_and_b32_e32 v82, 0xffff0000, v214
	v_lshlrev_b32_e32 v81, 16, v215
	v_lshlrev_b32_e32 v80, 16, v214
	v_pk_mul_f32 v[84:85], v[86:87], v[82:83]
	v_cvt_pk_bf16_f32 v101, v102, v103
	v_pk_fma_f32 v[84:85], v[70:71], v[80:81], v[84:85] neg_lo:[0,0,1] neg_hi:[0,0,1]
	v_pk_mul_f32 v[80:81], v[86:87], v[80:81]
	v_cvt_pk_bf16_f32 v103, v84, v85
	v_pk_fma_f32 v[70:71], v[70:71], v[82:83], v[80:81]
	s_waitcnt vmcnt(6)
	v_and_b32_e32 v83, 0xffff0000, v213
	v_and_b32_e32 v82, 0xffff0000, v212
	v_lshlrev_b32_e32 v81, 16, v213
	v_lshlrev_b32_e32 v80, 16, v212
	v_pk_mul_f32 v[86:87], v[88:89], v[82:83]
	v_cvt_pk_bf16_f32 v110, v68, v69
	v_pk_fma_f32 v[86:87], v[72:73], v[80:81], v[86:87] neg_lo:[0,0,1] neg_hi:[0,0,1]
	v_pk_mul_f32 v[80:81], v[88:89], v[80:81]
	v_cvt_pk_bf16_f32 v111, v70, v71
	v_pk_fma_f32 v[72:73], v[72:73], v[82:83], v[80:81]
	s_waitcnt vmcnt(4)
	v_and_b32_e32 v83, 0xffff0000, v211
	v_and_b32_e32 v82, 0xffff0000, v210
	v_lshlrev_b32_e32 v81, 16, v211
	v_lshlrev_b32_e32 v80, 16, v210
	v_pk_mul_f32 v[88:89], v[90:91], v[82:83]
	v_cvt_pk_bf16_f32 v104, v86, v87
	v_pk_fma_f32 v[88:89], v[74:75], v[80:81], v[88:89] neg_lo:[0,0,1] neg_hi:[0,0,1]
	v_pk_mul_f32 v[80:81], v[90:91], v[80:81]
	v_cvt_pk_bf16_f32 v116, v72, v73
	v_pk_fma_f32 v[74:75], v[74:75], v[82:83], v[80:81]
	s_waitcnt vmcnt(2)
	v_and_b32_e32 v83, 0xffff0000, v209
	v_and_b32_e32 v82, 0xffff0000, v208
	v_lshlrev_b32_e32 v81, 16, v209
	v_lshlrev_b32_e32 v80, 16, v208
	v_pk_mul_f32 v[90:91], v[92:93], v[82:83]
	v_cvt_pk_bf16_f32 v117, v74, v75
	v_pk_fma_f32 v[90:91], v[76:77], v[80:81], v[90:91] neg_lo:[0,0,1] neg_hi:[0,0,1]
	v_pk_mul_f32 v[80:81], v[92:93], v[80:81]
	v_cvt_pk_bf16_f32 v102, v106, v107
	v_pk_fma_f32 v[76:77], v[76:77], v[82:83], v[80:81]
	s_waitcnt vmcnt(0)
	v_and_b32_e32 v83, 0xffff0000, v207
	v_and_b32_e32 v82, 0xffff0000, v173
	v_lshlrev_b32_e32 v81, 16, v207
	v_lshlrev_b32_e32 v80, 16, v173
	v_pk_mul_f32 v[92:93], v[94:95], v[82:83]
	v_cvt_pk_bf16_f32 v118, v76, v77
	v_pk_fma_f32 v[92:93], v[78:79], v[80:81], v[92:93] neg_lo:[0,0,1] neg_hi:[0,0,1]
	v_pk_mul_f32 v[80:81], v[94:95], v[80:81]
	v_cvt_pk_bf16_f32 v105, v88, v89
	v_pk_fma_f32 v[78:79], v[78:79], v[82:83], v[80:81]
	ds_read2_b64 v[80:83], v181 offset1:2
	ds_read2_b64 v[128:131], v181 offset0:4 offset1:6
	ds_read2_b64 v[84:87], v203 offset0:64 offset1:66
	ds_read2_b64 v[132:135], v204 offset0:128 offset1:130
	ds_read2_b64 v[136:139], v203 offset0:68 offset1:70
	ds_read2_b64 v[140:143], v204 offset0:132 offset1:134
	v_cvt_pk_bf16_f32 v119, v78, v79
	s_waitcnt lgkmcnt(5)
	v_mfma_f32_32x32x16_bf16 v[64:79], v[120:123], v[80:83], 0
	v_cvt_pk_bf16_f32 v106, v90, v91
	v_cvt_pk_bf16_f32 v107, v92, v93
	v_lshl_add_u32 v208, v152, 1, v180
	v_lshlrev_b32_e32 v207, 2, v175
	v_add_u32_e32 v209, 0x2000, v208
	v_add_u32_e32 v210, 0x4000, v208
	s_waitcnt lgkmcnt(3)
	v_mfma_f32_32x32x16_bf16 v[64:79], v[124:127], v[84:87], v[64:79]
	v_add_u32_e32 v211, v172, v207
	v_mfma_f32_32x32x16_bf16 v[80:95], v[124:127], v[80:83], 0
	s_waitcnt lgkmcnt(2)
	v_mfma_f32_32x32x16_bf16 v[80:95], v[120:123], v[132:135], v[80:95]
	ds_read2_b64 v[132:135], v181 offset0:8 offset1:10
	ds_read2_b64 v[144:147], v203 offset0:72 offset1:74
	ds_read2_b64 v[148:151], v204 offset0:136 offset1:138
	v_mfma_f32_32x32x16_bf16 v[64:79], v[96:99], v[128:131], v[64:79]
	v_mfma_f32_32x32x16_bf16 v[80:95], v[112:115], v[128:131], v[80:95]
	s_waitcnt lgkmcnt(4)
	v_mfma_f32_32x32x16_bf16 v[64:79], v[112:115], v[136:139], v[64:79]
	s_waitcnt lgkmcnt(3)
	v_mfma_f32_32x32x16_bf16 v[80:95], v[96:99], v[140:143], v[80:95]
	ds_read2_b64 v[128:131], v181 offset0:12 offset1:14
	ds_read2_b64 v[136:139], v203 offset0:76 offset1:78
	ds_read2_b64 v[140:143], v204 offset0:140 offset1:142
	s_waitcnt lgkmcnt(5)
	v_mfma_f32_32x32x16_bf16 v[64:79], v[100:103], v[132:135], v[64:79]
	v_mfma_f32_32x32x16_bf16 v[80:95], v[108:111], v[132:135], v[80:95]
	s_waitcnt lgkmcnt(4)
	v_mfma_f32_32x32x16_bf16 v[64:79], v[108:111], v[144:147], v[64:79]
	s_waitcnt lgkmcnt(3)
	v_mfma_f32_32x32x16_bf16 v[80:95], v[100:103], v[148:151], v[80:95]
	s_waitcnt lgkmcnt(2)
	v_mfma_f32_32x32x16_bf16 v[64:79], v[104:107], v[128:131], v[64:79]
	v_mfma_f32_32x32x16_bf16 v[80:95], v[116:119], v[128:131], v[80:95]
	s_waitcnt lgkmcnt(1)
	v_mfma_f32_32x32x16_bf16 v[64:79], v[116:119], v[136:139], v[64:79]
	s_waitcnt lgkmcnt(0)
	v_mfma_f32_32x32x16_bf16 v[80:95], v[104:107], v[140:143], v[80:95]
	ds_read2_b64 v[140:143], v208 offset1:2
	ds_read2_b64 v[128:131], v208 offset0:4 offset1:6
	ds_read2_b64 v[148:151], v209 offset0:64 offset1:66
	ds_read2_b64 v[144:147], v210 offset0:128 offset1:130
	ds_read2_b64 v[136:139], v209 offset0:68 offset1:70
	ds_read2_b64 v[132:135], v210 offset0:132 offset1:134
	ds_read_b32 v244, v172
	ds_read_b32 v235, v211
	v_add_u32_e32 v241, v211, v207
	v_add_u32_e32 v233, v241, v207
	ds_read_b32 v248, v241
	ds_read_b32 v245, v233
	v_add_u32_e32 v243, v233, v186
	v_add_u32_e32 v237, v243, v207
	ds_read_b32 v240, v243
	ds_read_b32 v247, v237
	v_add_u32_e32 v250, v237, v207
	v_add_u32_e32 v234, v250, v207
	ds_read_b32 v242, v250
	ds_read_b32 v249, v234
	s_waitcnt lgkmcnt(7)
	s_waitcnt lgkmcnt(6)
	v_add_u32_e32 v236, v234, v186
	v_add_u32_e32 v252, v236, v207
	ds_read_b32 v253, v236
	ds_read_b32 v246, v252
	v_add_u32_e32 v251, v252, v207
	v_add_u32_e32 v239, v251, v207
	ds_read_b32 v238, v251
	ds_read_b32 v241, v239
	v_add_u32_e32 v233, v239, v186
	v_add_u32_e32 v243, v233, v207
	ds_read_b32 v237, v233
	ds_read_b32 v250, v243
	v_add_u32_e32 v234, v243, v207
	ds_read_b32 v236, v234
	v_add_u32_e32 v252, v234, v207
	ds_read_b32 v251, v252
	v_cvt_f32_f16_sdwa v214, v244 dst_sel:DWORD dst_unused:UNUSED_PAD src0_sel:WORD_1
	s_waitcnt lgkmcnt(14)
	v_cvt_f32_f16_sdwa v215, v235 dst_sel:DWORD dst_unused:UNUSED_PAD src0_sel:WORD_1
	v_cvt_f32_f16_e32 v213, v235
	v_cvt_f32_f16_e32 v212, v244
	v_pk_mul_f32 v[172:173], v[64:65], v[214:215]
	s_nop 0
	v_pk_fma_f32 v[172:173], v[80:81], v[212:213], v[172:173] neg_lo:[0,0,1] neg_hi:[0,0,1]
	v_pk_mul_f32 v[80:81], v[80:81], v[214:215]
	s_nop 0
	v_pk_fma_f32 v[64:65], v[64:65], v[212:213], v[80:81]
	v_cvt_pk_bf16_f32 v64, v64, v65
	s_waitcnt lgkmcnt(13)
	v_cvt_f32_f16_sdwa v214, v248 dst_sel:DWORD dst_unused:UNUSED_PAD src0_sel:WORD_1
	s_waitcnt lgkmcnt(12)
	v_cvt_f32_f16_sdwa v215, v245 dst_sel:DWORD dst_unused:UNUSED_PAD src0_sel:WORD_1
	v_cvt_f32_f16_e32 v213, v245
	v_cvt_f32_f16_e32 v212, v248
	v_pk_mul_f32 v[80:81], v[66:67], v[214:215]
	s_nop 0
	v_pk_fma_f32 v[80:81], v[82:83], v[212:213], v[80:81] neg_lo:[0,0,1] neg_hi:[0,0,1]
	v_pk_mul_f32 v[82:83], v[82:83], v[214:215]
	s_nop 0
	v_pk_fma_f32 v[66:67], v[66:67], v[212:213], v[82:83]
	v_cvt_pk_bf16_f32 v65, v66, v67
	s_waitcnt lgkmcnt(11)
	v_cvt_f32_f16_sdwa v214, v240 dst_sel:DWORD dst_unused:UNUSED_PAD src0_sel:WORD_1
	s_waitcnt lgkmcnt(10)
	v_cvt_f32_f16_sdwa v215, v247 dst_sel:DWORD dst_unused:UNUSED_PAD src0_sel:WORD_1
	v_cvt_f32_f16_e32 v213, v247
	v_cvt_f32_f16_e32 v212, v240
	v_pk_mul_f32 v[82:83], v[68:69], v[214:215]
	s_nop 0
	v_pk_fma_f32 v[82:83], v[84:85], v[212:213], v[82:83] neg_lo:[0,0,1] neg_hi:[0,0,1]
	v_pk_mul_f32 v[84:85], v[84:85], v[214:215]
	s_nop 0
	v_pk_fma_f32 v[68:69], v[68:69], v[212:213], v[84:85]
	v_cvt_pk_bf16_f32 v66, v68, v69
	v_cvt_pk_bf16_f32 v68, v172, v173
	v_cvt_pk_bf16_f32 v69, v80, v81
	s_waitcnt lgkmcnt(9)
	v_cvt_f32_f16_e32 v84, v242
	s_waitcnt lgkmcnt(8)
	v_cvt_f32_f16_e32 v85, v249
	v_cvt_f32_f16_sdwa v213, v249 dst_sel:DWORD dst_unused:UNUSED_PAD src0_sel:WORD_1
	v_cvt_f32_f16_sdwa v212, v242 dst_sel:DWORD dst_unused:UNUSED_PAD src0_sel:WORD_1
	v_pk_mul_f32 v[214:215], v[70:71], v[212:213]
	s_nop 0
	v_pk_fma_f32 v[214:215], v[86:87], v[84:85], v[214:215] neg_lo:[0,0,1] neg_hi:[0,0,1]
	v_pk_mul_f32 v[86:87], v[86:87], v[212:213]
	s_nop 0
	v_pk_fma_f32 v[70:71], v[70:71], v[84:85], v[86:87]
	v_cvt_pk_bf16_f32 v67, v70, v71
	v_cvt_pk_bf16_f32 v70, v82, v83
	v_cvt_pk_bf16_f32 v71, v214, v215
	s_waitcnt lgkmcnt(7)
	v_cvt_f32_f16_e32 v84, v253
	s_waitcnt lgkmcnt(6)
	v_cvt_f32_f16_e32 v85, v246
	v_cvt_f32_f16_sdwa v87, v246 dst_sel:DWORD dst_unused:UNUSED_PAD src0_sel:WORD_1
	v_cvt_f32_f16_sdwa v86, v253 dst_sel:DWORD dst_unused:UNUSED_PAD src0_sel:WORD_1
	v_mfma_f32_32x32x16_bf16 v[48:63], v[140:143], v[64:67], v[48:63]
	v_mul_f32_e64 v212, v72, v86
	v_mul_f32_e64 v213, v73, v87
	v_mul_f32_e64 v86, v88, v86
	v_mul_f32_e64 v87, v89, v87
	v_fma_f32 v212, v88, v84, -v212
	v_fma_f32 v213, v89, v85, -v213
	v_pk_fma_f32 v[72:73], v[72:73], v[84:85], v[86:87]
	v_mfma_f32_32x32x16_bf16 v[32:47], v[140:143], v[68:71], v[32:47]
	s_waitcnt lgkmcnt(5)
	v_cvt_f32_f16_e32 v84, v238
	s_waitcnt lgkmcnt(4)
	v_cvt_f32_f16_e32 v85, v241
	v_cvt_f32_f16_sdwa v87, v241 dst_sel:DWORD dst_unused:UNUSED_PAD src0_sel:WORD_1
	v_cvt_f32_f16_sdwa v86, v238 dst_sel:DWORD dst_unused:UNUSED_PAD src0_sel:WORD_1
	v_pk_mul_f32 v[88:89], v[74:75], v[86:87]
	v_pk_mul_f32 v[86:87], v[90:91], v[86:87]
	v_pk_fma_f32 v[88:89], v[90:91], v[84:85], v[88:89] neg_lo:[0,0,1] neg_hi:[0,0,1]
	v_pk_fma_f32 v[74:75], v[74:75], v[84:85], v[86:87]
	v_mfma_f32_32x32x16_bf16 v[48:63], v[148:151], v[68:71], v[48:63]
	v_cvt_pk_bf16_f32 v68, v212, v213
	v_cvt_pk_bf16_f32 v69, v88, v89
	s_waitcnt lgkmcnt(3)
	v_cvt_f32_f16_e32 v84, v237
	s_waitcnt lgkmcnt(2)
	v_cvt_f32_f16_e32 v85, v250
	v_cvt_f32_f16_sdwa v87, v250 dst_sel:DWORD dst_unused:UNUSED_PAD src0_sel:WORD_1
	v_cvt_f32_f16_sdwa v86, v237 dst_sel:DWORD dst_unused:UNUSED_PAD src0_sel:WORD_1
	v_pk_mul_f32 v[90:91], v[76:77], v[86:87]
	v_pk_mul_f32 v[86:87], v[92:93], v[86:87]
	v_pk_fma_f32 v[90:91], v[92:93], v[84:85], v[90:91] neg_lo:[0,0,1] neg_hi:[0,0,1]
	v_pk_fma_f32 v[76:77], v[76:77], v[84:85], v[86:87]
	v_mfma_f32_32x32x16_bf16 v[32:47], v[144:147], v[64:67], v[32:47]
	v_cvt_pk_bf16_f32 v64, v72, v73
	s_waitcnt lgkmcnt(1)
	v_cvt_f32_f16_e32 v84, v236
	v_cvt_f32_f16_sdwa v86, v236 dst_sel:DWORD dst_unused:UNUSED_PAD src0_sel:WORD_1
	s_waitcnt lgkmcnt(0)
	v_cvt_f32_f16_e32 v85, v251
	v_cvt_f32_f16_sdwa v87, v251 dst_sel:DWORD dst_unused:UNUSED_PAD src0_sel:WORD_1
	v_cvt_pk_bf16_f32 v65, v74, v75
	v_cvt_pk_bf16_f32 v66, v76, v77
	v_cvt_pk_bf16_f32 v70, v90, v91
	v_pk_mul_f32 v[92:93], v[78:79], v[86:87]
	v_pk_mul_f32 v[86:87], v[94:95], v[86:87]
	v_pk_fma_f32 v[92:93], v[94:95], v[84:85], v[92:93] neg_lo:[0,0,1] neg_hi:[0,0,1]
	v_pk_fma_f32 v[78:79], v[78:79], v[84:85], v[86:87]
	v_cvt_pk_bf16_f32 v71, v92, v93
	v_cvt_pk_bf16_f32 v67, v78, v79
	s_nop 0
	v_mfma_f32_32x32x16_bf16 v[32:47], v[128:131], v[68:71], v[32:47]
	v_mfma_f32_32x32x16_bf16 v[48:63], v[128:131], v[64:67], v[48:63]
	v_mfma_f32_32x32x16_bf16 v[48:63], v[136:139], v[68:71], v[48:63]
	v_mfma_f32_32x32x16_bf16 v[32:47], v[132:135], v[64:67], v[32:47]
	ds_read2_b64 v[80:83], v183 offset1:2
	ds_read2_b64 v[136:139], v183 offset0:4 offset1:6
	ds_read2_b64 v[84:87], v205 offset0:64 offset1:66
	ds_read2_b64 v[132:135], v206 offset0:128 offset1:130
	ds_read2_b64 v[140:143], v205 offset0:68 offset1:70
	ds_read2_b64 v[128:131], v206 offset0:132 offset1:134
	s_waitcnt lgkmcnt(5)
	v_mfma_f32_32x32x16_bf16 v[64:79], v[120:123], v[80:83], 0
	s_waitcnt lgkmcnt(3)
	v_mfma_f32_32x32x16_bf16 v[64:79], v[124:127], v[84:87], v[64:79]
	v_mfma_f32_32x32x16_bf16 v[80:95], v[124:127], v[80:83], 0
	s_waitcnt lgkmcnt(2)
	v_mfma_f32_32x32x16_bf16 v[80:95], v[120:123], v[132:135], v[80:95]
	ds_read2_b64 v[120:123], v183 offset0:8 offset1:10
	ds_read2_b64 v[132:135], v205 offset0:72 offset1:74
	ds_read2_b64 v[124:127], v206 offset0:136 offset1:138
	v_mfma_f32_32x32x16_bf16 v[64:79], v[96:99], v[136:139], v[64:79]
	v_mfma_f32_32x32x16_bf16 v[80:95], v[112:115], v[136:139], v[80:95]
	s_waitcnt lgkmcnt(4)
	v_mfma_f32_32x32x16_bf16 v[64:79], v[112:115], v[140:143], v[64:79]
	s_waitcnt lgkmcnt(3)
	v_mfma_f32_32x32x16_bf16 v[80:95], v[96:99], v[128:131], v[80:95]
	ds_read2_b64 v[96:99], v183 offset0:12 offset1:14
	ds_read2_b64 v[112:115], v205 offset0:76 offset1:78
	ds_read2_b64 v[128:131], v206 offset0:140 offset1:142
	s_waitcnt lgkmcnt(5)
	v_mfma_f32_32x32x16_bf16 v[64:79], v[100:103], v[120:123], v[64:79]
	v_mfma_f32_32x32x16_bf16 v[80:95], v[108:111], v[120:123], v[80:95]
	v_mul_u32_u24_e32 v120, v152, v182
	v_lshl_add_u32 v120, v120, 2, s24
	s_waitcnt lgkmcnt(4)
	v_mfma_f32_32x32x16_bf16 v[64:79], v[108:111], v[132:135], v[64:79]
	s_waitcnt lgkmcnt(3)
	v_mfma_f32_32x32x16_bf16 v[80:95], v[100:103], v[124:127], v[80:95]
	s_waitcnt lgkmcnt(2)
	v_mfma_f32_32x32x16_bf16 v[64:79], v[104:107], v[96:99], v[64:79]
	v_mfma_f32_32x32x16_bf16 v[80:95], v[116:119], v[96:99], v[80:95]
	s_waitcnt lgkmcnt(1)
	v_mfma_f32_32x32x16_bf16 v[64:79], v[116:119], v[112:115], v[64:79]
	s_waitcnt lgkmcnt(0)
	v_mfma_f32_32x32x16_bf16 v[80:95], v[104:107], v[128:131], v[80:95]
	ds_read2_b64 v[112:115], v208 offset1:2
	ds_read2_b64 v[100:103], v208 offset0:4 offset1:6
	ds_read2_b64 v[116:119], v209 offset0:64 offset1:66
	ds_read2_b64 v[108:111], v210 offset0:128 offset1:130
	ds_read2_b64 v[104:107], v209 offset0:68 offset1:70
	ds_read2_b64 v[96:99], v210 offset0:132 offset1:134
	v_lshlrev_b32_e32 v239, 2, v182
	v_add_u32_e32 v233, v120, v239
	ds_read_b32 v243, v120
	ds_read_b32 v234, v233
	v_add_u32_e32 v252, v233, v239
	v_add_u32_e32 v244, v252, v239
	ds_read_b32 v235, v252
	ds_read_b32 v248, v244
	v_add_u32_e32 v245, v244, v187
	v_add_u32_e32 v240, v245, v239
	ds_read_b32 v247, v245
	ds_read_b32 v242, v240
	v_add_u32_e32 v249, v240, v239
	v_add_u32_e32 v253, v249, v239
	ds_read_b32 v246, v249
	ds_read_b32 v238, v253
	s_waitcnt lgkmcnt(7)
	s_waitcnt lgkmcnt(6)
	v_add_u32_e32 v241, v253, v187
	v_add_u32_e32 v237, v241, v239
	ds_read_b32 v250, v241
	ds_read_b32 v236, v237
	v_add_u32_e32 v251, v237, v239
	v_add_u32_e32 v233, v251, v239
	ds_read_b32 v252, v251
	ds_read_b32 v244, v233
	v_add_u32_e32 v245, v233, v187
	v_add_u32_e32 v240, v245, v239
	ds_read_b32 v249, v245
	ds_read_b32 v253, v240
	v_add_u32_e32 v241, v240, v239
	ds_read_b32 v237, v241
	v_add_u32_e32 v251, v241, v239
	ds_read_b32 v233, v251
	v_mov_b32_e32 v208, v239
	v_cvt_f32_f16_sdwa v124, v243 dst_sel:DWORD dst_unused:UNUSED_PAD src0_sel:WORD_1
	s_waitcnt lgkmcnt(14)
	v_cvt_f32_f16_sdwa v125, v234 dst_sel:DWORD dst_unused:UNUSED_PAD src0_sel:WORD_1
	v_cvt_f32_f16_e32 v123, v234
	v_cvt_f32_f16_e32 v122, v243
	v_pk_mul_f32 v[120:121], v[64:65], v[124:125]
	s_nop 0
	v_pk_fma_f32 v[120:121], v[80:81], v[122:123], v[120:121] neg_lo:[0,0,1] neg_hi:[0,0,1]
	v_pk_mul_f32 v[80:81], v[80:81], v[124:125]
	s_nop 0
	v_pk_fma_f32 v[80:81], v[64:65], v[122:123], v[80:81]
	v_cvt_pk_bf16_f32 v80, v80, v81
	s_waitcnt lgkmcnt(13)
	v_cvt_f32_f16_sdwa v124, v235 dst_sel:DWORD dst_unused:UNUSED_PAD src0_sel:WORD_1
	s_waitcnt lgkmcnt(12)
	v_cvt_f32_f16_sdwa v125, v248 dst_sel:DWORD dst_unused:UNUSED_PAD src0_sel:WORD_1
	v_cvt_f32_f16_e32 v65, v248
	v_cvt_f32_f16_e32 v64, v235
	v_pk_mul_f32 v[122:123], v[66:67], v[124:125]
	s_nop 0
	v_pk_fma_f32 v[122:123], v[82:83], v[64:65], v[122:123] neg_lo:[0,0,1] neg_hi:[0,0,1]
	v_pk_mul_f32 v[82:83], v[82:83], v[124:125]
	s_nop 0
	v_pk_fma_f32 v[82:83], v[66:67], v[64:65], v[82:83]
	v_cvt_pk_bf16_f32 v81, v82, v83
	s_waitcnt lgkmcnt(11)
	v_cvt_f32_f16_e32 v64, v247
	s_waitcnt lgkmcnt(10)
	v_cvt_f32_f16_e32 v65, v242
	v_cvt_f32_f16_sdwa v67, v242 dst_sel:DWORD dst_unused:UNUSED_PAD src0_sel:WORD_1
	v_cvt_f32_f16_sdwa v66, v247 dst_sel:DWORD dst_unused:UNUSED_PAD src0_sel:WORD_1
	v_pk_mul_f32 v[124:125], v[68:69], v[66:67]
	v_pk_mul_f32 v[66:67], v[84:85], v[66:67]
	v_pk_fma_f32 v[124:125], v[84:85], v[64:65], v[124:125] neg_lo:[0,0,1] neg_hi:[0,0,1]
	v_pk_fma_f32 v[84:85], v[68:69], v[64:65], v[66:67]
	v_cvt_pk_bf16_f32 v82, v84, v85
	v_cvt_pk_bf16_f32 v84, v120, v121
	v_cvt_pk_bf16_f32 v85, v122, v123
	s_waitcnt lgkmcnt(9)
	v_cvt_f32_f16_e32 v64, v246
	s_waitcnt lgkmcnt(8)
	v_cvt_f32_f16_e32 v65, v238
	v_cvt_f32_f16_sdwa v67, v238 dst_sel:DWORD dst_unused:UNUSED_PAD src0_sel:WORD_1
	v_cvt_f32_f16_sdwa v66, v246 dst_sel:DWORD dst_unused:UNUSED_PAD src0_sel:WORD_1
	v_pk_mul_f32 v[68:69], v[70:71], v[66:67]
	v_pk_mul_f32 v[66:67], v[86:87], v[66:67]
	v_pk_fma_f32 v[126:127], v[86:87], v[64:65], v[68:69] neg_lo:[0,0,1] neg_hi:[0,0,1]
	v_pk_fma_f32 v[86:87], v[70:71], v[64:65], v[66:67]
	v_cvt_pk_bf16_f32 v83, v86, v87
	v_cvt_pk_bf16_f32 v86, v124, v125
	v_cvt_pk_bf16_f32 v87, v126, v127
	s_waitcnt lgkmcnt(7)
	v_cvt_f32_f16_sdwa v68, v250 dst_sel:DWORD dst_unused:UNUSED_PAD src0_sel:WORD_1
	s_waitcnt lgkmcnt(6)
	v_cvt_f32_f16_sdwa v69, v236 dst_sel:DWORD dst_unused:UNUSED_PAD src0_sel:WORD_1
	v_cvt_f32_f16_e32 v67, v236
	v_cvt_f32_f16_e32 v66, v250
	v_mfma_f32_32x32x16_bf16 v[16:31], v[112:115], v[80:83], v[16:31]
	v_mul_f32_e64 v64, v72, v68
	v_mul_f32_e64 v65, v73, v69
	v_mul_f32_e64 v68, v88, v68
	v_mul_f32_e64 v69, v89, v69
	v_fma_f32 v64, v88, v66, -v64
	v_fma_f32 v65, v89, v67, -v65
	v_pk_fma_f32 v[66:67], v[72:73], v[66:67], v[68:69]
	v_mfma_f32_32x32x16_bf16 v[0:15], v[112:115], v[84:87], v[0:15]
	v_cvt_pk_bf16_f32 v64, v64, v65
	s_waitcnt lgkmcnt(5)
	v_cvt_f32_f16_sdwa v72, v252 dst_sel:DWORD dst_unused:UNUSED_PAD src0_sel:WORD_1
	s_waitcnt lgkmcnt(4)
	v_cvt_f32_f16_sdwa v73, v244 dst_sel:DWORD dst_unused:UNUSED_PAD src0_sel:WORD_1
	v_cvt_f32_f16_e32 v71, v244
	v_cvt_f32_f16_e32 v70, v252
	v_pk_mul_f32 v[68:69], v[74:75], v[72:73]
	v_pk_mul_f32 v[72:73], v[90:91], v[72:73]
	v_pk_fma_f32 v[68:69], v[90:91], v[70:71], v[68:69] neg_lo:[0,0,1] neg_hi:[0,0,1]
	v_pk_fma_f32 v[70:71], v[74:75], v[70:71], v[72:73]
	v_mfma_f32_32x32x16_bf16 v[16:31], v[116:119], v[84:87], v[16:31]
	v_cvt_pk_bf16_f32 v65, v68, v69
	s_waitcnt lgkmcnt(3)
	v_cvt_f32_f16_sdwa v88, v249 dst_sel:DWORD dst_unused:UNUSED_PAD src0_sel:WORD_1
	s_waitcnt lgkmcnt(2)
	v_cvt_f32_f16_sdwa v89, v253 dst_sel:DWORD dst_unused:UNUSED_PAD src0_sel:WORD_1
	v_cvt_f32_f16_e32 v75, v253
	v_cvt_f32_f16_e32 v74, v249
	v_pk_mul_f32 v[72:73], v[76:77], v[88:89]
	v_pk_mul_f32 v[88:89], v[92:93], v[88:89]
	v_pk_fma_f32 v[72:73], v[92:93], v[74:75], v[72:73] neg_lo:[0,0,1] neg_hi:[0,0,1]
	v_pk_fma_f32 v[74:75], v[76:77], v[74:75], v[88:89]
	v_mfma_f32_32x32x16_bf16 v[0:15], v[108:111], v[80:83], v[0:15]
	v_cvt_pk_bf16_f32 v80, v66, v67
	s_waitcnt lgkmcnt(1)
	v_cvt_f32_f16_sdwa v90, v237 dst_sel:DWORD dst_unused:UNUSED_PAD src0_sel:WORD_1
	v_cvt_f32_f16_e32 v88, v237
	s_waitcnt lgkmcnt(0)
	v_cvt_f32_f16_sdwa v91, v233 dst_sel:DWORD dst_unused:UNUSED_PAD src0_sel:WORD_1
	v_cvt_f32_f16_e32 v89, v233
	v_cvt_pk_bf16_f32 v81, v70, v71
	v_cvt_pk_bf16_f32 v82, v74, v75
	v_pk_mul_f32 v[76:77], v[78:79], v[90:91]
	v_pk_mul_f32 v[90:91], v[94:95], v[90:91]
	v_pk_fma_f32 v[76:77], v[94:95], v[88:89], v[76:77] neg_lo:[0,0,1] neg_hi:[0,0,1]
	v_pk_fma_f32 v[78:79], v[78:79], v[88:89], v[90:91]
	v_cvt_pk_bf16_f32 v66, v72, v73
	v_cvt_pk_bf16_f32 v83, v78, v79
	v_cvt_pk_bf16_f32 v67, v76, v77
	s_nop 0
	v_mfma_f32_32x32x16_bf16 v[16:31], v[100:103], v[80:83], v[16:31]
	v_mfma_f32_32x32x16_bf16 v[0:15], v[100:103], v[64:67], v[0:15]
	v_mfma_f32_32x32x16_bf16 v[16:31], v[104:107], v[64:67], v[16:31]
	v_mfma_f32_32x32x16_bf16 v[0:15], v[96:99], v[80:83], v[0:15]
	s_cbranch_vccnz .LBB0_2783
	v_cvt_pk_bf16_f32 v32, v32, s0
	s_waitcnt lgkmcnt(0)
	v_cvt_pk_bf16_f32 v48, v48, s0
	ds_write_b16 v188, v32 offset:6144
	v_cvt_pk_bf16_f32 v32, v49, s0
	v_add_u32_e32 v209, s42, v184
	ds_write_b16 v188, v48
	ds_write_b16 v209, v32
	v_cvt_pk_bf16_f32 v32, v33, s0
	ds_write_b16 v209, v32 offset:6144
	v_cvt_pk_bf16_f32 v32, v50, s0
	ds_write_b16 v189, v32
	v_cvt_pk_bf16_f32 v32, v34, s0
	ds_write_b16 v189, v32 offset:6144
	v_cvt_pk_bf16_f32 v32, v51, s0
	ds_write_b16 v190, v32
	v_cvt_pk_bf16_f32 v32, v35, s0
	ds_write_b16 v190, v32 offset:6144
	v_cvt_pk_bf16_f32 v32, v52, s0
	ds_write_b16 v191, v32
	v_cvt_pk_bf16_f32 v32, v36, s0
	ds_write_b16 v191, v32 offset:6144
	v_cvt_pk_bf16_f32 v32, v53, s0
	ds_write_b16 v192, v32
	v_cvt_pk_bf16_f32 v32, v37, s0
	ds_write_b16 v192, v32 offset:6144
	v_cvt_pk_bf16_f32 v32, v54, s0
	ds_write_b16 v193, v32
	v_cvt_pk_bf16_f32 v32, v38, s0
	ds_write_b16 v193, v32 offset:6144
	v_cvt_pk_bf16_f32 v32, v55, s0
	ds_write_b16 v194, v32
	v_cvt_pk_bf16_f32 v32, v39, s0
	ds_write_b16 v194, v32 offset:6144
	v_cvt_pk_bf16_f32 v32, v56, s0
	ds_write_b16 v195, v32
	v_cvt_pk_bf16_f32 v32, v40, s0
	ds_write_b16 v195, v32 offset:6144
	v_cvt_pk_bf16_f32 v32, v57, s0
	ds_write_b16 v196, v32
	v_cvt_pk_bf16_f32 v32, v41, s0
	ds_write_b16 v196, v32 offset:6144
	v_cvt_pk_bf16_f32 v32, v58, s0
	ds_write_b16 v197, v32
	v_cvt_pk_bf16_f32 v32, v42, s0
	ds_write_b16 v197, v32 offset:6144
	v_cvt_pk_bf16_f32 v32, v59, s0
	ds_write_b16 v198, v32
	v_cvt_pk_bf16_f32 v32, v43, s0
	ds_write_b16 v198, v32 offset:6144
	v_cvt_pk_bf16_f32 v32, v60, s0
	ds_write_b16 v199, v32
	v_cvt_pk_bf16_f32 v32, v44, s0
	ds_write_b16 v199, v32 offset:6144
	v_cvt_pk_bf16_f32 v32, v61, s0
	ds_write_b16 v200, v32
	v_cvt_pk_bf16_f32 v32, v45, s0
	ds_write_b16 v200, v32 offset:6144
	v_cvt_pk_bf16_f32 v32, v62, s0
	ds_write_b16 v201, v32
	v_cvt_pk_bf16_f32 v32, v46, s0
	ds_write_b16 v201, v32 offset:6144
	v_cvt_pk_bf16_f32 v32, v63, s0
	ds_write_b16 v202, v32
	v_cvt_pk_bf16_f32 v32, v47, s0
	v_cvt_pk_bf16_f32 v0, v0, s0
	ds_write_b16 v202, v32 offset:6144
	v_cvt_pk_bf16_f32 v16, v16, s0
	ds_write_b16 v188, v0 offset:6208
	v_cvt_pk_bf16_f32 v0, v17, s0
	ds_write_b16 v188, v16 offset:64
	ds_write_b16 v209, v0 offset:64
	v_cvt_pk_bf16_f32 v0, v1, s0
	ds_write_b16 v209, v0 offset:6208
	v_cvt_pk_bf16_f32 v0, v18, s0
	ds_write_b16 v189, v0 offset:64
	v_cvt_pk_bf16_f32 v0, v2, s0
	ds_write_b16 v189, v0 offset:6208
	v_cvt_pk_bf16_f32 v0, v19, s0
	ds_write_b16 v190, v0 offset:64
	v_cvt_pk_bf16_f32 v0, v3, s0
	ds_write_b16 v190, v0 offset:6208
	v_cvt_pk_bf16_f32 v0, v20, s0
	ds_write_b16 v191, v0 offset:64
	v_cvt_pk_bf16_f32 v0, v4, s0
	ds_write_b16 v191, v0 offset:6208
	v_cvt_pk_bf16_f32 v0, v21, s0
	ds_write_b16 v192, v0 offset:64
	v_cvt_pk_bf16_f32 v0, v5, s0
	ds_write_b16 v192, v0 offset:6208
	v_cvt_pk_bf16_f32 v0, v22, s0
	ds_write_b16 v193, v0 offset:64
	v_cvt_pk_bf16_f32 v0, v6, s0
	ds_write_b16 v193, v0 offset:6208
	v_cvt_pk_bf16_f32 v0, v23, s0
	ds_write_b16 v194, v0 offset:64
	v_cvt_pk_bf16_f32 v0, v7, s0
	ds_write_b16 v194, v0 offset:6208
	v_cvt_pk_bf16_f32 v0, v24, s0
	ds_write_b16 v195, v0 offset:64
	v_cvt_pk_bf16_f32 v0, v8, s0
	ds_write_b16 v195, v0 offset:6208
	v_cvt_pk_bf16_f32 v0, v25, s0
	ds_write_b16 v196, v0 offset:64
	v_cvt_pk_bf16_f32 v0, v9, s0
	ds_write_b16 v196, v0 offset:6208
	v_cvt_pk_bf16_f32 v0, v26, s0
	ds_write_b16 v197, v0 offset:64
	v_cvt_pk_bf16_f32 v0, v10, s0
	ds_write_b16 v197, v0 offset:6208
	v_cvt_pk_bf16_f32 v0, v27, s0
	ds_write_b16 v198, v0 offset:64
	v_cvt_pk_bf16_f32 v0, v11, s0
	ds_write_b16 v198, v0 offset:6208
	v_cvt_pk_bf16_f32 v0, v28, s0
	ds_write_b16 v199, v0 offset:64
	v_cvt_pk_bf16_f32 v0, v12, s0
	ds_write_b16 v199, v0 offset:6208
	v_cvt_pk_bf16_f32 v0, v29, s0
	ds_write_b16 v200, v0 offset:64
	v_cvt_pk_bf16_f32 v0, v13, s0
	ds_write_b16 v200, v0 offset:6208
	v_cvt_pk_bf16_f32 v0, v30, s0
	ds_write_b16 v201, v0 offset:64
	v_cvt_pk_bf16_f32 v0, v14, s0
	ds_write_b16 v201, v0 offset:6208
	v_cvt_pk_bf16_f32 v0, v31, s0
	s_or_b32 s2, s43, 0x200
	ds_write_b16 v202, v0 offset:64
	v_cvt_pk_bf16_f32 v0, v15, s0
	s_lshl_b32 s10, s2, 11
	ds_write_b16 v202, v0 offset:6208
	v_lshl_add_u64 v[0:1], v[170:171], 0, s[10:11]
	v_or_b32_e32 v0, v0, v154
	v_lshl_add_u64 v[40:41], v[0:1], 4, s[18:19]
	v_mov_b32_e32 v4, 0
	v_mov_b32_e32 v0, 0
	v_mov_b32_e32 v1, 0
	v_mov_b32_e32 v2, 0
	v_mov_b32_e32 v3, 0
	s_waitcnt lgkmcnt(0)
	s_barrier
	s_and_saveexec_b64 s[20:21], s[4:5]
	s_cbranch_execz .LBB0_2786
	global_load_dwordx4 v[0:3], v[40:41], off offset:-16

.LBB0_2789:
	v_or_b32_e32 v144, s2, v175
	v_mad_u32_u24 v145, v144, s28, v176
	ds_read_b64_tr_b16 v[80:81], v185
	ds_read_b64_tr_b16 v[82:83], v185 offset:768
	ds_read_b64_tr_b16 v[96:97], v185 offset:6144
	ds_read_b64_tr_b16 v[98:99], v185 offset:6912
	ds_read2_b64 v[100:103], v145 offset1:1
	v_add_u32_e32 v108, 0x2200, v145
	ds_read2_b64 v[84:87], v108 offset1:1
	v_add_u32_e32 v112, 0x4400, v145
	s_waitcnt lgkmcnt(1)
	v_mfma_f32_32x32x16_bf16 v[64:79], v[80:83], v[100:103], 0
	ds_read2_b64 v[88:91], v112 offset1:1
	ds_read_b64_tr_b16 v[116:117], v185 offset:3072
	ds_read_b64_tr_b16 v[118:119], v185 offset:3840
	ds_read_b64_tr_b16 v[120:121], v185 offset:9216
	ds_read_b64_tr_b16 v[122:123], v185 offset:9984
	ds_read2_b64 v[124:127], v145 offset0:4 offset1:5
	v_add_u32_e32 v146, 0x2220, v145
	ds_read2_b64 v[128:131], v146 offset1:1
	v_add_u32_e32 v150, 0x4420, v145
	ds_read2_b64 v[132:135], v150 offset1:1
	v_lshlrev_b32_e32 v151, 2, v144
	s_waitcnt lgkmcnt(7)
	v_mfma_f32_32x32x16_bf16 v[64:79], v[96:99], v[88:91], v[64:79]
	v_mfma_f32_32x32x16_bf16 v[80:95], v[80:83], v[84:87], 0
	v_mfma_f32_32x32x16_bf16 v[80:95], v[96:99], v[100:103], v[80:95]
	ds_read_b64_tr_b16 v[96:97], v185 offset:64
	ds_read_b64_tr_b16 v[98:99], v185 offset:832
	ds_read_b64_tr_b16 v[100:101], v185 offset:6208
	ds_read_b64_tr_b16 v[102:103], v185 offset:6976
	ds_read2_b64 v[104:107], v145 offset1:1
	ds_read2_b64 v[108:111], v108 offset1:1
	ds_read2_b64 v[112:115], v112 offset1:1
	s_waitcnt lgkmcnt(6)
	v_mul_u32_u24_e32 v233, v144, v177
	v_lshl_add_u32 v234, v233, 2, s24
	ds_read_b32 v235, v234
	v_add_u32_e32 v236, v234, v151
	ds_read_b32 v237, v236
	v_add_u32_e32 v238, v236, v151
	v_add_u32_e32 v239, v238, v151
	ds_read_b32 v240, v238
	ds_read_b32 v241, v239
	v_mul_u32_u24_e32 v242, 5, v144
	v_lshlrev_b32_e32 v243, 2, v242
	v_add_u32_e32 v244, v239, v243
	v_add_u32_e32 v245, v244, v151
	ds_read_b32 v246, v244
	ds_read_b32 v247, v245
	v_add_u32_e32 v248, v245, v151
	v_add_u32_e32 v249, v248, v151
	ds_read_b32 v250, v248
	ds_read_b32 v251, v249
	s_waitcnt lgkmcnt(15)
	v_mfma_f32_32x32x16_bf16 v[64:79], v[116:119], v[124:127], v[64:79]
	s_waitcnt lgkmcnt(15)
	v_mfma_f32_32x32x16_bf16 v[80:95], v[116:119], v[128:131], v[80:95]
	s_waitcnt lgkmcnt(15)
	v_mfma_f32_32x32x16_bf16 v[64:79], v[120:123], v[132:135], v[64:79]
	v_mfma_f32_32x32x16_bf16 v[80:95], v[120:123], v[124:127], v[80:95]
	s_waitcnt lgkmcnt(7)
	s_waitcnt lgkmcnt(6)
	v_add_u32_e32 v252, v249, v243
	v_add_u32_e32 v253, v252, v151
	ds_read_b32 v233, v252
	ds_read_b32 v234, v253
	v_add_u32_e32 v236, v253, v151
	v_add_u32_e32 v238, v236, v151
	ds_read_b32 v242, v236
	ds_read_b32 v239, v238
	v_add_u32_e32 v244, v238, v243
	v_add_u32_e32 v245, v244, v151
	ds_read_b32 v248, v244
	ds_read_b32 v249, v245
	v_add_u32_e32 v252, v245, v151
	v_add_u32_e32 v253, v252, v151
	ds_read_b32 v236, v252
	ds_read_b32 v238, v253
	v_mov_b32_e32 v172, v253
	v_mov_b32_e32 v152, v243
	v_cvt_f32_f16_e32 v116, v235
	v_cvt_f32_f16_sdwa v118, v235 dst_sel:DWORD dst_unused:UNUSED_PAD src0_sel:WORD_1
	s_waitcnt lgkmcnt(14)
	v_cvt_f32_f16_e32 v117, v237
	v_cvt_f32_f16_sdwa v119, v237 dst_sel:DWORD dst_unused:UNUSED_PAD src0_sel:WORD_1
	s_nop 3
	v_pk_mul_f32 v[120:121], v[80:81], v[118:119]
	s_nop 0
	v_pk_fma_f32 v[120:121], v[64:65], v[116:117], v[120:121] neg_lo:[0,0,1] neg_hi:[0,0,1]
	v_pk_mul_f32 v[64:65], v[64:65], v[118:119]
	v_cvt_pk_bf16_f32 v136, v120, v121
	v_pk_fma_f32 v[64:65], v[80:81], v[116:117], v[64:65]
	v_cvt_pk_bf16_f32 v140, v64, v65
	s_waitcnt lgkmcnt(13)
	v_cvt_f32_f16_e32 v80, v240
	s_waitcnt lgkmcnt(12)
	v_cvt_f32_f16_e32 v81, v241
	v_cvt_f32_f16_sdwa v117, v241 dst_sel:DWORD dst_unused:UNUSED_PAD src0_sel:WORD_1
	v_cvt_f32_f16_sdwa v116, v240 dst_sel:DWORD dst_unused:UNUSED_PAD src0_sel:WORD_1
	v_pk_mul_f32 v[118:119], v[82:83], v[116:117]
	s_nop 0
	v_pk_fma_f32 v[118:119], v[66:67], v[80:81], v[118:119] neg_lo:[0,0,1] neg_hi:[0,0,1]
	v_pk_mul_f32 v[66:67], v[66:67], v[116:117]
	v_cvt_pk_bf16_f32 v137, v118, v119
	v_pk_fma_f32 v[66:67], v[82:83], v[80:81], v[66:67]
	v_cvt_pk_bf16_f32 v141, v66, v67
	s_waitcnt lgkmcnt(11)
	v_cvt_f32_f16_e32 v80, v246
	s_waitcnt lgkmcnt(10)
	v_cvt_f32_f16_e32 v81, v247
	v_cvt_f32_f16_sdwa v82, v246 dst_sel:DWORD dst_unused:UNUSED_PAD src0_sel:WORD_1
	v_cvt_f32_f16_sdwa v83, v247 dst_sel:DWORD dst_unused:UNUSED_PAD src0_sel:WORD_1
	v_pk_mul_f32 v[116:117], v[84:85], v[82:83]
	s_nop 0
	v_pk_fma_f32 v[116:117], v[68:69], v[80:81], v[116:117] neg_lo:[0,0,1] neg_hi:[0,0,1]
	v_pk_mul_f32 v[68:69], v[68:69], v[82:83]
	v_cvt_pk_bf16_f32 v138, v116, v117
	v_pk_fma_f32 v[68:69], v[84:85], v[80:81], v[68:69]
	v_cvt_pk_bf16_f32 v142, v68, v69
	s_waitcnt lgkmcnt(9)
	v_cvt_f32_f16_e32 v80, v250
	s_waitcnt lgkmcnt(8)
	v_cvt_f32_f16_e32 v81, v251
	v_cvt_f32_f16_sdwa v82, v250 dst_sel:DWORD dst_unused:UNUSED_PAD src0_sel:WORD_1
	v_cvt_f32_f16_sdwa v83, v251 dst_sel:DWORD dst_unused:UNUSED_PAD src0_sel:WORD_1
	v_pk_mul_f32 v[84:85], v[86:87], v[82:83]
	s_nop 0
	v_pk_fma_f32 v[84:85], v[70:71], v[80:81], v[84:85] neg_lo:[0,0,1] neg_hi:[0,0,1]
	v_pk_mul_f32 v[70:71], v[70:71], v[82:83]
	v_cvt_pk_bf16_f32 v139, v84, v85
	v_pk_fma_f32 v[70:71], v[86:87], v[80:81], v[70:71]
	v_cvt_pk_bf16_f32 v143, v70, v71
	s_waitcnt lgkmcnt(7)
	v_cvt_f32_f16_e32 v80, v233
	s_waitcnt lgkmcnt(6)
	v_cvt_f32_f16_e32 v81, v234
	v_cvt_f32_f16_sdwa v82, v233 dst_sel:DWORD dst_unused:UNUSED_PAD src0_sel:WORD_1
	v_cvt_f32_f16_sdwa v83, v234 dst_sel:DWORD dst_unused:UNUSED_PAD src0_sel:WORD_1
	v_pk_mul_f32 v[86:87], v[88:89], v[82:83]
	s_nop 0
	v_pk_fma_f32 v[86:87], v[72:73], v[80:81], v[86:87] neg_lo:[0,0,1] neg_hi:[0,0,1]
	v_pk_mul_f32 v[72:73], v[72:73], v[82:83]
	v_cvt_pk_bf16_f32 v132, v86, v87
	v_pk_fma_f32 v[72:73], v[88:89], v[80:81], v[72:73]
	v_cvt_pk_bf16_f32 v128, v72, v73
	s_waitcnt lgkmcnt(5)
	v_cvt_f32_f16_e32 v80, v242
	s_waitcnt lgkmcnt(4)
	v_cvt_f32_f16_e32 v81, v239
	v_cvt_f32_f16_sdwa v82, v242 dst_sel:DWORD dst_unused:UNUSED_PAD src0_sel:WORD_1
	v_cvt_f32_f16_sdwa v83, v239 dst_sel:DWORD dst_unused:UNUSED_PAD src0_sel:WORD_1
	v_pk_mul_f32 v[88:89], v[90:91], v[82:83]
	s_nop 0
	v_pk_fma_f32 v[88:89], v[74:75], v[80:81], v[88:89] neg_lo:[0,0,1] neg_hi:[0,0,1]
	v_pk_mul_f32 v[74:75], v[74:75], v[82:83]
	v_cvt_pk_bf16_f32 v133, v88, v89
	v_pk_fma_f32 v[74:75], v[90:91], v[80:81], v[74:75]
	v_cvt_pk_bf16_f32 v129, v74, v75
	s_waitcnt lgkmcnt(3)
	v_cvt_f32_f16_e32 v80, v248
	s_waitcnt lgkmcnt(2)
	v_cvt_f32_f16_e32 v81, v249
	v_cvt_f32_f16_sdwa v82, v248 dst_sel:DWORD dst_unused:UNUSED_PAD src0_sel:WORD_1
	v_cvt_f32_f16_sdwa v83, v249 dst_sel:DWORD dst_unused:UNUSED_PAD src0_sel:WORD_1
	v_pk_mul_f32 v[90:91], v[92:93], v[82:83]
	s_nop 0
	v_pk_fma_f32 v[90:91], v[76:77], v[80:81], v[90:91] neg_lo:[0,0,1] neg_hi:[0,0,1]
	v_pk_mul_f32 v[76:77], v[76:77], v[82:83]
	v_cvt_pk_bf16_f32 v134, v90, v91
	v_pk_fma_f32 v[76:77], v[92:93], v[80:81], v[76:77]
	v_cvt_pk_bf16_f32 v130, v76, v77
	ds_read_b64_tr_b16 v[116:117], v185 offset:3136
	ds_read_b64_tr_b16 v[118:119], v185 offset:3904
	ds_read_b64_tr_b16 v[120:121], v185 offset:9280
	ds_read_b64_tr_b16 v[122:123], v185 offset:10048
	ds_read2_b64 v[124:127], v145 offset0:4 offset1:5
	ds_read2_b64 v[146:149], v146 offset1:1
	ds_read2_b64 v[210:213], v150 offset1:1
	s_waitcnt lgkmcnt(8)
	v_cvt_f32_f16_e32 v80, v236
	s_waitcnt lgkmcnt(7)
	v_cvt_f32_f16_e32 v81, v238
	v_cvt_f32_f16_sdwa v82, v236 dst_sel:DWORD dst_unused:UNUSED_PAD src0_sel:WORD_1
	v_cvt_f32_f16_sdwa v83, v238 dst_sel:DWORD dst_unused:UNUSED_PAD src0_sel:WORD_1
	s_waitcnt lgkmcnt(6)
	v_add_u32_e32 v244, v172, v152
	ds_read_b32 v245, v244
	v_add_u32_e32 v252, v244, v151
	ds_read_b32 v253, v252
	v_add_u32_e32 v243, v252, v151
	v_add_u32_e32 v235, v243, v151
	ds_read_b32 v237, v243
	ds_read_b32 v240, v235
	v_add_u32_e32 v241, v235, v152
	v_add_u32_e32 v246, v241, v151
	ds_read_b32 v247, v241
	ds_read_b32 v250, v246
	v_add_u32_e32 v251, v246, v151
	v_add_u32_e32 v233, v251, v151
	ds_read_b32 v234, v251
	ds_read_b32 v242, v233
	v_pk_mul_f32 v[92:93], v[94:95], v[82:83]
	s_nop 0
	v_pk_fma_f32 v[92:93], v[78:79], v[80:81], v[92:93] neg_lo:[0,0,1] neg_hi:[0,0,1]
	v_pk_mul_f32 v[78:79], v[78:79], v[82:83]
	v_cvt_pk_bf16_f32 v135, v92, v93
	v_pk_fma_f32 v[78:79], v[94:95], v[80:81], v[78:79]
	v_mfma_f32_32x32x16_bf16 v[80:95], v[96:99], v[108:111], 0
	v_cvt_pk_bf16_f32 v131, v78, v79
	v_mfma_f32_32x32x16_bf16 v[64:79], v[96:99], v[104:107], 0
	v_mfma_f32_32x32x16_bf16 v[80:95], v[100:103], v[104:107], v[80:95]
	v_mfma_f32_32x32x16_bf16 v[64:79], v[100:103], v[112:115], v[64:79]
	s_waitcnt lgkmcnt(7)
	s_waitcnt lgkmcnt(6)
	v_add_u32_e32 v239, v233, v152
	v_add_u32_e32 v248, v239, v151
	ds_read_b32 v249, v239
	ds_read_b32 v236, v248
	v_add_u32_e32 v238, v248, v151
	v_add_u32_e32 v252, v238, v151
	ds_read_b32 v243, v238
	ds_read_b32 v235, v252
	v_add_u32_e32 v241, v252, v152
	v_add_u32_e32 v246, v241, v151
	ds_read_b32 v251, v241
	ds_read_b32 v233, v246
	v_add_u32_e32 v239, v246, v151
	ds_read_b32 v248, v239
	v_add_u32_e32 v238, v239, v151
	ds_read_b32 v252, v238
	v_mov_b32_e32 v96, v244
	v_cvt_f32_f16_e32 v96, v245
	v_cvt_f32_f16_sdwa v98, v245 dst_sel:DWORD dst_unused:UNUSED_PAD src0_sel:WORD_1
	s_waitcnt lgkmcnt(14)
	v_cvt_f32_f16_e32 v97, v253
	v_mfma_f32_32x32x16_bf16 v[80:95], v[116:119], v[146:149], v[80:95]
	v_cvt_f32_f16_sdwa v99, v253 dst_sel:DWORD dst_unused:UNUSED_PAD src0_sel:WORD_1
	v_mfma_f32_32x32x16_bf16 v[64:79], v[116:119], v[124:127], v[64:79]
	v_mfma_f32_32x32x16_bf16 v[80:95], v[120:123], v[124:127], v[80:95]
	v_mfma_f32_32x32x16_bf16 v[64:79], v[120:123], v[210:213], v[64:79]
	s_nop 10
	v_mul_f32_e64 v100, v80, v98
	v_mul_f32_e64 v101, v81, v99
	v_pk_fma_f32 v[100:101], v[64:65], v[96:97], v[100:101] neg_lo:[0,0,1] neg_hi:[0,0,1]
	v_pk_mul_f32 v[64:65], v[64:65], v[98:99]
	v_cvt_pk_bf16_f32 v124, v100, v101
	v_pk_fma_f32 v[64:65], v[80:81], v[96:97], v[64:65]
	v_cvt_pk_bf16_f32 v120, v64, v65
	s_waitcnt lgkmcnt(13)
	v_cvt_f32_f16_e32 v80, v237
	s_waitcnt lgkmcnt(12)
	v_cvt_f32_f16_e32 v81, v240
	v_cvt_f32_f16_sdwa v96, v237 dst_sel:DWORD dst_unused:UNUSED_PAD src0_sel:WORD_1
	v_cvt_f32_f16_sdwa v97, v240 dst_sel:DWORD dst_unused:UNUSED_PAD src0_sel:WORD_1
	v_pk_mul_f32 v[98:99], v[82:83], v[96:97]
	s_nop 0
	v_pk_fma_f32 v[98:99], v[66:67], v[80:81], v[98:99] neg_lo:[0,0,1] neg_hi:[0,0,1]
	v_pk_mul_f32 v[66:67], v[66:67], v[96:97]
	v_cvt_pk_bf16_f32 v125, v98, v99
	v_pk_fma_f32 v[66:67], v[82:83], v[80:81], v[66:67]
	v_cvt_pk_bf16_f32 v121, v66, v67
	s_waitcnt lgkmcnt(11)
	v_cvt_f32_f16_e32 v80, v247
	s_waitcnt lgkmcnt(10)
	v_cvt_f32_f16_e32 v81, v250
	v_cvt_f32_f16_sdwa v82, v247 dst_sel:DWORD dst_unused:UNUSED_PAD src0_sel:WORD_1
	v_cvt_f32_f16_sdwa v83, v250 dst_sel:DWORD dst_unused:UNUSED_PAD src0_sel:WORD_1
	v_pk_mul_f32 v[96:97], v[84:85], v[82:83]
	s_nop 0
	v_pk_fma_f32 v[96:97], v[68:69], v[80:81], v[96:97] neg_lo:[0,0,1] neg_hi:[0,0,1]
	v_pk_mul_f32 v[68:69], v[68:69], v[82:83]
	v_cvt_pk_bf16_f32 v126, v96, v97
	v_pk_fma_f32 v[68:69], v[84:85], v[80:81], v[68:69]
	v_cvt_pk_bf16_f32 v122, v68, v69
	v_or_b32_e32 v96, v144, v179
	v_mov_b32_e32 v97, v153
	s_waitcnt lgkmcnt(9)
	v_cvt_f32_f16_e32 v80, v234
	s_waitcnt lgkmcnt(8)
	v_cvt_f32_f16_e32 v81, v242
	v_cvt_f32_f16_sdwa v82, v234 dst_sel:DWORD dst_unused:UNUSED_PAD src0_sel:WORD_1
	v_cvt_f32_f16_sdwa v83, v242 dst_sel:DWORD dst_unused:UNUSED_PAD src0_sel:WORD_1
	v_lshl_add_u64 v[96:97], v[96:97], 2, s[14:15]
	v_pk_mul_f32 v[84:85], v[86:87], v[82:83]
	s_nop 0
	v_pk_fma_f32 v[84:85], v[70:71], v[80:81], v[84:85] neg_lo:[0,0,1] neg_hi:[0,0,1]
	v_pk_mul_f32 v[70:71], v[70:71], v[82:83]
	v_cvt_pk_bf16_f32 v127, v84, v85
	v_pk_fma_f32 v[70:71], v[86:87], v[80:81], v[70:71]
	v_cvt_pk_bf16_f32 v123, v70, v71
	s_waitcnt lgkmcnt(7)
	v_cvt_f32_f16_e32 v80, v249
	s_waitcnt lgkmcnt(6)
	v_cvt_f32_f16_e32 v81, v236
	v_cvt_f32_f16_sdwa v82, v249 dst_sel:DWORD dst_unused:UNUSED_PAD src0_sel:WORD_1
	v_cvt_f32_f16_sdwa v83, v236 dst_sel:DWORD dst_unused:UNUSED_PAD src0_sel:WORD_1
	v_pk_mul_f32 v[86:87], v[88:89], v[82:83]
	s_nop 0
	v_pk_fma_f32 v[86:87], v[72:73], v[80:81], v[86:87] neg_lo:[0,0,1] neg_hi:[0,0,1]
	v_pk_mul_f32 v[72:73], v[72:73], v[82:83]
	v_cvt_pk_bf16_f32 v112, v86, v87
	v_pk_fma_f32 v[72:73], v[88:89], v[80:81], v[72:73]
	v_cvt_pk_bf16_f32 v116, v72, v73
	s_waitcnt lgkmcnt(5)
	v_cvt_f32_f16_e32 v80, v243
	s_waitcnt lgkmcnt(4)
	v_cvt_f32_f16_e32 v81, v235
	v_cvt_f32_f16_sdwa v82, v243 dst_sel:DWORD dst_unused:UNUSED_PAD src0_sel:WORD_1
	v_cvt_f32_f16_sdwa v83, v235 dst_sel:DWORD dst_unused:UNUSED_PAD src0_sel:WORD_1
	v_pk_mul_f32 v[88:89], v[90:91], v[82:83]
	s_nop 0
	v_pk_fma_f32 v[88:89], v[74:75], v[80:81], v[88:89] neg_lo:[0,0,1] neg_hi:[0,0,1]
	v_pk_mul_f32 v[74:75], v[74:75], v[82:83]
	v_cvt_pk_bf16_f32 v113, v88, v89
	v_pk_fma_f32 v[74:75], v[90:91], v[80:81], v[74:75]
	v_or_b32_e32 v152, v144, v178
	v_lshl_add_u64 v[64:65], v[152:153], 2, s[14:15]
	v_cvt_pk_bf16_f32 v117, v74, v75
	s_waitcnt lgkmcnt(3)
	v_cvt_f32_f16_e32 v80, v251
	s_waitcnt lgkmcnt(2)
	v_cvt_f32_f16_e32 v81, v233
	v_cvt_f32_f16_sdwa v82, v251 dst_sel:DWORD dst_unused:UNUSED_PAD src0_sel:WORD_1
	v_cvt_f32_f16_sdwa v83, v233 dst_sel:DWORD dst_unused:UNUSED_PAD src0_sel:WORD_1
	v_pk_mul_f32 v[90:91], v[92:93], v[82:83]
	s_nop 0
	v_pk_fma_f32 v[90:91], v[76:77], v[80:81], v[90:91] neg_lo:[0,0,1] neg_hi:[0,0,1]
	v_pk_mul_f32 v[76:77], v[76:77], v[82:83]
	v_cvt_pk_bf16_f32 v114, v90, v91
	v_pk_fma_f32 v[76:77], v[92:93], v[80:81], v[76:77]
	global_load_dword v104, v[64:65], off
	global_load_dword v105, v[64:65], off offset:256
	global_load_dword v102, v[64:65], off offset:512
	global_load_dword v103, v[64:65], off offset:768
	global_load_dword v100, v[64:65], off offset:2048
	global_load_dword v101, v[64:65], off offset:2304
	global_load_dword v98, v[64:65], off offset:2560
	global_load_dword v99, v[64:65], off offset:2816
	v_add_co_u32_e32 v64, vcc, s1, v64
	s_waitcnt lgkmcnt(1)
	v_cvt_f32_f16_e32 v80, v248
	s_waitcnt lgkmcnt(0)
	v_cvt_f32_f16_e32 v81, v252
	v_cvt_f32_f16_sdwa v82, v248 dst_sel:DWORD dst_unused:UNUSED_PAD src0_sel:WORD_1
	v_cvt_f32_f16_sdwa v83, v252 dst_sel:DWORD dst_unused:UNUSED_PAD src0_sel:WORD_1
	v_addc_co_u32_e32 v65, vcc, 0, v65, vcc
	v_cvt_pk_bf16_f32 v118, v76, v77
	v_pk_mul_f32 v[92:93], v[94:95], v[82:83]
	global_load_dword v110, v[64:65], off
	global_load_dword v111, v[64:65], off offset:256
	global_load_dword v222, v[64:65], off offset:512
	global_load_dword v223, v[64:65], off offset:768
	global_load_dword v224, v[64:65], off offset:2048
	global_load_dword v225, v[64:65], off offset:2304
	global_load_dword v226, v[64:65], off offset:2560
	global_load_dword v227, v[64:65], off offset:2816
	v_pk_fma_f32 v[92:93], v[78:79], v[80:81], v[92:93] neg_lo:[0,0,1] neg_hi:[0,0,1]
	v_pk_mul_f32 v[78:79], v[78:79], v[82:83]
	v_cvt_pk_bf16_f32 v115, v92, v93
	v_pk_fma_f32 v[78:79], v[94:95], v[80:81], v[78:79]
	ds_read2_b64 v[106:109], v181 offset1:2
	ds_read2_b64 v[144:147], v181 offset0:4 offset1:6
	ds_read2_b64 v[80:83], v203 offset0:64 offset1:66
	ds_read2_b64 v[84:87], v204 offset0:128 offset1:130
	ds_read2_b64 v[148:151], v203 offset0:68 offset1:70
	ds_read2_b64 v[210:213], v204 offset0:132 offset1:134
	v_cvt_pk_bf16_f32 v119, v78, v79
	s_waitcnt lgkmcnt(5)
	v_mfma_f32_32x32x16_bf16 v[64:79], v[106:109], v[136:139], 0
	s_waitcnt lgkmcnt(2)
	v_mfma_f32_32x32x16_bf16 v[64:79], v[84:87], v[140:143], v[64:79]
	v_mfma_f32_32x32x16_bf16 v[80:95], v[80:83], v[136:139], 0
	v_mfma_f32_32x32x16_bf16 v[80:95], v[106:109], v[140:143], v[80:95]
	ds_read2_b64 v[106:109], v181 offset0:8 offset1:10
	ds_read2_b64 v[214:217], v203 offset0:72 offset1:74
	ds_read2_b64 v[218:221], v204 offset0:136 offset1:138
	s_waitcnt lgkmcnt(4)
	v_mfma_f32_32x32x16_bf16 v[80:95], v[148:151], v[132:135], v[80:95]
	v_mfma_f32_32x32x16_bf16 v[64:79], v[144:147], v[132:135], v[64:79]
	v_mfma_f32_32x32x16_bf16 v[80:95], v[144:147], v[128:131], v[80:95]
	s_waitcnt lgkmcnt(3)
	v_mfma_f32_32x32x16_bf16 v[64:79], v[210:213], v[128:131], v[64:79]
	ds_read2_b64 v[144:147], v181 offset0:12 offset1:14
	ds_read2_b64 v[148:151], v203 offset0:76 offset1:78
	ds_read2_b64 v[210:213], v204 offset0:140 offset1:142
	s_waitcnt lgkmcnt(4)
	v_mfma_f32_32x32x16_bf16 v[80:95], v[214:217], v[124:127], v[80:95]
	v_mfma_f32_32x32x16_bf16 v[64:79], v[106:109], v[124:127], v[64:79]
	v_mfma_f32_32x32x16_bf16 v[80:95], v[106:109], v[120:123], v[80:95]
	s_waitcnt lgkmcnt(3)
	v_mfma_f32_32x32x16_bf16 v[64:79], v[218:221], v[120:123], v[64:79]
	s_waitcnt lgkmcnt(1)
	v_mfma_f32_32x32x16_bf16 v[80:95], v[148:151], v[112:115], v[80:95]
	v_mfma_f32_32x32x16_bf16 v[64:79], v[144:147], v[112:115], v[64:79]
	v_mfma_f32_32x32x16_bf16 v[80:95], v[144:147], v[116:119], v[80:95]
	s_waitcnt lgkmcnt(0)
	v_mfma_f32_32x32x16_bf16 v[64:79], v[210:213], v[116:119], v[64:79]
	global_load_dword v217, v[96:97], off
	global_load_dword v218, v[96:97], off offset:256
	global_load_dword v215, v[96:97], off offset:512
	global_load_dword v216, v[96:97], off offset:768
	global_load_dword v213, v[96:97], off offset:2048
	global_load_dword v214, v[96:97], off offset:2304
	global_load_dword v211, v[96:97], off offset:2560
	global_load_dword v212, v[96:97], off offset:2816
	v_add_co_u32_e32 v96, vcc, s1, v96
	s_nop 1
	v_addc_co_u32_e32 v97, vcc, 0, v97, vcc
	global_load_dword v173, v[96:97], off
	global_load_dword v210, v[96:97], off offset:256
	global_load_dword v152, v[96:97], off offset:512
	global_load_dword v172, v[96:97], off offset:768
	global_load_dword v150, v[96:97], off offset:2048
	global_load_dword v151, v[96:97], off offset:2304
	global_load_dword v148, v[96:97], off offset:2560
	global_load_dword v149, v[96:97], off offset:2816
	s_waitcnt vmcnt(30)
	v_lshlrev_b32_e32 v97, 16, v105
	v_lshlrev_b32_e32 v96, 16, v104
	v_and_b32_e32 v105, 0xffff0000, v105
	v_and_b32_e32 v104, 0xffff0000, v104
	v_pk_mul_f32 v[106:107], v[80:81], v[104:105]
	v_pk_mul_f32 v[80:81], v[80:81], v[96:97]
	v_pk_fma_f32 v[106:107], v[64:65], v[96:97], v[106:107] neg_lo:[0,0,1] neg_hi:[0,0,1]
	s_waitcnt vmcnt(28)
	v_and_b32_e32 v97, 0xffff0000, v103
	v_and_b32_e32 v96, 0xffff0000, v102
	v_pk_fma_f32 v[64:65], v[64:65], v[104:105], v[80:81]
	v_lshlrev_b32_e32 v81, 16, v103
	v_lshlrev_b32_e32 v80, 16, v102
	v_pk_mul_f32 v[102:103], v[82:83], v[96:97]
	v_cvt_pk_bf16_f32 v104, v106, v107
	v_pk_fma_f32 v[102:103], v[66:67], v[80:81], v[102:103] neg_lo:[0,0,1] neg_hi:[0,0,1]
	v_pk_mul_f32 v[80:81], v[82:83], v[80:81]
	s_waitcnt vmcnt(26)
	v_and_b32_e32 v83, 0xffff0000, v101
	v_and_b32_e32 v82, 0xffff0000, v100
	v_pk_fma_f32 v[66:67], v[66:67], v[96:97], v[80:81]
	v_lshlrev_b32_e32 v81, 16, v101
	v_lshlrev_b32_e32 v80, 16, v100
	v_pk_mul_f32 v[96:97], v[84:85], v[82:83]
	v_cvt_pk_bf16_f32 v105, v102, v103
	v_pk_fma_f32 v[96:97], v[68:69], v[80:81], v[96:97] neg_lo:[0,0,1] neg_hi:[0,0,1]
	v_pk_mul_f32 v[80:81], v[84:85], v[80:81]
	v_cvt_pk_bf16_f32 v106, v96, v97
	v_pk_fma_f32 v[68:69], v[68:69], v[82:83], v[80:81]
	s_waitcnt vmcnt(24)
	v_and_b32_e32 v83, 0xffff0000, v99
	v_and_b32_e32 v82, 0xffff0000, v98
	v_lshlrev_b32_e32 v81, 16, v99
	v_lshlrev_b32_e32 v80, 16, v98
	v_pk_mul_f32 v[84:85], v[86:87], v[82:83]
	v_cvt_pk_bf16_f32 v108, v64, v65
	v_pk_fma_f32 v[84:85], v[70:71], v[80:81], v[84:85] neg_lo:[0,0,1] neg_hi:[0,0,1]
	v_pk_mul_f32 v[80:81], v[86:87], v[80:81]
	v_cvt_pk_bf16_f32 v107, v84, v85
	v_pk_fma_f32 v[70:71], v[70:71], v[82:83], v[80:81]
	s_waitcnt vmcnt(22)
	v_and_b32_e32 v83, 0xffff0000, v111
	v_and_b32_e32 v82, 0xffff0000, v110
	v_lshlrev_b32_e32 v81, 16, v111
	v_lshlrev_b32_e32 v80, 16, v110
	v_pk_mul_f32 v[86:87], v[88:89], v[82:83]
	v_cvt_pk_bf16_f32 v109, v66, v67
	v_pk_fma_f32 v[86:87], v[72:73], v[80:81], v[86:87] neg_lo:[0,0,1] neg_hi:[0,0,1]
	v_pk_mul_f32 v[80:81], v[88:89], v[80:81]
	v_cvt_pk_bf16_f32 v110, v68, v69
	v_pk_fma_f32 v[72:73], v[72:73], v[82:83], v[80:81]
	s_waitcnt vmcnt(20)
	v_and_b32_e32 v83, 0xffff0000, v223
	v_and_b32_e32 v82, 0xffff0000, v222
	v_lshlrev_b32_e32 v81, 16, v223
	v_lshlrev_b32_e32 v80, 16, v222
	v_pk_mul_f32 v[88:89], v[90:91], v[82:83]
	v_cvt_pk_bf16_f32 v111, v70, v71
	v_pk_fma_f32 v[88:89], v[74:75], v[80:81], v[88:89] neg_lo:[0,0,1] neg_hi:[0,0,1]
	v_pk_mul_f32 v[80:81], v[90:91], v[80:81]
	v_cvt_pk_bf16_f32 v96, v86, v87
	v_pk_fma_f32 v[74:75], v[74:75], v[82:83], v[80:81]
	s_waitcnt vmcnt(18)
	v_and_b32_e32 v83, 0xffff0000, v225
	v_and_b32_e32 v82, 0xffff0000, v224
	v_lshlrev_b32_e32 v81, 16, v225
	v_lshlrev_b32_e32 v80, 16, v224
	v_pk_mul_f32 v[90:91], v[92:93], v[82:83]
	v_cvt_pk_bf16_f32 v100, v72, v73
	v_pk_fma_f32 v[90:91], v[76:77], v[80:81], v[90:91] neg_lo:[0,0,1] neg_hi:[0,0,1]
	v_pk_mul_f32 v[80:81], v[92:93], v[80:81]
	v_cvt_pk_bf16_f32 v101, v74, v75
	v_pk_fma_f32 v[76:77], v[76:77], v[82:83], v[80:81]
	s_waitcnt vmcnt(16)
	v_and_b32_e32 v83, 0xffff0000, v227
	v_and_b32_e32 v82, 0xffff0000, v226
	v_lshlrev_b32_e32 v81, 16, v227
	v_lshlrev_b32_e32 v80, 16, v226
	v_pk_mul_f32 v[92:93], v[94:95], v[82:83]
	v_cvt_pk_bf16_f32 v102, v76, v77
	v_pk_fma_f32 v[92:93], v[78:79], v[80:81], v[92:93] neg_lo:[0,0,1] neg_hi:[0,0,1]
	v_pk_mul_f32 v[80:81], v[94:95], v[80:81]
	v_cvt_pk_bf16_f32 v97, v88, v89
	v_pk_fma_f32 v[78:79], v[78:79], v[82:83], v[80:81]
	ds_read2_b64 v[220:223], v183 offset1:2
	ds_read2_b64 v[144:147], v183 offset0:4 offset1:6
	ds_read2_b64 v[80:83], v205 offset0:64 offset1:66
	ds_read2_b64 v[84:87], v206 offset0:128 offset1:130
	ds_read2_b64 v[224:227], v205 offset0:68 offset1:70
	ds_read2_b64 v[228:231], v206 offset0:132 offset1:134
	v_cvt_pk_bf16_f32 v103, v78, v79
	s_waitcnt lgkmcnt(5)
	v_mfma_f32_32x32x16_bf16 v[64:79], v[220:223], v[136:139], 0
	v_cvt_pk_bf16_f32 v98, v90, v91
	v_cvt_pk_bf16_f32 v99, v92, v93
	s_and_b64 vcc, exec, s[20:21]
	s_mov_b64 s[20:21], 0
	s_waitcnt lgkmcnt(2)
	v_mfma_f32_32x32x16_bf16 v[64:79], v[84:87], v[140:143], v[64:79]
	v_mfma_f32_32x32x16_bf16 v[80:95], v[80:83], v[136:139], 0
	v_mfma_f32_32x32x16_bf16 v[80:95], v[220:223], v[140:143], v[80:95]
	ds_read2_b64 v[136:139], v183 offset0:8 offset1:10
	ds_read2_b64 v[140:143], v205 offset0:72 offset1:74
	ds_read2_b64 v[220:223], v206 offset0:136 offset1:138
	s_waitcnt lgkmcnt(4)
	v_mfma_f32_32x32x16_bf16 v[80:95], v[224:227], v[132:135], v[80:95]
	v_mfma_f32_32x32x16_bf16 v[64:79], v[144:147], v[132:135], v[64:79]
	v_mfma_f32_32x32x16_bf16 v[80:95], v[144:147], v[128:131], v[80:95]
	s_waitcnt lgkmcnt(3)
	v_mfma_f32_32x32x16_bf16 v[64:79], v[228:231], v[128:131], v[64:79]
	ds_read2_b64 v[128:131], v183 offset0:12 offset1:14
	ds_read2_b64 v[132:135], v205 offset0:76 offset1:78
	ds_read2_b64 v[144:147], v206 offset0:140 offset1:142
	s_waitcnt lgkmcnt(4)
	v_mfma_f32_32x32x16_bf16 v[80:95], v[140:143], v[124:127], v[80:95]
	v_mfma_f32_32x32x16_bf16 v[64:79], v[136:139], v[124:127], v[64:79]
	v_mfma_f32_32x32x16_bf16 v[80:95], v[136:139], v[120:123], v[80:95]
	s_waitcnt lgkmcnt(3)
	v_mfma_f32_32x32x16_bf16 v[64:79], v[220:223], v[120:123], v[64:79]
	s_waitcnt lgkmcnt(1)
	v_mfma_f32_32x32x16_bf16 v[80:95], v[132:135], v[112:115], v[80:95]
	v_mfma_f32_32x32x16_bf16 v[64:79], v[128:131], v[112:115], v[64:79]
	s_waitcnt vmcnt(14)
	v_and_b32_e32 v115, 0xffff0000, v218
	v_and_b32_e32 v114, 0xffff0000, v217
	v_lshlrev_b32_e32 v113, 16, v218
	v_lshlrev_b32_e32 v112, 16, v217
	v_mfma_f32_32x32x16_bf16 v[80:95], v[128:131], v[116:119], v[80:95]
	s_waitcnt lgkmcnt(0)
	v_mfma_f32_32x32x16_bf16 v[64:79], v[144:147], v[116:119], v[64:79]
	s_nop 9
	v_mul_f32_e64 v116, v80, v114
	v_mul_f32_e64 v117, v81, v115
	v_mul_f32_e64 v80, v80, v112
	v_mul_f32_e64 v81, v81, v113
	v_pk_fma_f32 v[116:117], v[64:65], v[112:113], v[116:117] neg_lo:[0,0,1] neg_hi:[0,0,1]
	s_waitcnt vmcnt(12)
	v_and_b32_e32 v113, 0xffff0000, v216
	v_and_b32_e32 v112, 0xffff0000, v215
	v_pk_fma_f32 v[64:65], v[64:65], v[114:115], v[80:81]
	v_lshlrev_b32_e32 v81, 16, v216
	v_lshlrev_b32_e32 v80, 16, v215
	v_pk_mul_f32 v[114:115], v[82:83], v[112:113]
	v_cvt_pk_bf16_f32 v120, v64, v65
	v_pk_fma_f32 v[114:115], v[66:67], v[80:81], v[114:115] neg_lo:[0,0,1] neg_hi:[0,0,1]
	v_pk_mul_f32 v[80:81], v[82:83], v[80:81]
	s_waitcnt vmcnt(10)
	v_and_b32_e32 v83, 0xffff0000, v214
	v_and_b32_e32 v82, 0xffff0000, v213
	v_pk_fma_f32 v[66:67], v[66:67], v[112:113], v[80:81]
	v_lshlrev_b32_e32 v81, 16, v214
	v_lshlrev_b32_e32 v80, 16, v213
	v_pk_mul_f32 v[112:113], v[84:85], v[82:83]
	v_cvt_pk_bf16_f32 v121, v66, v67
	v_pk_fma_f32 v[118:119], v[68:69], v[80:81], v[112:113] neg_lo:[0,0,1] neg_hi:[0,0,1]
	v_pk_mul_f32 v[80:81], v[84:85], v[80:81]
	v_cvt_pk_bf16_f32 v112, v116, v117
	v_pk_fma_f32 v[68:69], v[68:69], v[82:83], v[80:81]
	s_waitcnt vmcnt(8)
	v_and_b32_e32 v83, 0xffff0000, v212
	v_and_b32_e32 v82, 0xffff0000, v211
	v_lshlrev_b32_e32 v81, 16, v212
	v_lshlrev_b32_e32 v80, 16, v211
	v_pk_mul_f32 v[84:85], v[86:87], v[82:83]
	v_cvt_pk_bf16_f32 v113, v114, v115
	v_pk_fma_f32 v[84:85], v[70:71], v[80:81], v[84:85] neg_lo:[0,0,1] neg_hi:[0,0,1]
	v_pk_mul_f32 v[80:81], v[86:87], v[80:81]
	v_cvt_pk_bf16_f32 v115, v84, v85
	v_pk_fma_f32 v[70:71], v[70:71], v[82:83], v[80:81]
	s_waitcnt vmcnt(6)
	v_and_b32_e32 v83, 0xffff0000, v210
	v_and_b32_e32 v82, 0xffff0000, v173
	v_lshlrev_b32_e32 v81, 16, v210
	v_lshlrev_b32_e32 v80, 16, v173
	v_pk_mul_f32 v[86:87], v[88:89], v[82:83]
	v_cvt_pk_bf16_f32 v122, v68, v69
	v_pk_fma_f32 v[86:87], v[72:73], v[80:81], v[86:87] neg_lo:[0,0,1] neg_hi:[0,0,1]
	v_pk_mul_f32 v[80:81], v[88:89], v[80:81]
	v_cvt_pk_bf16_f32 v123, v70, v71
	v_pk_fma_f32 v[72:73], v[72:73], v[82:83], v[80:81]
	s_waitcnt vmcnt(4)
	v_and_b32_e32 v83, 0xffff0000, v172
	v_and_b32_e32 v82, 0xffff0000, v152
	v_lshlrev_b32_e32 v81, 16, v172
	v_lshlrev_b32_e32 v80, 16, v152
	v_pk_mul_f32 v[88:89], v[90:91], v[82:83]
	v_cvt_pk_bf16_f32 v116, v86, v87
	v_pk_fma_f32 v[88:89], v[74:75], v[80:81], v[88:89] neg_lo:[0,0,1] neg_hi:[0,0,1]
	v_pk_mul_f32 v[80:81], v[90:91], v[80:81]
	v_cvt_pk_bf16_f32 v124, v72, v73
	v_pk_fma_f32 v[74:75], v[74:75], v[82:83], v[80:81]
	s_waitcnt vmcnt(2)
	v_and_b32_e32 v83, 0xffff0000, v151
	v_and_b32_e32 v82, 0xffff0000, v150
	v_lshlrev_b32_e32 v81, 16, v151
	v_lshlrev_b32_e32 v80, 16, v150
	v_pk_mul_f32 v[90:91], v[92:93], v[82:83]
	v_cvt_pk_bf16_f32 v125, v74, v75
	v_pk_fma_f32 v[90:91], v[76:77], v[80:81], v[90:91] neg_lo:[0,0,1] neg_hi:[0,0,1]
	v_pk_mul_f32 v[80:81], v[92:93], v[80:81]
	v_cvt_pk_bf16_f32 v114, v118, v119
	v_pk_fma_f32 v[76:77], v[76:77], v[82:83], v[80:81]
	s_waitcnt vmcnt(0)
	v_and_b32_e32 v83, 0xffff0000, v149
	v_and_b32_e32 v82, 0xffff0000, v148
	v_lshlrev_b32_e32 v81, 16, v149
	v_lshlrev_b32_e32 v80, 16, v148
	v_pk_mul_f32 v[92:93], v[94:95], v[82:83]
	v_cvt_pk_bf16_f32 v126, v76, v77
	v_pk_fma_f32 v[92:93], v[78:79], v[80:81], v[92:93] neg_lo:[0,0,1] neg_hi:[0,0,1]
	v_pk_mul_f32 v[80:81], v[94:95], v[80:81]
	v_cvt_pk_bf16_f32 v117, v88, v89
	v_pk_fma_f32 v[78:79], v[78:79], v[82:83], v[80:81]
	ds_read2_b64 v[80:83], v181 offset1:2
	ds_read2_b64 v[128:131], v181 offset0:4 offset1:6
	ds_read2_b64 v[84:87], v203 offset0:64 offset1:66
	ds_read2_b64 v[132:135], v204 offset0:128 offset1:130
	ds_read2_b64 v[136:139], v203 offset0:68 offset1:70
	ds_read2_b64 v[140:143], v204 offset0:132 offset1:134
	v_cvt_pk_bf16_f32 v127, v78, v79
	s_waitcnt lgkmcnt(5)
	v_mfma_f32_32x32x16_bf16 v[64:79], v[104:107], v[80:83], 0
	v_cvt_pk_bf16_f32 v118, v90, v91
	v_cvt_pk_bf16_f32 v119, v92, v93
	v_or_b32_e32 v152, s2, v177
	v_mul_u32_u24_e32 v172, v152, v175
	v_lshl_add_u32 v210, v152, 1, v180
	v_lshl_add_u32 v172, v172, 2, s24
	s_waitcnt lgkmcnt(3)
	v_mfma_f32_32x32x16_bf16 v[64:79], v[108:111], v[84:87], v[64:79]
	v_add_u32_e32 v211, 0x2000, v210
	v_add_u32_e32 v212, 0x4000, v210
	v_add_u32_e32 v213, v172, v207
	s_mov_b32 s2, 32
	v_mfma_f32_32x32x16_bf16 v[80:95], v[108:111], v[80:83], 0
	s_waitcnt lgkmcnt(2)
	v_mfma_f32_32x32x16_bf16 v[80:95], v[104:107], v[132:135], v[80:95]
	ds_read2_b64 v[132:135], v181 offset0:8 offset1:10
	ds_read2_b64 v[144:147], v203 offset0:72 offset1:74
	ds_read2_b64 v[148:151], v204 offset0:136 offset1:138
	v_mfma_f32_32x32x16_bf16 v[64:79], v[96:99], v[128:131], v[64:79]
	v_mfma_f32_32x32x16_bf16 v[80:95], v[100:103], v[128:131], v[80:95]
	s_waitcnt lgkmcnt(4)
	v_mfma_f32_32x32x16_bf16 v[64:79], v[100:103], v[136:139], v[64:79]
	s_waitcnt lgkmcnt(3)
	v_mfma_f32_32x32x16_bf16 v[80:95], v[96:99], v[140:143], v[80:95]
	ds_read2_b64 v[128:131], v181 offset0:12 offset1:14
	ds_read2_b64 v[136:139], v203 offset0:76 offset1:78
	ds_read2_b64 v[140:143], v204 offset0:140 offset1:142
	s_waitcnt lgkmcnt(5)
	v_mfma_f32_32x32x16_bf16 v[64:79], v[112:115], v[132:135], v[64:79]
	v_mfma_f32_32x32x16_bf16 v[80:95], v[120:123], v[132:135], v[80:95]
	s_waitcnt lgkmcnt(4)
	v_mfma_f32_32x32x16_bf16 v[64:79], v[120:123], v[144:147], v[64:79]
	s_waitcnt lgkmcnt(3)
	v_mfma_f32_32x32x16_bf16 v[80:95], v[112:115], v[148:151], v[80:95]
	s_waitcnt lgkmcnt(2)
	v_mfma_f32_32x32x16_bf16 v[64:79], v[116:119], v[128:131], v[64:79]
	v_mfma_f32_32x32x16_bf16 v[80:95], v[124:127], v[128:131], v[80:95]
	s_waitcnt lgkmcnt(1)
	v_mfma_f32_32x32x16_bf16 v[64:79], v[124:127], v[136:139], v[64:79]
	s_waitcnt lgkmcnt(0)
	v_mfma_f32_32x32x16_bf16 v[80:95], v[116:119], v[140:143], v[80:95]
	ds_read2_b64 v[140:143], v210 offset1:2
	ds_read2_b64 v[128:131], v210 offset0:4 offset1:6
	ds_read2_b64 v[148:151], v211 offset0:64 offset1:66
	ds_read2_b64 v[144:147], v212 offset0:128 offset1:130
	ds_read2_b64 v[136:139], v211 offset0:68 offset1:70
	ds_read2_b64 v[132:135], v212 offset0:132 offset1:134
	ds_read_b32 v241, v172
	ds_read_b32 v246, v213
	v_add_u32_e32 v239, v213, v207
	v_add_u32_e32 v238, v239, v207
	ds_read_b32 v244, v239
	ds_read_b32 v245, v238
	v_add_u32_e32 v253, v238, v186
	v_add_u32_e32 v237, v253, v207
	ds_read_b32 v240, v253
	ds_read_b32 v247, v237
	v_add_u32_e32 v250, v237, v207
	v_add_u32_e32 v234, v250, v207
	ds_read_b32 v242, v250
	ds_read_b32 v249, v234
	s_waitcnt lgkmcnt(7)
	s_waitcnt lgkmcnt(6)
	v_add_u32_e32 v236, v234, v186
	v_add_u32_e32 v243, v236, v207
	ds_read_b32 v235, v236
	ds_read_b32 v251, v243
	v_add_u32_e32 v233, v243, v207
	v_add_u32_e32 v248, v233, v207
	ds_read_b32 v252, v233
	ds_read_b32 v239, v248
	v_add_u32_e32 v238, v248, v186
	v_add_u32_e32 v253, v238, v207
	ds_read_b32 v237, v238
	ds_read_b32 v250, v253
	v_add_u32_e32 v234, v253, v207
	ds_read_b32 v236, v234
	v_add_u32_e32 v243, v234, v207
	ds_read_b32 v233, v243
	v_cvt_f32_f16_sdwa v216, v241 dst_sel:DWORD dst_unused:UNUSED_PAD src0_sel:WORD_1
	s_waitcnt lgkmcnt(14)
	v_cvt_f32_f16_sdwa v217, v246 dst_sel:DWORD dst_unused:UNUSED_PAD src0_sel:WORD_1
	v_cvt_f32_f16_e32 v215, v246
	v_cvt_f32_f16_e32 v214, v241
	v_pk_mul_f32 v[172:173], v[64:65], v[216:217]
	s_nop 0
	v_pk_fma_f32 v[172:173], v[80:81], v[214:215], v[172:173] neg_lo:[0,0,1] neg_hi:[0,0,1]
	v_pk_mul_f32 v[80:81], v[80:81], v[216:217]
	s_nop 0
	v_pk_fma_f32 v[64:65], v[64:65], v[214:215], v[80:81]
	v_cvt_pk_bf16_f32 v64, v64, v65
	s_waitcnt lgkmcnt(13)
	v_cvt_f32_f16_sdwa v216, v244 dst_sel:DWORD dst_unused:UNUSED_PAD src0_sel:WORD_1
	s_waitcnt lgkmcnt(12)
	v_cvt_f32_f16_sdwa v217, v245 dst_sel:DWORD dst_unused:UNUSED_PAD src0_sel:WORD_1
	v_cvt_f32_f16_e32 v215, v245
	v_cvt_f32_f16_e32 v214, v244
	v_pk_mul_f32 v[80:81], v[66:67], v[216:217]
	s_nop 0
	v_pk_fma_f32 v[80:81], v[82:83], v[214:215], v[80:81] neg_lo:[0,0,1] neg_hi:[0,0,1]
	v_pk_mul_f32 v[82:83], v[82:83], v[216:217]
	s_nop 0
	v_pk_fma_f32 v[66:67], v[66:67], v[214:215], v[82:83]
	v_cvt_pk_bf16_f32 v65, v66, v67
	s_waitcnt lgkmcnt(11)
	v_cvt_f32_f16_sdwa v216, v240 dst_sel:DWORD dst_unused:UNUSED_PAD src0_sel:WORD_1
	s_waitcnt lgkmcnt(10)
	v_cvt_f32_f16_sdwa v217, v247 dst_sel:DWORD dst_unused:UNUSED_PAD src0_sel:WORD_1
	v_cvt_f32_f16_e32 v215, v247
	v_cvt_f32_f16_e32 v214, v240
	v_pk_mul_f32 v[82:83], v[68:69], v[216:217]
	s_nop 0
	v_pk_fma_f32 v[82:83], v[84:85], v[214:215], v[82:83] neg_lo:[0,0,1] neg_hi:[0,0,1]
	v_pk_mul_f32 v[84:85], v[84:85], v[216:217]
	s_nop 0
	v_pk_fma_f32 v[68:69], v[68:69], v[214:215], v[84:85]
	v_cvt_pk_bf16_f32 v66, v68, v69
	v_cvt_pk_bf16_f32 v68, v172, v173
	v_cvt_pk_bf16_f32 v69, v80, v81
	s_waitcnt lgkmcnt(9)
	v_cvt_f32_f16_e32 v84, v242
	s_waitcnt lgkmcnt(8)
	v_cvt_f32_f16_e32 v85, v249
	v_cvt_f32_f16_sdwa v215, v249 dst_sel:DWORD dst_unused:UNUSED_PAD src0_sel:WORD_1
	v_cvt_f32_f16_sdwa v214, v242 dst_sel:DWORD dst_unused:UNUSED_PAD src0_sel:WORD_1
	v_pk_mul_f32 v[216:217], v[70:71], v[214:215]
	s_nop 0
	v_pk_fma_f32 v[216:217], v[86:87], v[84:85], v[216:217] neg_lo:[0,0,1] neg_hi:[0,0,1]
	v_pk_mul_f32 v[86:87], v[86:87], v[214:215]
	s_nop 0
	v_pk_fma_f32 v[70:71], v[70:71], v[84:85], v[86:87]
	v_cvt_pk_bf16_f32 v67, v70, v71
	v_cvt_pk_bf16_f32 v70, v82, v83
	v_cvt_pk_bf16_f32 v71, v216, v217
	s_waitcnt lgkmcnt(7)
	v_cvt_f32_f16_e32 v84, v235
	s_waitcnt lgkmcnt(6)
	v_cvt_f32_f16_e32 v85, v251
	v_cvt_f32_f16_sdwa v87, v251 dst_sel:DWORD dst_unused:UNUSED_PAD src0_sel:WORD_1
	v_cvt_f32_f16_sdwa v86, v235 dst_sel:DWORD dst_unused:UNUSED_PAD src0_sel:WORD_1
	v_mfma_f32_32x32x16_bf16 v[48:63], v[140:143], v[64:67], v[48:63]
	v_mul_f32_e64 v214, v72, v86
	v_mul_f32_e64 v215, v73, v87
	v_mul_f32_e64 v86, v88, v86
	v_mul_f32_e64 v87, v89, v87
	v_fma_f32 v214, v88, v84, -v214
	v_fma_f32 v215, v89, v85, -v215
	v_pk_fma_f32 v[72:73], v[72:73], v[84:85], v[86:87]
	v_mfma_f32_32x32x16_bf16 v[32:47], v[140:143], v[68:71], v[32:47]
	s_waitcnt lgkmcnt(5)
	v_cvt_f32_f16_e32 v84, v252
	s_waitcnt lgkmcnt(4)
	v_cvt_f32_f16_e32 v85, v239
	v_cvt_f32_f16_sdwa v87, v239 dst_sel:DWORD dst_unused:UNUSED_PAD src0_sel:WORD_1
	v_cvt_f32_f16_sdwa v86, v252 dst_sel:DWORD dst_unused:UNUSED_PAD src0_sel:WORD_1
	v_pk_mul_f32 v[88:89], v[74:75], v[86:87]
	v_pk_mul_f32 v[86:87], v[90:91], v[86:87]
	v_pk_fma_f32 v[88:89], v[90:91], v[84:85], v[88:89] neg_lo:[0,0,1] neg_hi:[0,0,1]
	v_pk_fma_f32 v[74:75], v[74:75], v[84:85], v[86:87]
	v_mfma_f32_32x32x16_bf16 v[48:63], v[148:151], v[68:71], v[48:63]
	v_cvt_pk_bf16_f32 v68, v214, v215
	v_cvt_pk_bf16_f32 v69, v88, v89
	s_waitcnt lgkmcnt(3)
	v_cvt_f32_f16_e32 v84, v237
	s_waitcnt lgkmcnt(2)
	v_cvt_f32_f16_e32 v85, v250
	v_cvt_f32_f16_sdwa v87, v250 dst_sel:DWORD dst_unused:UNUSED_PAD src0_sel:WORD_1
	v_cvt_f32_f16_sdwa v86, v237 dst_sel:DWORD dst_unused:UNUSED_PAD src0_sel:WORD_1
	v_pk_mul_f32 v[90:91], v[76:77], v[86:87]
	v_pk_mul_f32 v[86:87], v[92:93], v[86:87]
	v_pk_fma_f32 v[90:91], v[92:93], v[84:85], v[90:91] neg_lo:[0,0,1] neg_hi:[0,0,1]
	v_pk_fma_f32 v[76:77], v[76:77], v[84:85], v[86:87]
	v_mfma_f32_32x32x16_bf16 v[32:47], v[144:147], v[64:67], v[32:47]
	v_cvt_pk_bf16_f32 v64, v72, v73
	s_waitcnt lgkmcnt(1)
	v_cvt_f32_f16_e32 v84, v236
	v_cvt_f32_f16_sdwa v86, v236 dst_sel:DWORD dst_unused:UNUSED_PAD src0_sel:WORD_1
	s_waitcnt lgkmcnt(0)
	v_cvt_f32_f16_e32 v85, v233
	v_cvt_f32_f16_sdwa v87, v233 dst_sel:DWORD dst_unused:UNUSED_PAD src0_sel:WORD_1
	v_cvt_pk_bf16_f32 v65, v74, v75
	v_cvt_pk_bf16_f32 v66, v76, v77
	v_cvt_pk_bf16_f32 v70, v90, v91
	v_pk_mul_f32 v[92:93], v[78:79], v[86:87]
	v_pk_mul_f32 v[86:87], v[94:95], v[86:87]
	v_pk_fma_f32 v[92:93], v[94:95], v[84:85], v[92:93] neg_lo:[0,0,1] neg_hi:[0,0,1]
	v_pk_fma_f32 v[78:79], v[78:79], v[84:85], v[86:87]
	v_cvt_pk_bf16_f32 v71, v92, v93
	v_cvt_pk_bf16_f32 v67, v78, v79
	s_nop 0
	v_mfma_f32_32x32x16_bf16 v[32:47], v[128:131], v[68:71], v[32:47]
	v_mfma_f32_32x32x16_bf16 v[48:63], v[128:131], v[64:67], v[48:63]
	v_mfma_f32_32x32x16_bf16 v[48:63], v[136:139], v[68:71], v[48:63]
	v_mfma_f32_32x32x16_bf16 v[32:47], v[132:135], v[64:67], v[32:47]
	ds_read2_b64 v[80:83], v183 offset1:2
	ds_read2_b64 v[132:135], v183 offset0:4 offset1:6
	ds_read2_b64 v[84:87], v205 offset0:64 offset1:66
	ds_read2_b64 v[128:131], v206 offset0:128 offset1:130
	ds_read2_b64 v[136:139], v205 offset0:68 offset1:70
	ds_read2_b64 v[140:143], v206 offset0:132 offset1:134
	s_waitcnt lgkmcnt(5)
	v_mfma_f32_32x32x16_bf16 v[64:79], v[104:107], v[80:83], 0
	s_waitcnt lgkmcnt(3)
	v_mfma_f32_32x32x16_bf16 v[64:79], v[108:111], v[84:87], v[64:79]
	v_mfma_f32_32x32x16_bf16 v[80:95], v[108:111], v[80:83], 0
	s_waitcnt lgkmcnt(2)
	v_mfma_f32_32x32x16_bf16 v[80:95], v[104:107], v[128:131], v[80:95]
	ds_read2_b64 v[104:107], v183 offset0:8 offset1:10
	ds_read2_b64 v[128:131], v205 offset0:72 offset1:74
	ds_read2_b64 v[108:111], v206 offset0:136 offset1:138
	v_mfma_f32_32x32x16_bf16 v[64:79], v[96:99], v[132:135], v[64:79]
	v_mfma_f32_32x32x16_bf16 v[80:95], v[100:103], v[132:135], v[80:95]
	s_waitcnt lgkmcnt(4)
	v_mfma_f32_32x32x16_bf16 v[64:79], v[100:103], v[136:139], v[64:79]
	s_waitcnt lgkmcnt(3)
	v_mfma_f32_32x32x16_bf16 v[80:95], v[96:99], v[140:143], v[80:95]
	ds_read2_b64 v[96:99], v183 offset0:12 offset1:14
	ds_read2_b64 v[100:103], v205 offset0:76 offset1:78
	ds_read2_b64 v[132:135], v206 offset0:140 offset1:142
	s_waitcnt lgkmcnt(5)
	v_mfma_f32_32x32x16_bf16 v[64:79], v[112:115], v[104:107], v[64:79]
	v_mfma_f32_32x32x16_bf16 v[80:95], v[120:123], v[104:107], v[80:95]
	s_waitcnt lgkmcnt(4)
	v_mfma_f32_32x32x16_bf16 v[64:79], v[120:123], v[128:131], v[64:79]
	v_mul_u32_u24_e32 v120, v152, v182
	v_lshl_add_u32 v120, v120, 2, s24
	s_waitcnt lgkmcnt(3)
	v_mfma_f32_32x32x16_bf16 v[80:95], v[112:115], v[108:111], v[80:95]
	s_waitcnt lgkmcnt(2)
	v_mfma_f32_32x32x16_bf16 v[64:79], v[116:119], v[96:99], v[64:79]
	v_mfma_f32_32x32x16_bf16 v[80:95], v[124:127], v[96:99], v[80:95]
	s_waitcnt lgkmcnt(1)
	v_mfma_f32_32x32x16_bf16 v[64:79], v[124:127], v[100:103], v[64:79]
	v_add_u32_e32 v126, v120, v208
	s_waitcnt lgkmcnt(0)
	v_mfma_f32_32x32x16_bf16 v[80:95], v[116:119], v[132:135], v[80:95]
	ds_read2_b64 v[112:115], v210 offset1:2
	ds_read2_b64 v[100:103], v210 offset0:4 offset1:6
	ds_read2_b64 v[116:119], v211 offset0:64 offset1:66
	ds_read2_b64 v[108:111], v212 offset0:128 offset1:130
	ds_read2_b64 v[104:107], v211 offset0:68 offset1:70
	ds_read2_b64 v[96:99], v212 offset0:132 offset1:134
	ds_read_b32 v248, v120
	ds_read_b32 v238, v126
	v_add_u32_e32 v253, v126, v208
	v_add_u32_e32 v234, v253, v208
	ds_read_b32 v243, v253
	ds_read_b32 v241, v234
	v_add_u32_e32 v246, v234, v187
	v_add_u32_e32 v244, v246, v208
	ds_read_b32 v245, v246
	ds_read_b32 v240, v244
	v_add_u32_e32 v247, v244, v208
	v_add_u32_e32 v242, v247, v208
	ds_read_b32 v249, v247
	ds_read_b32 v235, v242
	s_waitcnt lgkmcnt(7)
	s_waitcnt lgkmcnt(6)
	v_add_u32_e32 v251, v242, v187
	v_add_u32_e32 v252, v251, v208
	ds_read_b32 v239, v251
	ds_read_b32 v237, v252
	v_add_u32_e32 v250, v252, v208
	v_add_u32_e32 v236, v250, v208
	ds_read_b32 v233, v250
	ds_read_b32 v253, v236
	v_add_u32_e32 v234, v236, v187
	v_add_u32_e32 v246, v234, v208
	ds_read_b32 v244, v234
	ds_read_b32 v247, v246
	v_add_u32_e32 v242, v246, v208
	ds_read_b32 v251, v242
	v_add_u32_e32 v252, v242, v208
	ds_read_b32 v250, v252
	v_cvt_f32_f16_sdwa v124, v248 dst_sel:DWORD dst_unused:UNUSED_PAD src0_sel:WORD_1
	s_waitcnt lgkmcnt(14)
	v_cvt_f32_f16_sdwa v125, v238 dst_sel:DWORD dst_unused:UNUSED_PAD src0_sel:WORD_1
	v_cvt_f32_f16_e32 v123, v238
	v_cvt_f32_f16_e32 v122, v248
	v_pk_mul_f32 v[120:121], v[64:65], v[124:125]
	s_nop 0
	v_pk_fma_f32 v[120:121], v[80:81], v[122:123], v[120:121] neg_lo:[0,0,1] neg_hi:[0,0,1]
	v_pk_mul_f32 v[80:81], v[80:81], v[124:125]
	s_nop 0
	v_pk_fma_f32 v[80:81], v[64:65], v[122:123], v[80:81]
	v_cvt_pk_bf16_f32 v80, v80, v81
	s_waitcnt lgkmcnt(13)
	v_cvt_f32_f16_sdwa v124, v243 dst_sel:DWORD dst_unused:UNUSED_PAD src0_sel:WORD_1
	s_waitcnt lgkmcnt(12)
	v_cvt_f32_f16_sdwa v125, v241 dst_sel:DWORD dst_unused:UNUSED_PAD src0_sel:WORD_1
	v_cvt_f32_f16_e32 v65, v241
	v_cvt_f32_f16_e32 v64, v243
	v_pk_mul_f32 v[122:123], v[66:67], v[124:125]
	s_nop 0
	v_pk_fma_f32 v[122:123], v[82:83], v[64:65], v[122:123] neg_lo:[0,0,1] neg_hi:[0,0,1]
	v_pk_mul_f32 v[82:83], v[82:83], v[124:125]
	s_nop 0
	v_pk_fma_f32 v[82:83], v[66:67], v[64:65], v[82:83]
	v_cvt_pk_bf16_f32 v81, v82, v83
	s_waitcnt lgkmcnt(11)
	v_cvt_f32_f16_e32 v64, v245
	s_waitcnt lgkmcnt(10)
	v_cvt_f32_f16_e32 v65, v240
	v_cvt_f32_f16_sdwa v67, v240 dst_sel:DWORD dst_unused:UNUSED_PAD src0_sel:WORD_1
	v_cvt_f32_f16_sdwa v66, v245 dst_sel:DWORD dst_unused:UNUSED_PAD src0_sel:WORD_1
	v_pk_mul_f32 v[124:125], v[68:69], v[66:67]
	v_pk_mul_f32 v[66:67], v[84:85], v[66:67]
	v_pk_fma_f32 v[124:125], v[84:85], v[64:65], v[124:125] neg_lo:[0,0,1] neg_hi:[0,0,1]
	v_pk_fma_f32 v[84:85], v[68:69], v[64:65], v[66:67]
	v_cvt_pk_bf16_f32 v82, v84, v85
	v_cvt_pk_bf16_f32 v84, v120, v121
	v_cvt_pk_bf16_f32 v85, v122, v123
	s_waitcnt lgkmcnt(9)
	v_cvt_f32_f16_e32 v64, v249
	s_waitcnt lgkmcnt(8)
	v_cvt_f32_f16_e32 v65, v235
	v_cvt_f32_f16_sdwa v67, v235 dst_sel:DWORD dst_unused:UNUSED_PAD src0_sel:WORD_1
	v_cvt_f32_f16_sdwa v66, v249 dst_sel:DWORD dst_unused:UNUSED_PAD src0_sel:WORD_1
	v_pk_mul_f32 v[68:69], v[70:71], v[66:67]
	v_pk_mul_f32 v[66:67], v[86:87], v[66:67]
	v_pk_fma_f32 v[126:127], v[86:87], v[64:65], v[68:69] neg_lo:[0,0,1] neg_hi:[0,0,1]
	v_pk_fma_f32 v[86:87], v[70:71], v[64:65], v[66:67]
	v_cvt_pk_bf16_f32 v83, v86, v87
	v_cvt_pk_bf16_f32 v86, v124, v125
	v_cvt_pk_bf16_f32 v87, v126, v127
	s_waitcnt lgkmcnt(7)
	v_cvt_f32_f16_sdwa v68, v239 dst_sel:DWORD dst_unused:UNUSED_PAD src0_sel:WORD_1
	s_waitcnt lgkmcnt(6)
	v_cvt_f32_f16_sdwa v69, v237 dst_sel:DWORD dst_unused:UNUSED_PAD src0_sel:WORD_1
	v_cvt_f32_f16_e32 v67, v237
	v_cvt_f32_f16_e32 v66, v239
	v_mfma_f32_32x32x16_bf16 v[16:31], v[112:115], v[80:83], v[16:31]
	v_mul_f32_e64 v64, v72, v68
	v_mul_f32_e64 v65, v73, v69
	v_mul_f32_e64 v68, v88, v68
	v_mul_f32_e64 v69, v89, v69
	v_fma_f32 v64, v88, v66, -v64
	v_fma_f32 v65, v89, v67, -v65
	v_pk_fma_f32 v[66:67], v[72:73], v[66:67], v[68:69]
	v_mfma_f32_32x32x16_bf16 v[0:15], v[112:115], v[84:87], v[0:15]
	v_cvt_pk_bf16_f32 v64, v64, v65
	s_waitcnt lgkmcnt(5)
	v_cvt_f32_f16_sdwa v72, v233 dst_sel:DWORD dst_unused:UNUSED_PAD src0_sel:WORD_1
	s_waitcnt lgkmcnt(4)
	v_cvt_f32_f16_sdwa v73, v253 dst_sel:DWORD dst_unused:UNUSED_PAD src0_sel:WORD_1
	v_cvt_f32_f16_e32 v71, v253
	v_cvt_f32_f16_e32 v70, v233
	v_pk_mul_f32 v[68:69], v[74:75], v[72:73]
	v_pk_mul_f32 v[72:73], v[90:91], v[72:73]
	v_pk_fma_f32 v[68:69], v[90:91], v[70:71], v[68:69] neg_lo:[0,0,1] neg_hi:[0,0,1]
	v_pk_fma_f32 v[70:71], v[74:75], v[70:71], v[72:73]
	v_mfma_f32_32x32x16_bf16 v[16:31], v[116:119], v[84:87], v[16:31]
	v_cvt_pk_bf16_f32 v65, v68, v69
	s_waitcnt lgkmcnt(3)
	v_cvt_f32_f16_sdwa v88, v244 dst_sel:DWORD dst_unused:UNUSED_PAD src0_sel:WORD_1
	s_waitcnt lgkmcnt(2)
	v_cvt_f32_f16_sdwa v89, v247 dst_sel:DWORD dst_unused:UNUSED_PAD src0_sel:WORD_1
	v_cvt_f32_f16_e32 v75, v247
	v_cvt_f32_f16_e32 v74, v244
	v_pk_mul_f32 v[72:73], v[76:77], v[88:89]
	v_pk_mul_f32 v[88:89], v[92:93], v[88:89]
	v_pk_fma_f32 v[72:73], v[92:93], v[74:75], v[72:73] neg_lo:[0,0,1] neg_hi:[0,0,1]
	v_pk_fma_f32 v[74:75], v[76:77], v[74:75], v[88:89]
	v_mfma_f32_32x32x16_bf16 v[0:15], v[108:111], v[80:83], v[0:15]
	v_cvt_pk_bf16_f32 v80, v66, v67
	s_waitcnt lgkmcnt(1)
	v_cvt_f32_f16_sdwa v90, v251 dst_sel:DWORD dst_unused:UNUSED_PAD src0_sel:WORD_1
	v_cvt_f32_f16_e32 v88, v251
	s_waitcnt lgkmcnt(0)
	v_cvt_f32_f16_sdwa v91, v250 dst_sel:DWORD dst_unused:UNUSED_PAD src0_sel:WORD_1
	v_cvt_f32_f16_e32 v89, v250
	v_cvt_pk_bf16_f32 v81, v70, v71
	v_cvt_pk_bf16_f32 v82, v74, v75
	v_pk_mul_f32 v[76:77], v[78:79], v[90:91]
	v_pk_mul_f32 v[90:91], v[94:95], v[90:91]
	v_pk_fma_f32 v[76:77], v[94:95], v[88:89], v[76:77] neg_lo:[0,0,1] neg_hi:[0,0,1]
	v_pk_fma_f32 v[78:79], v[78:79], v[88:89], v[90:91]
	v_cvt_pk_bf16_f32 v66, v72, v73
	v_cvt_pk_bf16_f32 v83, v78, v79
	v_cvt_pk_bf16_f32 v67, v76, v77
	s_nop 0
	v_mfma_f32_32x32x16_bf16 v[16:31], v[100:103], v[80:83], v[16:31]
	v_mfma_f32_32x32x16_bf16 v[0:15], v[100:103], v[64:67], v[0:15]
	v_mfma_f32_32x32x16_bf16 v[16:31], v[104:107], v[64:67], v[16:31]
	v_mfma_f32_32x32x16_bf16 v[0:15], v[96:99], v[80:83], v[0:15]
	s_cbranch_vccnz .LBB0_2789
	v_cvt_pk_bf16_f32 v32, v32, s0
	s_waitcnt lgkmcnt(0)
	v_cvt_pk_bf16_f32 v48, v48, s0
	ds_write_b16 v188, v32 offset:6144
	v_cvt_pk_bf16_f32 v32, v49, s0
	ds_write_b16 v188, v48
	ds_write_b16 v209, v32
	v_cvt_pk_bf16_f32 v32, v33, s0
	ds_write_b16 v209, v32 offset:6144
	v_cvt_pk_bf16_f32 v32, v50, s0
	ds_write_b16 v189, v32
	v_cvt_pk_bf16_f32 v32, v34, s0
	ds_write_b16 v189, v32 offset:6144
	v_cvt_pk_bf16_f32 v32, v51, s0
	ds_write_b16 v190, v32
	v_cvt_pk_bf16_f32 v32, v35, s0
	ds_write_b16 v190, v32 offset:6144
	v_cvt_pk_bf16_f32 v32, v52, s0
	ds_write_b16 v191, v32
	v_cvt_pk_bf16_f32 v32, v36, s0
	ds_write_b16 v191, v32 offset:6144
	v_cvt_pk_bf16_f32 v32, v53, s0
	ds_write_b16 v192, v32
	v_cvt_pk_bf16_f32 v32, v37, s0
	ds_write_b16 v192, v32 offset:6144
	v_cvt_pk_bf16_f32 v32, v54, s0
	ds_write_b16 v193, v32
	v_cvt_pk_bf16_f32 v32, v38, s0
	ds_write_b16 v193, v32 offset:6144
	v_cvt_pk_bf16_f32 v32, v55, s0
	ds_write_b16 v194, v32
	v_cvt_pk_bf16_f32 v32, v39, s0
	ds_write_b16 v194, v32 offset:6144
	v_cvt_pk_bf16_f32 v32, v56, s0
	ds_write_b16 v195, v32
	v_cvt_pk_bf16_f32 v32, v40, s0
	ds_write_b16 v195, v32 offset:6144
	v_cvt_pk_bf16_f32 v32, v57, s0
	ds_write_b16 v196, v32
	v_cvt_pk_bf16_f32 v32, v41, s0
	ds_write_b16 v196, v32 offset:6144
	v_cvt_pk_bf16_f32 v32, v58, s0
	ds_write_b16 v197, v32
	v_cvt_pk_bf16_f32 v32, v42, s0
	ds_write_b16 v197, v32 offset:6144
	v_cvt_pk_bf16_f32 v32, v59, s0
	ds_write_b16 v198, v32
	v_cvt_pk_bf16_f32 v32, v43, s0
	ds_write_b16 v198, v32 offset:6144
	v_cvt_pk_bf16_f32 v32, v60, s0
	ds_write_b16 v199, v32
	v_cvt_pk_bf16_f32 v32, v44, s0
	ds_write_b16 v199, v32 offset:6144
	v_cvt_pk_bf16_f32 v32, v61, s0
	ds_write_b16 v200, v32
	v_cvt_pk_bf16_f32 v32, v45, s0
	ds_write_b16 v200, v32 offset:6144
	v_cvt_pk_bf16_f32 v32, v62, s0
	ds_write_b16 v201, v32
	v_cvt_pk_bf16_f32 v32, v46, s0
	ds_write_b16 v201, v32 offset:6144
	v_cvt_pk_bf16_f32 v32, v63, s0
	ds_write_b16 v202, v32
	v_cvt_pk_bf16_f32 v32, v47, s0
	v_cvt_pk_bf16_f32 v0, v0, s0
	ds_write_b16 v202, v32 offset:6144
	v_cvt_pk_bf16_f32 v16, v16, s0
	ds_write_b16 v188, v0 offset:6208
	v_cvt_pk_bf16_f32 v0, v17, s0
	ds_write_b16 v188, v16 offset:64
	ds_write_b16 v209, v0 offset:64
	v_cvt_pk_bf16_f32 v0, v1, s0
	ds_write_b16 v209, v0 offset:6208
	v_cvt_pk_bf16_f32 v0, v18, s0
	ds_write_b16 v189, v0 offset:64
	v_cvt_pk_bf16_f32 v0, v2, s0
	ds_write_b16 v189, v0 offset:6208
	v_cvt_pk_bf16_f32 v0, v19, s0
	ds_write_b16 v190, v0 offset:64
	v_cvt_pk_bf16_f32 v0, v3, s0
	ds_write_b16 v190, v0 offset:6208
	v_cvt_pk_bf16_f32 v0, v20, s0
	ds_write_b16 v191, v0 offset:64
	v_cvt_pk_bf16_f32 v0, v4, s0
	ds_write_b16 v191, v0 offset:6208
	v_cvt_pk_bf16_f32 v0, v21, s0
	ds_write_b16 v192, v0 offset:64
	v_cvt_pk_bf16_f32 v0, v5, s0
	ds_write_b16 v192, v0 offset:6208
	v_cvt_pk_bf16_f32 v0, v22, s0
	ds_write_b16 v193, v0 offset:64
	v_cvt_pk_bf16_f32 v0, v6, s0
	ds_write_b16 v193, v0 offset:6208
	v_cvt_pk_bf16_f32 v0, v23, s0
	ds_write_b16 v194, v0 offset:64
	v_cvt_pk_bf16_f32 v0, v7, s0
	ds_write_b16 v194, v0 offset:6208
	v_cvt_pk_bf16_f32 v0, v24, s0
	ds_write_b16 v195, v0 offset:64
	v_cvt_pk_bf16_f32 v0, v8, s0
	ds_write_b16 v195, v0 offset:6208
	v_cvt_pk_bf16_f32 v0, v25, s0
	ds_write_b16 v196, v0 offset:64
	v_cvt_pk_bf16_f32 v0, v9, s0
	ds_write_b16 v196, v0 offset:6208
	v_cvt_pk_bf16_f32 v0, v26, s0
	ds_write_b16 v197, v0 offset:64
	v_cvt_pk_bf16_f32 v0, v10, s0
	ds_write_b16 v197, v0 offset:6208
	v_cvt_pk_bf16_f32 v0, v27, s0
	ds_write_b16 v198, v0 offset:64
	v_cvt_pk_bf16_f32 v0, v11, s0
	ds_write_b16 v198, v0 offset:6208
	v_cvt_pk_bf16_f32 v0, v28, s0
	ds_write_b16 v199, v0 offset:64
	v_cvt_pk_bf16_f32 v0, v12, s0
	ds_write_b16 v199, v0 offset:6208
	v_cvt_pk_bf16_f32 v0, v29, s0
	ds_write_b16 v200, v0 offset:64
	v_cvt_pk_bf16_f32 v0, v13, s0
	ds_write_b16 v200, v0 offset:6208
	v_cvt_pk_bf16_f32 v0, v30, s0
	ds_write_b16 v201, v0 offset:64
	v_cvt_pk_bf16_f32 v0, v14, s0
	ds_write_b16 v201, v0 offset:6208
	v_cvt_pk_bf16_f32 v0, v31, s0
	s_or_b32 s2, s43, 0x400
	ds_write_b16 v202, v0 offset:64
	v_cvt_pk_bf16_f32 v0, v15, s0
	s_lshl_b32 s10, s2, 11
	ds_write_b16 v202, v0 offset:6208
	v_lshl_add_u64 v[0:1], v[170:171], 0, s[10:11]
	v_or_b32_e32 v0, v0, v154
	v_lshl_add_u64 v[40:41], v[0:1], 4, s[18:19]
	v_mov_b32_e32 v4, 0
	v_mov_b32_e32 v0, 0
	v_mov_b32_e32 v1, 0
	v_mov_b32_e32 v2, 0
	v_mov_b32_e32 v3, 0
	s_waitcnt lgkmcnt(0)
	s_barrier
	s_and_saveexec_b64 s[14:15], s[4:5]
	s_cbranch_execz .LBB0_2792
	global_load_dwordx4 v[0:3], v[40:41], off offset:-16

.LBB0_3232:
	s_lshl_b32 s43, s56, 8
	v_add_u32_e32 v148, s43, v168
	v_ashrrev_i32_e32 v149, 31, v148
	s_lshl_b32 s58, s54, 8
	v_lshlrev_b64 v[150:151], 11, v[148:149]
	s_ashr_i32 s59, s58, 31
	v_lshl_add_u64 v[150:151], s[22:23], 0, v[150:151]
	v_lshl_add_u64 v[150:151], s[58:59], 1, v[150:151]
	s_lshl_b32 s14, s34, 1
	v_lshl_add_u64 v[150:151], v[150:151], 0, s[14:15]
	v_lshlrev_b32_e32 v0, 1, v142
	v_lshl_add_u64 v[194:195], v[150:151], 0, v[0:1]
	global_load_dwordx4 v[200:203], v[194:195], off
	global_load_dwordx4 v[204:207], v[194:195], off offset:256
	v_or_b32_e32 v234, 16, v148
	v_ashrrev_i32_e32 v235, 31, v234
	v_lshlrev_b64 v[234:235], 11, v[234:235]
	v_lshl_add_u64 v[234:235], s[22:23], 0, v[234:235]
	v_lshl_add_u64 v[234:235], s[58:59], 1, v[234:235]
	v_lshl_add_u64 v[234:235], v[234:235], 0, s[14:15]
	v_lshl_add_u64 v[252:253], v[234:235], 0, v[0:1]
	global_load_dwordx4 v[208:211], v[252:253], off
	global_load_dwordx4 v[212:215], v[252:253], off offset:256
	v_or_b32_e32 v234, 32, v148
	v_ashrrev_i32_e32 v235, 31, v234
	v_lshlrev_b64 v[234:235], 11, v[234:235]
	v_lshl_add_u64 v[234:235], s[22:23], 0, v[234:235]
	v_lshl_add_u64 v[234:235], s[58:59], 1, v[234:235]
	v_lshl_add_u64 v[234:235], v[234:235], 0, s[14:15]
	v_lshl_add_u64 v[252:253], v[234:235], 0, v[0:1]
	global_load_dwordx4 v[216:219], v[252:253], off
	global_load_dwordx4 v[220:223], v[252:253], off offset:256
	v_or_b32_e32 v234, 48, v148
	v_ashrrev_i32_e32 v235, 31, v234
	v_lshlrev_b64 v[234:235], 11, v[234:235]
	v_lshl_add_u64 v[234:235], s[22:23], 0, v[234:235]
	v_lshl_add_u64 v[234:235], s[58:59], 1, v[234:235]
	v_lshl_add_u64 v[234:235], v[234:235], 0, s[14:15]
	v_lshl_add_u64 v[252:253], v[234:235], 0, v[0:1]
	global_load_dwordx4 v[224:227], v[252:253], off
	global_load_dwordx4 v[228:231], v[252:253], off offset:256
	v_add_u32_e32 v234, 0x80, v148
	v_ashrrev_i32_e32 v235, 31, v234
	v_lshlrev_b64 v[234:235], 11, v[234:235]
	v_lshl_add_u64 v[234:235], s[22:23], 0, v[234:235]
	v_lshl_add_u64 v[234:235], s[58:59], 1, v[234:235]
	v_lshl_add_u64 v[234:235], v[234:235], 0, s[14:15]
	v_lshl_add_u64 v[252:253], v[234:235], 0, v[0:1]
	global_load_dwordx4 v[236:239], v[252:253], off
	global_load_dwordx4 v[240:243], v[252:253], off offset:256
	v_add_u32_e32 v234, 0x90, v148
	v_ashrrev_i32_e32 v235, 31, v234
	v_lshlrev_b64 v[234:235], 11, v[234:235]
	v_lshl_add_u64 v[234:235], s[22:23], 0, v[234:235]
	v_lshl_add_u64 v[234:235], s[58:59], 1, v[234:235]
	v_lshl_add_u64 v[234:235], v[234:235], 0, s[14:15]
	v_lshl_add_u64 v[252:253], v[234:235], 0, v[0:1]
	global_load_dwordx4 v[244:247], v[252:253], off
	global_load_dwordx4 v[248:251], v[252:253], off offset:256
	v_and_b32_e32 v151, 64, v164
	v_xor_b32_e32 v150, 16, v164
	v_add_u32_e32 v160, 64, v151
	v_cmp_lt_i32_e32 vcc, v150, v160
	v_xor_b32_e32 v153, 32, v164
	s_waitcnt vmcnt(10)
	v_and_b32_e32 v151, 0xffff0000, v200
	v_cndmask_b32_e32 v150, v164, v150, vcc
	v_lshlrev_b32_e32 v152, 2, v150
	v_lshlrev_b32_e32 v150, 16, v200
	v_lshlrev_b32_e32 v158, 16, v202
	v_and_b32_e32 v159, 0xffff0000, v202
	v_lshlrev_b32_e32 v156, 16, v203
	v_and_b32_e32 v157, 0xffff0000, v203
	v_pk_add_f32 v[126:127], v[126:127], v[150:151]
	v_lshlrev_b32_e32 v154, 16, v201
	v_and_b32_e32 v155, 0xffff0000, v201
	v_pk_add_f32 v[122:123], v[122:123], v[158:159]
	v_pk_add_f32 v[124:125], v[124:125], v[156:157]
	v_cvt_pk_bf16_f32 v156, v126, v127
	v_pk_add_f32 v[128:129], v[128:129], v[154:155]
	v_cvt_pk_bf16_f32 v158, v122, v123
	v_and_b32_e32 v123, 0xffff0000, v156
	v_cvt_pk_bf16_f32 v157, v128, v129
	v_lshlrev_b32_e32 v122, 16, v156
	v_mul_f32_e32 v151, v123, v123
	v_lshlrev_b32_e32 v126, 16, v157
	v_fmac_f32_e32 v151, v122, v122
	v_and_b32_e32 v127, 0xffff0000, v157
	v_fmac_f32_e32 v151, v126, v126
	v_cvt_pk_bf16_f32 v159, v124, v125
	v_lshlrev_b32_e32 v124, 16, v158
	v_fmac_f32_e32 v151, v127, v127
	v_lshlrev_b32_e32 v196, 16, v204
	v_and_b32_e32 v197, 0xffff0000, v204
	v_and_b32_e32 v125, 0xffff0000, v158
	v_fmac_f32_e32 v151, v124, v124
	v_lshlrev_b32_e32 v190, 16, v205
	v_and_b32_e32 v191, 0xffff0000, v205
	v_lshlrev_b32_e32 v198, 16, v206
	v_and_b32_e32 v199, 0xffff0000, v206
	v_pk_add_f32 v[118:119], v[118:119], v[196:197]
	v_lshlrev_b32_e32 v128, 16, v159
	v_fmac_f32_e32 v151, v125, v125
	v_lshlrev_b32_e32 v192, 16, v207
	v_and_b32_e32 v193, 0xffff0000, v207
	v_pk_add_f32 v[120:121], v[120:121], v[190:191]
	v_pk_add_f32 v[114:115], v[114:115], v[198:199]
	v_cvt_pk_bf16_f32 v190, v118, v119
	v_and_b32_e32 v129, 0xffff0000, v159
	v_fmac_f32_e32 v151, v128, v128
	v_pk_add_f32 v[116:117], v[116:117], v[192:193]
	v_cvt_pk_bf16_f32 v192, v114, v115
	v_lshlrev_b32_e32 v114, 16, v190
	v_max3_f32 v150, |v122|, 0, |v123|
	v_fmac_f32_e32 v151, v129, v129
	v_cvt_pk_bf16_f32 v191, v120, v121
	v_and_b32_e32 v115, 0xffff0000, v190
	v_max3_f32 v150, v150, |v126|, |v127|
	v_fmac_f32_e32 v151, v114, v114
	v_lshlrev_b32_e32 v118, 16, v191
	v_max3_f32 v150, v150, |v124|, |v125|
	v_fmac_f32_e32 v151, v115, v115
	v_and_b32_e32 v119, 0xffff0000, v191
	v_max3_f32 v150, v150, |v128|, |v129|
	v_fmac_f32_e32 v151, v118, v118
	v_cvt_pk_bf16_f32 v193, v116, v117
	v_lshlrev_b32_e32 v116, 16, v192
	v_max3_f32 v150, v150, |v114|, |v115|
	v_fmac_f32_e32 v151, v119, v119
	v_and_b32_e32 v117, 0xffff0000, v192
	v_max3_f32 v150, v150, |v118|, |v119|
	v_fmac_f32_e32 v151, v116, v116
	v_lshlrev_b32_e32 v120, 16, v193
	v_and_b32_e32 v121, 0xffff0000, v193
	v_max3_f32 v150, v150, |v116|, |v117|
	v_fmac_f32_e32 v151, v117, v117
	v_max3_f32 v150, v150, |v120|, |v121|
	v_fmac_f32_e32 v151, v120, v120
	ds_bpermute_b32 v154, v152, v150
	v_fmac_f32_e32 v151, v121, v121
	ds_bpermute_b32 v155, v152, v151
	v_cmp_lt_i32_e32 vcc, v153, v160
	global_store_dwordx4 v[194:195], v[156:159], off
	global_store_dwordx4 v[194:195], v[190:193], off offset:256
	v_cndmask_b32_e32 v153, v164, v153, vcc
	s_waitcnt lgkmcnt(1)
	v_max_f32_e32 v154, v154, v154
	v_lshlrev_b32_e32 v153, 2, v153
	v_max_f32_e32 v150, v150, v154
	s_waitcnt lgkmcnt(0)
	v_add_f32_e32 v151, v151, v155
	ds_bpermute_b32 v154, v153, v151
	ds_bpermute_b32 v155, v153, v150
	s_and_saveexec_b64 s[48:49], s[4:5]
	s_cbranch_execz .LBB0_3234
	s_waitcnt lgkmcnt(1)
	v_add_f32_e32 v151, v151, v154
	s_waitcnt lgkmcnt(0)
	v_max_f32_e32 v154, v155, v155
	v_max_f32_e32 v150, v150, v150
	v_max_f32_e32 v150, v150, v154
	ds_write2st64_b32 v177, v151, v150 offset1:16
.LBB0_3234:
	s_or_b64 exec, exec, s[48:49]
	v_add_u32_e32 v234, 0xa0, v148
	v_ashrrev_i32_e32 v235, 31, v234
	v_lshlrev_b64 v[234:235], 11, v[234:235]
	v_lshl_add_u64 v[234:235], s[22:23], 0, v[234:235]
	v_lshl_add_u64 v[234:235], s[58:59], 1, v[234:235]
	v_lshl_add_u64 v[234:235], v[234:235], 0, s[14:15]
	v_lshl_add_u64 v[252:253], v[234:235], 0, v[0:1]
	global_load_dwordx4 v[200:203], v[252:253], off
	global_load_dwordx4 v[204:207], v[252:253], off offset:256
	v_or_b32_e32 v150, 16, v148
	v_ashrrev_i32_e32 v151, 31, v150
	v_lshlrev_b64 v[150:151], 11, v[150:151]
	v_lshl_add_u64 v[150:151], s[22:23], 0, v[150:151]
	v_lshl_add_u64 v[150:151], s[58:59], 1, v[150:151]
	v_lshl_add_u64 v[150:151], v[150:151], 0, s[14:15]
	v_lshl_add_u64 v[194:195], v[150:151], 0, v[0:1]
	s_waitcnt lgkmcnt(0)
	s_waitcnt vmcnt(13)
	v_lshlrev_b32_e32 v150, 16, v208
	v_and_b32_e32 v151, 0xffff0000, v208
	v_lshlrev_b32_e32 v158, 16, v210
	v_and_b32_e32 v159, 0xffff0000, v210
	v_lshlrev_b32_e32 v156, 16, v211
	v_and_b32_e32 v157, 0xffff0000, v211
	v_pk_add_f32 v[110:111], v[110:111], v[150:151]
	v_lshlrev_b32_e32 v154, 16, v209
	v_and_b32_e32 v155, 0xffff0000, v209
	v_pk_add_f32 v[106:107], v[106:107], v[158:159]
	v_pk_add_f32 v[108:109], v[108:109], v[156:157]
	v_cvt_pk_bf16_f32 v156, v110, v111
	v_pk_add_f32 v[112:113], v[112:113], v[154:155]
	v_cvt_pk_bf16_f32 v158, v106, v107
	v_and_b32_e32 v107, 0xffff0000, v156
	v_cvt_pk_bf16_f32 v157, v112, v113
	v_lshlrev_b32_e32 v106, 16, v156
	v_mul_f32_e32 v151, v107, v107
	v_lshlrev_b32_e32 v110, 16, v157
	v_fmac_f32_e32 v151, v106, v106
	v_and_b32_e32 v111, 0xffff0000, v157
	v_fmac_f32_e32 v151, v110, v110
	v_cvt_pk_bf16_f32 v159, v108, v109
	v_lshlrev_b32_e32 v108, 16, v158
	v_fmac_f32_e32 v151, v111, v111
	s_waitcnt vmcnt(12)
	v_lshlrev_b32_e32 v196, 16, v212
	v_and_b32_e32 v197, 0xffff0000, v212
	v_and_b32_e32 v109, 0xffff0000, v158
	v_fmac_f32_e32 v151, v108, v108
	v_lshlrev_b32_e32 v190, 16, v213
	v_and_b32_e32 v191, 0xffff0000, v213
	v_lshlrev_b32_e32 v198, 16, v214
	v_and_b32_e32 v199, 0xffff0000, v214
	v_pk_add_f32 v[102:103], v[102:103], v[196:197]
	v_lshlrev_b32_e32 v112, 16, v159
	v_fmac_f32_e32 v151, v109, v109
	v_lshlrev_b32_e32 v192, 16, v215
	v_and_b32_e32 v193, 0xffff0000, v215
	v_pk_add_f32 v[104:105], v[104:105], v[190:191]
	v_pk_add_f32 v[98:99], v[98:99], v[198:199]
	v_cvt_pk_bf16_f32 v190, v102, v103
	v_and_b32_e32 v113, 0xffff0000, v159
	v_fmac_f32_e32 v151, v112, v112
	v_pk_add_f32 v[100:101], v[100:101], v[192:193]
	v_cvt_pk_bf16_f32 v192, v98, v99
	v_lshlrev_b32_e32 v98, 16, v190
	v_max3_f32 v150, |v106|, 0, |v107|
	v_fmac_f32_e32 v151, v113, v113
	v_cvt_pk_bf16_f32 v191, v104, v105
	v_and_b32_e32 v99, 0xffff0000, v190
	v_max3_f32 v150, v150, |v110|, |v111|
	v_fmac_f32_e32 v151, v98, v98
	v_lshlrev_b32_e32 v102, 16, v191
	v_max3_f32 v150, v150, |v108|, |v109|
	v_fmac_f32_e32 v151, v99, v99
	v_and_b32_e32 v103, 0xffff0000, v191
	v_max3_f32 v150, v150, |v112|, |v113|
	v_fmac_f32_e32 v151, v102, v102
	v_cvt_pk_bf16_f32 v193, v100, v101
	v_lshlrev_b32_e32 v100, 16, v192
	v_max3_f32 v150, v150, |v98|, |v99|
	v_fmac_f32_e32 v151, v103, v103
	v_and_b32_e32 v101, 0xffff0000, v192
	v_max3_f32 v150, v150, |v102|, |v103|
	v_fmac_f32_e32 v151, v100, v100
	v_lshlrev_b32_e32 v104, 16, v193
	v_and_b32_e32 v105, 0xffff0000, v193
	v_max3_f32 v150, v150, |v100|, |v101|
	v_fmac_f32_e32 v151, v101, v101
	v_max3_f32 v150, v150, |v104|, |v105|
	v_fmac_f32_e32 v151, v104, v104
	ds_bpermute_b32 v154, v152, v150
	v_fmac_f32_e32 v151, v105, v105
	ds_bpermute_b32 v155, v152, v151
	global_store_dwordx4 v[194:195], v[156:159], off
	global_store_dwordx4 v[194:195], v[190:193], off offset:256
	s_waitcnt lgkmcnt(1)
	v_max_f32_e32 v154, v154, v154
	v_max_f32_e32 v150, v150, v154
	s_waitcnt lgkmcnt(0)
	v_add_f32_e32 v151, v151, v155
	ds_bpermute_b32 v154, v153, v151
	ds_bpermute_b32 v155, v153, v150
	s_and_saveexec_b64 s[48:49], s[4:5]
	s_cbranch_execz .LBB0_3236
	s_waitcnt lgkmcnt(1)
	v_add_f32_e32 v151, v151, v154
	s_waitcnt lgkmcnt(0)
	v_max_f32_e32 v154, v155, v155
	v_max_f32_e32 v150, v150, v150
	v_max_f32_e32 v150, v150, v154
	ds_write2st64_b32 v177, v151, v150 offset0:1 offset1:17
.LBB0_3236:
	s_or_b64 exec, exec, s[48:49]
	v_add_u32_e32 v234, 0xb0, v148
	v_ashrrev_i32_e32 v235, 31, v234
	v_lshlrev_b64 v[234:235], 11, v[234:235]
	v_lshl_add_u64 v[234:235], s[22:23], 0, v[234:235]
	v_lshl_add_u64 v[234:235], s[58:59], 1, v[234:235]
	v_lshl_add_u64 v[234:235], v[234:235], 0, s[14:15]
	v_lshl_add_u64 v[252:253], v[234:235], 0, v[0:1]
	global_load_dwordx4 v[208:211], v[252:253], off
	global_load_dwordx4 v[212:215], v[252:253], off offset:256
	v_or_b32_e32 v150, 32, v148
	v_ashrrev_i32_e32 v151, 31, v150
	v_lshlrev_b64 v[150:151], 11, v[150:151]
	v_lshl_add_u64 v[150:151], s[22:23], 0, v[150:151]
	v_lshl_add_u64 v[150:151], s[58:59], 1, v[150:151]
	v_lshl_add_u64 v[150:151], v[150:151], 0, s[14:15]
	v_lshl_add_u64 v[194:195], v[150:151], 0, v[0:1]
	s_waitcnt lgkmcnt(0)
	s_waitcnt vmcnt(15)
	v_lshlrev_b32_e32 v150, 16, v216
	v_and_b32_e32 v151, 0xffff0000, v216
	v_lshlrev_b32_e32 v158, 16, v218
	v_and_b32_e32 v159, 0xffff0000, v218
	v_lshlrev_b32_e32 v156, 16, v219
	v_and_b32_e32 v157, 0xffff0000, v219
	v_pk_add_f32 v[94:95], v[94:95], v[150:151]
	v_lshlrev_b32_e32 v154, 16, v217
	v_and_b32_e32 v155, 0xffff0000, v217
	v_pk_add_f32 v[90:91], v[90:91], v[158:159]
	v_pk_add_f32 v[92:93], v[92:93], v[156:157]
	v_cvt_pk_bf16_f32 v156, v94, v95
	v_pk_add_f32 v[96:97], v[96:97], v[154:155]
	v_cvt_pk_bf16_f32 v158, v90, v91
	v_and_b32_e32 v91, 0xffff0000, v156
	v_cvt_pk_bf16_f32 v157, v96, v97
	v_lshlrev_b32_e32 v90, 16, v156
	v_mul_f32_e32 v151, v91, v91
	v_lshlrev_b32_e32 v94, 16, v157
	v_fmac_f32_e32 v151, v90, v90
	v_and_b32_e32 v95, 0xffff0000, v157
	v_fmac_f32_e32 v151, v94, v94
	v_cvt_pk_bf16_f32 v159, v92, v93
	v_lshlrev_b32_e32 v92, 16, v158
	v_fmac_f32_e32 v151, v95, v95
	s_waitcnt vmcnt(14)
	v_lshlrev_b32_e32 v196, 16, v220
	v_and_b32_e32 v197, 0xffff0000, v220
	v_and_b32_e32 v93, 0xffff0000, v158
	v_fmac_f32_e32 v151, v92, v92
	v_lshlrev_b32_e32 v190, 16, v221
	v_and_b32_e32 v191, 0xffff0000, v221
	v_lshlrev_b32_e32 v198, 16, v222
	v_and_b32_e32 v199, 0xffff0000, v222
	v_pk_add_f32 v[86:87], v[86:87], v[196:197]
	v_lshlrev_b32_e32 v96, 16, v159
	v_fmac_f32_e32 v151, v93, v93
	v_lshlrev_b32_e32 v192, 16, v223
	v_and_b32_e32 v193, 0xffff0000, v223
	v_pk_add_f32 v[88:89], v[88:89], v[190:191]
	v_pk_add_f32 v[82:83], v[82:83], v[198:199]
	v_cvt_pk_bf16_f32 v190, v86, v87
	v_and_b32_e32 v97, 0xffff0000, v159
	v_fmac_f32_e32 v151, v96, v96
	v_pk_add_f32 v[84:85], v[84:85], v[192:193]
	v_cvt_pk_bf16_f32 v192, v82, v83
	v_lshlrev_b32_e32 v82, 16, v190
	v_max3_f32 v150, |v90|, 0, |v91|
	v_fmac_f32_e32 v151, v97, v97
	v_cvt_pk_bf16_f32 v191, v88, v89
	v_and_b32_e32 v83, 0xffff0000, v190
	v_max3_f32 v150, v150, |v94|, |v95|
	v_fmac_f32_e32 v151, v82, v82
	v_lshlrev_b32_e32 v86, 16, v191
	v_max3_f32 v150, v150, |v92|, |v93|
	v_fmac_f32_e32 v151, v83, v83
	v_and_b32_e32 v87, 0xffff0000, v191
	v_max3_f32 v150, v150, |v96|, |v97|
	v_fmac_f32_e32 v151, v86, v86
	v_cvt_pk_bf16_f32 v193, v84, v85
	v_lshlrev_b32_e32 v84, 16, v192
	v_max3_f32 v150, v150, |v82|, |v83|
	v_fmac_f32_e32 v151, v87, v87
	v_and_b32_e32 v85, 0xffff0000, v192
	v_max3_f32 v150, v150, |v86|, |v87|
	v_fmac_f32_e32 v151, v84, v84
	v_lshlrev_b32_e32 v88, 16, v193
	v_and_b32_e32 v89, 0xffff0000, v193
	v_max3_f32 v150, v150, |v84|, |v85|
	v_fmac_f32_e32 v151, v85, v85
	v_max3_f32 v150, v150, |v88|, |v89|
	v_fmac_f32_e32 v151, v88, v88
	ds_bpermute_b32 v154, v152, v150
	v_fmac_f32_e32 v151, v89, v89
	ds_bpermute_b32 v155, v152, v151
	global_store_dwordx4 v[194:195], v[156:159], off
	global_store_dwordx4 v[194:195], v[190:193], off offset:256
	s_waitcnt lgkmcnt(1)
	v_max_f32_e32 v154, v154, v154
	v_max_f32_e32 v150, v150, v154
	s_waitcnt lgkmcnt(0)
	v_add_f32_e32 v151, v151, v155
	ds_bpermute_b32 v154, v153, v151
	ds_bpermute_b32 v155, v153, v150
	s_and_saveexec_b64 s[48:49], s[4:5]
	s_cbranch_execz .LBB0_3238
	s_waitcnt lgkmcnt(1)
	v_add_f32_e32 v151, v151, v154
	s_waitcnt lgkmcnt(0)
	v_max_f32_e32 v154, v155, v155
	v_max_f32_e32 v150, v150, v150
	v_max_f32_e32 v150, v150, v154
	ds_write2st64_b32 v177, v151, v150 offset0:2 offset1:18
.LBB0_3238:
	s_or_b64 exec, exec, s[48:49]
	v_or_b32_e32 v150, 48, v148
	v_ashrrev_i32_e32 v151, 31, v150
	v_lshlrev_b64 v[150:151], 11, v[150:151]
	v_lshl_add_u64 v[150:151], s[22:23], 0, v[150:151]
	v_lshl_add_u64 v[150:151], s[58:59], 1, v[150:151]
	v_lshl_add_u64 v[150:151], v[150:151], 0, s[14:15]
	v_lshl_add_u64 v[194:195], v[150:151], 0, v[0:1]
	s_waitcnt lgkmcnt(0)
	s_waitcnt vmcnt(15)
	v_lshlrev_b32_e32 v150, 16, v224
	v_and_b32_e32 v151, 0xffff0000, v224
	v_lshlrev_b32_e32 v158, 16, v226
	v_and_b32_e32 v159, 0xffff0000, v226
	v_lshlrev_b32_e32 v156, 16, v227
	v_and_b32_e32 v157, 0xffff0000, v227
	v_pk_add_f32 v[78:79], v[78:79], v[150:151]
	v_lshlrev_b32_e32 v154, 16, v225
	v_and_b32_e32 v155, 0xffff0000, v225
	v_pk_add_f32 v[74:75], v[74:75], v[158:159]
	v_pk_add_f32 v[76:77], v[76:77], v[156:157]
	v_cvt_pk_bf16_f32 v156, v78, v79
	v_pk_add_f32 v[80:81], v[80:81], v[154:155]
	v_cvt_pk_bf16_f32 v158, v74, v75
	v_and_b32_e32 v75, 0xffff0000, v156
	v_cvt_pk_bf16_f32 v157, v80, v81
	v_lshlrev_b32_e32 v74, 16, v156
	v_mul_f32_e32 v151, v75, v75
	v_lshlrev_b32_e32 v78, 16, v157
	v_fmac_f32_e32 v151, v74, v74
	v_and_b32_e32 v79, 0xffff0000, v157
	v_fmac_f32_e32 v151, v78, v78
	v_cvt_pk_bf16_f32 v159, v76, v77
	v_lshlrev_b32_e32 v76, 16, v158
	v_fmac_f32_e32 v151, v79, v79
	s_waitcnt vmcnt(14)
	v_lshlrev_b32_e32 v196, 16, v228
	v_and_b32_e32 v197, 0xffff0000, v228
	v_and_b32_e32 v77, 0xffff0000, v158
	v_fmac_f32_e32 v151, v76, v76
	v_lshlrev_b32_e32 v190, 16, v229
	v_and_b32_e32 v191, 0xffff0000, v229
	v_lshlrev_b32_e32 v198, 16, v230
	v_and_b32_e32 v199, 0xffff0000, v230
	v_pk_add_f32 v[70:71], v[70:71], v[196:197]
	v_lshlrev_b32_e32 v80, 16, v159
	v_fmac_f32_e32 v151, v77, v77
	v_lshlrev_b32_e32 v192, 16, v231
	v_and_b32_e32 v193, 0xffff0000, v231
	v_pk_add_f32 v[72:73], v[72:73], v[190:191]
	v_pk_add_f32 v[66:67], v[66:67], v[198:199]
	v_cvt_pk_bf16_f32 v190, v70, v71
	v_and_b32_e32 v81, 0xffff0000, v159
	v_fmac_f32_e32 v151, v80, v80
	v_pk_add_f32 v[68:69], v[68:69], v[192:193]
	v_cvt_pk_bf16_f32 v192, v66, v67
	v_lshlrev_b32_e32 v66, 16, v190
	v_max3_f32 v150, |v74|, 0, |v75|
	v_fmac_f32_e32 v151, v81, v81
	v_cvt_pk_bf16_f32 v191, v72, v73
	v_and_b32_e32 v67, 0xffff0000, v190
	v_max3_f32 v150, v150, |v78|, |v79|
	v_fmac_f32_e32 v151, v66, v66
	v_lshlrev_b32_e32 v70, 16, v191
	v_max3_f32 v150, v150, |v76|, |v77|
	v_fmac_f32_e32 v151, v67, v67
	v_and_b32_e32 v71, 0xffff0000, v191
	v_max3_f32 v150, v150, |v80|, |v81|
	v_fmac_f32_e32 v151, v70, v70
	v_cvt_pk_bf16_f32 v193, v68, v69
	v_lshlrev_b32_e32 v68, 16, v192
	v_max3_f32 v150, v150, |v66|, |v67|
	v_fmac_f32_e32 v151, v71, v71
	v_and_b32_e32 v69, 0xffff0000, v192
	v_max3_f32 v150, v150, |v70|, |v71|
	v_fmac_f32_e32 v151, v68, v68
	v_lshlrev_b32_e32 v72, 16, v193
	v_and_b32_e32 v73, 0xffff0000, v193
	v_max3_f32 v150, v150, |v68|, |v69|
	v_fmac_f32_e32 v151, v69, v69
	v_max3_f32 v150, v150, |v72|, |v73|
	v_fmac_f32_e32 v151, v72, v72
	ds_bpermute_b32 v154, v152, v150
	v_fmac_f32_e32 v151, v73, v73
	ds_bpermute_b32 v155, v152, v151
	global_store_dwordx4 v[194:195], v[156:159], off
	global_store_dwordx4 v[194:195], v[190:193], off offset:256
	s_waitcnt lgkmcnt(1)
	v_max_f32_e32 v154, v154, v154
	v_max_f32_e32 v150, v150, v154
	s_waitcnt lgkmcnt(0)
	v_add_f32_e32 v151, v151, v155
	ds_bpermute_b32 v154, v153, v151
	ds_bpermute_b32 v155, v153, v150
	s_and_saveexec_b64 s[48:49], s[4:5]
	s_cbranch_execz .LBB0_3240
	s_waitcnt lgkmcnt(1)
	v_add_f32_e32 v151, v151, v154
	s_waitcnt lgkmcnt(0)
	v_max_f32_e32 v154, v155, v155
	v_max_f32_e32 v150, v150, v150
	v_max_f32_e32 v150, v150, v154
	ds_write2st64_b32 v177, v151, v150 offset0:3 offset1:19
.LBB0_3240:
	s_or_b64 exec, exec, s[48:49]
	v_add_u32_e32 v150, 0x80, v148
	v_ashrrev_i32_e32 v151, 31, v150
	v_lshlrev_b64 v[150:151], 11, v[150:151]
	v_lshl_add_u64 v[150:151], s[22:23], 0, v[150:151]
	v_lshl_add_u64 v[150:151], s[58:59], 1, v[150:151]
	v_lshl_add_u64 v[150:151], v[150:151], 0, s[14:15]
	v_lshl_add_u64 v[194:195], v[150:151], 0, v[0:1]
	s_waitcnt lgkmcnt(0)
	s_waitcnt vmcnt(15)
	v_lshlrev_b32_e32 v150, 16, v236
	v_and_b32_e32 v151, 0xffff0000, v236
	v_lshlrev_b32_e32 v158, 16, v238
	v_and_b32_e32 v159, 0xffff0000, v238
	v_lshlrev_b32_e32 v156, 16, v239
	v_and_b32_e32 v157, 0xffff0000, v239
	v_pk_add_f32 v[62:63], v[62:63], v[150:151]
	v_lshlrev_b32_e32 v154, 16, v237
	v_and_b32_e32 v155, 0xffff0000, v237
	v_pk_add_f32 v[58:59], v[58:59], v[158:159]
	v_pk_add_f32 v[60:61], v[60:61], v[156:157]
	v_cvt_pk_bf16_f32 v156, v62, v63
	v_pk_add_f32 v[64:65], v[64:65], v[154:155]
	v_cvt_pk_bf16_f32 v158, v58, v59
	v_and_b32_e32 v59, 0xffff0000, v156
	v_cvt_pk_bf16_f32 v157, v64, v65
	v_lshlrev_b32_e32 v58, 16, v156
	v_mul_f32_e32 v151, v59, v59
	v_lshlrev_b32_e32 v62, 16, v157
	v_fmac_f32_e32 v151, v58, v58
	v_and_b32_e32 v63, 0xffff0000, v157
	v_fmac_f32_e32 v151, v62, v62
	v_cvt_pk_bf16_f32 v159, v60, v61
	v_lshlrev_b32_e32 v60, 16, v158
	v_fmac_f32_e32 v151, v63, v63
	s_waitcnt vmcnt(14)
	v_lshlrev_b32_e32 v196, 16, v240
	v_and_b32_e32 v197, 0xffff0000, v240
	v_and_b32_e32 v61, 0xffff0000, v158
	v_fmac_f32_e32 v151, v60, v60
	v_lshlrev_b32_e32 v190, 16, v241
	v_and_b32_e32 v191, 0xffff0000, v241
	v_lshlrev_b32_e32 v198, 16, v242
	v_and_b32_e32 v199, 0xffff0000, v242
	v_pk_add_f32 v[54:55], v[54:55], v[196:197]
	v_lshlrev_b32_e32 v64, 16, v159
	v_fmac_f32_e32 v151, v61, v61
	v_lshlrev_b32_e32 v192, 16, v243
	v_and_b32_e32 v193, 0xffff0000, v243
	v_pk_add_f32 v[56:57], v[56:57], v[190:191]
	v_pk_add_f32 v[50:51], v[50:51], v[198:199]
	v_cvt_pk_bf16_f32 v190, v54, v55
	v_and_b32_e32 v65, 0xffff0000, v159
	v_fmac_f32_e32 v151, v64, v64
	v_pk_add_f32 v[52:53], v[52:53], v[192:193]
	v_cvt_pk_bf16_f32 v192, v50, v51
	v_lshlrev_b32_e32 v50, 16, v190
	v_max3_f32 v150, |v58|, 0, |v59|
	v_fmac_f32_e32 v151, v65, v65
	v_cvt_pk_bf16_f32 v191, v56, v57
	v_and_b32_e32 v51, 0xffff0000, v190
	v_max3_f32 v150, v150, |v62|, |v63|
	v_fmac_f32_e32 v151, v50, v50
	v_lshlrev_b32_e32 v54, 16, v191
	v_max3_f32 v150, v150, |v60|, |v61|
	v_fmac_f32_e32 v151, v51, v51
	v_and_b32_e32 v55, 0xffff0000, v191
	v_max3_f32 v150, v150, |v64|, |v65|
	v_fmac_f32_e32 v151, v54, v54
	v_cvt_pk_bf16_f32 v193, v52, v53
	v_lshlrev_b32_e32 v52, 16, v192
	v_max3_f32 v150, v150, |v50|, |v51|
	v_fmac_f32_e32 v151, v55, v55
	v_and_b32_e32 v53, 0xffff0000, v192
	v_max3_f32 v150, v150, |v54|, |v55|
	v_fmac_f32_e32 v151, v52, v52
	v_lshlrev_b32_e32 v56, 16, v193
	v_and_b32_e32 v57, 0xffff0000, v193
	v_max3_f32 v150, v150, |v52|, |v53|
	v_fmac_f32_e32 v151, v53, v53
	v_max3_f32 v150, v150, |v56|, |v57|
	v_fmac_f32_e32 v151, v56, v56
	ds_bpermute_b32 v154, v152, v150
	v_fmac_f32_e32 v151, v57, v57
	ds_bpermute_b32 v155, v152, v151
	global_store_dwordx4 v[194:195], v[156:159], off
	global_store_dwordx4 v[194:195], v[190:193], off offset:256
	s_waitcnt lgkmcnt(1)
	v_max_f32_e32 v154, v154, v154
	v_max_f32_e32 v150, v150, v154
	s_waitcnt lgkmcnt(0)
	v_add_f32_e32 v151, v151, v155
	ds_bpermute_b32 v154, v153, v151
	ds_bpermute_b32 v155, v153, v150
	s_and_saveexec_b64 s[48:49], s[4:5]
	s_cbranch_execz .LBB0_3242
	s_waitcnt lgkmcnt(1)
	v_add_f32_e32 v151, v151, v154
	s_waitcnt lgkmcnt(0)
	v_max_f32_e32 v154, v155, v155
	v_max_f32_e32 v150, v150, v150
	v_max_f32_e32 v150, v150, v154
	ds_write2st64_b32 v178, v151, v150 offset1:16
.LBB0_3242:
	s_or_b64 exec, exec, s[48:49]
	v_add_u32_e32 v150, 0x90, v148
	v_ashrrev_i32_e32 v151, 31, v150
	v_lshlrev_b64 v[150:151], 11, v[150:151]
	v_lshl_add_u64 v[150:151], s[22:23], 0, v[150:151]
	v_lshl_add_u64 v[150:151], s[58:59], 1, v[150:151]
	v_lshl_add_u64 v[150:151], v[150:151], 0, s[14:15]
	v_lshl_add_u64 v[194:195], v[150:151], 0, v[0:1]
	s_waitcnt lgkmcnt(0)
	s_waitcnt vmcnt(15)
	v_lshlrev_b32_e32 v150, 16, v244
	v_and_b32_e32 v151, 0xffff0000, v244
	v_lshlrev_b32_e32 v158, 16, v246
	v_and_b32_e32 v159, 0xffff0000, v246
	v_lshlrev_b32_e32 v156, 16, v247
	v_and_b32_e32 v157, 0xffff0000, v247
	v_pk_add_f32 v[46:47], v[46:47], v[150:151]
	v_lshlrev_b32_e32 v154, 16, v245
	v_and_b32_e32 v155, 0xffff0000, v245
	v_pk_add_f32 v[42:43], v[42:43], v[158:159]
	v_pk_add_f32 v[44:45], v[44:45], v[156:157]
	v_cvt_pk_bf16_f32 v156, v46, v47
	v_pk_add_f32 v[48:49], v[48:49], v[154:155]
	v_cvt_pk_bf16_f32 v158, v42, v43
	v_and_b32_e32 v43, 0xffff0000, v156
	v_cvt_pk_bf16_f32 v157, v48, v49
	v_lshlrev_b32_e32 v42, 16, v156
	v_mul_f32_e32 v151, v43, v43
	v_lshlrev_b32_e32 v46, 16, v157
	v_fmac_f32_e32 v151, v42, v42
	v_and_b32_e32 v47, 0xffff0000, v157
	v_fmac_f32_e32 v151, v46, v46
	v_cvt_pk_bf16_f32 v159, v44, v45
	v_lshlrev_b32_e32 v44, 16, v158
	v_fmac_f32_e32 v151, v47, v47
	s_waitcnt vmcnt(14)
	v_lshlrev_b32_e32 v196, 16, v248
	v_and_b32_e32 v197, 0xffff0000, v248
	v_and_b32_e32 v45, 0xffff0000, v158
	v_fmac_f32_e32 v151, v44, v44
	v_lshlrev_b32_e32 v190, 16, v249
	v_and_b32_e32 v191, 0xffff0000, v249
	v_lshlrev_b32_e32 v198, 16, v250
	v_and_b32_e32 v199, 0xffff0000, v250
	v_pk_add_f32 v[38:39], v[38:39], v[196:197]
	v_lshlrev_b32_e32 v48, 16, v159
	v_fmac_f32_e32 v151, v45, v45
	v_lshlrev_b32_e32 v192, 16, v251
	v_and_b32_e32 v193, 0xffff0000, v251
	v_pk_add_f32 v[40:41], v[40:41], v[190:191]
	v_pk_add_f32 v[34:35], v[34:35], v[198:199]
	v_cvt_pk_bf16_f32 v190, v38, v39
	v_and_b32_e32 v49, 0xffff0000, v159
	v_fmac_f32_e32 v151, v48, v48
	v_pk_add_f32 v[36:37], v[36:37], v[192:193]
	v_cvt_pk_bf16_f32 v192, v34, v35
	v_lshlrev_b32_e32 v34, 16, v190
	v_max3_f32 v150, |v42|, 0, |v43|
	v_fmac_f32_e32 v151, v49, v49
	v_cvt_pk_bf16_f32 v191, v40, v41
	v_and_b32_e32 v35, 0xffff0000, v190
	v_max3_f32 v150, v150, |v46|, |v47|
	v_fmac_f32_e32 v151, v34, v34
	v_lshlrev_b32_e32 v38, 16, v191
	v_max3_f32 v150, v150, |v44|, |v45|
	v_fmac_f32_e32 v151, v35, v35
	v_and_b32_e32 v39, 0xffff0000, v191
	v_max3_f32 v150, v150, |v48|, |v49|
	v_fmac_f32_e32 v151, v38, v38
	v_cvt_pk_bf16_f32 v193, v36, v37
	v_lshlrev_b32_e32 v36, 16, v192
	v_max3_f32 v150, v150, |v34|, |v35|
	v_fmac_f32_e32 v151, v39, v39
	v_and_b32_e32 v37, 0xffff0000, v192
	v_max3_f32 v150, v150, |v38|, |v39|
	v_fmac_f32_e32 v151, v36, v36
	v_lshlrev_b32_e32 v40, 16, v193
	v_and_b32_e32 v41, 0xffff0000, v193
	v_max3_f32 v150, v150, |v36|, |v37|
	v_fmac_f32_e32 v151, v37, v37
	v_max3_f32 v150, v150, |v40|, |v41|
	v_fmac_f32_e32 v151, v40, v40
	ds_bpermute_b32 v154, v152, v150
	v_fmac_f32_e32 v151, v41, v41
	ds_bpermute_b32 v155, v152, v151
	global_store_dwordx4 v[194:195], v[156:159], off
	global_store_dwordx4 v[194:195], v[190:193], off offset:256
	s_waitcnt lgkmcnt(1)
	v_max_f32_e32 v154, v154, v154
	v_max_f32_e32 v150, v150, v154
	s_waitcnt lgkmcnt(0)
	v_add_f32_e32 v151, v151, v155
	ds_bpermute_b32 v154, v153, v151
	ds_bpermute_b32 v155, v153, v150
	s_and_saveexec_b64 s[48:49], s[4:5]
	s_cbranch_execz .LBB0_3244
	s_waitcnt lgkmcnt(1)
	v_add_f32_e32 v151, v151, v154
	s_waitcnt lgkmcnt(0)
	v_max_f32_e32 v154, v155, v155
	v_max_f32_e32 v150, v150, v150
	v_max_f32_e32 v150, v150, v154
	ds_write2st64_b32 v177, v151, v150 offset0:9 offset1:25
.LBB0_3244:
	s_or_b64 exec, exec, s[48:49]
	v_add_u32_e32 v150, 0xa0, v148
	v_ashrrev_i32_e32 v151, 31, v150
	v_lshlrev_b64 v[150:151], 11, v[150:151]
	v_lshl_add_u64 v[150:151], s[22:23], 0, v[150:151]
	v_lshl_add_u64 v[150:151], s[58:59], 1, v[150:151]
	v_lshl_add_u64 v[150:151], v[150:151], 0, s[14:15]
	v_lshl_add_u64 v[194:195], v[150:151], 0, v[0:1]
	s_waitcnt lgkmcnt(0)
	s_waitcnt vmcnt(13)
	v_lshlrev_b32_e32 v150, 16, v200
	v_and_b32_e32 v151, 0xffff0000, v200
	v_lshlrev_b32_e32 v158, 16, v202
	v_and_b32_e32 v159, 0xffff0000, v202
	v_lshlrev_b32_e32 v156, 16, v203
	v_and_b32_e32 v157, 0xffff0000, v203
	v_pk_add_f32 v[30:31], v[30:31], v[150:151]
	v_lshlrev_b32_e32 v154, 16, v201
	v_and_b32_e32 v155, 0xffff0000, v201
	v_pk_add_f32 v[26:27], v[26:27], v[158:159]
	v_pk_add_f32 v[28:29], v[28:29], v[156:157]
	v_cvt_pk_bf16_f32 v156, v30, v31
	v_pk_add_f32 v[32:33], v[32:33], v[154:155]
	v_cvt_pk_bf16_f32 v158, v26, v27
	v_and_b32_e32 v27, 0xffff0000, v156
	v_cvt_pk_bf16_f32 v157, v32, v33
	v_lshlrev_b32_e32 v26, 16, v156
	v_mul_f32_e32 v151, v27, v27
	v_lshlrev_b32_e32 v30, 16, v157
	v_fmac_f32_e32 v151, v26, v26
	v_and_b32_e32 v31, 0xffff0000, v157
	v_fmac_f32_e32 v151, v30, v30
	v_cvt_pk_bf16_f32 v159, v28, v29
	v_lshlrev_b32_e32 v28, 16, v158
	v_fmac_f32_e32 v151, v31, v31
	s_waitcnt vmcnt(12)
	v_lshlrev_b32_e32 v196, 16, v204
	v_and_b32_e32 v197, 0xffff0000, v204
	v_and_b32_e32 v29, 0xffff0000, v158
	v_fmac_f32_e32 v151, v28, v28
	v_lshlrev_b32_e32 v190, 16, v205
	v_and_b32_e32 v191, 0xffff0000, v205
	v_lshlrev_b32_e32 v198, 16, v206
	v_and_b32_e32 v199, 0xffff0000, v206
	v_pk_add_f32 v[22:23], v[22:23], v[196:197]
	v_lshlrev_b32_e32 v32, 16, v159
	v_fmac_f32_e32 v151, v29, v29
	v_lshlrev_b32_e32 v192, 16, v207
	v_and_b32_e32 v193, 0xffff0000, v207
	v_pk_add_f32 v[24:25], v[24:25], v[190:191]
	v_pk_add_f32 v[18:19], v[18:19], v[198:199]
	v_cvt_pk_bf16_f32 v190, v22, v23
	v_and_b32_e32 v33, 0xffff0000, v159
	v_fmac_f32_e32 v151, v32, v32
	v_pk_add_f32 v[20:21], v[20:21], v[192:193]
	v_cvt_pk_bf16_f32 v192, v18, v19
	v_lshlrev_b32_e32 v18, 16, v190
	v_max3_f32 v150, |v26|, 0, |v27|
	v_fmac_f32_e32 v151, v33, v33
	v_cvt_pk_bf16_f32 v191, v24, v25
	v_and_b32_e32 v19, 0xffff0000, v190
	v_max3_f32 v150, v150, |v30|, |v31|
	v_fmac_f32_e32 v151, v18, v18
	v_lshlrev_b32_e32 v22, 16, v191
	v_max3_f32 v150, v150, |v28|, |v29|
	v_fmac_f32_e32 v151, v19, v19
	v_and_b32_e32 v23, 0xffff0000, v191
	v_max3_f32 v150, v150, |v32|, |v33|
	v_fmac_f32_e32 v151, v22, v22
	v_cvt_pk_bf16_f32 v193, v20, v21
	v_lshlrev_b32_e32 v20, 16, v192
	v_max3_f32 v150, v150, |v18|, |v19|
	v_fmac_f32_e32 v151, v23, v23
	v_and_b32_e32 v21, 0xffff0000, v192
	v_max3_f32 v150, v150, |v22|, |v23|
	v_fmac_f32_e32 v151, v20, v20
	v_lshlrev_b32_e32 v24, 16, v193
	v_and_b32_e32 v25, 0xffff0000, v193
	v_max3_f32 v150, v150, |v20|, |v21|
	v_fmac_f32_e32 v151, v21, v21
	v_max3_f32 v150, v150, |v24|, |v25|
	v_fmac_f32_e32 v151, v24, v24
	ds_bpermute_b32 v154, v152, v150
	v_fmac_f32_e32 v151, v25, v25
	ds_bpermute_b32 v155, v152, v151
	global_store_dwordx4 v[194:195], v[156:159], off
	global_store_dwordx4 v[194:195], v[190:193], off offset:256
	s_waitcnt lgkmcnt(1)
	v_max_f32_e32 v154, v154, v154
	v_max_f32_e32 v150, v150, v154
	s_waitcnt lgkmcnt(0)
	v_add_f32_e32 v151, v151, v155
	ds_bpermute_b32 v154, v153, v151
	ds_bpermute_b32 v155, v153, v150
	s_and_saveexec_b64 s[48:49], s[4:5]
	s_cbranch_execz .LBB0_3246
	s_waitcnt lgkmcnt(1)
	v_add_f32_e32 v151, v151, v154
	s_waitcnt lgkmcnt(0)
	v_max_f32_e32 v154, v155, v155
	v_max_f32_e32 v150, v150, v150
	v_max_f32_e32 v150, v150, v154
	ds_write2st64_b32 v177, v151, v150 offset0:10 offset1:26
.LBB0_3246:
	s_or_b64 exec, exec, s[48:49]
	v_add_u32_e32 v150, 0xb0, v148
	v_ashrrev_i32_e32 v151, 31, v150
	v_lshlrev_b64 v[150:151], 11, v[150:151]
	v_lshl_add_u64 v[150:151], s[22:23], 0, v[150:151]
	v_lshl_add_u64 v[150:151], s[58:59], 1, v[150:151]
	v_lshl_add_u64 v[150:151], v[150:151], 0, s[14:15]
	v_lshl_add_u64 v[158:159], v[150:151], 0, v[0:1]
	s_waitcnt lgkmcnt(0)
	s_waitcnt vmcnt(11)
	v_lshlrev_b32_e32 v150, 16, v208
	v_and_b32_e32 v151, 0xffff0000, v208
	v_lshlrev_b32_e32 v154, 16, v209
	v_and_b32_e32 v155, 0xffff0000, v209
	v_pk_add_f32 v[14:15], v[14:15], v[150:151]
	s_waitcnt vmcnt(10)
	v_lshlrev_b32_e32 v198, 16, v214
	v_and_b32_e32 v199, 0xffff0000, v214
	v_pk_add_f32 v[16:17], v[16:17], v[154:155]
	v_cvt_pk_bf16_f32 v154, v14, v15
	v_lshlrev_b32_e32 v192, 16, v215
	v_and_b32_e32 v193, 0xffff0000, v215
	v_pk_add_f32 v[2:3], v[2:3], v[198:199]
	v_and_b32_e32 v15, 0xffff0000, v154
	v_lshlrev_b32_e32 v194, 16, v210
	v_and_b32_e32 v195, 0xffff0000, v210
	v_pk_add_f32 v[4:5], v[4:5], v[192:193]
	v_cvt_pk_bf16_f32 v155, v16, v17
	v_cvt_pk_bf16_f32 v192, v2, v3
	v_lshlrev_b32_e32 v14, 16, v154
	v_mul_f32_e32 v2, v15, v15
	v_lshlrev_b32_e32 v156, 16, v211
	v_and_b32_e32 v157, 0xffff0000, v211
	v_pk_add_f32 v[10:11], v[10:11], v[194:195]
	v_lshlrev_b32_e32 v150, 16, v155
	v_fmac_f32_e32 v2, v14, v14
	v_pk_add_f32 v[12:13], v[12:13], v[156:157]
	v_cvt_pk_bf16_f32 v156, v10, v11
	v_and_b32_e32 v151, 0xffff0000, v155
	v_fmac_f32_e32 v2, v150, v150
	v_cvt_pk_bf16_f32 v157, v12, v13
	v_lshlrev_b32_e32 v12, 16, v156
	v_fmac_f32_e32 v2, v151, v151
	v_lshlrev_b32_e32 v196, 16, v212
	v_and_b32_e32 v197, 0xffff0000, v212
	v_and_b32_e32 v13, 0xffff0000, v156
	v_fmac_f32_e32 v2, v12, v12
	v_lshlrev_b32_e32 v190, 16, v213
	v_and_b32_e32 v191, 0xffff0000, v213
	v_pk_add_f32 v[6:7], v[6:7], v[196:197]
	v_lshlrev_b32_e32 v16, 16, v157
	v_fmac_f32_e32 v2, v13, v13
	v_pk_add_f32 v[8:9], v[8:9], v[190:191]
	v_cvt_pk_bf16_f32 v190, v6, v7
	v_and_b32_e32 v17, 0xffff0000, v157
	v_fmac_f32_e32 v2, v16, v16
	v_lshlrev_b32_e32 v6, 16, v190
	v_max3_f32 v0, |v14|, 0, |v15|
	v_fmac_f32_e32 v2, v17, v17
	v_cvt_pk_bf16_f32 v191, v8, v9
	v_and_b32_e32 v7, 0xffff0000, v190
	v_max3_f32 v0, v0, |v150|, |v151|
	v_fmac_f32_e32 v2, v6, v6
	v_lshlrev_b32_e32 v10, 16, v191
	v_max3_f32 v0, v0, |v12|, |v13|
	v_fmac_f32_e32 v2, v7, v7
	v_and_b32_e32 v11, 0xffff0000, v191
	v_max3_f32 v0, v0, |v16|, |v17|
	v_fmac_f32_e32 v2, v10, v10
	v_cvt_pk_bf16_f32 v193, v4, v5
	v_lshlrev_b32_e32 v4, 16, v192
	v_max3_f32 v0, v0, |v6|, |v7|
	v_fmac_f32_e32 v2, v11, v11
	v_and_b32_e32 v5, 0xffff0000, v192
	v_max3_f32 v0, v0, |v10|, |v11|
	v_fmac_f32_e32 v2, v4, v4
	v_lshlrev_b32_e32 v8, 16, v193
	v_and_b32_e32 v9, 0xffff0000, v193
	v_max3_f32 v0, v0, |v4|, |v5|
	v_fmac_f32_e32 v2, v5, v5
	v_max3_f32 v0, v0, |v8|, |v9|
	v_fmac_f32_e32 v2, v8, v8
	ds_bpermute_b32 v3, v152, v0
	v_fmac_f32_e32 v2, v9, v9
	ds_bpermute_b32 v152, v152, v2
	global_store_dwordx4 v[158:159], v[154:157], off
	global_store_dwordx4 v[158:159], v[190:193], off offset:256
	s_waitcnt lgkmcnt(1)
	v_max_f32_e32 v3, v3, v3
	v_max_f32_e32 v0, v0, v3
	s_waitcnt lgkmcnt(0)
	v_add_f32_e32 v2, v2, v152
	ds_bpermute_b32 v3, v153, v2
	ds_bpermute_b32 v152, v153, v0
	s_and_saveexec_b64 s[48:49], s[4:5]
	s_cbranch_execz .LBB0_3248
	s_waitcnt lgkmcnt(1)
	v_add_f32_e32 v2, v2, v3
	s_waitcnt lgkmcnt(0)
	v_max_f32_e32 v3, v152, v152
	v_max_f32_e32 v0, v0, v0
	v_max_f32_e32 v0, v0, v3
	ds_write2st64_b32 v177, v2, v0 offset0:11 offset1:27
